# GEMM K-loops: remaining scalar ops between MFMA blocks and barriers moved behind the barrier; loop compare hoisted above the last MFMA block
# baseline (speedup 1.0000x reference)
; #define PG8_STAGE(bufoff, gbase, voff) do { _Pragma("unroll") for (int _i = 0; _i < 2; ++_i) \
;         __builtin_amdgcn_global_load_lds((const unsigned*)((const char*)(gbase) + (voff)[_i]), (PG8_LAS unsigned*)(lds + (bufoff) + ldsw + _i * 8192), 16, 0, 0); } while (0)
; #define PG8_LDA(dst, b, h) do { _Pragma("unroll") for (int m = 0; m < 4; ++m) _Pragma("unroll") for (int k = 0; k < 2; ++k) dst[m][k] = *(const PG8_LAS bf16x8*)(lds + PG8_SA(b, h) + aoff + m * 2048 + k * 1024); } while (0)
; #define PG8_LDB(dst, b, h) do { _Pragma("unroll") for (int n = 0; n < 2; ++n) _Pragma("unroll") for (int k = 0; k < 2; ++k) dst[n][k] = *(const PG8_LAS bf16x8*)(lds + PG8_SB(b, h) + boff + n * 2048 + k * 1024); } while (0)
; #define PG8_MMA(ai, bj, At, Bt) do { __builtin_amdgcn_s_setprio(1); _Pragma("unroll") for (int m = 0; m < 4; ++m) _Pragma("unroll") for (int n = 0; n < 2; ++n) _Pragma("unroll") for (int k = 0; k < 2; ++k) \
;         acc[ai][bj][m][n] = __builtin_amdgcn_mfma_f32_16x16x32_bf16(Bt[n][k], At[m][k], acc[ai][bj][m][n], 0, 0, 0); __builtin_amdgcn_s_setprio(0); } while (0)
; #define PG8_BAR __builtin_amdgcn_s_barrier()
; template <class Epi, class Sched, bool STAMP = false>
; __device__ __forceinline__ void gemm_phase(PG8_LAS unsigned char* lds, const Gemm g, const Sched& S, const Epi& E, unsigned long long* stamps) {
;     ...
;         for (int t = 0; t < nt; t += 2) {
;             const bool last = (t == nt - 2);
;             const char* a1 = cA + (size_t)(t + 1) * kstep;
;             const char* a2 = last ? nA : cA + (size_t)(t + 2) * kstep; const char* b2 = last ? nB : cB + (size_t)(t + 2) * kstep;
;             const char* a3 = a2 + kstep; const char* b3 = b2 + kstep;
;             if (last && has_next) S.a_ready(nxt);
;             PG8_LDB(B0, 0, 0); PG8_SCHED; PG8_LDA(At, 0, 0); PG8_STAGE(PG8_SA(1, 1), a1 + hstep, voffA);
;             PG8_WAIT_L(8); PG8_BAR; PG8_WAIT_L(0); PG8_MMA(0, 0, At, B0); PG8_BAR; PG8_SCHED;
;             PG8_LDB(B1, 0, 1); PG8_STAGE(PG8_SB(0, 0), b2, voffB);
;             PG8_BAR; PG8_WAIT_L(0); PG8_MMA(0, 1, At, B1); PG8_BAR;
;             PG8_LDA(At, 0, 1); PG8_STAGE(PG8_SA(0, 0), a2, voffA);
;             PG8_BAR; PG8_WAIT_L(0); PG8_MMA(1, 0, At, B0); PG8_BAR; PG8_SCHED;
;             PG8_STAGE(PG8_SB(0, 1), b2 + hstep, voffB);
;             PG8_WAIT_V(6); PG8_BAR; PG8_MMA(1, 1, At, B1); PG8_BAR;
.LBB0_44:
	s_add_u32 s14, s24, 0xfffc0080
	s_addc_u32 s15, s25, -1
	s_add_i32 s16, 0, 0x10000
	ds_read_b128 v[158:161], v248
	ds_read_b128 v[162:165], v248 offset:1024
	ds_read_b128 v[170:173], v248 offset:2048
	ds_read_b128 v[174:177], v248 offset:3072
	s_cmp_eq_u32 s61, 12
	s_cselect_b32 s31, s7, s15
	s_cselect_b32 s30, s57, s14
	s_cselect_b32 s27, s5, s60
	s_cselect_b32 s26, s58, s59
	s_add_i32 m0, s23, 0xc000
	ds_read_b128 v[178:181], v168
	ds_read_b128 v[192:195], v168 offset:1024
	ds_read_b128 v[196:199], v168 offset:2048
	ds_read_b128 v[200:203], v168 offset:3072
	ds_read_b128 v[204:207], v168 offset:4096
	ds_read_b128 v[208:211], v168 offset:5120
	ds_read_b128 v[212:215], v168 offset:6144
	global_load_lds_dwordx4 v154, s[24:25]
	s_add_i32 m0, s23, 0xe000
	ds_read_b128 v[216:219], v168 offset:7168
	global_load_lds_dwordx4 v156, s[24:25]
	s_waitcnt lgkmcnt(8)
	s_barrier
	s_waitcnt lgkmcnt(0)
	v_mfma_f32_16x16x32_bf16 v[124:127], v[158:161], v[178:181], v[124:127]
	v_mfma_f32_16x16x32_bf16 v[120:123], v[170:173], v[178:181], v[120:123]
	v_mfma_f32_16x16x32_bf16 v[108:111], v[158:161], v[196:199], v[108:111]
	v_mfma_f32_16x16x32_bf16 v[104:107], v[170:173], v[196:199], v[104:107]
	v_mfma_f32_16x16x32_bf16 v[92:95], v[158:161], v[204:207], v[92:95]
	v_mfma_f32_16x16x32_bf16 v[88:91], v[170:173], v[204:207], v[88:91]
	v_mfma_f32_16x16x32_bf16 v[76:79], v[158:161], v[212:215], v[76:79]
	v_mfma_f32_16x16x32_bf16 v[72:75], v[170:173], v[212:215], v[72:75]
	v_mfma_f32_16x16x32_bf16 v[124:127], v[162:165], v[192:195], v[124:127]
	v_mfma_f32_16x16x32_bf16 v[120:123], v[174:177], v[192:195], v[120:123]
	v_mfma_f32_16x16x32_bf16 v[108:111], v[162:165], v[200:203], v[108:111]
	v_mfma_f32_16x16x32_bf16 v[104:107], v[174:177], v[200:203], v[104:107]
	v_mfma_f32_16x16x32_bf16 v[92:95], v[162:165], v[208:211], v[92:95]
	v_mfma_f32_16x16x32_bf16 v[88:91], v[174:177], v[208:211], v[88:91]
	v_mfma_f32_16x16x32_bf16 v[76:79], v[162:165], v[216:219], v[76:79]
	v_mfma_f32_16x16x32_bf16 v[72:75], v[174:177], v[216:219], v[72:75]
	s_barrier
	s_add_i32 s17, 0, 0x14000
	s_add_i32 s14, s16, s43
	s_mov_b32 m0, s14
	ds_read_b128 v[220:223], v249
	ds_read_b128 v[224:227], v249 offset:1024
	ds_read_b128 v[228:231], v249 offset:2048
	global_load_lds_dwordx4 v128, s[26:27]
	s_add_i32 m0, s14, 0x2000
	ds_read_b128 v[232:235], v249 offset:3072
	global_load_lds_dwordx4 v148, s[26:27]
	s_barrier
	s_waitcnt lgkmcnt(0)
	v_mfma_f32_16x16x32_bf16 v[116:119], v[220:223], v[178:181], v[116:119]
	v_mfma_f32_16x16x32_bf16 v[112:115], v[228:231], v[178:181], v[112:115]
	v_mfma_f32_16x16x32_bf16 v[100:103], v[220:223], v[196:199], v[100:103]
	v_mfma_f32_16x16x32_bf16 v[96:99], v[228:231], v[196:199], v[96:99]
	v_mfma_f32_16x16x32_bf16 v[84:87], v[220:223], v[204:207], v[84:87]
	v_mfma_f32_16x16x32_bf16 v[80:83], v[228:231], v[204:207], v[80:83]
	v_mfma_f32_16x16x32_bf16 v[68:71], v[220:223], v[212:215], v[68:71]
	v_mfma_f32_16x16x32_bf16 v[64:67], v[228:231], v[212:215], v[64:67]
	v_mfma_f32_16x16x32_bf16 v[116:119], v[224:227], v[192:195], v[116:119]
	v_mfma_f32_16x16x32_bf16 v[112:115], v[232:235], v[192:195], v[112:115]
	v_mfma_f32_16x16x32_bf16 v[100:103], v[224:227], v[200:203], v[100:103]
	v_mfma_f32_16x16x32_bf16 v[96:99], v[232:235], v[200:203], v[96:99]
	v_mfma_f32_16x16x32_bf16 v[84:87], v[224:227], v[208:211], v[84:87]
	v_mfma_f32_16x16x32_bf16 v[80:83], v[232:235], v[208:211], v[80:83]
	v_mfma_f32_16x16x32_bf16 v[68:71], v[224:227], v[216:219], v[68:71]
	v_mfma_f32_16x16x32_bf16 v[64:67], v[232:235], v[216:219], v[64:67]
	s_barrier
	s_mov_b32 m0, s23
	ds_read_b128 v[178:181], v168 offset:16384
	ds_read_b128 v[192:195], v168 offset:17408
	ds_read_b128 v[196:199], v168 offset:18432
	ds_read_b128 v[200:203], v168 offset:19456
	ds_read_b128 v[204:207], v168 offset:20480
	ds_read_b128 v[208:211], v168 offset:21504
	ds_read_b128 v[212:215], v168 offset:22528
	global_load_lds_dwordx4 v152, s[30:31]
	s_mov_b32 m0, s45
	ds_read_b128 v[216:219], v168 offset:23552
	global_load_lds_dwordx4 v150, s[30:31]
	s_barrier
	s_waitcnt lgkmcnt(0)
	v_mfma_f32_16x16x32_bf16 v[60:63], v[158:161], v[178:181], v[60:63]
	v_mfma_f32_16x16x32_bf16 v[56:59], v[170:173], v[178:181], v[56:59]
	v_mfma_f32_16x16x32_bf16 v[44:47], v[158:161], v[196:199], v[44:47]
	v_mfma_f32_16x16x32_bf16 v[40:43], v[170:173], v[196:199], v[40:43]
	v_mfma_f32_16x16x32_bf16 v[28:31], v[158:161], v[204:207], v[28:31]
	v_mfma_f32_16x16x32_bf16 v[24:27], v[170:173], v[204:207], v[24:27]
	v_mfma_f32_16x16x32_bf16 v[12:15], v[158:161], v[212:215], v[12:15]
	v_mfma_f32_16x16x32_bf16 v[8:11], v[170:173], v[212:215], v[8:11]
	v_mfma_f32_16x16x32_bf16 v[60:63], v[162:165], v[192:195], v[60:63]
	v_mfma_f32_16x16x32_bf16 v[56:59], v[174:177], v[192:195], v[56:59]
	v_mfma_f32_16x16x32_bf16 v[44:47], v[162:165], v[200:203], v[44:47]
	v_mfma_f32_16x16x32_bf16 v[40:43], v[174:177], v[200:203], v[40:43]
	v_mfma_f32_16x16x32_bf16 v[28:31], v[162:165], v[208:211], v[28:31]
	v_mfma_f32_16x16x32_bf16 v[24:27], v[174:177], v[208:211], v[24:27]
	v_mfma_f32_16x16x32_bf16 v[12:15], v[162:165], v[216:219], v[12:15]
	v_mfma_f32_16x16x32_bf16 v[8:11], v[174:177], v[216:219], v[8:11]
	s_barrier
	s_add_u32 s14, s26, 0x40000
	s_addc_u32 s15, s27, 0
	s_add_i32 s16, s17, s43
	s_mov_b32 m0, s16
	s_nop 0
	global_load_lds_dwordx4 v128, s[14:15]
	s_add_i32 m0, s16, 0x2000
	s_nop 0
	global_load_lds_dwordx4 v148, s[14:15]
	s_add_i32 s61, s61, 2
	s_add_u32 s24, s24, 0x100
	s_addc_u32 s25, s25, 0
	s_add_u32 s59, s59, 0x100
	s_addc_u32 s60, s60, 0
	s_waitcnt vmcnt(6)
	s_barrier
; #define PG8_STAGE(bufoff, gbase, voff) do { _Pragma("unroll") for (int _i = 0; _i < 2; ++_i) \
;         __builtin_amdgcn_global_load_lds((const unsigned*)((const char*)(gbase) + (voff)[_i]), (PG8_LAS unsigned*)(lds + (bufoff) + ldsw + _i * 8192), 16, 0, 0); } while (0)
; #define PG8_LDA(dst, b, h) do { _Pragma("unroll") for (int m = 0; m < 4; ++m) _Pragma("unroll") for (int k = 0; k < 2; ++k) dst[m][k] = *(const PG8_LAS bf16x8*)(lds + PG8_SA(b, h) + aoff + m * 2048 + k * 1024); } while (0)
; #define PG8_LDB(dst, b, h) do { _Pragma("unroll") for (int n = 0; n < 2; ++n) _Pragma("unroll") for (int k = 0; k < 2; ++k) dst[n][k] = *(const PG8_LAS bf16x8*)(lds + PG8_SB(b, h) + boff + n * 2048 + k * 1024); } while (0)
; #define PG8_MMA(ai, bj, At, Bt) do { __builtin_amdgcn_s_setprio(1); _Pragma("unroll") for (int m = 0; m < 4; ++m) _Pragma("unroll") for (int n = 0; n < 2; ++n) _Pragma("unroll") for (int k = 0; k < 2; ++k) \
;         acc[ai][bj][m][n] = __builtin_amdgcn_mfma_f32_16x16x32_bf16(Bt[n][k], At[m][k], acc[ai][bj][m][n], 0, 0, 0); __builtin_amdgcn_s_setprio(0); } while (0)
; #define PG8_WAIT_V(n) asm volatile("s_waitcnt vmcnt(" #n ")" ::: "memory")
; #define PG8_WAIT_L(n) asm volatile("s_waitcnt lgkmcnt(" #n ")" ::: "memory")
; #define PG8_BAR __builtin_amdgcn_s_barrier()
; #define PG8_SCHED __builtin_amdgcn_sched_barrier(0)
; template <class Epi, class Sched, bool STAMP = false>
; __device__ __forceinline__ void gemm_phase(PG8_LAS unsigned char* lds, const Gemm g, const Sched& S, const Epi& E, unsigned long long* stamps) {
;     ...
;             PG8_WAIT_V(6); PG8_BAR; PG8_MMA(1, 1, At, B1); PG8_BAR;
;             PG8_LDB(B0, 1, 0); PG8_SCHED; PG8_LDA(At, 1, 0); PG8_STAGE(PG8_SA(0, 1), a2 + hstep, voffA);
;             PG8_WAIT_L(8); PG8_BAR; PG8_WAIT_L(0); PG8_MMA(0, 0, At, B0); PG8_BAR; PG8_SCHED;
;             PG8_LDB(B1, 1, 1); PG8_STAGE(PG8_SB(1, 0), b3, voffB);
;             PG8_BAR; PG8_WAIT_L(0); PG8_MMA(0, 1, At, B1); PG8_BAR;
;             PG8_LDA(At, 1, 1); PG8_STAGE(PG8_SA(1, 0), a3, voffA);
;             PG8_BAR; PG8_WAIT_L(0); PG8_MMA(1, 0, At, B0); PG8_BAR; PG8_SCHED;
	v_mfma_f32_16x16x32_bf16 v[52:55], v[220:223], v[178:181], v[52:55]
	v_mfma_f32_16x16x32_bf16 v[48:51], v[228:231], v[178:181], v[48:51]
	v_mfma_f32_16x16x32_bf16 v[36:39], v[220:223], v[196:199], v[36:39]
	v_mfma_f32_16x16x32_bf16 v[32:35], v[228:231], v[196:199], v[32:35]
	v_mfma_f32_16x16x32_bf16 v[20:23], v[220:223], v[204:207], v[20:23]
	v_mfma_f32_16x16x32_bf16 v[16:19], v[228:231], v[204:207], v[16:19]
	v_mfma_f32_16x16x32_bf16 v[4:7], v[220:223], v[212:215], v[4:7]
	v_mfma_f32_16x16x32_bf16 v[0:3], v[228:231], v[212:215], v[0:3]
	v_mfma_f32_16x16x32_bf16 v[52:55], v[224:227], v[192:195], v[52:55]
	v_mfma_f32_16x16x32_bf16 v[48:51], v[232:235], v[192:195], v[48:51]
	v_mfma_f32_16x16x32_bf16 v[36:39], v[224:227], v[200:203], v[36:39]
	v_mfma_f32_16x16x32_bf16 v[32:35], v[232:235], v[200:203], v[32:35]
	v_mfma_f32_16x16x32_bf16 v[20:23], v[224:227], v[208:211], v[20:23]
	v_mfma_f32_16x16x32_bf16 v[16:19], v[232:235], v[208:211], v[16:19]
	v_mfma_f32_16x16x32_bf16 v[4:7], v[224:227], v[216:219], v[4:7]
	v_mfma_f32_16x16x32_bf16 v[0:3], v[232:235], v[216:219], v[0:3]
	s_barrier
	s_add_i32 s16, 0, 0x18000
	ds_read_b128 v[158:161], v250
	ds_read_b128 v[162:165], v250 offset:1024
	ds_read_b128 v[170:173], v250 offset:2048
	ds_read_b128 v[174:177], v250 offset:3072
	s_add_u32 s14, s30, 0x40000
	s_addc_u32 s15, s31, 0
	s_mov_b32 m0, s46
	ds_read_b128 v[178:181], v168 offset:32768
	ds_read_b128 v[192:195], v168 offset:33792
	ds_read_b128 v[196:199], v168 offset:34816
	ds_read_b128 v[200:203], v168 offset:35840
	ds_read_b128 v[204:207], v168 offset:36864
	ds_read_b128 v[208:211], v168 offset:37888
	ds_read_b128 v[212:215], v168 offset:38912
	global_load_lds_dwordx4 v152, s[14:15]
	s_mov_b32 m0, s47
	ds_read_b128 v[216:219], v168 offset:39936
	global_load_lds_dwordx4 v150, s[14:15]
	s_waitcnt lgkmcnt(8)
	s_barrier
	s_waitcnt lgkmcnt(0)
	v_mfma_f32_16x16x32_bf16 v[124:127], v[158:161], v[178:181], v[124:127]
	v_mfma_f32_16x16x32_bf16 v[120:123], v[170:173], v[178:181], v[120:123]
	v_mfma_f32_16x16x32_bf16 v[108:111], v[158:161], v[196:199], v[108:111]
	v_mfma_f32_16x16x32_bf16 v[104:107], v[170:173], v[196:199], v[104:107]
	v_mfma_f32_16x16x32_bf16 v[92:95], v[158:161], v[204:207], v[92:95]
	v_mfma_f32_16x16x32_bf16 v[88:91], v[170:173], v[204:207], v[88:91]
	v_mfma_f32_16x16x32_bf16 v[76:79], v[158:161], v[212:215], v[76:79]
	v_mfma_f32_16x16x32_bf16 v[72:75], v[170:173], v[212:215], v[72:75]
	v_mfma_f32_16x16x32_bf16 v[124:127], v[162:165], v[192:195], v[124:127]
	v_mfma_f32_16x16x32_bf16 v[120:123], v[174:177], v[192:195], v[120:123]
	v_mfma_f32_16x16x32_bf16 v[108:111], v[162:165], v[200:203], v[108:111]
	v_mfma_f32_16x16x32_bf16 v[104:107], v[174:177], v[200:203], v[104:107]
	v_mfma_f32_16x16x32_bf16 v[92:95], v[162:165], v[208:211], v[92:95]
	v_mfma_f32_16x16x32_bf16 v[88:91], v[174:177], v[208:211], v[88:91]
	v_mfma_f32_16x16x32_bf16 v[76:79], v[162:165], v[216:219], v[76:79]
	v_mfma_f32_16x16x32_bf16 v[72:75], v[174:177], v[216:219], v[72:75]
	s_barrier
	s_add_i32 s17, 0, 0x1c000
	s_add_i32 s14, s16, s43
	s_mov_b32 m0, s14
	ds_read_b128 v[220:223], v251
	ds_read_b128 v[224:227], v251 offset:1024
	ds_read_b128 v[228:231], v251 offset:2048
	global_load_lds_dwordx4 v244, s[26:27]
	s_add_i32 m0, s14, 0x2000
	ds_read_b128 v[232:235], v251 offset:3072
	global_load_lds_dwordx4 v245, s[26:27]
	s_barrier
	s_waitcnt lgkmcnt(0)
	v_mfma_f32_16x16x32_bf16 v[116:119], v[220:223], v[178:181], v[116:119]
	v_mfma_f32_16x16x32_bf16 v[112:115], v[228:231], v[178:181], v[112:115]
	v_mfma_f32_16x16x32_bf16 v[100:103], v[220:223], v[196:199], v[100:103]
	v_mfma_f32_16x16x32_bf16 v[96:99], v[228:231], v[196:199], v[96:99]
	v_mfma_f32_16x16x32_bf16 v[84:87], v[220:223], v[204:207], v[84:87]
	v_mfma_f32_16x16x32_bf16 v[80:83], v[228:231], v[204:207], v[80:83]
	v_mfma_f32_16x16x32_bf16 v[68:71], v[220:223], v[212:215], v[68:71]
	v_mfma_f32_16x16x32_bf16 v[64:67], v[228:231], v[212:215], v[64:67]
	v_mfma_f32_16x16x32_bf16 v[116:119], v[224:227], v[192:195], v[116:119]
	v_mfma_f32_16x16x32_bf16 v[112:115], v[232:235], v[192:195], v[112:115]
	v_mfma_f32_16x16x32_bf16 v[100:103], v[224:227], v[200:203], v[100:103]
	v_mfma_f32_16x16x32_bf16 v[96:99], v[232:235], v[200:203], v[96:99]
	v_mfma_f32_16x16x32_bf16 v[84:87], v[224:227], v[208:211], v[84:87]
	v_mfma_f32_16x16x32_bf16 v[80:83], v[232:235], v[208:211], v[80:83]
	v_mfma_f32_16x16x32_bf16 v[68:71], v[224:227], v[216:219], v[68:71]
	v_mfma_f32_16x16x32_bf16 v[64:67], v[232:235], v[216:219], v[64:67]
	s_barrier
	s_mov_b32 m0, s49
	ds_read_b128 v[178:181], v168 offset:49152
	ds_read_b128 v[192:195], v168 offset:50176
	ds_read_b128 v[196:199], v168 offset:51200
	ds_read_b128 v[200:203], v168 offset:52224
	ds_read_b128 v[204:207], v168 offset:53248
	ds_read_b128 v[208:211], v168 offset:54272
	ds_read_b128 v[212:215], v168 offset:55296
	global_load_lds_dwordx4 v246, s[30:31]
	s_mov_b32 m0, s53
	ds_read_b128 v[216:219], v168 offset:56320
	global_load_lds_dwordx4 v247, s[30:31]
	s_barrier
	s_waitcnt lgkmcnt(0)
	v_mfma_f32_16x16x32_bf16 v[60:63], v[158:161], v[178:181], v[60:63]
	v_mfma_f32_16x16x32_bf16 v[56:59], v[170:173], v[178:181], v[56:59]
	v_mfma_f32_16x16x32_bf16 v[44:47], v[158:161], v[196:199], v[44:47]
	v_mfma_f32_16x16x32_bf16 v[40:43], v[170:173], v[196:199], v[40:43]
	v_mfma_f32_16x16x32_bf16 v[28:31], v[158:161], v[204:207], v[28:31]
	v_mfma_f32_16x16x32_bf16 v[24:27], v[170:173], v[204:207], v[24:27]
	v_mfma_f32_16x16x32_bf16 v[12:15], v[158:161], v[212:215], v[12:15]
	v_mfma_f32_16x16x32_bf16 v[8:11], v[170:173], v[212:215], v[8:11]
	v_mfma_f32_16x16x32_bf16 v[60:63], v[162:165], v[192:195], v[60:63]
	v_mfma_f32_16x16x32_bf16 v[56:59], v[174:177], v[192:195], v[56:59]
	v_mfma_f32_16x16x32_bf16 v[44:47], v[162:165], v[200:203], v[44:47]
	v_mfma_f32_16x16x32_bf16 v[40:43], v[174:177], v[200:203], v[40:43]
	v_mfma_f32_16x16x32_bf16 v[28:31], v[162:165], v[208:211], v[28:31]
	v_mfma_f32_16x16x32_bf16 v[24:27], v[174:177], v[208:211], v[24:27]
	v_mfma_f32_16x16x32_bf16 v[12:15], v[162:165], v[216:219], v[12:15]
	v_mfma_f32_16x16x32_bf16 v[8:11], v[174:177], v[216:219], v[8:11]
	s_barrier
; __device__ __forceinline__ unsigned cvt_pk_bf16(float lo, float hi) { const f32x2_cv v = {lo, hi}; const bf16x2_cv b = __builtin_convertvector(v, bf16x2_cv); return __builtin_bit_cast(unsigned, b); }
; #define PG8_STAGE(bufoff, gbase, voff) do { _Pragma("unroll") for (int _i = 0; _i < 2; ++_i) \
;         __builtin_amdgcn_global_load_lds((const unsigned*)((const char*)(gbase) + (voff)[_i]), (PG8_LAS unsigned*)(lds + (bufoff) + ldsw + _i * 8192), 16, 0, 0); } while (0)
; #define PG8_MMA(ai, bj, At, Bt) do { __builtin_amdgcn_s_setprio(1); _Pragma("unroll") for (int m = 0; m < 4; ++m) _Pragma("unroll") for (int n = 0; n < 2; ++n) _Pragma("unroll") for (int k = 0; k < 2; ++k) \
;         acc[ai][bj][m][n] = __builtin_amdgcn_mfma_f32_16x16x32_bf16(Bt[n][k], At[m][k], acc[ai][bj][m][n], 0, 0, 0); __builtin_amdgcn_s_setprio(0); } while (0)
; #define PG8_WAIT_V(n) asm volatile("s_waitcnt vmcnt(" #n ")" ::: "memory")
; template <class Epi, class Sched, bool STAMP = false>
; __device__ __forceinline__ void gemm_phase(PG8_LAS unsigned char* lds, const Gemm g, const Sched& S, const Epi& E, unsigned long long* stamps) {
;     ...
;             PG8_STAGE(PG8_SB(1, 1), b3 + hstep, voffB);
;             PG8_WAIT_V(6); PG8_BAR; PG8_MMA(1, 1, At, B1); PG8_BAR;
;     __device__ __forceinline__ void operator()(const f32x4 (&acc)[2][2][4][2], const pg8::Unit& u, int wr, int wc, int fr, int fq) const {
;         const int row0 = u.pm * 256 + wr * 64 + fr, col0 = u.pn * 256 + wc * 32 + 8 * fq;
; #pragma unroll
;         for (int ai = 0; ai < 2; ++ai)
; #pragma unroll
;             for (int m = 0; m < 4; ++m) {
;                 const int row = row0 + ai * 128 + m * 16;
;                 const float s = (MODE == 2) ? 1.0f : rstd_of(rowss, row);
;                 bf16_t* rowp = O + (size_t)row * ldc + col0;
; #pragma unroll
;                 for (int bj = 0; bj < 2; ++bj) {
;                     f32x4 v0 = acc[ai][bj][m][0] * s, v1 = acc[ai][bj][m][1] * s;
;                     if (MODE == 1) {
; #pragma unroll
;                         for (int j = 0; j < 4; ++j) { const float a = fmaxf(v0[j], 0.f), b = fmaxf(v1[j], 0.f); v0[j] = a * a; v1[j] = b * b; } }
;                     u32x4 w; w.x = cvt_pk_bf16(v0[0], v0[1]); w.y = cvt_pk_bf16(v0[2], v0[3]); w.z = cvt_pk_bf16(v1[0], v1[1]); w.w = cvt_pk_bf16(v1[2], v1[3]);
;                     *(u32x4*)(rowp + bj * 128) = w; } }
	s_add_u32 s14, s26, 0x40080
	s_addc_u32 s15, s27, 0
	s_add_i32 s16, s17, s43
	s_mov_b32 m0, s16
	s_nop 0
	global_load_lds_dwordx4 v128, s[14:15]
	s_add_i32 m0, s16, 0x2000
	s_nop 0
	global_load_lds_dwordx4 v148, s[14:15]
	s_waitcnt vmcnt(6)
	s_barrier
	s_cmp_gt_u32 s61, 13
	v_mfma_f32_16x16x32_bf16 v[52:55], v[220:223], v[178:181], v[52:55]
	v_mfma_f32_16x16x32_bf16 v[48:51], v[228:231], v[178:181], v[48:51]
	v_mfma_f32_16x16x32_bf16 v[36:39], v[220:223], v[196:199], v[36:39]
	v_mfma_f32_16x16x32_bf16 v[32:35], v[228:231], v[196:199], v[32:35]
	v_mfma_f32_16x16x32_bf16 v[20:23], v[220:223], v[204:207], v[20:23]
	v_mfma_f32_16x16x32_bf16 v[16:19], v[228:231], v[204:207], v[16:19]
	v_mfma_f32_16x16x32_bf16 v[4:7], v[220:223], v[212:215], v[4:7]
	v_mfma_f32_16x16x32_bf16 v[0:3], v[228:231], v[212:215], v[0:3]
	v_mfma_f32_16x16x32_bf16 v[52:55], v[224:227], v[192:195], v[52:55]
	v_mfma_f32_16x16x32_bf16 v[48:51], v[232:235], v[192:195], v[48:51]
	v_mfma_f32_16x16x32_bf16 v[36:39], v[224:227], v[200:203], v[36:39]
	v_mfma_f32_16x16x32_bf16 v[32:35], v[232:235], v[200:203], v[32:35]
	v_mfma_f32_16x16x32_bf16 v[20:23], v[224:227], v[208:211], v[20:23]
	v_mfma_f32_16x16x32_bf16 v[16:19], v[232:235], v[208:211], v[16:19]
	v_mfma_f32_16x16x32_bf16 v[4:7], v[224:227], v[216:219], v[4:7]
	v_mfma_f32_16x16x32_bf16 v[0:3], v[232:235], v[216:219], v[0:3]
	s_barrier
	s_cbranch_scc0 .LBB0_44
	v_lshl_add_u32 v162, s22, 8, v139
	v_ashrrev_i32_e32 v163, 31, v162
	v_lshl_add_u64 v[158:159], v[162:163], 2, s[0:1]
	global_load_dword v164, v[158:159], off
	global_load_dword v193, v[158:159], off offset:64
	global_load_dword v194, v[158:159], off offset:128
	global_load_dword v195, v[158:159], off offset:192
	global_load_dword v196, v[158:159], off offset:512
	global_load_dword v197, v[158:159], off offset:576
	global_load_dword v198, v[158:159], off offset:640
	global_load_dword v199, v[158:159], off offset:704
	v_lshl_or_b32 v160, s56, 8, v167
	v_ashrrev_i32_e32 v161, 31, v160
	s_mov_b32 s5, 0x100000
	s_mov_b64 s[14:15], 0x100000
	s_mov_b32 s56, s4
	s_mov_b32 s22, s6
	s_mov_b64 s[26:27], s[20:21]
	s_mov_b64 s[24:25], s[12:13]
	s_waitcnt vmcnt(0)
	v_fmamk_f32 v164, v164, 0x3a800000, v187
	v_cmp_gt_f32_e32 vcc, s67, v164
	v_mul_f32_e32 v165, 0x4b800000, v164
	s_nop 0
	v_cndmask_b32_e32 v164, v164, v165, vcc
	v_rsq_f32_e32 v164, v164
	s_nop 0
	v_mul_f32_e32 v165, 0x45800000, v164
	v_cndmask_b32_e32 v170, v164, v165, vcc
	v_lshlrev_b64 v[164:165], 13, v[162:163]
	v_pk_mul_f32 v[120:121], v[120:121], v[170:171] op_sel_hi:[1,0]
	v_lshl_add_u64 v[172:173], s[2:3], 0, v[164:165]
	v_lshlrev_b64 v[164:165], 1, v[160:161]
	v_pk_mul_f32 v[126:127], v[126:127], v[170:171] op_sel_hi:[1,0]
	v_pk_mul_f32 v[124:125], v[124:125], v[170:171] op_sel_hi:[1,0]
	v_pk_mul_f32 v[122:123], v[122:123], v[170:171] op_sel_hi:[1,0]
	v_max_f32_e32 v120, 0, v120
	v_max_f32_e32 v121, 0, v121
	v_lshl_add_u64 v[160:161], v[172:173], 0, v[164:165]
	v_max_f32_e32 v124, 0, v124
	v_max_f32_e32 v125, 0, v125
	v_pk_mul_f32 v[172:173], v[120:121], v[120:121]
	v_max_f32_e32 v120, 0, v126
	v_max_f32_e32 v122, 0, v122
	v_max_f32_e32 v121, 0, v127
	v_max_f32_e32 v123, 0, v123
	v_pk_mul_f32 v[124:125], v[124:125], v[124:125]
	v_pk_mul_f32 v[126:127], v[120:121], v[120:121]
	v_pk_mul_f32 v[174:175], v[122:123], v[122:123]
	v_pk_mul_f32 v[112:113], v[112:113], v[170:171] op_sel_hi:[1,0]
	v_cvt_pk_bf16_f32 v120, v124, v125
	v_cvt_pk_bf16_f32 v121, v126, v127
	v_cvt_pk_bf16_f32 v122, v172, v173
	v_cvt_pk_bf16_f32 v123, v174, v175
	v_pk_mul_f32 v[118:119], v[118:119], v[170:171] op_sel_hi:[1,0]
	v_pk_mul_f32 v[116:117], v[116:117], v[170:171] op_sel_hi:[1,0]
	v_pk_mul_f32 v[114:115], v[114:115], v[170:171] op_sel_hi:[1,0]
	v_max_f32_e32 v112, 0, v112
	v_max_f32_e32 v113, 0, v113
	global_store_dwordx4 v[160:161], v[120:123], off
	v_max_f32_e32 v116, 0, v116
	v_max_f32_e32 v117, 0, v117
	v_pk_mul_f32 v[120:121], v[112:113], v[112:113]
	v_max_f32_e32 v112, 0, v118
	v_max_f32_e32 v114, 0, v114
	v_max_f32_e32 v113, 0, v119
	v_max_f32_e32 v115, 0, v115
	v_pk_mul_f32 v[116:117], v[116:117], v[116:117]
	v_pk_mul_f32 v[118:119], v[112:113], v[112:113]
	v_pk_mul_f32 v[122:123], v[114:115], v[114:115]
	v_cvt_pk_bf16_f32 v112, v116, v117
	v_cvt_pk_bf16_f32 v113, v118, v119
	v_cvt_pk_bf16_f32 v114, v120, v121
	v_cvt_pk_bf16_f32 v115, v122, v123
	global_store_dwordx4 v[160:161], v[112:115], off offset:256
	s_nop 1
	v_mov_b32_e32 v114, v193
	s_nop 0
	v_or_b32_e32 v112, 16, v162
	v_ashrrev_i32_e32 v113, 31, v112
	v_lshlrev_b64 v[112:113], 13, v[112:113]
	v_lshl_add_u64 v[112:113], s[2:3], 0, v[112:113]
	v_lshl_add_u64 v[112:113], v[112:113], 0, v[164:165]
	v_fmamk_f32 v114, v114, 0x3a800000, v187
	v_cmp_gt_f32_e32 vcc, s67, v114
	v_mul_f32_e32 v115, 0x4b800000, v114
	s_nop 0
	v_cndmask_b32_e32 v114, v114, v115, vcc
	v_rsq_f32_e32 v114, v114
	s_nop 0
	v_mul_f32_e32 v115, 0x45800000, v114
	v_cndmask_b32_e32 v114, v114, v115, vcc
	v_pk_mul_f32 v[104:105], v[104:105], v[114:115] op_sel_hi:[1,0]
	v_pk_mul_f32 v[110:111], v[110:111], v[114:115] op_sel_hi:[1,0]
	v_pk_mul_f32 v[108:109], v[108:109], v[114:115] op_sel_hi:[1,0]
	v_pk_mul_f32 v[106:107], v[106:107], v[114:115] op_sel_hi:[1,0]
	v_max_f32_e32 v104, 0, v104
	v_max_f32_e32 v105, 0, v105
	v_max_f32_e32 v108, 0, v108
	v_max_f32_e32 v109, 0, v109
	v_pk_mul_f32 v[116:117], v[104:105], v[104:105]
	v_max_f32_e32 v104, 0, v110
	v_max_f32_e32 v106, 0, v106
	v_max_f32_e32 v105, 0, v111
	v_max_f32_e32 v107, 0, v107
	v_pk_mul_f32 v[108:109], v[108:109], v[108:109]
	v_pk_mul_f32 v[110:111], v[104:105], v[104:105]
	v_pk_mul_f32 v[118:119], v[106:107], v[106:107]
; __device__ __forceinline__ unsigned cvt_pk_bf16(float lo, float hi) { const f32x2_cv v = {lo, hi}; const bf16x2_cv b = __builtin_convertvector(v, bf16x2_cv); return __builtin_bit_cast(unsigned, b); }
; __device__ __forceinline__ float rstd_of(const float* rowss, int row) { return rsqrtf(rowss[row] * (1.0f / 1024.0f) + 1e-6f); }
;     __device__ __forceinline__ void operator()(const f32x4 (&acc)[2][2][4][2], const pg8::Unit& u, int wr, int wc, int fr, int fq) const {
;     ...
;             for (int m = 0; m < 4; ++m) {
;                 const int row = row0 + ai * 128 + m * 16;
;                 const float s = (MODE == 2) ? 1.0f : rstd_of(rowss, row);
;                 bf16_t* rowp = O + (size_t)row * ldc + col0;
; #pragma unroll
;                 for (int bj = 0; bj < 2; ++bj) {
;                     f32x4 v0 = acc[ai][bj][m][0] * s, v1 = acc[ai][bj][m][1] * s;
;                     if (MODE == 1) {
; #pragma unroll
;                         for (int j = 0; j < 4; ++j) { const float a = fmaxf(v0[j], 0.f), b = fmaxf(v1[j], 0.f); v0[j] = a * a; v1[j] = b * b; } }
;                     u32x4 w; w.x = cvt_pk_bf16(v0[0], v0[1]); w.y = cvt_pk_bf16(v0[2], v0[3]); w.z = cvt_pk_bf16(v1[0], v1[1]); w.w = cvt_pk_bf16(v1[2], v1[3]);
;                     *(u32x4*)(rowp + bj * 128) = w; } }
	v_pk_mul_f32 v[96:97], v[96:97], v[114:115] op_sel_hi:[1,0]
	v_cvt_pk_bf16_f32 v104, v108, v109
	v_cvt_pk_bf16_f32 v105, v110, v111
	v_cvt_pk_bf16_f32 v106, v116, v117
	v_cvt_pk_bf16_f32 v107, v118, v119
	v_pk_mul_f32 v[102:103], v[102:103], v[114:115] op_sel_hi:[1,0]
	v_pk_mul_f32 v[100:101], v[100:101], v[114:115] op_sel_hi:[1,0]
	v_pk_mul_f32 v[98:99], v[98:99], v[114:115] op_sel_hi:[1,0]
	v_max_f32_e32 v96, 0, v96
	v_max_f32_e32 v97, 0, v97
	global_store_dwordx4 v[112:113], v[104:107], off
	v_max_f32_e32 v100, 0, v100
	v_max_f32_e32 v101, 0, v101
	v_pk_mul_f32 v[104:105], v[96:97], v[96:97]
	v_max_f32_e32 v96, 0, v102
	v_max_f32_e32 v98, 0, v98
	v_max_f32_e32 v97, 0, v103
	v_max_f32_e32 v99, 0, v99
	v_pk_mul_f32 v[100:101], v[100:101], v[100:101]
	v_pk_mul_f32 v[102:103], v[96:97], v[96:97]
	v_pk_mul_f32 v[106:107], v[98:99], v[98:99]
	v_cvt_pk_bf16_f32 v96, v100, v101
	v_cvt_pk_bf16_f32 v97, v102, v103
	v_cvt_pk_bf16_f32 v98, v104, v105
	v_cvt_pk_bf16_f32 v99, v106, v107
	global_store_dwordx4 v[112:113], v[96:99], off offset:256
	s_nop 1
	v_mov_b32_e32 v98, v194
	s_nop 0
	v_or_b32_e32 v96, 32, v162
	v_ashrrev_i32_e32 v97, 31, v96
	v_lshlrev_b64 v[96:97], 13, v[96:97]
	v_lshl_add_u64 v[96:97], s[2:3], 0, v[96:97]
	v_lshl_add_u64 v[96:97], v[96:97], 0, v[164:165]
	v_fmamk_f32 v98, v98, 0x3a800000, v187
	v_cmp_gt_f32_e32 vcc, s67, v98
	v_mul_f32_e32 v99, 0x4b800000, v98
	s_nop 0
	v_cndmask_b32_e32 v98, v98, v99, vcc
	v_rsq_f32_e32 v98, v98
	s_nop 0
	v_mul_f32_e32 v99, 0x45800000, v98
	v_cndmask_b32_e32 v98, v98, v99, vcc
	v_pk_mul_f32 v[88:89], v[88:89], v[98:99] op_sel_hi:[1,0]
	v_pk_mul_f32 v[94:95], v[94:95], v[98:99] op_sel_hi:[1,0]
	v_pk_mul_f32 v[92:93], v[92:93], v[98:99] op_sel_hi:[1,0]
	v_pk_mul_f32 v[90:91], v[90:91], v[98:99] op_sel_hi:[1,0]
	v_max_f32_e32 v88, 0, v88
	v_max_f32_e32 v89, 0, v89
	v_max_f32_e32 v92, 0, v92
	v_max_f32_e32 v93, 0, v93
	v_pk_mul_f32 v[100:101], v[88:89], v[88:89]
	v_max_f32_e32 v88, 0, v94
	v_max_f32_e32 v90, 0, v90
	v_max_f32_e32 v89, 0, v95
	v_max_f32_e32 v91, 0, v91
	v_pk_mul_f32 v[92:93], v[92:93], v[92:93]
	v_pk_mul_f32 v[94:95], v[88:89], v[88:89]
	v_pk_mul_f32 v[102:103], v[90:91], v[90:91]
	v_pk_mul_f32 v[80:81], v[80:81], v[98:99] op_sel_hi:[1,0]
	v_cvt_pk_bf16_f32 v88, v92, v93
	v_cvt_pk_bf16_f32 v89, v94, v95
	v_cvt_pk_bf16_f32 v90, v100, v101
	v_cvt_pk_bf16_f32 v91, v102, v103
	v_pk_mul_f32 v[86:87], v[86:87], v[98:99] op_sel_hi:[1,0]
	v_pk_mul_f32 v[84:85], v[84:85], v[98:99] op_sel_hi:[1,0]
	v_pk_mul_f32 v[82:83], v[82:83], v[98:99] op_sel_hi:[1,0]
	v_max_f32_e32 v80, 0, v80
	v_max_f32_e32 v81, 0, v81
	global_store_dwordx4 v[96:97], v[88:91], off
	v_max_f32_e32 v84, 0, v84
	v_max_f32_e32 v85, 0, v85
	v_pk_mul_f32 v[88:89], v[80:81], v[80:81]
	v_max_f32_e32 v80, 0, v86
	v_max_f32_e32 v82, 0, v82
	v_max_f32_e32 v81, 0, v87
	v_max_f32_e32 v83, 0, v83
	v_pk_mul_f32 v[84:85], v[84:85], v[84:85]
	v_pk_mul_f32 v[86:87], v[80:81], v[80:81]
	v_pk_mul_f32 v[90:91], v[82:83], v[82:83]
	v_cvt_pk_bf16_f32 v80, v84, v85
	v_cvt_pk_bf16_f32 v81, v86, v87
	v_cvt_pk_bf16_f32 v82, v88, v89
	v_cvt_pk_bf16_f32 v83, v90, v91
	global_store_dwordx4 v[96:97], v[80:83], off offset:256
	s_nop 1
	v_mov_b32_e32 v82, v195
	s_nop 0
	v_or_b32_e32 v80, 48, v162
	v_ashrrev_i32_e32 v81, 31, v80
	v_lshlrev_b64 v[80:81], 13, v[80:81]
	v_lshl_add_u64 v[80:81], s[2:3], 0, v[80:81]
	v_lshl_add_u64 v[80:81], v[80:81], 0, v[164:165]
	v_fmamk_f32 v82, v82, 0x3a800000, v187
	v_cmp_gt_f32_e32 vcc, s67, v82
	v_mul_f32_e32 v83, 0x4b800000, v82
	s_nop 0
	v_cndmask_b32_e32 v82, v82, v83, vcc
	v_rsq_f32_e32 v82, v82
	s_nop 0
	v_mul_f32_e32 v83, 0x45800000, v82
	v_cndmask_b32_e32 v82, v82, v83, vcc
	v_pk_mul_f32 v[72:73], v[72:73], v[82:83] op_sel_hi:[1,0]
	v_pk_mul_f32 v[78:79], v[78:79], v[82:83] op_sel_hi:[1,0]
	v_pk_mul_f32 v[76:77], v[76:77], v[82:83] op_sel_hi:[1,0]
	v_pk_mul_f32 v[74:75], v[74:75], v[82:83] op_sel_hi:[1,0]
	v_max_f32_e32 v72, 0, v72
	v_max_f32_e32 v73, 0, v73
	v_max_f32_e32 v76, 0, v76
	v_max_f32_e32 v77, 0, v77
	v_pk_mul_f32 v[84:85], v[72:73], v[72:73]
	v_max_f32_e32 v72, 0, v78
	v_max_f32_e32 v74, 0, v74
	v_max_f32_e32 v73, 0, v79
	v_max_f32_e32 v75, 0, v75
	v_pk_mul_f32 v[76:77], v[76:77], v[76:77]
	v_pk_mul_f32 v[78:79], v[72:73], v[72:73]
	v_pk_mul_f32 v[86:87], v[74:75], v[74:75]
	v_pk_mul_f32 v[64:65], v[64:65], v[82:83] op_sel_hi:[1,0]
	v_cvt_pk_bf16_f32 v72, v76, v77
	v_cvt_pk_bf16_f32 v73, v78, v79
	v_cvt_pk_bf16_f32 v74, v84, v85
	v_cvt_pk_bf16_f32 v75, v86, v87
	v_pk_mul_f32 v[70:71], v[70:71], v[82:83] op_sel_hi:[1,0]
	v_pk_mul_f32 v[68:69], v[68:69], v[82:83] op_sel_hi:[1,0]
	v_pk_mul_f32 v[66:67], v[66:67], v[82:83] op_sel_hi:[1,0]
	v_max_f32_e32 v64, 0, v64
	v_max_f32_e32 v65, 0, v65
	global_store_dwordx4 v[80:81], v[72:75], off
	v_max_f32_e32 v68, 0, v68
	v_max_f32_e32 v69, 0, v69
	v_pk_mul_f32 v[72:73], v[64:65], v[64:65]
	v_max_f32_e32 v64, 0, v70
	v_max_f32_e32 v66, 0, v66
	v_max_f32_e32 v65, 0, v71
	v_max_f32_e32 v67, 0, v67
	v_pk_mul_f32 v[68:69], v[68:69], v[68:69]
	v_pk_mul_f32 v[70:71], v[64:65], v[64:65]
	v_pk_mul_f32 v[74:75], v[66:67], v[66:67]
	v_cvt_pk_bf16_f32 v64, v68, v69
	v_cvt_pk_bf16_f32 v65, v70, v71
	v_cvt_pk_bf16_f32 v66, v72, v73
	v_cvt_pk_bf16_f32 v67, v74, v75
	global_store_dwordx4 v[80:81], v[64:67], off offset:256
	s_nop 1
	v_mov_b32_e32 v64, v196
	v_fmamk_f32 v64, v64, 0x3a800000, v187
	v_cmp_gt_f32_e32 vcc, s67, v64
	v_mul_f32_e32 v65, 0x4b800000, v64
	s_nop 0
	v_cndmask_b32_e32 v64, v64, v65, vcc
	v_rsq_f32_e32 v64, v64
	s_nop 0
	v_mul_f32_e32 v65, 0x45800000, v64
	v_cndmask_b32_e32 v66, v64, v65, vcc
	v_pk_mul_f32 v[60:61], v[60:61], v[66:67] op_sel_hi:[1,0]
; __device__ __forceinline__ unsigned cvt_pk_bf16(float lo, float hi) { const f32x2_cv v = {lo, hi}; const bf16x2_cv b = __builtin_convertvector(v, bf16x2_cv); return __builtin_bit_cast(unsigned, b); }
; __device__ __forceinline__ float rstd_of(const float* rowss, int row) { return rsqrtf(rowss[row] * (1.0f / 1024.0f) + 1e-6f); }
;     __device__ __forceinline__ void operator()(const f32x4 (&acc)[2][2][4][2], const pg8::Unit& u, int wr, int wc, int fr, int fq) const {
;     ...
;             for (int m = 0; m < 4; ++m) {
;                 const int row = row0 + ai * 128 + m * 16;
;                 const float s = (MODE == 2) ? 1.0f : rstd_of(rowss, row);
;                 bf16_t* rowp = O + (size_t)row * ldc + col0;
; #pragma unroll
;                 for (int bj = 0; bj < 2; ++bj) {
;                     f32x4 v0 = acc[ai][bj][m][0] * s, v1 = acc[ai][bj][m][1] * s;
;                     if (MODE == 1) {
; #pragma unroll
;                         for (int j = 0; j < 4; ++j) { const float a = fmaxf(v0[j], 0.f), b = fmaxf(v1[j], 0.f); v0[j] = a * a; v1[j] = b * b; } }
;                     u32x4 w; w.x = cvt_pk_bf16(v0[0], v0[1]); w.y = cvt_pk_bf16(v0[2], v0[3]); w.z = cvt_pk_bf16(v1[0], v1[1]); w.w = cvt_pk_bf16(v1[2], v1[3]);
;                     *(u32x4*)(rowp + bj * 128) = w; } }
	v_pk_mul_f32 v[56:57], v[56:57], v[66:67] op_sel_hi:[1,0]
	v_pk_mul_f32 v[62:63], v[62:63], v[66:67] op_sel_hi:[1,0]
	v_pk_mul_f32 v[58:59], v[58:59], v[66:67] op_sel_hi:[1,0]
	v_max_f32_e32 v60, 0, v60
	v_max_f32_e32 v56, 0, v56
	v_max_f32_e32 v61, 0, v61
	v_max_f32_e32 v57, 0, v57
	v_pk_mul_f32 v[60:61], v[60:61], v[60:61]
	v_pk_mul_f32 v[68:69], v[56:57], v[56:57]
	v_max_f32_e32 v56, 0, v62
	v_max_f32_e32 v58, 0, v58
	v_max_f32_e32 v57, 0, v63
	v_max_f32_e32 v59, 0, v59
	v_pk_mul_f32 v[62:63], v[56:57], v[56:57]
	v_pk_mul_f32 v[70:71], v[58:59], v[58:59]
	v_cvt_pk_bf16_f32 v56, v60, v61
	v_add_co_u32_e32 v60, vcc, s5, v160
	v_pk_mul_f32 v[48:49], v[48:49], v[66:67] op_sel_hi:[1,0]
	v_cvt_pk_bf16_f32 v57, v62, v63
	v_cvt_pk_bf16_f32 v58, v68, v69
	v_cvt_pk_bf16_f32 v59, v70, v71
	v_addc_co_u32_e32 v61, vcc, 0, v161, vcc
	v_pk_mul_f32 v[54:55], v[54:55], v[66:67] op_sel_hi:[1,0]
	v_pk_mul_f32 v[52:53], v[52:53], v[66:67] op_sel_hi:[1,0]
	v_pk_mul_f32 v[50:51], v[50:51], v[66:67] op_sel_hi:[1,0]
	v_max_f32_e32 v48, 0, v48
	v_max_f32_e32 v49, 0, v49
	global_store_dwordx4 v[60:61], v[56:59], off
	v_max_f32_e32 v52, 0, v52
	v_max_f32_e32 v53, 0, v53
	v_pk_mul_f32 v[56:57], v[48:49], v[48:49]
	v_max_f32_e32 v48, 0, v54
	v_max_f32_e32 v50, 0, v50
	v_max_f32_e32 v49, 0, v55
	v_max_f32_e32 v51, 0, v51
	v_pk_mul_f32 v[52:53], v[52:53], v[52:53]
	v_pk_mul_f32 v[54:55], v[48:49], v[48:49]
	v_pk_mul_f32 v[58:59], v[50:51], v[50:51]
	v_lshl_add_u64 v[64:65], v[160:161], 0, s[14:15]
	v_cvt_pk_bf16_f32 v48, v52, v53
	v_cvt_pk_bf16_f32 v49, v54, v55
	v_cvt_pk_bf16_f32 v50, v56, v57
	v_cvt_pk_bf16_f32 v51, v58, v59
	global_store_dwordx4 v[64:65], v[48:51], off offset:256
	s_nop 1
	v_mov_b32_e32 v48, v197
	s_mov_b32 s5, 0x120000
	s_mov_b64 s[14:15], 0x120000
	v_fmamk_f32 v48, v48, 0x3a800000, v187
	v_cmp_gt_f32_e32 vcc, s67, v48
	v_mul_f32_e32 v49, 0x4b800000, v48
	s_nop 0
	v_cndmask_b32_e32 v48, v48, v49, vcc
	v_rsq_f32_e32 v48, v48
	s_nop 0
	v_mul_f32_e32 v49, 0x45800000, v48
	v_cndmask_b32_e32 v50, v48, v49, vcc
	v_pk_mul_f32 v[44:45], v[44:45], v[50:51] op_sel_hi:[1,0]
	v_pk_mul_f32 v[40:41], v[40:41], v[50:51] op_sel_hi:[1,0]
	v_pk_mul_f32 v[46:47], v[46:47], v[50:51] op_sel_hi:[1,0]
	v_pk_mul_f32 v[42:43], v[42:43], v[50:51] op_sel_hi:[1,0]
	v_max_f32_e32 v44, 0, v44
	v_max_f32_e32 v40, 0, v40
	v_max_f32_e32 v45, 0, v45
	v_max_f32_e32 v41, 0, v41
	v_pk_mul_f32 v[44:45], v[44:45], v[44:45]
	v_pk_mul_f32 v[52:53], v[40:41], v[40:41]
	v_max_f32_e32 v40, 0, v46
	v_max_f32_e32 v42, 0, v42
	v_max_f32_e32 v41, 0, v47
	v_max_f32_e32 v43, 0, v43
	v_pk_mul_f32 v[46:47], v[40:41], v[40:41]
	v_pk_mul_f32 v[54:55], v[42:43], v[42:43]
	v_cvt_pk_bf16_f32 v40, v44, v45
	v_add_co_u32_e32 v44, vcc, s5, v160
	v_pk_mul_f32 v[32:33], v[32:33], v[50:51] op_sel_hi:[1,0]
	v_cvt_pk_bf16_f32 v41, v46, v47
	v_cvt_pk_bf16_f32 v42, v52, v53
	v_cvt_pk_bf16_f32 v43, v54, v55
	v_addc_co_u32_e32 v45, vcc, 0, v161, vcc
	v_pk_mul_f32 v[38:39], v[38:39], v[50:51] op_sel_hi:[1,0]
	v_pk_mul_f32 v[36:37], v[36:37], v[50:51] op_sel_hi:[1,0]
	v_pk_mul_f32 v[34:35], v[34:35], v[50:51] op_sel_hi:[1,0]
	v_max_f32_e32 v32, 0, v32
	v_max_f32_e32 v33, 0, v33
	global_store_dwordx4 v[44:45], v[40:43], off
	v_max_f32_e32 v36, 0, v36
	v_max_f32_e32 v37, 0, v37
	v_pk_mul_f32 v[40:41], v[32:33], v[32:33]
	v_max_f32_e32 v32, 0, v38
	v_max_f32_e32 v34, 0, v34
	v_max_f32_e32 v33, 0, v39
	v_max_f32_e32 v35, 0, v35
	v_pk_mul_f32 v[36:37], v[36:37], v[36:37]
	v_pk_mul_f32 v[38:39], v[32:33], v[32:33]
	v_pk_mul_f32 v[42:43], v[34:35], v[34:35]
	v_lshl_add_u64 v[48:49], v[160:161], 0, s[14:15]
	v_cvt_pk_bf16_f32 v32, v36, v37
	v_cvt_pk_bf16_f32 v33, v38, v39
	v_cvt_pk_bf16_f32 v34, v40, v41
	v_cvt_pk_bf16_f32 v35, v42, v43
	global_store_dwordx4 v[48:49], v[32:35], off offset:256
	s_nop 1
	v_mov_b32_e32 v32, v198
	s_mov_b32 s5, 0x140000
	s_mov_b64 s[14:15], 0x140000
	v_fmamk_f32 v32, v32, 0x3a800000, v187
	v_cmp_gt_f32_e32 vcc, s67, v32
	v_mul_f32_e32 v33, 0x4b800000, v32
	s_nop 0
; __device__ __forceinline__ unsigned cvt_pk_bf16(float lo, float hi) { const f32x2_cv v = {lo, hi}; const bf16x2_cv b = __builtin_convertvector(v, bf16x2_cv); return __builtin_bit_cast(unsigned, b); }
; #define PG8_WAIT_V(n) asm volatile("s_waitcnt vmcnt(" #n ")" ::: "memory")
; #define PG8_BAR __builtin_amdgcn_s_barrier()
; __device__ __forceinline__ float rstd_of(const float* rowss, int row) { return rsqrtf(rowss[row] * (1.0f / 1024.0f) + 1e-6f); }
; template <class Epi, class Sched, bool STAMP = false>
; __device__ __forceinline__ void gemm_phase(PG8_LAS unsigned char* lds, const Gemm g, const Sched& S, const Epi& E, unsigned long long* stamps) {
;     ...
;         if (!has_next) break;
; #pragma unroll
;         for (int a = 0; a < 2; ++a)
; #pragma unroll
;             for (int b = 0; b < 2; ++b)
; #pragma unroll
;                 for (int m = 0; m < 4; ++m)
; #pragma unroll
;                     for (int n = 0; n < 2; ++n) acc[a][b][m][n] = (f32x4){0.f, 0.f, 0.f, 0.f};
;         cur = nxt; cA = nA; cB = nB; ++ui;
;     }
;     PG8_WAIT_V(0);
;     if (wr == 0) PG8_BAR;
;     PG8_BAR;
;     __device__ __forceinline__ void operator()(const f32x4 (&acc)[2][2][4][2], const pg8::Unit& u, int wr, int wc, int fr, int fq) const {
;     ...
;             for (int m = 0; m < 4; ++m) {
;                 const int row = row0 + ai * 128 + m * 16;
;                 const float s = (MODE == 2) ? 1.0f : rstd_of(rowss, row);
;                 bf16_t* rowp = O + (size_t)row * ldc + col0;
; #pragma unroll
;                 for (int bj = 0; bj < 2; ++bj) {
;                     f32x4 v0 = acc[ai][bj][m][0] * s, v1 = acc[ai][bj][m][1] * s;
;                     if (MODE == 1) {
; #pragma unroll
;                         for (int j = 0; j < 4; ++j) { const float a = fmaxf(v0[j], 0.f), b = fmaxf(v1[j], 0.f); v0[j] = a * a; v1[j] = b * b; } }
;                     u32x4 w; w.x = cvt_pk_bf16(v0[0], v0[1]); w.y = cvt_pk_bf16(v0[2], v0[3]); w.z = cvt_pk_bf16(v1[0], v1[1]); w.w = cvt_pk_bf16(v1[2], v1[3]);
;                     *(u32x4*)(rowp + bj * 128) = w; } }
	v_cndmask_b32_e32 v32, v32, v33, vcc
	v_rsq_f32_e32 v32, v32
	s_nop 0
	v_mul_f32_e32 v33, 0x45800000, v32
	v_cndmask_b32_e32 v34, v32, v33, vcc
	v_pk_mul_f32 v[28:29], v[28:29], v[34:35] op_sel_hi:[1,0]
	v_pk_mul_f32 v[24:25], v[24:25], v[34:35] op_sel_hi:[1,0]
	v_pk_mul_f32 v[30:31], v[30:31], v[34:35] op_sel_hi:[1,0]
	v_pk_mul_f32 v[26:27], v[26:27], v[34:35] op_sel_hi:[1,0]
	v_max_f32_e32 v28, 0, v28
	v_max_f32_e32 v24, 0, v24
	v_max_f32_e32 v29, 0, v29
	v_max_f32_e32 v25, 0, v25
	v_pk_mul_f32 v[28:29], v[28:29], v[28:29]
	v_pk_mul_f32 v[36:37], v[24:25], v[24:25]
	v_max_f32_e32 v24, 0, v30
	v_max_f32_e32 v26, 0, v26
	v_max_f32_e32 v25, 0, v31
	v_max_f32_e32 v27, 0, v27
	v_pk_mul_f32 v[30:31], v[24:25], v[24:25]
	v_pk_mul_f32 v[38:39], v[26:27], v[26:27]
	v_cvt_pk_bf16_f32 v24, v28, v29
	v_add_co_u32_e32 v28, vcc, s5, v160
	v_pk_mul_f32 v[16:17], v[16:17], v[34:35] op_sel_hi:[1,0]
	v_cvt_pk_bf16_f32 v25, v30, v31
	v_cvt_pk_bf16_f32 v26, v36, v37
	v_cvt_pk_bf16_f32 v27, v38, v39
	v_addc_co_u32_e32 v29, vcc, 0, v161, vcc
	v_pk_mul_f32 v[22:23], v[22:23], v[34:35] op_sel_hi:[1,0]
	v_pk_mul_f32 v[20:21], v[20:21], v[34:35] op_sel_hi:[1,0]
	v_pk_mul_f32 v[18:19], v[18:19], v[34:35] op_sel_hi:[1,0]
	v_max_f32_e32 v16, 0, v16
	v_max_f32_e32 v17, 0, v17
	global_store_dwordx4 v[28:29], v[24:27], off
	v_max_f32_e32 v20, 0, v20
	v_max_f32_e32 v21, 0, v21
	v_pk_mul_f32 v[24:25], v[16:17], v[16:17]
	v_max_f32_e32 v16, 0, v22
	v_max_f32_e32 v18, 0, v18
	v_max_f32_e32 v17, 0, v23
	v_max_f32_e32 v19, 0, v19
	v_pk_mul_f32 v[20:21], v[20:21], v[20:21]
	v_pk_mul_f32 v[22:23], v[16:17], v[16:17]
	v_pk_mul_f32 v[26:27], v[18:19], v[18:19]
	v_lshl_add_u64 v[32:33], v[160:161], 0, s[14:15]
	v_cvt_pk_bf16_f32 v16, v20, v21
	v_cvt_pk_bf16_f32 v17, v22, v23
	v_cvt_pk_bf16_f32 v18, v24, v25
	v_cvt_pk_bf16_f32 v19, v26, v27
	global_store_dwordx4 v[32:33], v[16:19], off offset:256
	s_nop 1
	v_mov_b32_e32 v16, v199
	s_mov_b32 s5, 0x160000
	s_mov_b64 s[14:15], 0x160000
	v_lshl_add_u64 v[18:19], v[160:161], 0, s[14:15]
	v_fmamk_f32 v16, v16, 0x3a800000, v187
	v_cmp_gt_f32_e32 vcc, s67, v16
	v_mul_f32_e32 v17, 0x4b800000, v16
	s_nop 0
	v_cndmask_b32_e32 v16, v16, v17, vcc
	v_rsq_f32_e32 v16, v16
	s_nop 0
	v_mul_f32_e32 v17, 0x45800000, v16
	v_cndmask_b32_e32 v16, v16, v17, vcc
	v_pk_mul_f32 v[12:13], v[12:13], v[16:17] op_sel_hi:[1,0]
	v_pk_mul_f32 v[8:9], v[8:9], v[16:17] op_sel_hi:[1,0]
	v_pk_mul_f32 v[14:15], v[14:15], v[16:17] op_sel_hi:[1,0]
	v_pk_mul_f32 v[10:11], v[10:11], v[16:17] op_sel_hi:[1,0]
	v_max_f32_e32 v12, 0, v12
	v_max_f32_e32 v8, 0, v8
	v_max_f32_e32 v13, 0, v13
	v_max_f32_e32 v9, 0, v9
	v_pk_mul_f32 v[12:13], v[12:13], v[12:13]
	v_pk_mul_f32 v[20:21], v[8:9], v[8:9]
	v_max_f32_e32 v8, 0, v14
	v_max_f32_e32 v10, 0, v10
	v_max_f32_e32 v9, 0, v15
	v_max_f32_e32 v11, 0, v11
	v_pk_mul_f32 v[14:15], v[8:9], v[8:9]
	v_pk_mul_f32 v[22:23], v[10:11], v[10:11]
	v_cvt_pk_bf16_f32 v8, v12, v13
	v_add_co_u32_e32 v12, vcc, s5, v160
	v_pk_mul_f32 v[0:1], v[0:1], v[16:17] op_sel_hi:[1,0]
	v_cvt_pk_bf16_f32 v9, v14, v15
	v_cvt_pk_bf16_f32 v10, v20, v21
	v_cvt_pk_bf16_f32 v11, v22, v23
	v_addc_co_u32_e32 v13, vcc, 0, v161, vcc
	v_pk_mul_f32 v[6:7], v[6:7], v[16:17] op_sel_hi:[1,0]
	v_pk_mul_f32 v[4:5], v[4:5], v[16:17] op_sel_hi:[1,0]
	v_pk_mul_f32 v[2:3], v[2:3], v[16:17] op_sel_hi:[1,0]
	v_max_f32_e32 v0, 0, v0
	v_max_f32_e32 v1, 0, v1
	global_store_dwordx4 v[12:13], v[8:11], off
	v_max_f32_e32 v4, 0, v4
	v_max_f32_e32 v5, 0, v5
	v_pk_mul_f32 v[8:9], v[0:1], v[0:1]
	v_max_f32_e32 v0, 0, v6
	v_max_f32_e32 v2, 0, v2
	v_max_f32_e32 v1, 0, v7
	v_max_f32_e32 v3, 0, v3
	v_pk_mul_f32 v[4:5], v[4:5], v[4:5]
	v_pk_mul_f32 v[6:7], v[0:1], v[0:1]
	v_pk_mul_f32 v[10:11], v[2:3], v[2:3]
	v_cvt_pk_bf16_f32 v0, v4, v5
	v_cvt_pk_bf16_f32 v1, v6, v7
	v_cvt_pk_bf16_f32 v2, v8, v9
	v_cvt_pk_bf16_f32 v3, v10, v11
	s_and_b64 vcc, exec, s[38:39]
	global_store_dwordx4 v[18:19], v[0:3], off offset:256
	s_cbranch_vccz .LBB0_41
	s_cmpk_gt_u32 s36, 0xff
	s_cbranch_scc1 .LBB0_48
	s_barrier

; #define PG8_STAGE(bufoff, gbase, voff) do { _Pragma("unroll") for (int _i = 0; _i < 2; ++_i) \
;         __builtin_amdgcn_global_load_lds((const unsigned*)((const char*)(gbase) + (voff)[_i]), (PG8_LAS unsigned*)(lds + (bufoff) + ldsw + _i * 8192), 16, 0, 0); } while (0)
; #define PG8_LDA(dst, b, h) do { _Pragma("unroll") for (int m = 0; m < 4; ++m) _Pragma("unroll") for (int k = 0; k < 2; ++k) dst[m][k] = *(const PG8_LAS bf16x8*)(lds + PG8_SA(b, h) + aoff + m * 2048 + k * 1024); } while (0)
; #define PG8_LDB(dst, b, h) do { _Pragma("unroll") for (int n = 0; n < 2; ++n) _Pragma("unroll") for (int k = 0; k < 2; ++k) dst[n][k] = *(const PG8_LAS bf16x8*)(lds + PG8_SB(b, h) + boff + n * 2048 + k * 1024); } while (0)
; #define PG8_MMA(ai, bj, At, Bt) do { __builtin_amdgcn_s_setprio(1); _Pragma("unroll") for (int m = 0; m < 4; ++m) _Pragma("unroll") for (int n = 0; n < 2; ++n) _Pragma("unroll") for (int k = 0; k < 2; ++k) \
;         acc[ai][bj][m][n] = __builtin_amdgcn_mfma_f32_16x16x32_bf16(Bt[n][k], At[m][k], acc[ai][bj][m][n], 0, 0, 0); __builtin_amdgcn_s_setprio(0); } while (0)
; #define PG8_BAR __builtin_amdgcn_s_barrier()
; template <class Epi, class Sched, bool STAMP = false>
; __device__ __forceinline__ void gemm_phase(PG8_LAS unsigned char* lds, const Gemm g, const Sched& S, const Epi& E, unsigned long long* stamps) {
;     ...
;         for (int t = 0; t < nt; t += 2) {
;             const bool last = (t == nt - 2);
;             const char* a1 = cA + (size_t)(t + 1) * kstep;
;             const char* a2 = last ? nA : cA + (size_t)(t + 2) * kstep; const char* b2 = last ? nB : cB + (size_t)(t + 2) * kstep;
;             const char* a3 = a2 + kstep; const char* b3 = b2 + kstep;
;             if (last && has_next) S.a_ready(nxt);
;             PG8_LDB(B0, 0, 0); PG8_SCHED; PG8_LDA(At, 0, 0); PG8_STAGE(PG8_SA(1, 1), a1 + hstep, voffA);
;             PG8_WAIT_L(8); PG8_BAR; PG8_WAIT_L(0); PG8_MMA(0, 0, At, B0); PG8_BAR; PG8_SCHED;
;             PG8_LDB(B1, 0, 1); PG8_STAGE(PG8_SB(0, 0), b2, voffB);
;             PG8_BAR; PG8_WAIT_L(0); PG8_MMA(0, 1, At, B1); PG8_BAR;
;             PG8_LDA(At, 0, 1); PG8_STAGE(PG8_SA(0, 0), a2, voffA);
;             PG8_BAR; PG8_WAIT_L(0); PG8_MMA(1, 0, At, B0); PG8_BAR; PG8_SCHED;
;             PG8_STAGE(PG8_SB(0, 1), b2 + hstep, voffB);
;             PG8_WAIT_V(6); PG8_BAR; PG8_MMA(1, 1, At, B1); PG8_BAR;
.LBB0_141:
	s_add_u32 s48, s44, 0x100
	s_addc_u32 s49, s45, 0
	s_add_i32 s14, 0, 0x10000
	ds_read_b128 v[156:159], v248
	ds_read_b128 v[160:163], v248 offset:1024
	ds_read_b128 v[170:173], v248 offset:2048
	ds_read_b128 v[174:177], v248 offset:3072
	s_cmp_eq_u32 s39, 12
	s_cselect_b32 s59, s23, s49
	s_cselect_b32 s58, s31, s48
	s_cselect_b32 s57, s21, s38
	s_cselect_b32 s56, vcc_lo, vcc_hi
	s_add_i32 m0, s37, 0xc000
	ds_read_b128 v[178:181], v168
	ds_read_b128 v[192:195], v168 offset:1024
	ds_read_b128 v[196:199], v168 offset:2048
	ds_read_b128 v[200:203], v168 offset:3072
	ds_read_b128 v[204:207], v168 offset:4096
	ds_read_b128 v[208:211], v168 offset:5120
	ds_read_b128 v[212:215], v168 offset:6144
	global_load_lds_dwordx4 v152, s[44:45]
	s_add_i32 m0, s37, 0xe000
	ds_read_b128 v[216:219], v168 offset:7168
	global_load_lds_dwordx4 v154, s[44:45]
	s_waitcnt lgkmcnt(8)
	s_barrier
	s_waitcnt lgkmcnt(0)
	v_mfma_f32_16x16x32_bf16 v[124:127], v[156:159], v[178:181], v[124:127]
	v_mfma_f32_16x16x32_bf16 v[120:123], v[170:173], v[178:181], v[120:123]
	v_mfma_f32_16x16x32_bf16 v[108:111], v[156:159], v[196:199], v[108:111]
	v_mfma_f32_16x16x32_bf16 v[104:107], v[170:173], v[196:199], v[104:107]
	v_mfma_f32_16x16x32_bf16 v[92:95], v[156:159], v[204:207], v[92:95]
	v_mfma_f32_16x16x32_bf16 v[88:91], v[170:173], v[204:207], v[88:91]
	v_mfma_f32_16x16x32_bf16 v[76:79], v[156:159], v[212:215], v[76:79]
	v_mfma_f32_16x16x32_bf16 v[72:75], v[170:173], v[212:215], v[72:75]
	v_mfma_f32_16x16x32_bf16 v[124:127], v[160:163], v[192:195], v[124:127]
	v_mfma_f32_16x16x32_bf16 v[120:123], v[174:177], v[192:195], v[120:123]
	v_mfma_f32_16x16x32_bf16 v[108:111], v[160:163], v[200:203], v[108:111]
	v_mfma_f32_16x16x32_bf16 v[104:107], v[174:177], v[200:203], v[104:107]
	v_mfma_f32_16x16x32_bf16 v[92:95], v[160:163], v[208:211], v[92:95]
	v_mfma_f32_16x16x32_bf16 v[88:91], v[174:177], v[208:211], v[88:91]
	v_mfma_f32_16x16x32_bf16 v[76:79], v[160:163], v[216:219], v[76:79]
	v_mfma_f32_16x16x32_bf16 v[72:75], v[174:177], v[216:219], v[72:75]
	s_barrier
	s_add_i32 s16, 0, 0x14000
	s_add_i32 s14, s14, s64
	s_mov_b32 m0, s14
	ds_read_b128 v[220:223], v249
	ds_read_b128 v[224:227], v249 offset:1024
	ds_read_b128 v[228:231], v249 offset:2048
	global_load_lds_dwordx4 v148, s[56:57]
	s_add_i32 m0, s14, 0x2000
	ds_read_b128 v[232:235], v249 offset:3072
	global_load_lds_dwordx4 v150, s[56:57]
	s_barrier
	s_waitcnt lgkmcnt(0)
	v_mfma_f32_16x16x32_bf16 v[116:119], v[220:223], v[178:181], v[116:119]
	v_mfma_f32_16x16x32_bf16 v[112:115], v[228:231], v[178:181], v[112:115]
	v_mfma_f32_16x16x32_bf16 v[100:103], v[220:223], v[196:199], v[100:103]
	v_mfma_f32_16x16x32_bf16 v[96:99], v[228:231], v[196:199], v[96:99]
	v_mfma_f32_16x16x32_bf16 v[84:87], v[220:223], v[204:207], v[84:87]
	v_mfma_f32_16x16x32_bf16 v[80:83], v[228:231], v[204:207], v[80:83]
	v_mfma_f32_16x16x32_bf16 v[68:71], v[220:223], v[212:215], v[68:71]
	v_mfma_f32_16x16x32_bf16 v[64:67], v[228:231], v[212:215], v[64:67]
	v_mfma_f32_16x16x32_bf16 v[116:119], v[224:227], v[192:195], v[116:119]
	v_mfma_f32_16x16x32_bf16 v[112:115], v[232:235], v[192:195], v[112:115]
	v_mfma_f32_16x16x32_bf16 v[100:103], v[224:227], v[200:203], v[100:103]
	v_mfma_f32_16x16x32_bf16 v[96:99], v[232:235], v[200:203], v[96:99]
	v_mfma_f32_16x16x32_bf16 v[84:87], v[224:227], v[208:211], v[84:87]
	v_mfma_f32_16x16x32_bf16 v[80:83], v[232:235], v[208:211], v[80:83]
	v_mfma_f32_16x16x32_bf16 v[68:71], v[224:227], v[216:219], v[68:71]
	v_mfma_f32_16x16x32_bf16 v[64:67], v[232:235], v[216:219], v[64:67]
	s_barrier
	s_mov_b32 m0, s37
	ds_read_b128 v[178:181], v168 offset:16384
	ds_read_b128 v[192:195], v168 offset:17408
	ds_read_b128 v[196:199], v168 offset:18432
	ds_read_b128 v[200:203], v168 offset:19456
	ds_read_b128 v[204:207], v168 offset:20480
	ds_read_b128 v[208:211], v168 offset:21504
	ds_read_b128 v[212:215], v168 offset:22528
	global_load_lds_dwordx4 v148, s[58:59]
	s_mov_b32 m0, s65
	ds_read_b128 v[216:219], v168 offset:23552
	global_load_lds_dwordx4 v150, s[58:59]
	s_barrier
	s_waitcnt lgkmcnt(0)
	v_mfma_f32_16x16x32_bf16 v[60:63], v[156:159], v[178:181], v[60:63]
	v_mfma_f32_16x16x32_bf16 v[56:59], v[170:173], v[178:181], v[56:59]
	v_mfma_f32_16x16x32_bf16 v[44:47], v[156:159], v[196:199], v[44:47]
	v_mfma_f32_16x16x32_bf16 v[40:43], v[170:173], v[196:199], v[40:43]
	v_mfma_f32_16x16x32_bf16 v[28:31], v[156:159], v[204:207], v[28:31]
	v_mfma_f32_16x16x32_bf16 v[24:27], v[170:173], v[204:207], v[24:27]
	v_mfma_f32_16x16x32_bf16 v[12:15], v[156:159], v[212:215], v[12:15]
	v_mfma_f32_16x16x32_bf16 v[8:11], v[170:173], v[212:215], v[8:11]
	v_mfma_f32_16x16x32_bf16 v[60:63], v[160:163], v[192:195], v[60:63]
	v_mfma_f32_16x16x32_bf16 v[56:59], v[174:177], v[192:195], v[56:59]
	v_mfma_f32_16x16x32_bf16 v[44:47], v[160:163], v[200:203], v[44:47]
	v_mfma_f32_16x16x32_bf16 v[40:43], v[174:177], v[200:203], v[40:43]
	v_mfma_f32_16x16x32_bf16 v[28:31], v[160:163], v[208:211], v[28:31]
	v_mfma_f32_16x16x32_bf16 v[24:27], v[174:177], v[208:211], v[24:27]
	v_mfma_f32_16x16x32_bf16 v[12:15], v[160:163], v[216:219], v[12:15]
	v_mfma_f32_16x16x32_bf16 v[8:11], v[174:177], v[216:219], v[8:11]
	s_barrier
	s_add_u32 s14, s56, 0x40000
	s_addc_u32 s15, s57, 0
	s_add_i32 s16, s16, s64
	s_mov_b32 m0, s16
	s_nop 0
	global_load_lds_dwordx4 v148, s[14:15]
	s_add_i32 m0, s16, 0x2000
	s_nop 0
	global_load_lds_dwordx4 v150, s[14:15]
	s_waitcnt vmcnt(6)
	s_barrier
; #define PG8_STAGE(bufoff, gbase, voff) do { _Pragma("unroll") for (int _i = 0; _i < 2; ++_i) \
;         __builtin_amdgcn_global_load_lds((const unsigned*)((const char*)(gbase) + (voff)[_i]), (PG8_LAS unsigned*)(lds + (bufoff) + ldsw + _i * 8192), 16, 0, 0); } while (0)
; #define PG8_LDA(dst, b, h) do { _Pragma("unroll") for (int m = 0; m < 4; ++m) _Pragma("unroll") for (int k = 0; k < 2; ++k) dst[m][k] = *(const PG8_LAS bf16x8*)(lds + PG8_SA(b, h) + aoff + m * 2048 + k * 1024); } while (0)
; #define PG8_LDB(dst, b, h) do { _Pragma("unroll") for (int n = 0; n < 2; ++n) _Pragma("unroll") for (int k = 0; k < 2; ++k) dst[n][k] = *(const PG8_LAS bf16x8*)(lds + PG8_SB(b, h) + boff + n * 2048 + k * 1024); } while (0)
; #define PG8_MMA(ai, bj, At, Bt) do { __builtin_amdgcn_s_setprio(1); _Pragma("unroll") for (int m = 0; m < 4; ++m) _Pragma("unroll") for (int n = 0; n < 2; ++n) _Pragma("unroll") for (int k = 0; k < 2; ++k) \
;         acc[ai][bj][m][n] = __builtin_amdgcn_mfma_f32_16x16x32_bf16(Bt[n][k], At[m][k], acc[ai][bj][m][n], 0, 0, 0); __builtin_amdgcn_s_setprio(0); } while (0)
; #define PG8_WAIT_V(n) asm volatile("s_waitcnt vmcnt(" #n ")" ::: "memory")
; #define PG8_WAIT_L(n) asm volatile("s_waitcnt lgkmcnt(" #n ")" ::: "memory")
; #define PG8_BAR __builtin_amdgcn_s_barrier()
; #define PG8_SCHED __builtin_amdgcn_sched_barrier(0)
; template <class Epi, class Sched, bool STAMP = false>
; __device__ __forceinline__ void gemm_phase(PG8_LAS unsigned char* lds, const Gemm g, const Sched& S, const Epi& E, unsigned long long* stamps) {
;     ...
;             PG8_WAIT_V(6); PG8_BAR; PG8_MMA(1, 1, At, B1); PG8_BAR;
;             PG8_LDB(B0, 1, 0); PG8_SCHED; PG8_LDA(At, 1, 0); PG8_STAGE(PG8_SA(0, 1), a2 + hstep, voffA);
;             PG8_WAIT_L(8); PG8_BAR; PG8_WAIT_L(0); PG8_MMA(0, 0, At, B0); PG8_BAR; PG8_SCHED;
;             PG8_LDB(B1, 1, 1); PG8_STAGE(PG8_SB(1, 0), b3, voffB);
;             PG8_BAR; PG8_WAIT_L(0); PG8_MMA(0, 1, At, B1); PG8_BAR;
;             PG8_LDA(At, 1, 1); PG8_STAGE(PG8_SA(1, 0), a3, voffA);
;             PG8_BAR; PG8_WAIT_L(0); PG8_MMA(1, 0, At, B0); PG8_BAR; PG8_SCHED;
	v_mfma_f32_16x16x32_bf16 v[52:55], v[220:223], v[178:181], v[52:55]
	v_mfma_f32_16x16x32_bf16 v[48:51], v[228:231], v[178:181], v[48:51]
	v_mfma_f32_16x16x32_bf16 v[36:39], v[220:223], v[196:199], v[36:39]
	v_mfma_f32_16x16x32_bf16 v[32:35], v[228:231], v[196:199], v[32:35]
	v_mfma_f32_16x16x32_bf16 v[20:23], v[220:223], v[204:207], v[20:23]
	v_mfma_f32_16x16x32_bf16 v[16:19], v[228:231], v[204:207], v[16:19]
	v_mfma_f32_16x16x32_bf16 v[4:7], v[220:223], v[212:215], v[4:7]
	v_mfma_f32_16x16x32_bf16 v[0:3], v[228:231], v[212:215], v[0:3]
	v_mfma_f32_16x16x32_bf16 v[52:55], v[224:227], v[192:195], v[52:55]
	v_mfma_f32_16x16x32_bf16 v[48:51], v[232:235], v[192:195], v[48:51]
	v_mfma_f32_16x16x32_bf16 v[36:39], v[224:227], v[200:203], v[36:39]
	v_mfma_f32_16x16x32_bf16 v[32:35], v[232:235], v[200:203], v[32:35]
	v_mfma_f32_16x16x32_bf16 v[20:23], v[224:227], v[208:211], v[20:23]
	v_mfma_f32_16x16x32_bf16 v[16:19], v[232:235], v[208:211], v[16:19]
	v_mfma_f32_16x16x32_bf16 v[4:7], v[224:227], v[216:219], v[4:7]
	v_mfma_f32_16x16x32_bf16 v[0:3], v[232:235], v[216:219], v[0:3]
	s_barrier
	s_add_i32 s16, 0, 0x18000
	ds_read_b128 v[156:159], v250
	ds_read_b128 v[160:163], v250 offset:1024
	ds_read_b128 v[170:173], v250 offset:2048
	ds_read_b128 v[174:177], v250 offset:3072
	s_add_u32 s14, s58, 0x40000
	s_addc_u32 s15, s59, 0
	s_mov_b32 m0, s76
	ds_read_b128 v[178:181], v168 offset:32768
	ds_read_b128 v[192:195], v168 offset:33792
	ds_read_b128 v[196:199], v168 offset:34816
	ds_read_b128 v[200:203], v168 offset:35840
	ds_read_b128 v[204:207], v168 offset:36864
	ds_read_b128 v[208:211], v168 offset:37888
	ds_read_b128 v[212:215], v168 offset:38912
	global_load_lds_dwordx4 v148, s[14:15]
	s_mov_b32 m0, s77
	ds_read_b128 v[216:219], v168 offset:39936
	global_load_lds_dwordx4 v150, s[14:15]
	s_waitcnt lgkmcnt(8)
	s_barrier
	s_waitcnt lgkmcnt(0)
	v_mfma_f32_16x16x32_bf16 v[124:127], v[156:159], v[178:181], v[124:127]
	v_mfma_f32_16x16x32_bf16 v[120:123], v[170:173], v[178:181], v[120:123]
	v_mfma_f32_16x16x32_bf16 v[108:111], v[156:159], v[196:199], v[108:111]
	v_mfma_f32_16x16x32_bf16 v[104:107], v[170:173], v[196:199], v[104:107]
	v_mfma_f32_16x16x32_bf16 v[92:95], v[156:159], v[204:207], v[92:95]
	v_mfma_f32_16x16x32_bf16 v[88:91], v[170:173], v[204:207], v[88:91]
	v_mfma_f32_16x16x32_bf16 v[76:79], v[156:159], v[212:215], v[76:79]
	v_mfma_f32_16x16x32_bf16 v[72:75], v[170:173], v[212:215], v[72:75]
	v_mfma_f32_16x16x32_bf16 v[124:127], v[160:163], v[192:195], v[124:127]
	v_mfma_f32_16x16x32_bf16 v[120:123], v[174:177], v[192:195], v[120:123]
	v_mfma_f32_16x16x32_bf16 v[108:111], v[160:163], v[200:203], v[108:111]
	v_mfma_f32_16x16x32_bf16 v[104:107], v[174:177], v[200:203], v[104:107]
	v_mfma_f32_16x16x32_bf16 v[92:95], v[160:163], v[208:211], v[92:95]
	v_mfma_f32_16x16x32_bf16 v[88:91], v[174:177], v[208:211], v[88:91]
	v_mfma_f32_16x16x32_bf16 v[76:79], v[160:163], v[216:219], v[76:79]
	v_mfma_f32_16x16x32_bf16 v[72:75], v[174:177], v[216:219], v[72:75]
	s_barrier
	s_add_i32 s17, 0, 0x1c000
	s_add_i32 s14, s16, s64
	s_mov_b32 m0, s14
	ds_read_b128 v[220:223], v251
	ds_read_b128 v[224:227], v251 offset:1024
	ds_read_b128 v[228:231], v251 offset:2048
	global_load_lds_dwordx4 v244, s[56:57]
	s_add_i32 m0, s14, 0x2000
	ds_read_b128 v[232:235], v251 offset:3072
	global_load_lds_dwordx4 v245, s[56:57]
	s_barrier
	s_waitcnt lgkmcnt(0)
	v_mfma_f32_16x16x32_bf16 v[116:119], v[220:223], v[178:181], v[116:119]
	v_mfma_f32_16x16x32_bf16 v[112:115], v[228:231], v[178:181], v[112:115]
	v_mfma_f32_16x16x32_bf16 v[100:103], v[220:223], v[196:199], v[100:103]
	v_mfma_f32_16x16x32_bf16 v[96:99], v[228:231], v[196:199], v[96:99]
	v_mfma_f32_16x16x32_bf16 v[84:87], v[220:223], v[204:207], v[84:87]
	v_mfma_f32_16x16x32_bf16 v[80:83], v[228:231], v[204:207], v[80:83]
	v_mfma_f32_16x16x32_bf16 v[68:71], v[220:223], v[212:215], v[68:71]
	v_mfma_f32_16x16x32_bf16 v[64:67], v[228:231], v[212:215], v[64:67]
	v_mfma_f32_16x16x32_bf16 v[116:119], v[224:227], v[192:195], v[116:119]
	v_mfma_f32_16x16x32_bf16 v[112:115], v[232:235], v[192:195], v[112:115]
	v_mfma_f32_16x16x32_bf16 v[100:103], v[224:227], v[200:203], v[100:103]
	v_mfma_f32_16x16x32_bf16 v[96:99], v[232:235], v[200:203], v[96:99]
	v_mfma_f32_16x16x32_bf16 v[84:87], v[224:227], v[208:211], v[84:87]
	v_mfma_f32_16x16x32_bf16 v[80:83], v[232:235], v[208:211], v[80:83]
	v_mfma_f32_16x16x32_bf16 v[68:71], v[224:227], v[216:219], v[68:71]
	v_mfma_f32_16x16x32_bf16 v[64:67], v[232:235], v[216:219], v[64:67]
	s_barrier
; __device__ __forceinline__ unsigned cvt_pk_bf16(float lo, float hi) { const f32x2_cv v = {lo, hi}; const bf16x2_cv b = __builtin_convertvector(v, bf16x2_cv); return __builtin_bit_cast(unsigned, b); }
; #define PG8_STAGE(bufoff, gbase, voff) do { _Pragma("unroll") for (int _i = 0; _i < 2; ++_i) \
;         __builtin_amdgcn_global_load_lds((const unsigned*)((const char*)(gbase) + (voff)[_i]), (PG8_LAS unsigned*)(lds + (bufoff) + ldsw + _i * 8192), 16, 0, 0); } while (0)
; #define PG8_BAR __builtin_amdgcn_s_barrier()
; template <class Epi, class Sched, bool STAMP = false>
; __device__ __forceinline__ void gemm_phase(PG8_LAS unsigned char* lds, const Gemm g, const Sched& S, const Epi& E, unsigned long long* stamps) {
;     ...
;             PG8_LDA(At, 1, 1); PG8_STAGE(PG8_SA(1, 0), a3, voffA);
;             PG8_BAR; PG8_WAIT_L(0); PG8_MMA(1, 0, At, B0); PG8_BAR; PG8_SCHED;
;             PG8_STAGE(PG8_SB(1, 1), b3 + hstep, voffB);
;             PG8_WAIT_V(6); PG8_BAR; PG8_MMA(1, 1, At, B1); PG8_BAR;
;     __device__ __forceinline__ void operator()(const f32x4 (&acc)[2][2][4][2], const pg8::Unit& u, int wr, int wc, int fr, int fq) const {
;         const int row0 = u.pm * 256 + wr * 64 + fr, col0 = u.pn * 256 + wc * 32 + 4 * fq;
; #pragma unroll
;         for (int ai = 0; ai < 2; ++ai)
; #pragma unroll
;             for (int m = 0; m < 4; ++m) {
;                 const int row = row0 + ai * 128 + m * 16;
;                 float* xp = X + (size_t)row * 1024 + col0; bf16_t* bp = XB + (size_t)row * 1024 + col0;
;                 const float* xi = Xp0 ? (row < T_P ? Xp0 + (size_t)row * 1024 + col0 : Xs0 + (size_t)(row - T_P) * 1024 + col0) : xp;
;                 float ss = 0.f;
; #pragma unroll
;                 for (int bj = 0; bj < 2; ++bj)
; #pragma unroll
;                     for (int n = 0; n < 2; ++n) {
;                         f32x4 xv = *(const f32x4*)(xi + bj * 128 + n * 16) + acc[ai][bj][m][n];
;                         *(f32x4*)(xp + bj * 128 + n * 16) = xv;
;                         ss += (xv[0] * xv[0] + xv[1] * xv[1]) + (xv[2] * xv[2] + xv[3] * xv[3]);
;                         u32x2 w; w.x = cvt_pk_bf16(xv[0], xv[1]); w.y = cvt_pk_bf16(xv[2], xv[3]);
;                         *(u32x2*)(bp + bj * 128 + n * 16) = w; }
;                 ss += __shfl_xor(ss, 16); ss += __shfl_xor(ss, 32);
;                 if (fq == 0) atomicAdd(rowss_out + row, ss); }
	s_mov_b32 m0, s88
	ds_read_b128 v[178:181], v168 offset:49152
	ds_read_b128 v[192:195], v168 offset:50176
	ds_read_b128 v[196:199], v168 offset:51200
	ds_read_b128 v[200:203], v168 offset:52224
	ds_read_b128 v[204:207], v168 offset:53248
	ds_read_b128 v[208:211], v168 offset:54272
	ds_read_b128 v[212:215], v168 offset:55296
	global_load_lds_dwordx4 v244, s[58:59]
	s_mov_b32 m0, s89
	ds_read_b128 v[216:219], v168 offset:56320
	global_load_lds_dwordx4 v245, s[58:59]
	s_barrier
	s_waitcnt lgkmcnt(0)
	v_mfma_f32_16x16x32_bf16 v[60:63], v[156:159], v[178:181], v[60:63]
	v_mfma_f32_16x16x32_bf16 v[56:59], v[170:173], v[178:181], v[56:59]
	v_mfma_f32_16x16x32_bf16 v[44:47], v[156:159], v[196:199], v[44:47]
	v_mfma_f32_16x16x32_bf16 v[40:43], v[170:173], v[196:199], v[40:43]
	v_mfma_f32_16x16x32_bf16 v[28:31], v[156:159], v[204:207], v[28:31]
	v_mfma_f32_16x16x32_bf16 v[24:27], v[170:173], v[204:207], v[24:27]
	v_mfma_f32_16x16x32_bf16 v[12:15], v[156:159], v[212:215], v[12:15]
	v_mfma_f32_16x16x32_bf16 v[8:11], v[170:173], v[212:215], v[8:11]
	v_mfma_f32_16x16x32_bf16 v[60:63], v[160:163], v[192:195], v[60:63]
	v_mfma_f32_16x16x32_bf16 v[56:59], v[174:177], v[192:195], v[56:59]
	v_mfma_f32_16x16x32_bf16 v[44:47], v[160:163], v[200:203], v[44:47]
	v_mfma_f32_16x16x32_bf16 v[40:43], v[174:177], v[200:203], v[40:43]
	v_mfma_f32_16x16x32_bf16 v[28:31], v[160:163], v[208:211], v[28:31]
	v_mfma_f32_16x16x32_bf16 v[24:27], v[174:177], v[208:211], v[24:27]
	v_mfma_f32_16x16x32_bf16 v[12:15], v[160:163], v[216:219], v[12:15]
	v_mfma_f32_16x16x32_bf16 v[8:11], v[174:177], v[216:219], v[8:11]
	s_barrier
	s_add_u32 s14, s56, 0x40080
	s_addc_u32 s15, s57, 0
	s_add_i32 s16, s17, s64
	s_mov_b32 m0, s16
	s_nop 0
	global_load_lds_dwordx4 v148, s[14:15]
	s_add_i32 m0, s16, 0x2000
	s_nop 0
	global_load_lds_dwordx4 v150, s[14:15]
	s_waitcnt vmcnt(6)
	s_barrier
	v_mfma_f32_16x16x32_bf16 v[52:55], v[220:223], v[178:181], v[52:55]
	v_mfma_f32_16x16x32_bf16 v[48:51], v[228:231], v[178:181], v[48:51]
	v_mfma_f32_16x16x32_bf16 v[36:39], v[220:223], v[196:199], v[36:39]
	v_mfma_f32_16x16x32_bf16 v[32:35], v[228:231], v[196:199], v[32:35]
	v_mfma_f32_16x16x32_bf16 v[20:23], v[220:223], v[204:207], v[20:23]
	v_mfma_f32_16x16x32_bf16 v[16:19], v[228:231], v[204:207], v[16:19]
	v_mfma_f32_16x16x32_bf16 v[4:7], v[220:223], v[212:215], v[4:7]
	v_mfma_f32_16x16x32_bf16 v[0:3], v[228:231], v[212:215], v[0:3]
	v_mfma_f32_16x16x32_bf16 v[52:55], v[224:227], v[192:195], v[52:55]
	v_mfma_f32_16x16x32_bf16 v[48:51], v[232:235], v[192:195], v[48:51]
	v_mfma_f32_16x16x32_bf16 v[36:39], v[224:227], v[200:203], v[36:39]
	v_mfma_f32_16x16x32_bf16 v[32:35], v[232:235], v[200:203], v[32:35]
	v_mfma_f32_16x16x32_bf16 v[20:23], v[224:227], v[208:211], v[20:23]
	v_mfma_f32_16x16x32_bf16 v[16:19], v[232:235], v[208:211], v[16:19]
	v_mfma_f32_16x16x32_bf16 v[4:7], v[224:227], v[216:219], v[4:7]
	v_mfma_f32_16x16x32_bf16 v[0:3], v[232:235], v[216:219], v[0:3]
	s_add_i32 s39, s39, 2
	s_add_u32 vcc_hi, vcc_hi, 0x100
	s_addc_u32 s38, s38, 0
	s_cmp_gt_u32 s39, 13
	s_mov_b64 s[44:45], s[48:49]
	s_barrier
	s_cbranch_scc0 .LBB0_141
	v_lshl_add_u32 v158, s30, 8, v139
	v_ashrrev_i32_e32 v159, 31, v158
	v_lshl_or_b32 v156, s36, 8, v167
	v_lshlrev_b64 v[160:161], 12, v[158:159]
	v_ashrrev_i32_e32 v157, 31, v156
	v_lshl_add_u64 v[160:161], s[84:85], 0, v[160:161]
	v_lshl_add_u64 v[160:161], v[156:157], 2, v[160:161]
	v_cndmask_b32_e64 v128, 0, 1, s[12:13]
	v_lshlrev_b64 v[164:165], 10, v[158:159]
	v_cmp_ne_u32_e64 s[44:45], 1, v128
	s_andn2_b64 vcc, exec, s[12:13]
	v_mov_b64_e32 v[162:163], v[160:161]
	v_readlane_b32 s39, v242, 28
	s_movk_i32 s21, 0x3fff
	s_mov_b32 s38, 0x1ffff
	s_cbranch_vccnz .LBB0_148
	v_cmp_lt_i32_e32 vcc, s21, v158
	s_and_saveexec_b64 s[14:15], vcc
	s_xor_b64 s[30:31], exec, s[14:15]
	v_add_u32_e32 v128, 0xffffc000, v158
	v_lshlrev_b64 v[162:163], 12, v[128:129]
	v_lshl_add_u64 v[162:163], s[4:5], 0, v[162:163]
	v_lshl_add_u64 v[162:163], v[156:157], 2, v[162:163]
	s_andn2_saveexec_b64 s[30:31], s[30:31]
	v_lshl_add_u64 v[162:163], v[164:165], 2, s[0:1]
	v_lshl_add_u64 v[162:163], v[156:157], 2, v[162:163]
	s_or_b64 exec, exec, s[30:31]

; #define PG8_STAGE(bufoff, gbase, voff) do { _Pragma("unroll") for (int _i = 0; _i < 2; ++_i) \
;         __builtin_amdgcn_global_load_lds((const unsigned*)((const char*)(gbase) + (voff)[_i]), (PG8_LAS unsigned*)(lds + (bufoff) + ldsw + _i * 8192), 16, 0, 0); } while (0)
; #define PG8_LDA(dst, b, h) do { _Pragma("unroll") for (int m = 0; m < 4; ++m) _Pragma("unroll") for (int k = 0; k < 2; ++k) dst[m][k] = *(const PG8_LAS bf16x8*)(lds + PG8_SA(b, h) + aoff + m * 2048 + k * 1024); } while (0)
; #define PG8_LDB(dst, b, h) do { _Pragma("unroll") for (int n = 0; n < 2; ++n) _Pragma("unroll") for (int k = 0; k < 2; ++k) dst[n][k] = *(const PG8_LAS bf16x8*)(lds + PG8_SB(b, h) + boff + n * 2048 + k * 1024); } while (0)
; #define PG8_MMA(ai, bj, At, Bt) do { __builtin_amdgcn_s_setprio(1); _Pragma("unroll") for (int m = 0; m < 4; ++m) _Pragma("unroll") for (int n = 0; n < 2; ++n) _Pragma("unroll") for (int k = 0; k < 2; ++k) \
;         acc[ai][bj][m][n] = __builtin_amdgcn_mfma_f32_16x16x32_bf16(Bt[n][k], At[m][k], acc[ai][bj][m][n], 0, 0, 0); __builtin_amdgcn_s_setprio(0); } while (0)
; #define PG8_BAR __builtin_amdgcn_s_barrier()
; template <class Epi, class Sched, bool STAMP = false>
; __device__ __forceinline__ void gemm_phase(PG8_LAS unsigned char* lds, const Gemm g, const Sched& S, const Epi& E, unsigned long long* stamps) {
;     ...
;         for (int t = 0; t < nt; t += 2) {
;             const bool last = (t == nt - 2);
;             const char* a1 = cA + (size_t)(t + 1) * kstep;
;             const char* a2 = last ? nA : cA + (size_t)(t + 2) * kstep; const char* b2 = last ? nB : cB + (size_t)(t + 2) * kstep;
;             const char* a3 = a2 + kstep; const char* b3 = b2 + kstep;
;             if (last && has_next) S.a_ready(nxt);
;             PG8_LDB(B0, 0, 0); PG8_SCHED; PG8_LDA(At, 0, 0); PG8_STAGE(PG8_SA(1, 1), a1 + hstep, voffA);
;             PG8_WAIT_L(8); PG8_BAR; PG8_WAIT_L(0); PG8_MMA(0, 0, At, B0); PG8_BAR; PG8_SCHED;
;             PG8_LDB(B1, 0, 1); PG8_STAGE(PG8_SB(0, 0), b2, voffB);
;             PG8_BAR; PG8_WAIT_L(0); PG8_MMA(0, 1, At, B1); PG8_BAR;
;             PG8_LDA(At, 0, 1); PG8_STAGE(PG8_SA(0, 0), a2, voffA);
;             PG8_BAR; PG8_WAIT_L(0); PG8_MMA(1, 0, At, B0); PG8_BAR; PG8_SCHED;
;             PG8_STAGE(PG8_SB(0, 1), b2 + hstep, voffB);
;             PG8_WAIT_V(6); PG8_BAR; PG8_MMA(1, 1, At, B1); PG8_BAR;
.LBB0_293:
	s_add_u32 s14, s24, 0xfffe0080
	s_addc_u32 s15, s25, -1
	s_add_i32 s16, 0, 0x10000
	ds_read_b128 v[162:165], v248
	ds_read_b128 v[166:169], v248 offset:1024
	ds_read_b128 v[170:173], v248 offset:2048
	ds_read_b128 v[174:177], v248 offset:3072
	s_cmp_eq_u32 s59, 4
	s_cselect_b32 s31, s7, s15
	s_cselect_b32 s30, s53, s14
	s_cselect_b32 s27, s5, s58
	s_cselect_b32 s26, s56, s57
	s_add_i32 m0, s3, 0xc000
	ds_read_b128 v[178:181], v160
	ds_read_b128 v[192:195], v160 offset:1024
	ds_read_b128 v[196:199], v160 offset:2048
	ds_read_b128 v[200:203], v160 offset:3072
	ds_read_b128 v[204:207], v160 offset:4096
	ds_read_b128 v[208:211], v160 offset:5120
	ds_read_b128 v[212:215], v160 offset:6144
	global_load_lds_dwordx4 v154, s[24:25]
	s_add_i32 m0, s3, 0xe000
	ds_read_b128 v[216:219], v160 offset:7168
	global_load_lds_dwordx4 v156, s[24:25]
	s_waitcnt lgkmcnt(8)
	s_barrier
	s_waitcnt lgkmcnt(0)
	v_mfma_f32_16x16x32_bf16 v[124:127], v[162:165], v[178:181], v[124:127]
	v_mfma_f32_16x16x32_bf16 v[120:123], v[170:173], v[178:181], v[120:123]
	v_mfma_f32_16x16x32_bf16 v[116:119], v[162:165], v[196:199], v[116:119]
	v_mfma_f32_16x16x32_bf16 v[112:115], v[170:173], v[196:199], v[112:115]
	v_mfma_f32_16x16x32_bf16 v[100:103], v[162:165], v[204:207], v[100:103]
	v_mfma_f32_16x16x32_bf16 v[96:99], v[170:173], v[204:207], v[96:99]
	v_mfma_f32_16x16x32_bf16 v[84:87], v[162:165], v[212:215], v[84:87]
	v_mfma_f32_16x16x32_bf16 v[80:83], v[170:173], v[212:215], v[80:83]
	v_mfma_f32_16x16x32_bf16 v[124:127], v[166:169], v[192:195], v[124:127]
	v_mfma_f32_16x16x32_bf16 v[120:123], v[174:177], v[192:195], v[120:123]
	v_mfma_f32_16x16x32_bf16 v[116:119], v[166:169], v[200:203], v[116:119]
	v_mfma_f32_16x16x32_bf16 v[112:115], v[174:177], v[200:203], v[112:115]
	v_mfma_f32_16x16x32_bf16 v[100:103], v[166:169], v[208:211], v[100:103]
	v_mfma_f32_16x16x32_bf16 v[96:99], v[174:177], v[208:211], v[96:99]
	v_mfma_f32_16x16x32_bf16 v[84:87], v[166:169], v[216:219], v[84:87]
	v_mfma_f32_16x16x32_bf16 v[80:83], v[174:177], v[216:219], v[80:83]
	s_barrier
	s_add_i32 s17, 0, 0x14000
	s_add_i32 s14, s16, s40
	s_mov_b32 m0, s14
	ds_read_b128 v[220:223], v249
	ds_read_b128 v[224:227], v249 offset:1024
	ds_read_b128 v[228:231], v249 offset:2048
	global_load_lds_dwordx4 v128, s[26:27]
	s_add_i32 m0, s14, 0x2000
	ds_read_b128 v[232:235], v249 offset:3072
	global_load_lds_dwordx4 v152, s[26:27]
	s_barrier
	s_waitcnt lgkmcnt(0)
	v_mfma_f32_16x16x32_bf16 v[108:111], v[220:223], v[178:181], v[108:111]
	v_mfma_f32_16x16x32_bf16 v[104:107], v[228:231], v[178:181], v[104:107]
	v_mfma_f32_16x16x32_bf16 v[92:95], v[220:223], v[196:199], v[92:95]
	v_mfma_f32_16x16x32_bf16 v[88:91], v[228:231], v[196:199], v[88:91]
	v_mfma_f32_16x16x32_bf16 v[76:79], v[220:223], v[204:207], v[76:79]
	v_mfma_f32_16x16x32_bf16 v[72:75], v[228:231], v[204:207], v[72:75]
	v_mfma_f32_16x16x32_bf16 v[68:71], v[220:223], v[212:215], v[68:71]
	v_mfma_f32_16x16x32_bf16 v[64:67], v[228:231], v[212:215], v[64:67]
	v_mfma_f32_16x16x32_bf16 v[108:111], v[224:227], v[192:195], v[108:111]
	v_mfma_f32_16x16x32_bf16 v[104:107], v[232:235], v[192:195], v[104:107]
	v_mfma_f32_16x16x32_bf16 v[92:95], v[224:227], v[200:203], v[92:95]
	v_mfma_f32_16x16x32_bf16 v[88:91], v[232:235], v[200:203], v[88:91]
	v_mfma_f32_16x16x32_bf16 v[76:79], v[224:227], v[208:211], v[76:79]
	v_mfma_f32_16x16x32_bf16 v[72:75], v[232:235], v[208:211], v[72:75]
	v_mfma_f32_16x16x32_bf16 v[68:71], v[224:227], v[216:219], v[68:71]
	v_mfma_f32_16x16x32_bf16 v[64:67], v[232:235], v[216:219], v[64:67]
	s_barrier
	s_mov_b32 m0, s3
	ds_read_b128 v[178:181], v160 offset:16384
	ds_read_b128 v[192:195], v160 offset:17408
	ds_read_b128 v[196:199], v160 offset:18432
	ds_read_b128 v[200:203], v160 offset:19456
	ds_read_b128 v[204:207], v160 offset:20480
	ds_read_b128 v[208:211], v160 offset:21504
	ds_read_b128 v[212:215], v160 offset:22528
	global_load_lds_dwordx4 v148, s[30:31]
	s_mov_b32 m0, s41
	ds_read_b128 v[216:219], v160 offset:23552
	global_load_lds_dwordx4 v150, s[30:31]
	s_barrier
	s_waitcnt lgkmcnt(0)
	v_mfma_f32_16x16x32_bf16 v[60:63], v[162:165], v[178:181], v[60:63]
	v_mfma_f32_16x16x32_bf16 v[56:59], v[170:173], v[178:181], v[56:59]
	v_mfma_f32_16x16x32_bf16 v[52:55], v[162:165], v[196:199], v[52:55]
	v_mfma_f32_16x16x32_bf16 v[48:51], v[170:173], v[196:199], v[48:51]
	v_mfma_f32_16x16x32_bf16 v[36:39], v[162:165], v[204:207], v[36:39]
	v_mfma_f32_16x16x32_bf16 v[32:35], v[170:173], v[204:207], v[32:35]
	v_mfma_f32_16x16x32_bf16 v[20:23], v[162:165], v[212:215], v[20:23]
	v_mfma_f32_16x16x32_bf16 v[16:19], v[170:173], v[212:215], v[16:19]
	v_mfma_f32_16x16x32_bf16 v[60:63], v[166:169], v[192:195], v[60:63]
	v_mfma_f32_16x16x32_bf16 v[56:59], v[174:177], v[192:195], v[56:59]
	v_mfma_f32_16x16x32_bf16 v[52:55], v[166:169], v[200:203], v[52:55]
	v_mfma_f32_16x16x32_bf16 v[48:51], v[174:177], v[200:203], v[48:51]
	v_mfma_f32_16x16x32_bf16 v[36:39], v[166:169], v[208:211], v[36:39]
	v_mfma_f32_16x16x32_bf16 v[32:35], v[174:177], v[208:211], v[32:35]
	v_mfma_f32_16x16x32_bf16 v[20:23], v[166:169], v[216:219], v[20:23]
	v_mfma_f32_16x16x32_bf16 v[16:19], v[174:177], v[216:219], v[16:19]
	s_barrier
	s_add_u32 s14, s26, 0x20000
	s_addc_u32 s15, s27, 0
	s_add_i32 s16, s17, s40
	s_mov_b32 m0, s16
	s_nop 0
	global_load_lds_dwordx4 v128, s[14:15]
	s_add_i32 m0, s16, 0x2000
	s_nop 0
	global_load_lds_dwordx4 v152, s[14:15]
	s_add_i32 s59, s59, 2
	s_add_u32 s24, s24, 0x100
	s_addc_u32 s25, s25, 0
	s_add_u32 s57, s57, 0x100
	s_addc_u32 s58, s58, 0
	s_waitcnt vmcnt(6)
	s_barrier
; #define PG8_STAGE(bufoff, gbase, voff) do { _Pragma("unroll") for (int _i = 0; _i < 2; ++_i) \
;         __builtin_amdgcn_global_load_lds((const unsigned*)((const char*)(gbase) + (voff)[_i]), (PG8_LAS unsigned*)(lds + (bufoff) + ldsw + _i * 8192), 16, 0, 0); } while (0)
; #define PG8_LDA(dst, b, h) do { _Pragma("unroll") for (int m = 0; m < 4; ++m) _Pragma("unroll") for (int k = 0; k < 2; ++k) dst[m][k] = *(const PG8_LAS bf16x8*)(lds + PG8_SA(b, h) + aoff + m * 2048 + k * 1024); } while (0)
; #define PG8_LDB(dst, b, h) do { _Pragma("unroll") for (int n = 0; n < 2; ++n) _Pragma("unroll") for (int k = 0; k < 2; ++k) dst[n][k] = *(const PG8_LAS bf16x8*)(lds + PG8_SB(b, h) + boff + n * 2048 + k * 1024); } while (0)
; #define PG8_MMA(ai, bj, At, Bt) do { __builtin_amdgcn_s_setprio(1); _Pragma("unroll") for (int m = 0; m < 4; ++m) _Pragma("unroll") for (int n = 0; n < 2; ++n) _Pragma("unroll") for (int k = 0; k < 2; ++k) \
;         acc[ai][bj][m][n] = __builtin_amdgcn_mfma_f32_16x16x32_bf16(Bt[n][k], At[m][k], acc[ai][bj][m][n], 0, 0, 0); __builtin_amdgcn_s_setprio(0); } while (0)
; #define PG8_WAIT_V(n) asm volatile("s_waitcnt vmcnt(" #n ")" ::: "memory")
; #define PG8_WAIT_L(n) asm volatile("s_waitcnt lgkmcnt(" #n ")" ::: "memory")
; #define PG8_BAR __builtin_amdgcn_s_barrier()
; #define PG8_SCHED __builtin_amdgcn_sched_barrier(0)
; template <class Epi, class Sched, bool STAMP = false>
; __device__ __forceinline__ void gemm_phase(PG8_LAS unsigned char* lds, const Gemm g, const Sched& S, const Epi& E, unsigned long long* stamps) {
;     ...
;             PG8_WAIT_V(6); PG8_BAR; PG8_MMA(1, 1, At, B1); PG8_BAR;
;             PG8_LDB(B0, 1, 0); PG8_SCHED; PG8_LDA(At, 1, 0); PG8_STAGE(PG8_SA(0, 1), a2 + hstep, voffA);
;             PG8_WAIT_L(8); PG8_BAR; PG8_WAIT_L(0); PG8_MMA(0, 0, At, B0); PG8_BAR; PG8_SCHED;
;             PG8_LDB(B1, 1, 1); PG8_STAGE(PG8_SB(1, 0), b3, voffB);
;             PG8_BAR; PG8_WAIT_L(0); PG8_MMA(0, 1, At, B1); PG8_BAR;
;             PG8_LDA(At, 1, 1); PG8_STAGE(PG8_SA(1, 0), a3, voffA);
;             PG8_BAR; PG8_WAIT_L(0); PG8_MMA(1, 0, At, B0); PG8_BAR; PG8_SCHED;
	v_mfma_f32_16x16x32_bf16 v[44:47], v[220:223], v[178:181], v[44:47]
	v_mfma_f32_16x16x32_bf16 v[40:43], v[228:231], v[178:181], v[40:43]
	v_mfma_f32_16x16x32_bf16 v[28:31], v[220:223], v[196:199], v[28:31]
	v_mfma_f32_16x16x32_bf16 v[24:27], v[228:231], v[196:199], v[24:27]
	v_mfma_f32_16x16x32_bf16 v[12:15], v[220:223], v[204:207], v[12:15]
	v_mfma_f32_16x16x32_bf16 v[8:11], v[228:231], v[204:207], v[8:11]
	v_mfma_f32_16x16x32_bf16 v[4:7], v[220:223], v[212:215], v[4:7]
	v_mfma_f32_16x16x32_bf16 v[0:3], v[228:231], v[212:215], v[0:3]
	v_mfma_f32_16x16x32_bf16 v[44:47], v[224:227], v[192:195], v[44:47]
	v_mfma_f32_16x16x32_bf16 v[40:43], v[232:235], v[192:195], v[40:43]
	v_mfma_f32_16x16x32_bf16 v[28:31], v[224:227], v[200:203], v[28:31]
	v_mfma_f32_16x16x32_bf16 v[24:27], v[232:235], v[200:203], v[24:27]
	v_mfma_f32_16x16x32_bf16 v[12:15], v[224:227], v[208:211], v[12:15]
	v_mfma_f32_16x16x32_bf16 v[8:11], v[232:235], v[208:211], v[8:11]
	v_mfma_f32_16x16x32_bf16 v[4:7], v[224:227], v[216:219], v[4:7]
	v_mfma_f32_16x16x32_bf16 v[0:3], v[232:235], v[216:219], v[0:3]
	s_barrier
	s_add_i32 s16, 0, 0x18000
	ds_read_b128 v[162:165], v250
	ds_read_b128 v[166:169], v250 offset:1024
	ds_read_b128 v[170:173], v250 offset:2048
	ds_read_b128 v[174:177], v250 offset:3072
	s_add_u32 s14, s30, 0x20000
	s_addc_u32 s15, s31, 0
	s_mov_b32 m0, s42
	ds_read_b128 v[178:181], v160 offset:32768
	ds_read_b128 v[192:195], v160 offset:33792
	ds_read_b128 v[196:199], v160 offset:34816
	ds_read_b128 v[200:203], v160 offset:35840
	ds_read_b128 v[204:207], v160 offset:36864
	ds_read_b128 v[208:211], v160 offset:37888
	ds_read_b128 v[212:215], v160 offset:38912
	global_load_lds_dwordx4 v148, s[14:15]
	s_mov_b32 m0, s43
	ds_read_b128 v[216:219], v160 offset:39936
	global_load_lds_dwordx4 v150, s[14:15]
	s_waitcnt lgkmcnt(8)
	s_barrier
	s_waitcnt lgkmcnt(0)
	v_mfma_f32_16x16x32_bf16 v[124:127], v[162:165], v[178:181], v[124:127]
	v_mfma_f32_16x16x32_bf16 v[120:123], v[170:173], v[178:181], v[120:123]
	v_mfma_f32_16x16x32_bf16 v[116:119], v[162:165], v[196:199], v[116:119]
	v_mfma_f32_16x16x32_bf16 v[112:115], v[170:173], v[196:199], v[112:115]
	v_mfma_f32_16x16x32_bf16 v[100:103], v[162:165], v[204:207], v[100:103]
	v_mfma_f32_16x16x32_bf16 v[96:99], v[170:173], v[204:207], v[96:99]
	v_mfma_f32_16x16x32_bf16 v[84:87], v[162:165], v[212:215], v[84:87]
	v_mfma_f32_16x16x32_bf16 v[80:83], v[170:173], v[212:215], v[80:83]
	v_mfma_f32_16x16x32_bf16 v[124:127], v[166:169], v[192:195], v[124:127]
	v_mfma_f32_16x16x32_bf16 v[120:123], v[174:177], v[192:195], v[120:123]
	v_mfma_f32_16x16x32_bf16 v[116:119], v[166:169], v[200:203], v[116:119]
	v_mfma_f32_16x16x32_bf16 v[112:115], v[174:177], v[200:203], v[112:115]
	v_mfma_f32_16x16x32_bf16 v[100:103], v[166:169], v[208:211], v[100:103]
	v_mfma_f32_16x16x32_bf16 v[96:99], v[174:177], v[208:211], v[96:99]
	v_mfma_f32_16x16x32_bf16 v[84:87], v[166:169], v[216:219], v[84:87]
	v_mfma_f32_16x16x32_bf16 v[80:83], v[174:177], v[216:219], v[80:83]
	s_barrier
	s_add_i32 s17, 0, 0x1c000
	s_add_i32 s14, s16, s40
	s_mov_b32 m0, s14
	ds_read_b128 v[220:223], v251
	ds_read_b128 v[224:227], v251 offset:1024
	ds_read_b128 v[228:231], v251 offset:2048
	global_load_lds_dwordx4 v244, s[26:27]
	s_add_i32 m0, s14, 0x2000
	ds_read_b128 v[232:235], v251 offset:3072
	global_load_lds_dwordx4 v245, s[26:27]
	s_barrier
	s_waitcnt lgkmcnt(0)
	v_mfma_f32_16x16x32_bf16 v[108:111], v[220:223], v[178:181], v[108:111]
	v_mfma_f32_16x16x32_bf16 v[104:107], v[228:231], v[178:181], v[104:107]
	v_mfma_f32_16x16x32_bf16 v[92:95], v[220:223], v[196:199], v[92:95]
	v_mfma_f32_16x16x32_bf16 v[88:91], v[228:231], v[196:199], v[88:91]
	v_mfma_f32_16x16x32_bf16 v[76:79], v[220:223], v[204:207], v[76:79]
	v_mfma_f32_16x16x32_bf16 v[72:75], v[228:231], v[204:207], v[72:75]
	v_mfma_f32_16x16x32_bf16 v[68:71], v[220:223], v[212:215], v[68:71]
	v_mfma_f32_16x16x32_bf16 v[64:67], v[228:231], v[212:215], v[64:67]
	v_mfma_f32_16x16x32_bf16 v[108:111], v[224:227], v[192:195], v[108:111]
	v_mfma_f32_16x16x32_bf16 v[104:107], v[232:235], v[192:195], v[104:107]
	v_mfma_f32_16x16x32_bf16 v[92:95], v[224:227], v[200:203], v[92:95]
	v_mfma_f32_16x16x32_bf16 v[88:91], v[232:235], v[200:203], v[88:91]
	v_mfma_f32_16x16x32_bf16 v[76:79], v[224:227], v[208:211], v[76:79]
	v_mfma_f32_16x16x32_bf16 v[72:75], v[232:235], v[208:211], v[72:75]
	v_mfma_f32_16x16x32_bf16 v[68:71], v[224:227], v[216:219], v[68:71]
	v_mfma_f32_16x16x32_bf16 v[64:67], v[232:235], v[216:219], v[64:67]
	s_barrier
	s_mov_b32 m0, s46
	ds_read_b128 v[178:181], v160 offset:49152
	ds_read_b128 v[192:195], v160 offset:50176
	ds_read_b128 v[196:199], v160 offset:51200
	ds_read_b128 v[200:203], v160 offset:52224
	ds_read_b128 v[204:207], v160 offset:53248
	ds_read_b128 v[208:211], v160 offset:54272
	ds_read_b128 v[212:215], v160 offset:55296
	global_load_lds_dwordx4 v246, s[30:31]
	s_mov_b32 m0, s47
	ds_read_b128 v[216:219], v160 offset:56320
	global_load_lds_dwordx4 v247, s[30:31]
	s_barrier
	s_waitcnt lgkmcnt(0)
	v_mfma_f32_16x16x32_bf16 v[60:63], v[162:165], v[178:181], v[60:63]
	v_mfma_f32_16x16x32_bf16 v[56:59], v[170:173], v[178:181], v[56:59]
	v_mfma_f32_16x16x32_bf16 v[52:55], v[162:165], v[196:199], v[52:55]
	v_mfma_f32_16x16x32_bf16 v[48:51], v[170:173], v[196:199], v[48:51]
	v_mfma_f32_16x16x32_bf16 v[36:39], v[162:165], v[204:207], v[36:39]
	v_mfma_f32_16x16x32_bf16 v[32:35], v[170:173], v[204:207], v[32:35]
	v_mfma_f32_16x16x32_bf16 v[20:23], v[162:165], v[212:215], v[20:23]
	v_mfma_f32_16x16x32_bf16 v[16:19], v[170:173], v[212:215], v[16:19]
	v_mfma_f32_16x16x32_bf16 v[60:63], v[166:169], v[192:195], v[60:63]
	v_mfma_f32_16x16x32_bf16 v[56:59], v[174:177], v[192:195], v[56:59]
	v_mfma_f32_16x16x32_bf16 v[52:55], v[166:169], v[200:203], v[52:55]
	v_mfma_f32_16x16x32_bf16 v[48:51], v[174:177], v[200:203], v[48:51]
	v_mfma_f32_16x16x32_bf16 v[36:39], v[166:169], v[208:211], v[36:39]
	v_mfma_f32_16x16x32_bf16 v[32:35], v[174:177], v[208:211], v[32:35]
	v_mfma_f32_16x16x32_bf16 v[20:23], v[166:169], v[216:219], v[20:23]
	v_mfma_f32_16x16x32_bf16 v[16:19], v[174:177], v[216:219], v[16:19]
	s_barrier
; __device__ __forceinline__ unsigned cvt_pk_bf16(float lo, float hi) { const f32x2_cv v = {lo, hi}; const bf16x2_cv b = __builtin_convertvector(v, bf16x2_cv); return __builtin_bit_cast(unsigned, b); }
; #define PG8_STAGE(bufoff, gbase, voff) do { _Pragma("unroll") for (int _i = 0; _i < 2; ++_i) \
;         __builtin_amdgcn_global_load_lds((const unsigned*)((const char*)(gbase) + (voff)[_i]), (PG8_LAS unsigned*)(lds + (bufoff) + ldsw + _i * 8192), 16, 0, 0); } while (0)
; #define PG8_WAIT_V(n) asm volatile("s_waitcnt vmcnt(" #n ")" ::: "memory")
; #define PG8_BAR __builtin_amdgcn_s_barrier()
; __device__ __forceinline__ float rstd_of(const float* rowss, int row) { return rsqrtf(rowss[row] * (1.0f / 1024.0f) + 1e-6f); }
; template <class Epi, class Sched, bool STAMP = false>
; __device__ __forceinline__ void gemm_phase(PG8_LAS unsigned char* lds, const Gemm g, const Sched& S, const Epi& E, unsigned long long* stamps) {
;     ...
;             PG8_STAGE(PG8_SB(1, 1), b3 + hstep, voffB);
;             PG8_WAIT_V(6); PG8_BAR; PG8_MMA(1, 1, At, B1); PG8_BAR;
;         }
;         if constexpr (!Epi::AFTER_DRAIN) { E(acc, cur, wr, wc, fr, fq); S.done(cur); }
;         if (!has_next) break;
;     __device__ __forceinline__ void operator()(const f32x4 (&acc)[2][2][4][2], const pg8::Unit& u, int wr, int wc, int fr, int fq) const {
;         const int row0 = u.pm * 256 + wr * 64 + fr, col0 = u.pn * 256 + wc * 32 + 8 * fq;
; #pragma unroll
;         for (int ai = 0; ai < 2; ++ai)
; #pragma unroll
;             for (int m = 0; m < 4; ++m) {
;                 const int row = row0 + ai * 128 + m * 16;
;                 const float s = (MODE == 2) ? 1.0f : rstd_of(rowss, row);
;                 bf16_t* rowp = O + (size_t)row * ldc + col0;
; #pragma unroll
;                 for (int bj = 0; bj < 2; ++bj) {
;                     f32x4 v0 = acc[ai][bj][m][0] * s, v1 = acc[ai][bj][m][1] * s;
;                     if (MODE == 1) {
; #pragma unroll
;                         for (int j = 0; j < 4; ++j) { const float a = fmaxf(v0[j], 0.f), b = fmaxf(v1[j], 0.f); v0[j] = a * a; v1[j] = b * b; } }
;                     u32x4 w; w.x = cvt_pk_bf16(v0[0], v0[1]); w.y = cvt_pk_bf16(v0[2], v0[3]); w.z = cvt_pk_bf16(v1[0], v1[1]); w.w = cvt_pk_bf16(v1[2], v1[3]);
;                     *(u32x4*)(rowp + bj * 128) = w; } }
	s_add_u32 s14, s26, 0x20080
	s_addc_u32 s15, s27, 0
	s_add_i32 s16, s17, s40
	s_mov_b32 m0, s16
	s_nop 0
	global_load_lds_dwordx4 v128, s[14:15]
	s_add_i32 m0, s16, 0x2000
	s_nop 0
	global_load_lds_dwordx4 v152, s[14:15]
	s_waitcnt vmcnt(6)
	s_barrier
	s_cmp_gt_u32 s59, 5
	v_mfma_f32_16x16x32_bf16 v[44:47], v[220:223], v[178:181], v[44:47]
	v_mfma_f32_16x16x32_bf16 v[40:43], v[228:231], v[178:181], v[40:43]
	v_mfma_f32_16x16x32_bf16 v[28:31], v[220:223], v[196:199], v[28:31]
	v_mfma_f32_16x16x32_bf16 v[24:27], v[228:231], v[196:199], v[24:27]
	v_mfma_f32_16x16x32_bf16 v[12:15], v[220:223], v[204:207], v[12:15]
	v_mfma_f32_16x16x32_bf16 v[8:11], v[228:231], v[204:207], v[8:11]
	v_mfma_f32_16x16x32_bf16 v[4:7], v[220:223], v[212:215], v[4:7]
	v_mfma_f32_16x16x32_bf16 v[0:3], v[228:231], v[212:215], v[0:3]
	v_mfma_f32_16x16x32_bf16 v[44:47], v[224:227], v[192:195], v[44:47]
	v_mfma_f32_16x16x32_bf16 v[40:43], v[232:235], v[192:195], v[40:43]
	v_mfma_f32_16x16x32_bf16 v[28:31], v[224:227], v[200:203], v[28:31]
	v_mfma_f32_16x16x32_bf16 v[24:27], v[232:235], v[200:203], v[24:27]
	v_mfma_f32_16x16x32_bf16 v[12:15], v[224:227], v[208:211], v[12:15]
	v_mfma_f32_16x16x32_bf16 v[8:11], v[232:235], v[208:211], v[8:11]
	v_mfma_f32_16x16x32_bf16 v[4:7], v[224:227], v[216:219], v[4:7]
	v_mfma_f32_16x16x32_bf16 v[0:3], v[232:235], v[216:219], v[0:3]
	s_barrier
	s_cbranch_scc0 .LBB0_293
	v_lshl_add_u32 v162, s2, 8, v139
	v_lshl_or_b32 v164, s49, 8, v159
	v_ashrrev_i32_e32 v163, 31, v162
	v_ashrrev_i32_e32 v165, 31, v164
	v_lshlrev_b64 v[166:167], 11, v[162:163]
	v_lshl_add_u64 v[166:167], s[0:1], 0, v[166:167]
	v_lshlrev_b64 v[164:165], 1, v[164:165]
	v_lshl_add_u64 v[166:167], v[166:167], 0, v[164:165]
	s_mov_b32 s2, 0x40000
	s_mov_b64 s[14:15], 0x40000
	v_cvt_pk_bf16_f32 v60, v60, v61
	v_cvt_pk_bf16_f32 v61, v62, v63
	v_cvt_pk_bf16_f32 v62, v56, v57
	v_add_co_u32_e32 v56, vcc, s2, v166
	v_cvt_pk_bf16_f32 v68, v68, v69
	v_cvt_pk_bf16_f32 v69, v70, v71
	v_cvt_pk_bf16_f32 v70, v64, v65
	v_lshl_add_u64 v[64:65], v[166:167], 0, s[14:15]
	v_addc_co_u32_e32 v57, vcc, 0, v167, vcc
	v_cvt_pk_bf16_f32 v44, v44, v45
	v_cvt_pk_bf16_f32 v45, v46, v47
	v_cvt_pk_bf16_f32 v46, v40, v41
	v_cvt_pk_bf16_f32 v47, v42, v43
	s_mov_b32 s2, 0x48000
	v_cvt_pk_bf16_f32 v108, v108, v109
	v_cvt_pk_bf16_f32 v109, v110, v111
	v_cvt_pk_bf16_f32 v110, v104, v105
	v_or_b32_e32 v104, 16, v162
	global_store_dwordx4 v[64:65], v[44:47], off offset:256
	s_mov_b64 s[14:15], 0x48000
	v_ashrrev_i32_e32 v105, 31, v104
	v_add_co_u32_e32 v46, vcc, s2, v166
	v_cvt_pk_bf16_f32 v92, v92, v93
	v_cvt_pk_bf16_f32 v93, v94, v95
	v_cvt_pk_bf16_f32 v94, v88, v89
	v_or_b32_e32 v88, 32, v162
	v_lshl_add_u64 v[44:45], v[166:167], 0, s[14:15]
	v_addc_co_u32_e32 v47, vcc, 0, v167, vcc
	v_cvt_pk_bf16_f32 v28, v28, v29
	v_cvt_pk_bf16_f32 v29, v30, v31
	v_cvt_pk_bf16_f32 v30, v24, v25
	v_cvt_pk_bf16_f32 v31, v26, v27
	s_mov_b32 s2, 0x50000
	v_lshlrev_b64 v[104:105], 11, v[104:105]
	v_ashrrev_i32_e32 v89, 31, v88
	v_cvt_pk_bf16_f32 v76, v76, v77
	v_cvt_pk_bf16_f32 v77, v78, v79
	v_cvt_pk_bf16_f32 v78, v72, v73
	v_or_b32_e32 v72, 48, v162
	global_store_dwordx4 v[44:45], v[28:31], off offset:256
	s_mov_b64 s[14:15], 0x50000
	v_cvt_pk_bf16_f32 v111, v106, v107
	v_add_co_u32_e32 v30, vcc, s2, v166
	v_lshl_add_u64 v[104:105], s[0:1], 0, v[104:105]
	v_lshlrev_b64 v[88:89], 11, v[88:89]
	v_ashrrev_i32_e32 v73, 31, v72
	v_lshl_add_u64 v[28:29], v[166:167], 0, s[14:15]
	v_addc_co_u32_e32 v31, vcc, 0, v167, vcc
	v_cvt_pk_bf16_f32 v12, v12, v13
	v_cvt_pk_bf16_f32 v13, v14, v15
	v_cvt_pk_bf16_f32 v14, v8, v9
	v_cvt_pk_bf16_f32 v15, v10, v11
	s_mov_b32 s2, 0x58000
	global_store_dwordx4 v[166:167], v[108:111], off offset:256
	v_cvt_pk_bf16_f32 v95, v90, v91
	v_lshl_add_u64 v[88:89], s[0:1], 0, v[88:89]
	v_lshl_add_u64 v[108:109], v[104:105], 0, v[164:165]
	v_lshlrev_b64 v[72:73], 11, v[72:73]
	global_store_dwordx4 v[28:29], v[12:15], off offset:256
	global_store_dwordx4 v[108:109], v[92:95], off offset:256
	v_cvt_pk_bf16_f32 v79, v74, v75
	v_add_co_u32_e32 v14, vcc, s2, v166
	v_lshl_add_u64 v[92:93], v[88:89], 0, v[164:165]
	v_lshl_add_u64 v[72:73], s[0:1], 0, v[72:73]
	s_mov_b64 s[14:15], 0x58000
	v_addc_co_u32_e32 v15, vcc, 0, v167, vcc
	v_cvt_pk_bf16_f32 v124, v124, v125
	v_cvt_pk_bf16_f32 v125, v126, v127
	v_cvt_pk_bf16_f32 v126, v120, v121
	v_cvt_pk_bf16_f32 v127, v122, v123
	v_cvt_pk_bf16_f32 v104, v116, v117
	v_cvt_pk_bf16_f32 v105, v118, v119
	v_cvt_pk_bf16_f32 v106, v112, v113
	v_cvt_pk_bf16_f32 v107, v114, v115
	v_cvt_pk_bf16_f32 v88, v100, v101
	v_cvt_pk_bf16_f32 v89, v102, v103
	v_cvt_pk_bf16_f32 v90, v96, v97
	v_cvt_pk_bf16_f32 v91, v98, v99
	global_store_dwordx4 v[92:93], v[76:79], off offset:256
	v_cvt_pk_bf16_f32 v74, v80, v81
	v_cvt_pk_bf16_f32 v75, v82, v83
	v_lshl_add_u64 v[76:77], v[72:73], 0, v[164:165]
	v_cvt_pk_bf16_f32 v72, v84, v85
	v_cvt_pk_bf16_f32 v73, v86, v87
	v_cvt_pk_bf16_f32 v71, v66, v67
	v_cvt_pk_bf16_f32 v63, v58, v59
	v_cvt_pk_bf16_f32 v40, v52, v53
	v_cvt_pk_bf16_f32 v41, v54, v55
	v_cvt_pk_bf16_f32 v42, v48, v49
	v_cvt_pk_bf16_f32 v43, v50, v51
	v_cvt_pk_bf16_f32 v24, v36, v37
	v_cvt_pk_bf16_f32 v25, v38, v39
	v_cvt_pk_bf16_f32 v26, v32, v33
	v_cvt_pk_bf16_f32 v27, v34, v35
	v_lshl_add_u64 v[12:13], v[166:167], 0, s[14:15]
	v_cvt_pk_bf16_f32 v8, v20, v21
	v_cvt_pk_bf16_f32 v9, v22, v23
	v_cvt_pk_bf16_f32 v10, v16, v17
	v_cvt_pk_bf16_f32 v11, v18, v19
	v_cvt_pk_bf16_f32 v4, v4, v5
	v_cvt_pk_bf16_f32 v5, v6, v7
	v_cvt_pk_bf16_f32 v6, v0, v1
	v_cvt_pk_bf16_f32 v7, v2, v3
	s_and_b64 vcc, exec, s[38:39]
	s_mov_b32 s49, s4
	s_mov_b32 s2, s6
	s_mov_b64 s[26:27], s[22:23]
	s_mov_b64 s[24:25], s[12:13]
	s_movk_i32 s58, 0xff60
	global_store_dwordx4 v[166:167], v[124:127], off
	global_store_dwordx4 v[108:109], v[104:107], off
	global_store_dwordx4 v[92:93], v[88:91], off
	global_store_dwordx4 v[76:77], v[72:75], off
	global_store_dwordx4 v[76:77], v[68:71], off offset:256
	global_store_dwordx4 v[56:57], v[60:63], off
	global_store_dwordx4 v[46:47], v[40:43], off
	global_store_dwordx4 v[30:31], v[24:27], off
	global_store_dwordx4 v[14:15], v[8:11], off
	global_store_dwordx4 v[12:13], v[4:7], off offset:256
	s_cbranch_vccz .LBB0_286
	s_cmpk_gt_u32 s36, 0xff
	s_cbranch_scc1 .LBB0_297
	s_barrier

; #define PG8_STAGE(bufoff, gbase, voff) do { _Pragma("unroll") for (int _i = 0; _i < 2; ++_i) \
;         __builtin_amdgcn_global_load_lds((const unsigned*)((const char*)(gbase) + (voff)[_i]), (PG8_LAS unsigned*)(lds + (bufoff) + ldsw + _i * 8192), 16, 0, 0); } while (0)
; #define PG8_LDA(dst, b, h) do { _Pragma("unroll") for (int m = 0; m < 4; ++m) _Pragma("unroll") for (int k = 0; k < 2; ++k) dst[m][k] = *(const PG8_LAS bf16x8*)(lds + PG8_SA(b, h) + aoff + m * 2048 + k * 1024); } while (0)
; #define PG8_LDB(dst, b, h) do { _Pragma("unroll") for (int n = 0; n < 2; ++n) _Pragma("unroll") for (int k = 0; k < 2; ++k) dst[n][k] = *(const PG8_LAS bf16x8*)(lds + PG8_SB(b, h) + boff + n * 2048 + k * 1024); } while (0)
; #define PG8_MMA(ai, bj, At, Bt) do { __builtin_amdgcn_s_setprio(1); _Pragma("unroll") for (int m = 0; m < 4; ++m) _Pragma("unroll") for (int n = 0; n < 2; ++n) _Pragma("unroll") for (int k = 0; k < 2; ++k) \
;         acc[ai][bj][m][n] = __builtin_amdgcn_mfma_f32_16x16x32_bf16(Bt[n][k], At[m][k], acc[ai][bj][m][n], 0, 0, 0); __builtin_amdgcn_s_setprio(0); } while (0)
; #define PG8_BAR __builtin_amdgcn_s_barrier()
; template <class Epi, class Sched, bool STAMP = false>
; __device__ __forceinline__ void gemm_phase(PG8_LAS unsigned char* lds, const Gemm g, const Sched& S, const Epi& E, unsigned long long* stamps) {
;     ...
;         for (int t = 0; t < nt; t += 2) {
;             const bool last = (t == nt - 2);
;             const char* a1 = cA + (size_t)(t + 1) * kstep;
;             const char* a2 = last ? nA : cA + (size_t)(t + 2) * kstep; const char* b2 = last ? nB : cB + (size_t)(t + 2) * kstep;
;             const char* a3 = a2 + kstep; const char* b3 = b2 + kstep;
;             if (last && has_next) S.a_ready(nxt);
;             PG8_LDB(B0, 0, 0); PG8_SCHED; PG8_LDA(At, 0, 0); PG8_STAGE(PG8_SA(1, 1), a1 + hstep, voffA);
;             PG8_WAIT_L(8); PG8_BAR; PG8_WAIT_L(0); PG8_MMA(0, 0, At, B0); PG8_BAR; PG8_SCHED;
;             PG8_LDB(B1, 0, 1); PG8_STAGE(PG8_SB(0, 0), b2, voffB);
;             PG8_BAR; PG8_WAIT_L(0); PG8_MMA(0, 1, At, B1); PG8_BAR;
;             PG8_LDA(At, 0, 1); PG8_STAGE(PG8_SA(0, 0), a2, voffA);
;             PG8_BAR; PG8_WAIT_L(0); PG8_MMA(1, 0, At, B0); PG8_BAR; PG8_SCHED;
;             PG8_STAGE(PG8_SB(0, 1), b2 + hstep, voffB);
;             PG8_WAIT_V(6); PG8_BAR; PG8_MMA(1, 1, At, B1); PG8_BAR;
.LBB0_313:
	s_add_u32 s12, s4, 0xfffc0080
	s_addc_u32 s13, s5, -1
	s_add_i32 s14, 0, 0x10000
	ds_read_b128 v[158:161], v248
	ds_read_b128 v[162:165], v248 offset:1024
	ds_read_b128 v[170:173], v248 offset:2048
	ds_read_b128 v[174:177], v248 offset:3072
	s_cmp_eq_u32 s65, 12
	s_cselect_b32 s27, s31, s13
	s_cselect_b32 s26, s47, s12
	s_cselect_b32 s13, s7, s63
	s_cselect_b32 s12, s53, s62
	s_add_i32 m0, s3, 0xc000
	ds_read_b128 v[178:181], v169
	ds_read_b128 v[192:195], v169 offset:1024
	ds_read_b128 v[196:199], v169 offset:2048
	ds_read_b128 v[200:203], v169 offset:3072
	ds_read_b128 v[204:207], v169 offset:4096
	ds_read_b128 v[208:211], v169 offset:5120
	ds_read_b128 v[212:215], v169 offset:6144
	global_load_lds_dwordx4 v154, s[4:5]
	s_add_i32 m0, s3, 0xe000
	ds_read_b128 v[216:219], v169 offset:7168
	global_load_lds_dwordx4 v156, s[4:5]
	s_waitcnt lgkmcnt(8)
	s_barrier
	s_waitcnt lgkmcnt(0)
	v_mfma_f32_16x16x32_bf16 v[124:127], v[158:161], v[178:181], v[124:127]
	v_mfma_f32_16x16x32_bf16 v[120:123], v[170:173], v[178:181], v[120:123]
	v_mfma_f32_16x16x32_bf16 v[108:111], v[158:161], v[196:199], v[108:111]
	v_mfma_f32_16x16x32_bf16 v[104:107], v[170:173], v[196:199], v[104:107]
	v_mfma_f32_16x16x32_bf16 v[92:95], v[158:161], v[204:207], v[92:95]
	v_mfma_f32_16x16x32_bf16 v[88:91], v[170:173], v[204:207], v[88:91]
	v_mfma_f32_16x16x32_bf16 v[76:79], v[158:161], v[212:215], v[76:79]
	v_mfma_f32_16x16x32_bf16 v[72:75], v[170:173], v[212:215], v[72:75]
	v_mfma_f32_16x16x32_bf16 v[124:127], v[162:165], v[192:195], v[124:127]
	v_mfma_f32_16x16x32_bf16 v[120:123], v[174:177], v[192:195], v[120:123]
	v_mfma_f32_16x16x32_bf16 v[108:111], v[162:165], v[200:203], v[108:111]
	v_mfma_f32_16x16x32_bf16 v[104:107], v[174:177], v[200:203], v[104:107]
	v_mfma_f32_16x16x32_bf16 v[92:95], v[162:165], v[208:211], v[92:95]
	v_mfma_f32_16x16x32_bf16 v[88:91], v[174:177], v[208:211], v[88:91]
	v_mfma_f32_16x16x32_bf16 v[76:79], v[162:165], v[216:219], v[76:79]
	v_mfma_f32_16x16x32_bf16 v[72:75], v[174:177], v[216:219], v[72:75]
	s_barrier
	s_add_i32 s16, 0, 0x14000
	s_add_i32 s14, s14, s56
	s_mov_b32 m0, s14
	ds_read_b128 v[220:223], v249
	ds_read_b128 v[224:227], v249 offset:1024
	ds_read_b128 v[228:231], v249 offset:2048
	global_load_lds_dwordx4 v128, s[12:13]
	s_add_i32 m0, s14, 0x2000
	ds_read_b128 v[232:235], v249 offset:3072
	global_load_lds_dwordx4 v152, s[12:13]
	s_barrier
	s_waitcnt lgkmcnt(0)
	v_mfma_f32_16x16x32_bf16 v[116:119], v[220:223], v[178:181], v[116:119]
	v_mfma_f32_16x16x32_bf16 v[112:115], v[228:231], v[178:181], v[112:115]
	v_mfma_f32_16x16x32_bf16 v[100:103], v[220:223], v[196:199], v[100:103]
	v_mfma_f32_16x16x32_bf16 v[96:99], v[228:231], v[196:199], v[96:99]
	v_mfma_f32_16x16x32_bf16 v[84:87], v[220:223], v[204:207], v[84:87]
	v_mfma_f32_16x16x32_bf16 v[80:83], v[228:231], v[204:207], v[80:83]
	v_mfma_f32_16x16x32_bf16 v[68:71], v[220:223], v[212:215], v[68:71]
	v_mfma_f32_16x16x32_bf16 v[64:67], v[228:231], v[212:215], v[64:67]
	v_mfma_f32_16x16x32_bf16 v[116:119], v[224:227], v[192:195], v[116:119]
	v_mfma_f32_16x16x32_bf16 v[112:115], v[232:235], v[192:195], v[112:115]
	v_mfma_f32_16x16x32_bf16 v[100:103], v[224:227], v[200:203], v[100:103]
	v_mfma_f32_16x16x32_bf16 v[96:99], v[232:235], v[200:203], v[96:99]
	v_mfma_f32_16x16x32_bf16 v[84:87], v[224:227], v[208:211], v[84:87]
	v_mfma_f32_16x16x32_bf16 v[80:83], v[232:235], v[208:211], v[80:83]
	v_mfma_f32_16x16x32_bf16 v[68:71], v[224:227], v[216:219], v[68:71]
	v_mfma_f32_16x16x32_bf16 v[64:67], v[232:235], v[216:219], v[64:67]
	s_barrier
	s_mov_b32 m0, s3
	ds_read_b128 v[178:181], v169 offset:16384
	ds_read_b128 v[192:195], v169 offset:17408
	ds_read_b128 v[196:199], v169 offset:18432
	ds_read_b128 v[200:203], v169 offset:19456
	ds_read_b128 v[204:207], v169 offset:20480
	ds_read_b128 v[208:211], v169 offset:21504
	ds_read_b128 v[212:215], v169 offset:22528
	global_load_lds_dwordx4 v148, s[26:27]
	s_mov_b32 m0, s57
	ds_read_b128 v[216:219], v169 offset:23552
	global_load_lds_dwordx4 v150, s[26:27]
	s_barrier
	s_waitcnt lgkmcnt(0)
	v_mfma_f32_16x16x32_bf16 v[60:63], v[158:161], v[178:181], v[60:63]
	v_mfma_f32_16x16x32_bf16 v[56:59], v[170:173], v[178:181], v[56:59]
	v_mfma_f32_16x16x32_bf16 v[44:47], v[158:161], v[196:199], v[44:47]
	v_mfma_f32_16x16x32_bf16 v[40:43], v[170:173], v[196:199], v[40:43]
	v_mfma_f32_16x16x32_bf16 v[28:31], v[158:161], v[204:207], v[28:31]
	v_mfma_f32_16x16x32_bf16 v[24:27], v[170:173], v[204:207], v[24:27]
	v_mfma_f32_16x16x32_bf16 v[12:15], v[158:161], v[212:215], v[12:15]
	v_mfma_f32_16x16x32_bf16 v[8:11], v[170:173], v[212:215], v[8:11]
	v_mfma_f32_16x16x32_bf16 v[60:63], v[162:165], v[192:195], v[60:63]
	v_mfma_f32_16x16x32_bf16 v[56:59], v[174:177], v[192:195], v[56:59]
	v_mfma_f32_16x16x32_bf16 v[44:47], v[162:165], v[200:203], v[44:47]
	v_mfma_f32_16x16x32_bf16 v[40:43], v[174:177], v[200:203], v[40:43]
	v_mfma_f32_16x16x32_bf16 v[28:31], v[162:165], v[208:211], v[28:31]
	v_mfma_f32_16x16x32_bf16 v[24:27], v[174:177], v[208:211], v[24:27]
	v_mfma_f32_16x16x32_bf16 v[12:15], v[162:165], v[216:219], v[12:15]
	v_mfma_f32_16x16x32_bf16 v[8:11], v[174:177], v[216:219], v[8:11]
	s_barrier
	s_add_u32 s14, s12, 0x40000
	s_addc_u32 s15, s13, 0
	s_add_i32 s16, s16, s56
	s_mov_b32 m0, s16
	s_nop 0
	global_load_lds_dwordx4 v128, s[14:15]
	s_add_i32 m0, s16, 0x2000
	s_nop 0
	global_load_lds_dwordx4 v152, s[14:15]
	s_add_i32 s65, s65, 2
	s_add_u32 s4, s4, 0x100
	s_addc_u32 s5, s5, 0
	s_add_u32 s62, s62, 0x100
	s_addc_u32 s63, s63, 0
	s_waitcnt vmcnt(6)
	s_barrier
; #define PG8_STAGE(bufoff, gbase, voff) do { _Pragma("unroll") for (int _i = 0; _i < 2; ++_i) \
;         __builtin_amdgcn_global_load_lds((const unsigned*)((const char*)(gbase) + (voff)[_i]), (PG8_LAS unsigned*)(lds + (bufoff) + ldsw + _i * 8192), 16, 0, 0); } while (0)
; #define PG8_LDA(dst, b, h) do { _Pragma("unroll") for (int m = 0; m < 4; ++m) _Pragma("unroll") for (int k = 0; k < 2; ++k) dst[m][k] = *(const PG8_LAS bf16x8*)(lds + PG8_SA(b, h) + aoff + m * 2048 + k * 1024); } while (0)
; #define PG8_LDB(dst, b, h) do { _Pragma("unroll") for (int n = 0; n < 2; ++n) _Pragma("unroll") for (int k = 0; k < 2; ++k) dst[n][k] = *(const PG8_LAS bf16x8*)(lds + PG8_SB(b, h) + boff + n * 2048 + k * 1024); } while (0)
; #define PG8_MMA(ai, bj, At, Bt) do { __builtin_amdgcn_s_setprio(1); _Pragma("unroll") for (int m = 0; m < 4; ++m) _Pragma("unroll") for (int n = 0; n < 2; ++n) _Pragma("unroll") for (int k = 0; k < 2; ++k) \
;         acc[ai][bj][m][n] = __builtin_amdgcn_mfma_f32_16x16x32_bf16(Bt[n][k], At[m][k], acc[ai][bj][m][n], 0, 0, 0); __builtin_amdgcn_s_setprio(0); } while (0)
; #define PG8_WAIT_V(n) asm volatile("s_waitcnt vmcnt(" #n ")" ::: "memory")
; #define PG8_WAIT_L(n) asm volatile("s_waitcnt lgkmcnt(" #n ")" ::: "memory")
; #define PG8_BAR __builtin_amdgcn_s_barrier()
; #define PG8_SCHED __builtin_amdgcn_sched_barrier(0)
; template <class Epi, class Sched, bool STAMP = false>
; __device__ __forceinline__ void gemm_phase(PG8_LAS unsigned char* lds, const Gemm g, const Sched& S, const Epi& E, unsigned long long* stamps) {
;     ...
;             PG8_WAIT_V(6); PG8_BAR; PG8_MMA(1, 1, At, B1); PG8_BAR;
;             PG8_LDB(B0, 1, 0); PG8_SCHED; PG8_LDA(At, 1, 0); PG8_STAGE(PG8_SA(0, 1), a2 + hstep, voffA);
;             PG8_WAIT_L(8); PG8_BAR; PG8_WAIT_L(0); PG8_MMA(0, 0, At, B0); PG8_BAR; PG8_SCHED;
;             PG8_LDB(B1, 1, 1); PG8_STAGE(PG8_SB(1, 0), b3, voffB);
;             PG8_BAR; PG8_WAIT_L(0); PG8_MMA(0, 1, At, B1); PG8_BAR;
;             PG8_LDA(At, 1, 1); PG8_STAGE(PG8_SA(1, 0), a3, voffA);
;             PG8_BAR; PG8_WAIT_L(0); PG8_MMA(1, 0, At, B0); PG8_BAR; PG8_SCHED;
	v_mfma_f32_16x16x32_bf16 v[52:55], v[220:223], v[178:181], v[52:55]
	v_mfma_f32_16x16x32_bf16 v[48:51], v[228:231], v[178:181], v[48:51]
	v_mfma_f32_16x16x32_bf16 v[36:39], v[220:223], v[196:199], v[36:39]
	v_mfma_f32_16x16x32_bf16 v[32:35], v[228:231], v[196:199], v[32:35]
	v_mfma_f32_16x16x32_bf16 v[20:23], v[220:223], v[204:207], v[20:23]
	v_mfma_f32_16x16x32_bf16 v[16:19], v[228:231], v[204:207], v[16:19]
	v_mfma_f32_16x16x32_bf16 v[4:7], v[220:223], v[212:215], v[4:7]
	v_mfma_f32_16x16x32_bf16 v[0:3], v[228:231], v[212:215], v[0:3]
	v_mfma_f32_16x16x32_bf16 v[52:55], v[224:227], v[192:195], v[52:55]
	v_mfma_f32_16x16x32_bf16 v[48:51], v[232:235], v[192:195], v[48:51]
	v_mfma_f32_16x16x32_bf16 v[36:39], v[224:227], v[200:203], v[36:39]
	v_mfma_f32_16x16x32_bf16 v[32:35], v[232:235], v[200:203], v[32:35]
	v_mfma_f32_16x16x32_bf16 v[20:23], v[224:227], v[208:211], v[20:23]
	v_mfma_f32_16x16x32_bf16 v[16:19], v[232:235], v[208:211], v[16:19]
	v_mfma_f32_16x16x32_bf16 v[4:7], v[224:227], v[216:219], v[4:7]
	v_mfma_f32_16x16x32_bf16 v[0:3], v[232:235], v[216:219], v[0:3]
	s_barrier
	s_add_i32 s16, 0, 0x18000
	ds_read_b128 v[158:161], v250
	ds_read_b128 v[162:165], v250 offset:1024
	ds_read_b128 v[170:173], v250 offset:2048
	ds_read_b128 v[174:177], v250 offset:3072
	s_add_u32 s14, s26, 0x40000
	s_addc_u32 s15, s27, 0
	s_mov_b32 m0, s58
	ds_read_b128 v[178:181], v169 offset:32768
	ds_read_b128 v[192:195], v169 offset:33792
	ds_read_b128 v[196:199], v169 offset:34816
	ds_read_b128 v[200:203], v169 offset:35840
	ds_read_b128 v[204:207], v169 offset:36864
	ds_read_b128 v[208:211], v169 offset:37888
	ds_read_b128 v[212:215], v169 offset:38912
	global_load_lds_dwordx4 v148, s[14:15]
	s_mov_b32 m0, s59
	ds_read_b128 v[216:219], v169 offset:39936
	global_load_lds_dwordx4 v150, s[14:15]
	s_waitcnt lgkmcnt(8)
	s_barrier
	s_waitcnt lgkmcnt(0)
	v_mfma_f32_16x16x32_bf16 v[124:127], v[158:161], v[178:181], v[124:127]
	v_mfma_f32_16x16x32_bf16 v[120:123], v[170:173], v[178:181], v[120:123]
	v_mfma_f32_16x16x32_bf16 v[108:111], v[158:161], v[196:199], v[108:111]
	v_mfma_f32_16x16x32_bf16 v[104:107], v[170:173], v[196:199], v[104:107]
	v_mfma_f32_16x16x32_bf16 v[92:95], v[158:161], v[204:207], v[92:95]
	v_mfma_f32_16x16x32_bf16 v[88:91], v[170:173], v[204:207], v[88:91]
	v_mfma_f32_16x16x32_bf16 v[76:79], v[158:161], v[212:215], v[76:79]
	v_mfma_f32_16x16x32_bf16 v[72:75], v[170:173], v[212:215], v[72:75]
	v_mfma_f32_16x16x32_bf16 v[124:127], v[162:165], v[192:195], v[124:127]
	v_mfma_f32_16x16x32_bf16 v[120:123], v[174:177], v[192:195], v[120:123]
	v_mfma_f32_16x16x32_bf16 v[108:111], v[162:165], v[200:203], v[108:111]
	v_mfma_f32_16x16x32_bf16 v[104:107], v[174:177], v[200:203], v[104:107]
	v_mfma_f32_16x16x32_bf16 v[92:95], v[162:165], v[208:211], v[92:95]
	v_mfma_f32_16x16x32_bf16 v[88:91], v[174:177], v[208:211], v[88:91]
	v_mfma_f32_16x16x32_bf16 v[76:79], v[162:165], v[216:219], v[76:79]
	v_mfma_f32_16x16x32_bf16 v[72:75], v[174:177], v[216:219], v[72:75]
	s_barrier
	s_add_i32 s14, 0, 0x1c000
	s_add_i32 s15, s16, s56
	s_mov_b32 m0, s15
	ds_read_b128 v[220:223], v251
	ds_read_b128 v[224:227], v251 offset:1024
	ds_read_b128 v[228:231], v251 offset:2048
	global_load_lds_dwordx4 v244, s[12:13]
	s_add_i32 m0, s15, 0x2000
	ds_read_b128 v[232:235], v251 offset:3072
	global_load_lds_dwordx4 v245, s[12:13]
	s_barrier
	s_waitcnt lgkmcnt(0)
	v_mfma_f32_16x16x32_bf16 v[116:119], v[220:223], v[178:181], v[116:119]
	v_mfma_f32_16x16x32_bf16 v[112:115], v[228:231], v[178:181], v[112:115]
	v_mfma_f32_16x16x32_bf16 v[100:103], v[220:223], v[196:199], v[100:103]
	v_mfma_f32_16x16x32_bf16 v[96:99], v[228:231], v[196:199], v[96:99]
	v_mfma_f32_16x16x32_bf16 v[84:87], v[220:223], v[204:207], v[84:87]
	v_mfma_f32_16x16x32_bf16 v[80:83], v[228:231], v[204:207], v[80:83]
	v_mfma_f32_16x16x32_bf16 v[68:71], v[220:223], v[212:215], v[68:71]
	v_mfma_f32_16x16x32_bf16 v[64:67], v[228:231], v[212:215], v[64:67]
	v_mfma_f32_16x16x32_bf16 v[116:119], v[224:227], v[192:195], v[116:119]
	v_mfma_f32_16x16x32_bf16 v[112:115], v[232:235], v[192:195], v[112:115]
	v_mfma_f32_16x16x32_bf16 v[100:103], v[224:227], v[200:203], v[100:103]
	v_mfma_f32_16x16x32_bf16 v[96:99], v[232:235], v[200:203], v[96:99]
	v_mfma_f32_16x16x32_bf16 v[84:87], v[224:227], v[208:211], v[84:87]
	v_mfma_f32_16x16x32_bf16 v[80:83], v[232:235], v[208:211], v[80:83]
	v_mfma_f32_16x16x32_bf16 v[68:71], v[224:227], v[216:219], v[68:71]
	v_mfma_f32_16x16x32_bf16 v[64:67], v[232:235], v[216:219], v[64:67]
	s_barrier
	s_mov_b32 m0, s60
	ds_read_b128 v[178:181], v169 offset:49152
	ds_read_b128 v[192:195], v169 offset:50176
	ds_read_b128 v[196:199], v169 offset:51200
	ds_read_b128 v[200:203], v169 offset:52224
	ds_read_b128 v[204:207], v169 offset:53248
	ds_read_b128 v[208:211], v169 offset:54272
	ds_read_b128 v[212:215], v169 offset:55296
	global_load_lds_dwordx4 v246, s[26:27]
	s_mov_b32 m0, s61
	ds_read_b128 v[216:219], v169 offset:56320
	global_load_lds_dwordx4 v247, s[26:27]
	s_barrier
	s_waitcnt lgkmcnt(0)
	v_mfma_f32_16x16x32_bf16 v[60:63], v[158:161], v[178:181], v[60:63]
	v_mfma_f32_16x16x32_bf16 v[56:59], v[170:173], v[178:181], v[56:59]
	v_mfma_f32_16x16x32_bf16 v[44:47], v[158:161], v[196:199], v[44:47]
	v_mfma_f32_16x16x32_bf16 v[40:43], v[170:173], v[196:199], v[40:43]
	v_mfma_f32_16x16x32_bf16 v[28:31], v[158:161], v[204:207], v[28:31]
	v_mfma_f32_16x16x32_bf16 v[24:27], v[170:173], v[204:207], v[24:27]
	v_mfma_f32_16x16x32_bf16 v[12:15], v[158:161], v[212:215], v[12:15]
	v_mfma_f32_16x16x32_bf16 v[8:11], v[170:173], v[212:215], v[8:11]
	v_mfma_f32_16x16x32_bf16 v[60:63], v[162:165], v[192:195], v[60:63]
	v_mfma_f32_16x16x32_bf16 v[56:59], v[174:177], v[192:195], v[56:59]
	v_mfma_f32_16x16x32_bf16 v[44:47], v[162:165], v[200:203], v[44:47]
	v_mfma_f32_16x16x32_bf16 v[40:43], v[174:177], v[200:203], v[40:43]
	v_mfma_f32_16x16x32_bf16 v[28:31], v[162:165], v[208:211], v[28:31]
	v_mfma_f32_16x16x32_bf16 v[24:27], v[174:177], v[208:211], v[24:27]
	v_mfma_f32_16x16x32_bf16 v[12:15], v[162:165], v[216:219], v[12:15]
	v_mfma_f32_16x16x32_bf16 v[8:11], v[174:177], v[216:219], v[8:11]
	s_barrier
; #define PG8_STAGE(bufoff, gbase, voff) do { _Pragma("unroll") for (int _i = 0; _i < 2; ++_i) \
;         __builtin_amdgcn_global_load_lds((const unsigned*)((const char*)(gbase) + (voff)[_i]), (PG8_LAS unsigned*)(lds + (bufoff) + ldsw + _i * 8192), 16, 0, 0); } while (0)
; #define PG8_MMA(ai, bj, At, Bt) do { __builtin_amdgcn_s_setprio(1); _Pragma("unroll") for (int m = 0; m < 4; ++m) _Pragma("unroll") for (int n = 0; n < 2; ++n) _Pragma("unroll") for (int k = 0; k < 2; ++k) \
;         acc[ai][bj][m][n] = __builtin_amdgcn_mfma_f32_16x16x32_bf16(Bt[n][k], At[m][k], acc[ai][bj][m][n], 0, 0, 0); __builtin_amdgcn_s_setprio(0); } while (0)
; #define PG8_WAIT_V(n) asm volatile("s_waitcnt vmcnt(" #n ")" ::: "memory")
; #define PG8_BAR __builtin_amdgcn_s_barrier()
; template <class Epi, class Sched, bool STAMP = false>
; __device__ __forceinline__ void gemm_phase(PG8_LAS unsigned char* lds, const Gemm g, const Sched& S, const Epi& E, unsigned long long* stamps) {
;     ...
;             PG8_STAGE(PG8_SB(1, 1), b3 + hstep, voffB);
;             PG8_WAIT_V(6); PG8_BAR; PG8_MMA(1, 1, At, B1); PG8_BAR;
;     __device__ __forceinline__ void operator()(const f32x4 (&acc)[2][2][4][2], const pg8::Unit& u, int wr, int wc, int fr, int fq) const {
;         const int row0 = u.pm * 256 + wr * 64 + fr, col0 = u.pn * 256 + wc * 32 + 8 * fq;
; #pragma unroll
;         for (int ai = 0; ai < 2; ++ai)
; #pragma unroll
;             for (int m = 0; m < 4; ++m) {
;                 const int row = row0 + ai * 128 + m * 16;
;                 const float s = rstd_of(rowss, row);
; #pragma unroll
;                 for (int bj = 0; bj < 2; ++bj) {
;                     const size_t off = (size_t)row * 1024 + col0 + bj * 128;
;                     const u32x4 tv = *(const u32x4*)(Tm + off);
;                     u32x4 pv = (u32x4){0u, 0u, 0u, 0u};
;                     if (ACC) pv = *(const u32x4*)(M + off);
;                     const f32x4 a0 = acc[ai][bj][m][0] * s, a1 = acc[ai][bj][m][1] * s;
;                     float o[8];
;                     o[0] = sigm(a0[0]) * lo16(tv.x); o[1] = sigm(a0[1]) * hi16(tv.x); o[2] = sigm(a0[2]) * lo16(tv.y); o[3] = sigm(a0[3]) * hi16(tv.y);
;                     o[4] = sigm(a1[0]) * lo16(tv.z); o[5] = sigm(a1[1]) * hi16(tv.z); o[6] = sigm(a1[2]) * lo16(tv.w); o[7] = sigm(a1[3]) * hi16(tv.w);
	s_add_u32 s12, s12, 0x40080
	s_addc_u32 s13, s13, 0
	s_add_i32 s14, s14, s56
	s_mov_b32 m0, s14
	s_nop 0
	global_load_lds_dwordx4 v128, s[12:13]
	s_add_i32 m0, s14, 0x2000
	s_nop 0
	global_load_lds_dwordx4 v152, s[12:13]
	s_waitcnt vmcnt(6)
	s_barrier
	s_cmp_gt_u32 s65, 13
	v_mfma_f32_16x16x32_bf16 v[52:55], v[220:223], v[178:181], v[52:55]
	v_mfma_f32_16x16x32_bf16 v[48:51], v[228:231], v[178:181], v[48:51]
	v_mfma_f32_16x16x32_bf16 v[36:39], v[220:223], v[196:199], v[36:39]
	v_mfma_f32_16x16x32_bf16 v[32:35], v[228:231], v[196:199], v[32:35]
	v_mfma_f32_16x16x32_bf16 v[20:23], v[220:223], v[204:207], v[20:23]
	v_mfma_f32_16x16x32_bf16 v[16:19], v[228:231], v[204:207], v[16:19]
	v_mfma_f32_16x16x32_bf16 v[4:7], v[220:223], v[212:215], v[4:7]
	v_mfma_f32_16x16x32_bf16 v[0:3], v[228:231], v[212:215], v[0:3]
	v_mfma_f32_16x16x32_bf16 v[52:55], v[224:227], v[192:195], v[52:55]
	v_mfma_f32_16x16x32_bf16 v[48:51], v[232:235], v[192:195], v[48:51]
	v_mfma_f32_16x16x32_bf16 v[36:39], v[224:227], v[200:203], v[36:39]
	v_mfma_f32_16x16x32_bf16 v[32:35], v[232:235], v[200:203], v[32:35]
	v_mfma_f32_16x16x32_bf16 v[20:23], v[224:227], v[208:211], v[20:23]
	v_mfma_f32_16x16x32_bf16 v[16:19], v[232:235], v[208:211], v[16:19]
	v_mfma_f32_16x16x32_bf16 v[4:7], v[224:227], v[216:219], v[4:7]
	v_mfma_f32_16x16x32_bf16 v[0:3], v[232:235], v[216:219], v[0:3]
	s_barrier
	s_cbranch_scc0 .LBB0_313
	v_lshl_add_u32 v162, s2, 8, v139
	v_ashrrev_i32_e32 v163, 31, v162
	v_lshl_add_u64 v[160:161], v[162:163], 2, s[40:41]
	global_load_dword v164, v[160:161], off
	v_lshl_or_b32 v158, s46, 8, v168
	v_ashrrev_i32_e32 v159, 31, v158
	s_mov_b32 s2, 0x40000
	s_mov_b64 s[4:5], 0x40000
	s_mov_b32 s46, s6
	s_mov_b64 s[12:13], s[24:25]
	s_mov_b32 s62, 0x1800000
	s_waitcnt vmcnt(0)
	v_fmamk_f32 v164, v164, 0x3a800000, v187
	v_cmp_gt_f32_e32 vcc, s67, v164
	v_mul_f32_e32 v165, 0x4b800000, v164
	s_nop 0
	v_cndmask_b32_e32 v164, v164, v165, vcc
	v_rsq_f32_e32 v164, v164
	s_nop 0
	v_mul_f32_e32 v165, 0x45800000, v164
	v_cndmask_b32_e32 v166, v164, v165, vcc
	v_lshlrev_b64 v[164:165], 11, v[162:163]
	v_lshl_add_u64 v[170:171], s[0:1], 0, v[164:165]
	v_lshlrev_b64 v[164:165], 1, v[158:159]
	v_lshl_add_u64 v[158:159], v[170:171], 0, v[164:165]
	v_mov_b32_e32 v170, v158
	v_mov_b32_e32 v171, v159
	global_load_dwordx4 v[192:195], v[170:171], off
	global_load_dwordx4 v[196:199], v[170:171], off offset:256
	v_add_co_u32_e32 v170, vcc, 0x8000, v170
	s_nop 1
	v_addc_co_u32_e32 v171, vcc, 0, v171, vcc
	global_load_dwordx4 v[200:203], v[170:171], off
	global_load_dwordx4 v[204:207], v[170:171], off offset:256
	v_add_co_u32_e32 v170, vcc, 0x8000, v170
	s_nop 1
	v_addc_co_u32_e32 v171, vcc, 0, v171, vcc
	global_load_dwordx4 v[208:211], v[170:171], off
	global_load_dwordx4 v[212:215], v[170:171], off offset:256
	v_add_co_u32_e32 v170, vcc, 0x8000, v170
	s_nop 1
	v_addc_co_u32_e32 v171, vcc, 0, v171, vcc
	global_load_dwordx4 v[216:219], v[170:171], off
	global_load_dwordx4 v[220:223], v[170:171], off offset:256
	v_lshl_add_u64 v[170:171], v[158:159], 0, s[4:5]
	global_load_dwordx4 v[224:227], v[170:171], off
	global_load_dwordx4 v[228:231], v[170:171], off offset:256
	v_add_co_u32_e32 v170, vcc, 0x8000, v170
	s_nop 1
	v_addc_co_u32_e32 v171, vcc, 0, v171, vcc
	global_load_dwordx4 v[232:235], v[170:171], off
	global_load_dwordx4 v[236:239], v[170:171], off offset:256
	v_add_co_u32_e32 v170, vcc, 0x8000, v170
	s_nop 1
	v_addc_co_u32_e32 v171, vcc, 0, v171, vcc
	global_load_dwordx4 v[244:247], v[170:171], off
	global_load_dwordx4 v[248:251], v[170:171], off offset:256
	v_add_co_u32_e32 v170, vcc, 0x8000, v170
	s_nop 1
	v_addc_co_u32_e32 v171, vcc, 0, v171, vcc
	global_load_dwordx4 v[176:179], v[170:171], off
	global_load_dwordx4 v[252:255], v[170:171], off offset:256
	global_load_dword v180, v[160:161], off offset:64
	global_load_dword v181, v[160:161], off offset:128
	global_load_dword v182, v[160:161], off offset:192
	global_load_dword v183, v[160:161], off offset:512
	global_load_dword v240, v[160:161], off offset:576
	global_load_dword v241, v[160:161], off offset:640
	global_load_dword v169, v[160:161], off offset:704
	v_pk_mul_f32 v[126:127], v[126:127], v[166:167] op_sel_hi:[1,0]
	v_pk_mul_f32 v[120:121], v[120:121], v[166:167] op_sel_hi:[1,0]
	v_mul_f32_e32 v126, 0xbfb8aa3b, v126
	v_mul_f32_e32 v127, 0xbfb8aa3b, v127
	v_exp_f32_e32 v126, v126
	v_exp_f32_e32 v127, v127
	v_mul_f32_e32 v120, 0xbfb8aa3b, v120
	v_mul_f32_e32 v121, 0xbfb8aa3b, v121
	v_exp_f32_e32 v120, v120
	v_exp_f32_e32 v121, v121
	v_add_f32_e32 v126, 1.0, v126
	v_add_f32_e32 v127, 1.0, v127
	v_rcp_f32_e32 v126, v126
	v_rcp_f32_e32 v127, v127
	v_add_f32_e32 v120, 1.0, v120
	v_add_f32_e32 v121, 1.0, v121
	v_rcp_f32_e32 v120, v120
	v_rcp_f32_e32 v121, v121
	v_pk_mul_f32 v[124:125], v[124:125], v[166:167] op_sel_hi:[1,0]
	v_pk_mul_f32 v[122:123], v[122:123], v[166:167] op_sel_hi:[1,0]
	v_mul_f32_e32 v124, 0xbfb8aa3b, v124
	v_mul_f32_e32 v125, 0xbfb8aa3b, v125
	v_exp_f32_e32 v124, v124
	v_exp_f32_e32 v125, v125
	v_pk_mul_f32 v[118:119], v[118:119], v[166:167] op_sel_hi:[1,0]
	v_pk_mul_f32 v[112:113], v[112:113], v[166:167] op_sel_hi:[1,0]
	v_add_f32_e32 v124, 1.0, v124
	v_add_f32_e32 v125, 1.0, v125
	v_rcp_f32_e32 v124, v124
	v_rcp_f32_e32 v125, v125
	v_mul_f32_e32 v118, 0xbfb8aa3b, v118
	v_mul_f32_e32 v119, 0xbfb8aa3b, v119
	v_exp_f32_e32 v118, v118
	v_exp_f32_e32 v119, v119
	v_mul_f32_e32 v112, 0xbfb8aa3b, v112
	v_mul_f32_e32 v113, 0xbfb8aa3b, v113
	v_exp_f32_e32 v112, v112
	v_exp_f32_e32 v113, v113
	v_add_f32_e32 v118, 1.0, v118
	v_add_f32_e32 v119, 1.0, v119
	v_rcp_f32_e32 v118, v118
	v_rcp_f32_e32 v119, v119
	v_add_f32_e32 v112, 1.0, v112
	v_add_f32_e32 v113, 1.0, v113
	v_rcp_f32_e32 v112, v112
	v_rcp_f32_e32 v113, v113
	v_pk_mul_f32 v[116:117], v[116:117], v[166:167] op_sel_hi:[1,0]
	v_pk_mul_f32 v[114:115], v[114:115], v[166:167] op_sel_hi:[1,0]
	v_mul_f32_e32 v116, 0xbfb8aa3b, v116
	v_mul_f32_e32 v117, 0xbfb8aa3b, v117
	v_exp_f32_e32 v116, v116
	v_exp_f32_e32 v117, v117
	v_add_f32_e32 v116, 1.0, v116
	v_add_f32_e32 v117, 1.0, v117
	v_rcp_f32_e32 v116, v116
	v_rcp_f32_e32 v117, v117
	s_waitcnt vmcnt(0)
; __device__ __forceinline__ unsigned cvt_pk_bf16(float lo, float hi) { const f32x2_cv v = {lo, hi}; const bf16x2_cv b = __builtin_convertvector(v, bf16x2_cv); return __builtin_bit_cast(unsigned, b); }
; __device__ __forceinline__ float sigm(float x) { return __builtin_amdgcn_rcpf(1.0f + __expf(-x)); }
; __device__ __forceinline__ float lo16(unsigned w) { return __uint_as_float(w << 16); }
; __device__ __forceinline__ float hi16(unsigned w) { return __uint_as_float(w & 0xffff0000u); }
; __device__ __forceinline__ float rstd_of(const float* rowss, int row) { return rsqrtf(rowss[row] * (1.0f / 1024.0f) + 1e-6f); }
;     __device__ __forceinline__ void operator()(const f32x4 (&acc)[2][2][4][2], const pg8::Unit& u, int wr, int wc, int fr, int fq) const {
;     ...
;                 const int row = row0 + ai * 128 + m * 16;
;                 const float s = rstd_of(rowss, row);
; #pragma unroll
;                 for (int bj = 0; bj < 2; ++bj) {
;                     const size_t off = (size_t)row * 1024 + col0 + bj * 128;
;                     const u32x4 tv = *(const u32x4*)(Tm + off);
;                     u32x4 pv = (u32x4){0u, 0u, 0u, 0u};
;                     if (ACC) pv = *(const u32x4*)(M + off);
;                     const f32x4 a0 = acc[ai][bj][m][0] * s, a1 = acc[ai][bj][m][1] * s;
;                     float o[8];
;                     o[0] = sigm(a0[0]) * lo16(tv.x); o[1] = sigm(a0[1]) * hi16(tv.x); o[2] = sigm(a0[2]) * lo16(tv.y); o[3] = sigm(a0[3]) * hi16(tv.y);
;                     o[4] = sigm(a1[0]) * lo16(tv.z); o[5] = sigm(a1[1]) * hi16(tv.z); o[6] = sigm(a1[2]) * lo16(tv.w); o[7] = sigm(a1[3]) * hi16(tv.w);
;                     if (ACC) { o[0] += lo16(pv.x); o[1] += hi16(pv.x); o[2] += lo16(pv.y); o[3] += hi16(pv.y); o[4] += lo16(pv.z); o[5] += hi16(pv.z); o[6] += lo16(pv.w); o[7] += hi16(pv.w); }
;                     u32x4 w; w.x = cvt_pk_bf16(o[0], o[1]); w.y = cvt_pk_bf16(o[2], o[3]); w.z = cvt_pk_bf16(o[4], o[5]); w.w = cvt_pk_bf16(o[6], o[7]);
;                     *(u32x4*)(M + off) = w; } }
	v_mov_b32_e32 v170, v192
	v_mov_b32_e32 v171, v193
	v_mov_b32_e32 v172, v194
	v_mov_b32_e32 v173, v195
	v_lshlrev_b32_e32 v174, 16, v170
	v_and_b32_e32 v175, 0xffff0000, v170
	v_lshlrev_b32_e32 v170, 16, v171
	v_and_b32_e32 v171, 0xffff0000, v171
	v_pk_mul_f32 v[126:127], v[126:127], v[170:171]
	v_lshlrev_b32_e32 v170, 16, v172
	v_and_b32_e32 v171, 0xffff0000, v172
	v_pk_mul_f32 v[170:171], v[120:121], v[170:171]
	v_mul_f32_e32 v120, 0xbfb8aa3b, v122
	v_mul_f32_e32 v121, 0xbfb8aa3b, v123
	v_exp_f32_e32 v120, v120
	v_exp_f32_e32 v121, v121
	v_lshlrev_b32_e32 v122, 16, v173
	v_and_b32_e32 v123, 0xffff0000, v173
	v_add_f32_e32 v120, 1.0, v120
	v_add_f32_e32 v121, 1.0, v121
	v_rcp_f32_e32 v120, v120
	v_rcp_f32_e32 v121, v121
	v_pk_mul_f32 v[124:125], v[124:125], v[174:175]
	v_pk_mul_f32 v[172:173], v[120:121], v[122:123]
	v_cvt_pk_bf16_f32 v120, v124, v125
	v_cvt_pk_bf16_f32 v121, v126, v127
	v_cvt_pk_bf16_f32 v122, v170, v171
	v_cvt_pk_bf16_f32 v123, v172, v173
	global_store_dwordx4 v[158:159], v[120:123], off
	s_nop 1
	v_mov_b32_e32 v120, v196
	v_mov_b32_e32 v121, v197
	v_mov_b32_e32 v122, v198
	v_mov_b32_e32 v123, v199
	v_lshlrev_b32_e32 v124, 16, v120
	v_and_b32_e32 v125, 0xffff0000, v120
	v_lshlrev_b32_e32 v120, 16, v121
	v_and_b32_e32 v121, 0xffff0000, v121
	v_pk_mul_f32 v[118:119], v[118:119], v[120:121]
	v_lshlrev_b32_e32 v120, 16, v122
	v_and_b32_e32 v121, 0xffff0000, v122
	v_pk_mul_f32 v[120:121], v[112:113], v[120:121]
	v_mul_f32_e32 v112, 0xbfb8aa3b, v114
	v_mul_f32_e32 v113, 0xbfb8aa3b, v115
	v_exp_f32_e32 v112, v112
	v_exp_f32_e32 v113, v113
	v_lshlrev_b32_e32 v114, 16, v123
	v_and_b32_e32 v115, 0xffff0000, v123
	v_add_f32_e32 v112, 1.0, v112
	v_add_f32_e32 v113, 1.0, v113
	v_rcp_f32_e32 v112, v112
	v_rcp_f32_e32 v113, v113
	v_pk_mul_f32 v[116:117], v[116:117], v[124:125]
	v_pk_mul_f32 v[122:123], v[112:113], v[114:115]
	v_cvt_pk_bf16_f32 v112, v116, v117
	v_cvt_pk_bf16_f32 v113, v118, v119
	v_cvt_pk_bf16_f32 v114, v120, v121
	v_cvt_pk_bf16_f32 v115, v122, v123
	global_store_dwordx4 v[158:159], v[112:115], off offset:256
	s_nop 1
	v_mov_b32_e32 v114, v180
	s_nop 0
	v_or_b32_e32 v112, 16, v162
	v_ashrrev_i32_e32 v113, 31, v112
	v_lshlrev_b64 v[112:113], 11, v[112:113]
	v_lshl_add_u64 v[112:113], s[0:1], 0, v[112:113]
	v_lshl_add_u64 v[112:113], v[112:113], 0, v[164:165]
	s_nop 1
	v_mov_b32_e32 v116, v200
	v_mov_b32_e32 v117, v201
	v_mov_b32_e32 v118, v202
	v_mov_b32_e32 v119, v203
	v_fmamk_f32 v114, v114, 0x3a800000, v187
	v_cmp_gt_f32_e32 vcc, s67, v114
	v_mul_f32_e32 v115, 0x4b800000, v114
	v_lshlrev_b32_e32 v120, 16, v116
	v_cndmask_b32_e32 v114, v114, v115, vcc
	v_rsq_f32_e32 v114, v114
	v_and_b32_e32 v121, 0xffff0000, v116
	v_lshlrev_b32_e32 v116, 16, v117
	v_and_b32_e32 v117, 0xffff0000, v117
	v_mul_f32_e32 v115, 0x45800000, v114
	v_cndmask_b32_e32 v114, v114, v115, vcc
	v_pk_mul_f32 v[110:111], v[110:111], v[114:115] op_sel_hi:[1,0]
	v_pk_mul_f32 v[104:105], v[104:105], v[114:115] op_sel_hi:[1,0]
	v_mul_f32_e32 v110, 0xbfb8aa3b, v110
	v_mul_f32_e32 v111, 0xbfb8aa3b, v111
	v_exp_f32_e32 v110, v110
	v_exp_f32_e32 v111, v111
	v_mul_f32_e32 v104, 0xbfb8aa3b, v104
	v_mul_f32_e32 v105, 0xbfb8aa3b, v105
	v_exp_f32_e32 v104, v104
	v_exp_f32_e32 v105, v105
	v_add_f32_e32 v110, 1.0, v110
	v_add_f32_e32 v111, 1.0, v111
	v_rcp_f32_e32 v110, v110
	v_rcp_f32_e32 v111, v111
	v_add_f32_e32 v104, 1.0, v104
	v_add_f32_e32 v105, 1.0, v105
	v_rcp_f32_e32 v104, v104
	v_rcp_f32_e32 v105, v105
	v_pk_mul_f32 v[108:109], v[108:109], v[114:115] op_sel_hi:[1,0]
	v_pk_mul_f32 v[106:107], v[106:107], v[114:115] op_sel_hi:[1,0]
	v_pk_mul_f32 v[110:111], v[110:111], v[116:117]
	v_lshlrev_b32_e32 v116, 16, v118
	v_and_b32_e32 v117, 0xffff0000, v118
	v_mul_f32_e32 v108, 0xbfb8aa3b, v108
	v_mul_f32_e32 v109, 0xbfb8aa3b, v109
	v_pk_mul_f32 v[116:117], v[104:105], v[116:117]
	v_mul_f32_e32 v104, 0xbfb8aa3b, v106
	v_mul_f32_e32 v105, 0xbfb8aa3b, v107
	v_exp_f32_e32 v108, v108
	v_exp_f32_e32 v109, v109
	v_exp_f32_e32 v104, v104
	v_exp_f32_e32 v105, v105
	v_add_f32_e32 v108, 1.0, v108
	v_add_f32_e32 v109, 1.0, v109
	v_add_f32_e32 v104, 1.0, v104
	v_add_f32_e32 v105, 1.0, v105
	v_rcp_f32_e32 v108, v108
	v_rcp_f32_e32 v109, v109
	v_rcp_f32_e32 v104, v104
	v_rcp_f32_e32 v105, v105
	v_lshlrev_b32_e32 v106, 16, v119
	v_and_b32_e32 v107, 0xffff0000, v119
	v_pk_mul_f32 v[108:109], v[108:109], v[120:121]
	v_pk_mul_f32 v[118:119], v[104:105], v[106:107]
	v_cvt_pk_bf16_f32 v104, v108, v109
	v_cvt_pk_bf16_f32 v105, v110, v111
	v_cvt_pk_bf16_f32 v106, v116, v117
	v_cvt_pk_bf16_f32 v107, v118, v119
	global_store_dwordx4 v[112:113], v[104:107], off
	s_nop 1
	v_mov_b32_e32 v104, v204
	v_mov_b32_e32 v105, v205
	v_mov_b32_e32 v106, v206
	v_mov_b32_e32 v107, v207
	v_pk_mul_f32 v[102:103], v[102:103], v[114:115] op_sel_hi:[1,0]
	v_pk_mul_f32 v[96:97], v[96:97], v[114:115] op_sel_hi:[1,0]
	v_mul_f32_e32 v102, 0xbfb8aa3b, v102
	v_mul_f32_e32 v103, 0xbfb8aa3b, v103
	v_exp_f32_e32 v102, v102
	v_exp_f32_e32 v103, v103
	v_mul_f32_e32 v96, 0xbfb8aa3b, v96
	v_mul_f32_e32 v97, 0xbfb8aa3b, v97
	v_exp_f32_e32 v96, v96
	v_exp_f32_e32 v97, v97
	v_add_f32_e32 v102, 1.0, v102
	v_add_f32_e32 v103, 1.0, v103
	v_rcp_f32_e32 v102, v102
	v_rcp_f32_e32 v103, v103
	v_add_f32_e32 v96, 1.0, v96
	v_add_f32_e32 v97, 1.0, v97
	v_rcp_f32_e32 v96, v96
	v_rcp_f32_e32 v97, v97
	v_pk_mul_f32 v[100:101], v[100:101], v[114:115] op_sel_hi:[1,0]
	v_pk_mul_f32 v[98:99], v[98:99], v[114:115] op_sel_hi:[1,0]
	v_mul_f32_e32 v100, 0xbfb8aa3b, v100
	v_mul_f32_e32 v101, 0xbfb8aa3b, v101
	v_exp_f32_e32 v100, v100
	v_exp_f32_e32 v101, v101
	v_add_f32_e32 v100, 1.0, v100
	v_add_f32_e32 v101, 1.0, v101
	v_rcp_f32_e32 v100, v100
; __device__ __forceinline__ unsigned cvt_pk_bf16(float lo, float hi) { const f32x2_cv v = {lo, hi}; const bf16x2_cv b = __builtin_convertvector(v, bf16x2_cv); return __builtin_bit_cast(unsigned, b); }
; __device__ __forceinline__ float sigm(float x) { return __builtin_amdgcn_rcpf(1.0f + __expf(-x)); }
; __device__ __forceinline__ float lo16(unsigned w) { return __uint_as_float(w << 16); }
; __device__ __forceinline__ float hi16(unsigned w) { return __uint_as_float(w & 0xffff0000u); }
; __device__ __forceinline__ float rstd_of(const float* rowss, int row) { return rsqrtf(rowss[row] * (1.0f / 1024.0f) + 1e-6f); }
;     __device__ __forceinline__ void operator()(const f32x4 (&acc)[2][2][4][2], const pg8::Unit& u, int wr, int wc, int fr, int fq) const {
;     ...
;                 const int row = row0 + ai * 128 + m * 16;
;                 const float s = rstd_of(rowss, row);
; #pragma unroll
;                 for (int bj = 0; bj < 2; ++bj) {
;                     const size_t off = (size_t)row * 1024 + col0 + bj * 128;
;                     const u32x4 tv = *(const u32x4*)(Tm + off);
;                     u32x4 pv = (u32x4){0u, 0u, 0u, 0u};
;                     if (ACC) pv = *(const u32x4*)(M + off);
;                     const f32x4 a0 = acc[ai][bj][m][0] * s, a1 = acc[ai][bj][m][1] * s;
;                     float o[8];
;                     o[0] = sigm(a0[0]) * lo16(tv.x); o[1] = sigm(a0[1]) * hi16(tv.x); o[2] = sigm(a0[2]) * lo16(tv.y); o[3] = sigm(a0[3]) * hi16(tv.y);
;                     o[4] = sigm(a1[0]) * lo16(tv.z); o[5] = sigm(a1[1]) * hi16(tv.z); o[6] = sigm(a1[2]) * lo16(tv.w); o[7] = sigm(a1[3]) * hi16(tv.w);
;                     if (ACC) { o[0] += lo16(pv.x); o[1] += hi16(pv.x); o[2] += lo16(pv.y); o[3] += hi16(pv.y); o[4] += lo16(pv.z); o[5] += hi16(pv.z); o[6] += lo16(pv.w); o[7] += hi16(pv.w); }
;                     u32x4 w; w.x = cvt_pk_bf16(o[0], o[1]); w.y = cvt_pk_bf16(o[2], o[3]); w.z = cvt_pk_bf16(o[4], o[5]); w.w = cvt_pk_bf16(o[6], o[7]);
;                     *(u32x4*)(M + off) = w; } }
	v_rcp_f32_e32 v101, v101
	v_lshlrev_b32_e32 v108, 16, v104
	v_and_b32_e32 v109, 0xffff0000, v104
	v_lshlrev_b32_e32 v104, 16, v105
	v_and_b32_e32 v105, 0xffff0000, v105
	v_pk_mul_f32 v[102:103], v[102:103], v[104:105]
	v_lshlrev_b32_e32 v104, 16, v106
	v_and_b32_e32 v105, 0xffff0000, v106
	v_pk_mul_f32 v[104:105], v[96:97], v[104:105]
	v_mul_f32_e32 v96, 0xbfb8aa3b, v98
	v_mul_f32_e32 v97, 0xbfb8aa3b, v99
	v_exp_f32_e32 v96, v96
	v_exp_f32_e32 v97, v97
	v_lshlrev_b32_e32 v98, 16, v107
	v_and_b32_e32 v99, 0xffff0000, v107
	v_add_f32_e32 v96, 1.0, v96
	v_add_f32_e32 v97, 1.0, v97
	v_rcp_f32_e32 v96, v96
	v_rcp_f32_e32 v97, v97
	v_pk_mul_f32 v[100:101], v[100:101], v[108:109]
	v_pk_mul_f32 v[106:107], v[96:97], v[98:99]
	v_cvt_pk_bf16_f32 v96, v100, v101
	v_cvt_pk_bf16_f32 v97, v102, v103
	v_cvt_pk_bf16_f32 v98, v104, v105
	v_cvt_pk_bf16_f32 v99, v106, v107
	global_store_dwordx4 v[112:113], v[96:99], off offset:256
	s_nop 1
	v_mov_b32_e32 v98, v181
	s_nop 0
	v_or_b32_e32 v96, 32, v162
	v_ashrrev_i32_e32 v97, 31, v96
	v_lshlrev_b64 v[96:97], 11, v[96:97]
	v_lshl_add_u64 v[96:97], s[0:1], 0, v[96:97]
	v_lshl_add_u64 v[96:97], v[96:97], 0, v[164:165]
	s_nop 1
	v_mov_b32_e32 v100, v208
	v_mov_b32_e32 v101, v209
	v_mov_b32_e32 v102, v210
	v_mov_b32_e32 v103, v211
	v_fmamk_f32 v98, v98, 0x3a800000, v187
	v_cmp_gt_f32_e32 vcc, s67, v98
	v_mul_f32_e32 v99, 0x4b800000, v98
	v_lshlrev_b32_e32 v104, 16, v100
	v_cndmask_b32_e32 v98, v98, v99, vcc
	v_rsq_f32_e32 v98, v98
	v_and_b32_e32 v105, 0xffff0000, v100
	v_lshlrev_b32_e32 v100, 16, v101
	v_and_b32_e32 v101, 0xffff0000, v101
	v_mul_f32_e32 v99, 0x45800000, v98
	v_cndmask_b32_e32 v98, v98, v99, vcc
	v_pk_mul_f32 v[94:95], v[94:95], v[98:99] op_sel_hi:[1,0]
	v_pk_mul_f32 v[88:89], v[88:89], v[98:99] op_sel_hi:[1,0]
	v_mul_f32_e32 v94, 0xbfb8aa3b, v94
	v_mul_f32_e32 v95, 0xbfb8aa3b, v95
	v_exp_f32_e32 v94, v94
	v_exp_f32_e32 v95, v95
	v_mul_f32_e32 v88, 0xbfb8aa3b, v88
	v_mul_f32_e32 v89, 0xbfb8aa3b, v89
	v_exp_f32_e32 v88, v88
	v_exp_f32_e32 v89, v89
	v_add_f32_e32 v94, 1.0, v94
	v_add_f32_e32 v95, 1.0, v95
	v_rcp_f32_e32 v94, v94
	v_rcp_f32_e32 v95, v95
	v_add_f32_e32 v88, 1.0, v88
	v_add_f32_e32 v89, 1.0, v89
	v_rcp_f32_e32 v88, v88
	v_rcp_f32_e32 v89, v89
	v_pk_mul_f32 v[92:93], v[92:93], v[98:99] op_sel_hi:[1,0]
	v_pk_mul_f32 v[90:91], v[90:91], v[98:99] op_sel_hi:[1,0]
	v_pk_mul_f32 v[94:95], v[94:95], v[100:101]
	v_lshlrev_b32_e32 v100, 16, v102
	v_and_b32_e32 v101, 0xffff0000, v102
	v_mul_f32_e32 v92, 0xbfb8aa3b, v92
	v_mul_f32_e32 v93, 0xbfb8aa3b, v93
	v_pk_mul_f32 v[100:101], v[88:89], v[100:101]
	v_mul_f32_e32 v88, 0xbfb8aa3b, v90
	v_mul_f32_e32 v89, 0xbfb8aa3b, v91
	v_exp_f32_e32 v92, v92
	v_exp_f32_e32 v93, v93
	v_exp_f32_e32 v88, v88
	v_exp_f32_e32 v89, v89
	v_add_f32_e32 v92, 1.0, v92
	v_add_f32_e32 v93, 1.0, v93
	v_add_f32_e32 v88, 1.0, v88
	v_add_f32_e32 v89, 1.0, v89
	v_rcp_f32_e32 v92, v92
	v_rcp_f32_e32 v93, v93
	v_rcp_f32_e32 v88, v88
	v_rcp_f32_e32 v89, v89
	v_lshlrev_b32_e32 v90, 16, v103
	v_and_b32_e32 v91, 0xffff0000, v103
	v_pk_mul_f32 v[92:93], v[92:93], v[104:105]
	v_pk_mul_f32 v[102:103], v[88:89], v[90:91]
	v_cvt_pk_bf16_f32 v88, v92, v93
	v_cvt_pk_bf16_f32 v89, v94, v95
	v_cvt_pk_bf16_f32 v90, v100, v101
	v_cvt_pk_bf16_f32 v91, v102, v103
	global_store_dwordx4 v[96:97], v[88:91], off
	s_nop 1
	v_mov_b32_e32 v88, v212
	v_mov_b32_e32 v89, v213
	v_mov_b32_e32 v90, v214
	v_mov_b32_e32 v91, v215
	v_pk_mul_f32 v[86:87], v[86:87], v[98:99] op_sel_hi:[1,0]
	v_pk_mul_f32 v[80:81], v[80:81], v[98:99] op_sel_hi:[1,0]
	v_mul_f32_e32 v86, 0xbfb8aa3b, v86
	v_mul_f32_e32 v87, 0xbfb8aa3b, v87
	v_exp_f32_e32 v86, v86
	v_exp_f32_e32 v87, v87
	v_mul_f32_e32 v80, 0xbfb8aa3b, v80
	v_mul_f32_e32 v81, 0xbfb8aa3b, v81
	v_exp_f32_e32 v80, v80
	v_exp_f32_e32 v81, v81
	v_add_f32_e32 v86, 1.0, v86
	v_add_f32_e32 v87, 1.0, v87
	v_rcp_f32_e32 v86, v86
	v_rcp_f32_e32 v87, v87
	v_add_f32_e32 v80, 1.0, v80
	v_add_f32_e32 v81, 1.0, v81
	v_rcp_f32_e32 v80, v80
	v_rcp_f32_e32 v81, v81
	v_pk_mul_f32 v[84:85], v[84:85], v[98:99] op_sel_hi:[1,0]
	v_pk_mul_f32 v[82:83], v[82:83], v[98:99] op_sel_hi:[1,0]
	v_mul_f32_e32 v84, 0xbfb8aa3b, v84
	v_mul_f32_e32 v85, 0xbfb8aa3b, v85
	v_exp_f32_e32 v84, v84
	v_exp_f32_e32 v85, v85
	v_add_f32_e32 v84, 1.0, v84
	v_add_f32_e32 v85, 1.0, v85
	v_rcp_f32_e32 v84, v84
	v_rcp_f32_e32 v85, v85
	v_lshlrev_b32_e32 v92, 16, v88
	v_and_b32_e32 v93, 0xffff0000, v88
	v_lshlrev_b32_e32 v88, 16, v89
	v_and_b32_e32 v89, 0xffff0000, v89
	v_pk_mul_f32 v[86:87], v[86:87], v[88:89]
	v_lshlrev_b32_e32 v88, 16, v90
	v_and_b32_e32 v89, 0xffff0000, v90
	v_pk_mul_f32 v[88:89], v[80:81], v[88:89]
	v_mul_f32_e32 v80, 0xbfb8aa3b, v82
	v_mul_f32_e32 v81, 0xbfb8aa3b, v83
	v_exp_f32_e32 v80, v80
	v_exp_f32_e32 v81, v81
	v_lshlrev_b32_e32 v82, 16, v91
	v_and_b32_e32 v83, 0xffff0000, v91
	v_add_f32_e32 v80, 1.0, v80
	v_add_f32_e32 v81, 1.0, v81
	v_rcp_f32_e32 v80, v80
	v_rcp_f32_e32 v81, v81
	v_pk_mul_f32 v[84:85], v[84:85], v[92:93]
	v_pk_mul_f32 v[90:91], v[80:81], v[82:83]
	v_cvt_pk_bf16_f32 v80, v84, v85
	v_cvt_pk_bf16_f32 v81, v86, v87
	v_cvt_pk_bf16_f32 v82, v88, v89
	v_cvt_pk_bf16_f32 v83, v90, v91
	global_store_dwordx4 v[96:97], v[80:83], off offset:256
	s_nop 1
	v_mov_b32_e32 v82, v182
	s_nop 0
	v_or_b32_e32 v80, 48, v162
	v_ashrrev_i32_e32 v81, 31, v80
	v_lshlrev_b64 v[80:81], 11, v[80:81]
	v_lshl_add_u64 v[80:81], s[0:1], 0, v[80:81]
	v_lshl_add_u64 v[80:81], v[80:81], 0, v[164:165]
	s_nop 1
	v_mov_b32_e32 v84, v216
	v_mov_b32_e32 v85, v217
	v_mov_b32_e32 v86, v218
	v_mov_b32_e32 v87, v219
	v_fmamk_f32 v82, v82, 0x3a800000, v187
	v_cmp_gt_f32_e32 vcc, s67, v82
	v_mul_f32_e32 v83, 0x4b800000, v82
; __device__ __forceinline__ unsigned cvt_pk_bf16(float lo, float hi) { const f32x2_cv v = {lo, hi}; const bf16x2_cv b = __builtin_convertvector(v, bf16x2_cv); return __builtin_bit_cast(unsigned, b); }
; __device__ __forceinline__ float sigm(float x) { return __builtin_amdgcn_rcpf(1.0f + __expf(-x)); }
; __device__ __forceinline__ float lo16(unsigned w) { return __uint_as_float(w << 16); }
; __device__ __forceinline__ float hi16(unsigned w) { return __uint_as_float(w & 0xffff0000u); }
; __device__ __forceinline__ float rstd_of(const float* rowss, int row) { return rsqrtf(rowss[row] * (1.0f / 1024.0f) + 1e-6f); }
;     __device__ __forceinline__ void operator()(const f32x4 (&acc)[2][2][4][2], const pg8::Unit& u, int wr, int wc, int fr, int fq) const {
;     ...
;                 const int row = row0 + ai * 128 + m * 16;
;                 const float s = rstd_of(rowss, row);
; #pragma unroll
;                 for (int bj = 0; bj < 2; ++bj) {
;                     const size_t off = (size_t)row * 1024 + col0 + bj * 128;
;                     const u32x4 tv = *(const u32x4*)(Tm + off);
;                     u32x4 pv = (u32x4){0u, 0u, 0u, 0u};
;                     if (ACC) pv = *(const u32x4*)(M + off);
;                     const f32x4 a0 = acc[ai][bj][m][0] * s, a1 = acc[ai][bj][m][1] * s;
;                     float o[8];
;                     o[0] = sigm(a0[0]) * lo16(tv.x); o[1] = sigm(a0[1]) * hi16(tv.x); o[2] = sigm(a0[2]) * lo16(tv.y); o[3] = sigm(a0[3]) * hi16(tv.y);
;                     o[4] = sigm(a1[0]) * lo16(tv.z); o[5] = sigm(a1[1]) * hi16(tv.z); o[6] = sigm(a1[2]) * lo16(tv.w); o[7] = sigm(a1[3]) * hi16(tv.w);
;                     if (ACC) { o[0] += lo16(pv.x); o[1] += hi16(pv.x); o[2] += lo16(pv.y); o[3] += hi16(pv.y); o[4] += lo16(pv.z); o[5] += hi16(pv.z); o[6] += lo16(pv.w); o[7] += hi16(pv.w); }
;                     u32x4 w; w.x = cvt_pk_bf16(o[0], o[1]); w.y = cvt_pk_bf16(o[2], o[3]); w.z = cvt_pk_bf16(o[4], o[5]); w.w = cvt_pk_bf16(o[6], o[7]);
;                     *(u32x4*)(M + off) = w; } }
	v_lshlrev_b32_e32 v88, 16, v84
	v_cndmask_b32_e32 v82, v82, v83, vcc
	v_rsq_f32_e32 v82, v82
	v_and_b32_e32 v89, 0xffff0000, v84
	v_lshlrev_b32_e32 v84, 16, v85
	v_and_b32_e32 v85, 0xffff0000, v85
	v_mul_f32_e32 v83, 0x45800000, v82
	v_cndmask_b32_e32 v82, v82, v83, vcc
	v_pk_mul_f32 v[78:79], v[78:79], v[82:83] op_sel_hi:[1,0]
	v_pk_mul_f32 v[72:73], v[72:73], v[82:83] op_sel_hi:[1,0]
	v_mul_f32_e32 v78, 0xbfb8aa3b, v78
	v_mul_f32_e32 v79, 0xbfb8aa3b, v79
	v_exp_f32_e32 v78, v78
	v_exp_f32_e32 v79, v79
	v_mul_f32_e32 v72, 0xbfb8aa3b, v72
	v_mul_f32_e32 v73, 0xbfb8aa3b, v73
	v_exp_f32_e32 v72, v72
	v_exp_f32_e32 v73, v73
	v_add_f32_e32 v78, 1.0, v78
	v_add_f32_e32 v79, 1.0, v79
	v_rcp_f32_e32 v78, v78
	v_rcp_f32_e32 v79, v79
	v_add_f32_e32 v72, 1.0, v72
	v_add_f32_e32 v73, 1.0, v73
	v_rcp_f32_e32 v72, v72
	v_rcp_f32_e32 v73, v73
	v_pk_mul_f32 v[76:77], v[76:77], v[82:83] op_sel_hi:[1,0]
	v_pk_mul_f32 v[74:75], v[74:75], v[82:83] op_sel_hi:[1,0]
	v_pk_mul_f32 v[78:79], v[78:79], v[84:85]
	v_lshlrev_b32_e32 v84, 16, v86
	v_and_b32_e32 v85, 0xffff0000, v86
	v_mul_f32_e32 v76, 0xbfb8aa3b, v76
	v_mul_f32_e32 v77, 0xbfb8aa3b, v77
	v_pk_mul_f32 v[84:85], v[72:73], v[84:85]
	v_mul_f32_e32 v72, 0xbfb8aa3b, v74
	v_mul_f32_e32 v73, 0xbfb8aa3b, v75
	v_exp_f32_e32 v76, v76
	v_exp_f32_e32 v77, v77
	v_exp_f32_e32 v72, v72
	v_exp_f32_e32 v73, v73
	v_add_f32_e32 v76, 1.0, v76
	v_add_f32_e32 v77, 1.0, v77
	v_add_f32_e32 v72, 1.0, v72
	v_add_f32_e32 v73, 1.0, v73
	v_rcp_f32_e32 v76, v76
	v_rcp_f32_e32 v77, v77
	v_rcp_f32_e32 v72, v72
	v_rcp_f32_e32 v73, v73
	v_lshlrev_b32_e32 v74, 16, v87
	v_and_b32_e32 v75, 0xffff0000, v87
	v_pk_mul_f32 v[76:77], v[76:77], v[88:89]
	v_pk_mul_f32 v[86:87], v[72:73], v[74:75]
	v_cvt_pk_bf16_f32 v72, v76, v77
	v_cvt_pk_bf16_f32 v73, v78, v79
	v_cvt_pk_bf16_f32 v74, v84, v85
	v_cvt_pk_bf16_f32 v75, v86, v87
	global_store_dwordx4 v[80:81], v[72:75], off
	s_nop 1
	v_mov_b32_e32 v72, v220
	v_mov_b32_e32 v73, v221
	v_mov_b32_e32 v74, v222
	v_mov_b32_e32 v75, v223
	v_pk_mul_f32 v[70:71], v[70:71], v[82:83] op_sel_hi:[1,0]
	v_pk_mul_f32 v[64:65], v[64:65], v[82:83] op_sel_hi:[1,0]
	v_mul_f32_e32 v70, 0xbfb8aa3b, v70
	v_mul_f32_e32 v71, 0xbfb8aa3b, v71
	v_exp_f32_e32 v70, v70
	v_exp_f32_e32 v71, v71
	v_mul_f32_e32 v64, 0xbfb8aa3b, v64
	v_mul_f32_e32 v65, 0xbfb8aa3b, v65
	v_exp_f32_e32 v64, v64
	v_exp_f32_e32 v65, v65
	v_add_f32_e32 v70, 1.0, v70
	v_add_f32_e32 v71, 1.0, v71
	v_rcp_f32_e32 v70, v70
	v_rcp_f32_e32 v71, v71
	v_add_f32_e32 v64, 1.0, v64
	v_add_f32_e32 v65, 1.0, v65
	v_rcp_f32_e32 v64, v64
	v_rcp_f32_e32 v65, v65
	v_pk_mul_f32 v[68:69], v[68:69], v[82:83] op_sel_hi:[1,0]
	v_pk_mul_f32 v[66:67], v[66:67], v[82:83] op_sel_hi:[1,0]
	v_mul_f32_e32 v68, 0xbfb8aa3b, v68
	v_mul_f32_e32 v69, 0xbfb8aa3b, v69
	v_exp_f32_e32 v68, v68
	v_exp_f32_e32 v69, v69
	v_add_f32_e32 v68, 1.0, v68
	v_add_f32_e32 v69, 1.0, v69
	v_rcp_f32_e32 v68, v68
	v_rcp_f32_e32 v69, v69
	v_lshlrev_b32_e32 v76, 16, v72
	v_and_b32_e32 v77, 0xffff0000, v72
	v_lshlrev_b32_e32 v72, 16, v73
	v_and_b32_e32 v73, 0xffff0000, v73
	v_pk_mul_f32 v[70:71], v[70:71], v[72:73]
	v_lshlrev_b32_e32 v72, 16, v74
	v_and_b32_e32 v73, 0xffff0000, v74
	v_pk_mul_f32 v[72:73], v[64:65], v[72:73]
	v_mul_f32_e32 v64, 0xbfb8aa3b, v66
	v_mul_f32_e32 v65, 0xbfb8aa3b, v67
	v_exp_f32_e32 v64, v64
	v_exp_f32_e32 v65, v65
	v_lshlrev_b32_e32 v66, 16, v75
	v_and_b32_e32 v67, 0xffff0000, v75
	v_add_f32_e32 v64, 1.0, v64
	v_add_f32_e32 v65, 1.0, v65
	v_rcp_f32_e32 v64, v64
	v_rcp_f32_e32 v65, v65
	v_pk_mul_f32 v[68:69], v[68:69], v[76:77]
	v_pk_mul_f32 v[74:75], v[64:65], v[66:67]
	v_cvt_pk_bf16_f32 v64, v68, v69
	v_cvt_pk_bf16_f32 v65, v70, v71
	v_cvt_pk_bf16_f32 v66, v72, v73
	v_cvt_pk_bf16_f32 v67, v74, v75
	global_store_dwordx4 v[80:81], v[64:67], off offset:256
	s_nop 1
	v_mov_b32_e32 v64, v183
	v_fmamk_f32 v64, v64, 0x3a800000, v187
	v_cmp_gt_f32_e32 vcc, s67, v64
	v_mul_f32_e32 v65, 0x4b800000, v64
	s_nop 0
	v_cndmask_b32_e32 v64, v64, v65, vcc
	v_rsq_f32_e32 v64, v64
	s_nop 0
	v_mul_f32_e32 v65, 0x45800000, v64
	v_cndmask_b32_e32 v66, v64, v65, vcc
	v_add_co_u32_e32 v72, vcc, s2, v158
	v_pk_mul_f32 v[62:63], v[62:63], v[66:67] op_sel_hi:[1,0]
	s_nop 0
	v_addc_co_u32_e32 v73, vcc, 0, v159, vcc
	s_nop 1
	v_mov_b32_e32 v68, v224
	v_mov_b32_e32 v69, v225
	v_mov_b32_e32 v70, v226
	v_mov_b32_e32 v71, v227
	v_pk_mul_f32 v[56:57], v[56:57], v[66:67] op_sel_hi:[1,0]
	v_mul_f32_e32 v62, 0xbfb8aa3b, v62
	v_mul_f32_e32 v63, 0xbfb8aa3b, v63
	v_exp_f32_e32 v62, v62
	v_exp_f32_e32 v63, v63
	v_mul_f32_e32 v56, 0xbfb8aa3b, v56
	v_mul_f32_e32 v57, 0xbfb8aa3b, v57
	v_exp_f32_e32 v56, v56
	v_exp_f32_e32 v57, v57
	v_add_f32_e32 v62, 1.0, v62
	v_add_f32_e32 v63, 1.0, v63
	v_rcp_f32_e32 v62, v62
	v_rcp_f32_e32 v63, v63
	v_add_f32_e32 v56, 1.0, v56
	v_add_f32_e32 v57, 1.0, v57
	v_rcp_f32_e32 v56, v56
	v_rcp_f32_e32 v57, v57
	v_pk_mul_f32 v[60:61], v[60:61], v[66:67] op_sel_hi:[1,0]
	v_pk_mul_f32 v[58:59], v[58:59], v[66:67] op_sel_hi:[1,0]
	v_mul_f32_e32 v60, 0xbfb8aa3b, v60
	v_mul_f32_e32 v61, 0xbfb8aa3b, v61
	v_exp_f32_e32 v60, v60
	v_exp_f32_e32 v61, v61
	v_lshl_add_u64 v[64:65], v[158:159], 0, s[4:5]
	v_pk_mul_f32 v[54:55], v[54:55], v[66:67] op_sel_hi:[1,0]
	v_add_f32_e32 v60, 1.0, v60
	v_add_f32_e32 v61, 1.0, v61
	v_rcp_f32_e32 v60, v60
	v_rcp_f32_e32 v61, v61
	v_pk_mul_f32 v[48:49], v[48:49], v[66:67] op_sel_hi:[1,0]
	v_mul_f32_e32 v54, 0xbfb8aa3b, v54
	v_mul_f32_e32 v55, 0xbfb8aa3b, v55
	v_exp_f32_e32 v54, v54
	v_exp_f32_e32 v55, v55
	v_mul_f32_e32 v48, 0xbfb8aa3b, v48
	v_mul_f32_e32 v49, 0xbfb8aa3b, v49
	v_exp_f32_e32 v48, v48
	v_exp_f32_e32 v49, v49
	v_add_f32_e32 v54, 1.0, v54
	v_add_f32_e32 v55, 1.0, v55
; __device__ __forceinline__ unsigned cvt_pk_bf16(float lo, float hi) { const f32x2_cv v = {lo, hi}; const bf16x2_cv b = __builtin_convertvector(v, bf16x2_cv); return __builtin_bit_cast(unsigned, b); }
; __device__ __forceinline__ float sigm(float x) { return __builtin_amdgcn_rcpf(1.0f + __expf(-x)); }
; __device__ __forceinline__ float lo16(unsigned w) { return __uint_as_float(w << 16); }
; __device__ __forceinline__ float hi16(unsigned w) { return __uint_as_float(w & 0xffff0000u); }
; __device__ __forceinline__ float rstd_of(const float* rowss, int row) { return rsqrtf(rowss[row] * (1.0f / 1024.0f) + 1e-6f); }
;     __device__ __forceinline__ void operator()(const f32x4 (&acc)[2][2][4][2], const pg8::Unit& u, int wr, int wc, int fr, int fq) const {
;     ...
;                 const int row = row0 + ai * 128 + m * 16;
;                 const float s = rstd_of(rowss, row);
; #pragma unroll
;                 for (int bj = 0; bj < 2; ++bj) {
;                     const size_t off = (size_t)row * 1024 + col0 + bj * 128;
;                     const u32x4 tv = *(const u32x4*)(Tm + off);
;                     u32x4 pv = (u32x4){0u, 0u, 0u, 0u};
;                     if (ACC) pv = *(const u32x4*)(M + off);
;                     const f32x4 a0 = acc[ai][bj][m][0] * s, a1 = acc[ai][bj][m][1] * s;
;                     float o[8];
;                     o[0] = sigm(a0[0]) * lo16(tv.x); o[1] = sigm(a0[1]) * hi16(tv.x); o[2] = sigm(a0[2]) * lo16(tv.y); o[3] = sigm(a0[3]) * hi16(tv.y);
;                     o[4] = sigm(a1[0]) * lo16(tv.z); o[5] = sigm(a1[1]) * hi16(tv.z); o[6] = sigm(a1[2]) * lo16(tv.w); o[7] = sigm(a1[3]) * hi16(tv.w);
;                     if (ACC) { o[0] += lo16(pv.x); o[1] += hi16(pv.x); o[2] += lo16(pv.y); o[3] += hi16(pv.y); o[4] += lo16(pv.z); o[5] += hi16(pv.z); o[6] += lo16(pv.w); o[7] += hi16(pv.w); }
;                     u32x4 w; w.x = cvt_pk_bf16(o[0], o[1]); w.y = cvt_pk_bf16(o[2], o[3]); w.z = cvt_pk_bf16(o[4], o[5]); w.w = cvt_pk_bf16(o[6], o[7]);
;                     *(u32x4*)(M + off) = w; } }
	v_rcp_f32_e32 v54, v54
	v_rcp_f32_e32 v55, v55
	v_add_f32_e32 v48, 1.0, v48
	v_add_f32_e32 v49, 1.0, v49
	v_rcp_f32_e32 v48, v48
	v_rcp_f32_e32 v49, v49
	v_pk_mul_f32 v[52:53], v[52:53], v[66:67] op_sel_hi:[1,0]
	v_pk_mul_f32 v[50:51], v[50:51], v[66:67] op_sel_hi:[1,0]
	v_mul_f32_e32 v52, 0xbfb8aa3b, v52
	v_mul_f32_e32 v53, 0xbfb8aa3b, v53
	v_exp_f32_e32 v52, v52
	v_exp_f32_e32 v53, v53
	s_mov_b32 s2, 0x48000
	s_mov_b64 s[4:5], 0x48000
	v_add_f32_e32 v52, 1.0, v52
	v_add_f32_e32 v53, 1.0, v53
	v_rcp_f32_e32 v52, v52
	v_rcp_f32_e32 v53, v53
	v_lshlrev_b32_e32 v74, 16, v68
	v_and_b32_e32 v75, 0xffff0000, v68
	v_lshlrev_b32_e32 v68, 16, v69
	v_and_b32_e32 v69, 0xffff0000, v69
	v_pk_mul_f32 v[62:63], v[62:63], v[68:69]
	v_lshlrev_b32_e32 v68, 16, v70
	v_and_b32_e32 v69, 0xffff0000, v70
	v_pk_mul_f32 v[68:69], v[56:57], v[68:69]
	v_mul_f32_e32 v56, 0xbfb8aa3b, v58
	v_mul_f32_e32 v57, 0xbfb8aa3b, v59
	v_exp_f32_e32 v56, v56
	v_exp_f32_e32 v57, v57
	v_lshlrev_b32_e32 v58, 16, v71
	v_and_b32_e32 v59, 0xffff0000, v71
	v_add_f32_e32 v56, 1.0, v56
	v_add_f32_e32 v57, 1.0, v57
	v_rcp_f32_e32 v56, v56
	v_rcp_f32_e32 v57, v57
	v_pk_mul_f32 v[60:61], v[60:61], v[74:75]
	v_pk_mul_f32 v[70:71], v[56:57], v[58:59]
	v_cvt_pk_bf16_f32 v56, v60, v61
	v_cvt_pk_bf16_f32 v57, v62, v63
	v_cvt_pk_bf16_f32 v58, v68, v69
	v_cvt_pk_bf16_f32 v59, v70, v71
	global_store_dwordx4 v[72:73], v[56:59], off
	s_nop 1
	v_mov_b32_e32 v56, v228
	v_mov_b32_e32 v57, v229
	v_mov_b32_e32 v58, v230
	v_mov_b32_e32 v59, v231
	v_lshlrev_b32_e32 v60, 16, v56
	v_and_b32_e32 v61, 0xffff0000, v56
	v_lshlrev_b32_e32 v56, 16, v57
	v_and_b32_e32 v57, 0xffff0000, v57
	v_pk_mul_f32 v[54:55], v[54:55], v[56:57]
	v_lshlrev_b32_e32 v56, 16, v58
	v_and_b32_e32 v57, 0xffff0000, v58
	v_pk_mul_f32 v[56:57], v[48:49], v[56:57]
	v_mul_f32_e32 v48, 0xbfb8aa3b, v50
	v_mul_f32_e32 v49, 0xbfb8aa3b, v51
	v_exp_f32_e32 v48, v48
	v_exp_f32_e32 v49, v49
	v_lshlrev_b32_e32 v50, 16, v59
	v_and_b32_e32 v51, 0xffff0000, v59
	v_add_f32_e32 v48, 1.0, v48
	v_add_f32_e32 v49, 1.0, v49
	v_rcp_f32_e32 v48, v48
	v_rcp_f32_e32 v49, v49
	v_pk_mul_f32 v[52:53], v[52:53], v[60:61]
	v_pk_mul_f32 v[58:59], v[48:49], v[50:51]
	v_cvt_pk_bf16_f32 v48, v52, v53
	v_cvt_pk_bf16_f32 v49, v54, v55
	v_cvt_pk_bf16_f32 v50, v56, v57
	v_cvt_pk_bf16_f32 v51, v58, v59
	global_store_dwordx4 v[64:65], v[48:51], off offset:256
	s_nop 1
	v_mov_b32_e32 v48, v240
	v_fmamk_f32 v48, v48, 0x3a800000, v187
	v_cmp_gt_f32_e32 vcc, s67, v48
	v_mul_f32_e32 v49, 0x4b800000, v48
	s_nop 0
	v_cndmask_b32_e32 v48, v48, v49, vcc
	v_rsq_f32_e32 v48, v48
	s_nop 0
	v_mul_f32_e32 v49, 0x45800000, v48
	v_cndmask_b32_e32 v50, v48, v49, vcc
	v_add_co_u32_e32 v56, vcc, s2, v158
	v_pk_mul_f32 v[46:47], v[46:47], v[50:51] op_sel_hi:[1,0]
	s_nop 0
	v_addc_co_u32_e32 v57, vcc, 0, v159, vcc
	s_nop 1
	v_mov_b32_e32 v52, v232
	v_mov_b32_e32 v53, v233
	v_mov_b32_e32 v54, v234
	v_mov_b32_e32 v55, v235
	v_pk_mul_f32 v[40:41], v[40:41], v[50:51] op_sel_hi:[1,0]
	v_mul_f32_e32 v46, 0xbfb8aa3b, v46
	v_mul_f32_e32 v47, 0xbfb8aa3b, v47
	v_exp_f32_e32 v46, v46
	v_exp_f32_e32 v47, v47
	v_mul_f32_e32 v40, 0xbfb8aa3b, v40
	v_mul_f32_e32 v41, 0xbfb8aa3b, v41
	v_exp_f32_e32 v40, v40
	v_exp_f32_e32 v41, v41
	v_add_f32_e32 v46, 1.0, v46
	v_add_f32_e32 v47, 1.0, v47
	v_rcp_f32_e32 v46, v46
	v_rcp_f32_e32 v47, v47
	v_add_f32_e32 v40, 1.0, v40
	v_add_f32_e32 v41, 1.0, v41
	v_rcp_f32_e32 v40, v40
	v_rcp_f32_e32 v41, v41
	v_pk_mul_f32 v[44:45], v[44:45], v[50:51] op_sel_hi:[1,0]
	v_pk_mul_f32 v[42:43], v[42:43], v[50:51] op_sel_hi:[1,0]
	v_mul_f32_e32 v44, 0xbfb8aa3b, v44
	v_mul_f32_e32 v45, 0xbfb8aa3b, v45
	v_exp_f32_e32 v44, v44
	v_exp_f32_e32 v45, v45
	v_lshl_add_u64 v[48:49], v[158:159], 0, s[4:5]
	v_pk_mul_f32 v[38:39], v[38:39], v[50:51] op_sel_hi:[1,0]
	v_add_f32_e32 v44, 1.0, v44
	v_add_f32_e32 v45, 1.0, v45
	v_rcp_f32_e32 v44, v44
	v_rcp_f32_e32 v45, v45
	v_pk_mul_f32 v[32:33], v[32:33], v[50:51] op_sel_hi:[1,0]
	v_mul_f32_e32 v38, 0xbfb8aa3b, v38
	v_mul_f32_e32 v39, 0xbfb8aa3b, v39
	v_exp_f32_e32 v38, v38
	v_exp_f32_e32 v39, v39
	v_mul_f32_e32 v32, 0xbfb8aa3b, v32
	v_mul_f32_e32 v33, 0xbfb8aa3b, v33
	v_exp_f32_e32 v32, v32
	v_exp_f32_e32 v33, v33
	v_add_f32_e32 v38, 1.0, v38
	v_add_f32_e32 v39, 1.0, v39
	v_rcp_f32_e32 v38, v38
	v_rcp_f32_e32 v39, v39
	v_add_f32_e32 v32, 1.0, v32
	v_add_f32_e32 v33, 1.0, v33
	v_rcp_f32_e32 v32, v32
	v_rcp_f32_e32 v33, v33
	v_pk_mul_f32 v[36:37], v[36:37], v[50:51] op_sel_hi:[1,0]
	v_pk_mul_f32 v[34:35], v[34:35], v[50:51] op_sel_hi:[1,0]
	v_mul_f32_e32 v36, 0xbfb8aa3b, v36
	v_mul_f32_e32 v37, 0xbfb8aa3b, v37
	v_exp_f32_e32 v36, v36
	v_exp_f32_e32 v37, v37
	s_mov_b32 s2, 0x50000
	s_mov_b64 s[4:5], 0x50000
	v_add_f32_e32 v36, 1.0, v36
	v_add_f32_e32 v37, 1.0, v37
	v_rcp_f32_e32 v36, v36
	v_rcp_f32_e32 v37, v37
	v_lshlrev_b32_e32 v58, 16, v52
	v_and_b32_e32 v59, 0xffff0000, v52
	v_lshlrev_b32_e32 v52, 16, v53
	v_and_b32_e32 v53, 0xffff0000, v53
	v_pk_mul_f32 v[46:47], v[46:47], v[52:53]
	v_lshlrev_b32_e32 v52, 16, v54
	v_and_b32_e32 v53, 0xffff0000, v54
	v_pk_mul_f32 v[52:53], v[40:41], v[52:53]
	v_mul_f32_e32 v40, 0xbfb8aa3b, v42
	v_mul_f32_e32 v41, 0xbfb8aa3b, v43
	v_exp_f32_e32 v40, v40
	v_exp_f32_e32 v41, v41
	v_lshlrev_b32_e32 v42, 16, v55
	v_and_b32_e32 v43, 0xffff0000, v55
	v_add_f32_e32 v40, 1.0, v40
	v_add_f32_e32 v41, 1.0, v41
	v_rcp_f32_e32 v40, v40
	v_rcp_f32_e32 v41, v41
	v_pk_mul_f32 v[44:45], v[44:45], v[58:59]
	v_pk_mul_f32 v[54:55], v[40:41], v[42:43]
	v_cvt_pk_bf16_f32 v40, v44, v45
	v_cvt_pk_bf16_f32 v41, v46, v47
	v_cvt_pk_bf16_f32 v42, v52, v53
	v_cvt_pk_bf16_f32 v43, v54, v55
	global_store_dwordx4 v[56:57], v[40:43], off
	s_nop 1
; __device__ __forceinline__ unsigned cvt_pk_bf16(float lo, float hi) { const f32x2_cv v = {lo, hi}; const bf16x2_cv b = __builtin_convertvector(v, bf16x2_cv); return __builtin_bit_cast(unsigned, b); }
; __device__ __forceinline__ float sigm(float x) { return __builtin_amdgcn_rcpf(1.0f + __expf(-x)); }
; __device__ __forceinline__ float lo16(unsigned w) { return __uint_as_float(w << 16); }
; __device__ __forceinline__ float hi16(unsigned w) { return __uint_as_float(w & 0xffff0000u); }
; __device__ __forceinline__ float rstd_of(const float* rowss, int row) { return rsqrtf(rowss[row] * (1.0f / 1024.0f) + 1e-6f); }
;     __device__ __forceinline__ void operator()(const f32x4 (&acc)[2][2][4][2], const pg8::Unit& u, int wr, int wc, int fr, int fq) const {
;     ...
;                 const int row = row0 + ai * 128 + m * 16;
;                 const float s = rstd_of(rowss, row);
; #pragma unroll
;                 for (int bj = 0; bj < 2; ++bj) {
;                     const size_t off = (size_t)row * 1024 + col0 + bj * 128;
;                     const u32x4 tv = *(const u32x4*)(Tm + off);
;                     u32x4 pv = (u32x4){0u, 0u, 0u, 0u};
;                     if (ACC) pv = *(const u32x4*)(M + off);
;                     const f32x4 a0 = acc[ai][bj][m][0] * s, a1 = acc[ai][bj][m][1] * s;
;                     float o[8];
;                     o[0] = sigm(a0[0]) * lo16(tv.x); o[1] = sigm(a0[1]) * hi16(tv.x); o[2] = sigm(a0[2]) * lo16(tv.y); o[3] = sigm(a0[3]) * hi16(tv.y);
;                     o[4] = sigm(a1[0]) * lo16(tv.z); o[5] = sigm(a1[1]) * hi16(tv.z); o[6] = sigm(a1[2]) * lo16(tv.w); o[7] = sigm(a1[3]) * hi16(tv.w);
;                     if (ACC) { o[0] += lo16(pv.x); o[1] += hi16(pv.x); o[2] += lo16(pv.y); o[3] += hi16(pv.y); o[4] += lo16(pv.z); o[5] += hi16(pv.z); o[6] += lo16(pv.w); o[7] += hi16(pv.w); }
;                     u32x4 w; w.x = cvt_pk_bf16(o[0], o[1]); w.y = cvt_pk_bf16(o[2], o[3]); w.z = cvt_pk_bf16(o[4], o[5]); w.w = cvt_pk_bf16(o[6], o[7]);
;                     *(u32x4*)(M + off) = w; } }
	v_mov_b32_e32 v40, v236
	v_mov_b32_e32 v41, v237
	v_mov_b32_e32 v42, v238
	v_mov_b32_e32 v43, v239
	v_lshlrev_b32_e32 v44, 16, v40
	v_and_b32_e32 v45, 0xffff0000, v40
	v_lshlrev_b32_e32 v40, 16, v41
	v_and_b32_e32 v41, 0xffff0000, v41
	v_pk_mul_f32 v[38:39], v[38:39], v[40:41]
	v_lshlrev_b32_e32 v40, 16, v42
	v_and_b32_e32 v41, 0xffff0000, v42
	v_pk_mul_f32 v[40:41], v[32:33], v[40:41]
	v_mul_f32_e32 v32, 0xbfb8aa3b, v34
	v_mul_f32_e32 v33, 0xbfb8aa3b, v35
	v_exp_f32_e32 v32, v32
	v_exp_f32_e32 v33, v33
	v_lshlrev_b32_e32 v34, 16, v43
	v_and_b32_e32 v35, 0xffff0000, v43
	v_add_f32_e32 v32, 1.0, v32
	v_add_f32_e32 v33, 1.0, v33
	v_rcp_f32_e32 v32, v32
	v_rcp_f32_e32 v33, v33
	v_pk_mul_f32 v[36:37], v[36:37], v[44:45]
	v_pk_mul_f32 v[42:43], v[32:33], v[34:35]
	v_cvt_pk_bf16_f32 v32, v36, v37
	v_cvt_pk_bf16_f32 v33, v38, v39
	v_cvt_pk_bf16_f32 v34, v40, v41
	v_cvt_pk_bf16_f32 v35, v42, v43
	global_store_dwordx4 v[48:49], v[32:35], off offset:256
	s_nop 1
	v_mov_b32_e32 v32, v241
	v_fmamk_f32 v32, v32, 0x3a800000, v187
	v_cmp_gt_f32_e32 vcc, s67, v32
	v_mul_f32_e32 v33, 0x4b800000, v32
	s_nop 0
	v_cndmask_b32_e32 v32, v32, v33, vcc
	v_rsq_f32_e32 v32, v32
	s_nop 0
	v_mul_f32_e32 v33, 0x45800000, v32
	v_cndmask_b32_e32 v34, v32, v33, vcc
	v_add_co_u32_e32 v40, vcc, s2, v158
	v_pk_mul_f32 v[30:31], v[30:31], v[34:35] op_sel_hi:[1,0]
	s_nop 0
	v_addc_co_u32_e32 v41, vcc, 0, v159, vcc
	s_nop 1
	v_mov_b32_e32 v36, v244
	v_mov_b32_e32 v37, v245
	v_mov_b32_e32 v38, v246
	v_mov_b32_e32 v39, v247
	v_pk_mul_f32 v[24:25], v[24:25], v[34:35] op_sel_hi:[1,0]
	v_mul_f32_e32 v30, 0xbfb8aa3b, v30
	v_mul_f32_e32 v31, 0xbfb8aa3b, v31
	v_exp_f32_e32 v30, v30
	v_exp_f32_e32 v31, v31
	v_mul_f32_e32 v24, 0xbfb8aa3b, v24
	v_mul_f32_e32 v25, 0xbfb8aa3b, v25
	v_exp_f32_e32 v24, v24
	v_exp_f32_e32 v25, v25
	v_add_f32_e32 v30, 1.0, v30
	v_add_f32_e32 v31, 1.0, v31
	v_rcp_f32_e32 v30, v30
	v_rcp_f32_e32 v31, v31
	v_add_f32_e32 v24, 1.0, v24
	v_add_f32_e32 v25, 1.0, v25
	v_rcp_f32_e32 v24, v24
	v_rcp_f32_e32 v25, v25
	v_pk_mul_f32 v[28:29], v[28:29], v[34:35] op_sel_hi:[1,0]
	v_pk_mul_f32 v[26:27], v[26:27], v[34:35] op_sel_hi:[1,0]
	v_mul_f32_e32 v28, 0xbfb8aa3b, v28
	v_mul_f32_e32 v29, 0xbfb8aa3b, v29
	v_exp_f32_e32 v28, v28
	v_exp_f32_e32 v29, v29
	v_lshl_add_u64 v[32:33], v[158:159], 0, s[4:5]
	v_pk_mul_f32 v[22:23], v[22:23], v[34:35] op_sel_hi:[1,0]
	v_add_f32_e32 v28, 1.0, v28
	v_add_f32_e32 v29, 1.0, v29
	v_rcp_f32_e32 v28, v28
	v_rcp_f32_e32 v29, v29
	v_pk_mul_f32 v[16:17], v[16:17], v[34:35] op_sel_hi:[1,0]
	v_mul_f32_e32 v22, 0xbfb8aa3b, v22
	v_mul_f32_e32 v23, 0xbfb8aa3b, v23
	v_exp_f32_e32 v22, v22
	v_exp_f32_e32 v23, v23
	v_mul_f32_e32 v16, 0xbfb8aa3b, v16
	v_mul_f32_e32 v17, 0xbfb8aa3b, v17
	v_exp_f32_e32 v16, v16
	v_exp_f32_e32 v17, v17
	v_add_f32_e32 v22, 1.0, v22
	v_add_f32_e32 v23, 1.0, v23
	v_rcp_f32_e32 v22, v22
	v_rcp_f32_e32 v23, v23
	v_add_f32_e32 v16, 1.0, v16
	v_add_f32_e32 v17, 1.0, v17
	v_rcp_f32_e32 v16, v16
	v_rcp_f32_e32 v17, v17
	v_pk_mul_f32 v[20:21], v[20:21], v[34:35] op_sel_hi:[1,0]
	v_pk_mul_f32 v[18:19], v[18:19], v[34:35] op_sel_hi:[1,0]
	v_mul_f32_e32 v20, 0xbfb8aa3b, v20
	v_mul_f32_e32 v21, 0xbfb8aa3b, v21
	v_exp_f32_e32 v20, v20
	v_exp_f32_e32 v21, v21
	s_mov_b32 s2, 0x58000
	s_mov_b64 s[4:5], 0x58000
	v_add_f32_e32 v20, 1.0, v20
	v_add_f32_e32 v21, 1.0, v21
	v_rcp_f32_e32 v20, v20
	v_rcp_f32_e32 v21, v21
	v_lshlrev_b32_e32 v42, 16, v36
	v_and_b32_e32 v43, 0xffff0000, v36
	v_lshlrev_b32_e32 v36, 16, v37
	v_and_b32_e32 v37, 0xffff0000, v37
	v_pk_mul_f32 v[30:31], v[30:31], v[36:37]
	v_lshlrev_b32_e32 v36, 16, v38
	v_and_b32_e32 v37, 0xffff0000, v38
	v_pk_mul_f32 v[36:37], v[24:25], v[36:37]
	v_mul_f32_e32 v24, 0xbfb8aa3b, v26
	v_mul_f32_e32 v25, 0xbfb8aa3b, v27
	v_exp_f32_e32 v24, v24
	v_exp_f32_e32 v25, v25
	v_lshlrev_b32_e32 v26, 16, v39
	v_and_b32_e32 v27, 0xffff0000, v39
	v_add_f32_e32 v24, 1.0, v24
	v_add_f32_e32 v25, 1.0, v25
	v_rcp_f32_e32 v24, v24
	v_rcp_f32_e32 v25, v25
	v_pk_mul_f32 v[28:29], v[28:29], v[42:43]
	v_pk_mul_f32 v[38:39], v[24:25], v[26:27]
	v_cvt_pk_bf16_f32 v24, v28, v29
	v_cvt_pk_bf16_f32 v25, v30, v31
	v_cvt_pk_bf16_f32 v26, v36, v37
	v_cvt_pk_bf16_f32 v27, v38, v39
	global_store_dwordx4 v[40:41], v[24:27], off
	s_nop 1
	v_mov_b32_e32 v24, v248
	v_mov_b32_e32 v25, v249
	v_mov_b32_e32 v26, v250
	v_mov_b32_e32 v27, v251
	v_lshlrev_b32_e32 v28, 16, v24
	v_and_b32_e32 v29, 0xffff0000, v24
	v_lshlrev_b32_e32 v24, 16, v25
	v_and_b32_e32 v25, 0xffff0000, v25
	v_pk_mul_f32 v[22:23], v[22:23], v[24:25]
	v_lshlrev_b32_e32 v24, 16, v26
	v_and_b32_e32 v25, 0xffff0000, v26
	v_pk_mul_f32 v[24:25], v[16:17], v[24:25]
	v_mul_f32_e32 v16, 0xbfb8aa3b, v18
	v_mul_f32_e32 v17, 0xbfb8aa3b, v19
; __device__ __forceinline__ unsigned cvt_pk_bf16(float lo, float hi) { const f32x2_cv v = {lo, hi}; const bf16x2_cv b = __builtin_convertvector(v, bf16x2_cv); return __builtin_bit_cast(unsigned, b); }
; __device__ __forceinline__ float sigm(float x) { return __builtin_amdgcn_rcpf(1.0f + __expf(-x)); }
; __device__ __forceinline__ float lo16(unsigned w) { return __uint_as_float(w << 16); }
; __device__ __forceinline__ float hi16(unsigned w) { return __uint_as_float(w & 0xffff0000u); }
; __device__ __forceinline__ float rstd_of(const float* rowss, int row) { return rsqrtf(rowss[row] * (1.0f / 1024.0f) + 1e-6f); }
;     __device__ __forceinline__ void operator()(const f32x4 (&acc)[2][2][4][2], const pg8::Unit& u, int wr, int wc, int fr, int fq) const {
;     ...
;                 const int row = row0 + ai * 128 + m * 16;
;                 const float s = rstd_of(rowss, row);
; #pragma unroll
;                 for (int bj = 0; bj < 2; ++bj) {
;                     const size_t off = (size_t)row * 1024 + col0 + bj * 128;
;                     const u32x4 tv = *(const u32x4*)(Tm + off);
;                     u32x4 pv = (u32x4){0u, 0u, 0u, 0u};
;                     if (ACC) pv = *(const u32x4*)(M + off);
;                     const f32x4 a0 = acc[ai][bj][m][0] * s, a1 = acc[ai][bj][m][1] * s;
;                     float o[8];
;                     o[0] = sigm(a0[0]) * lo16(tv.x); o[1] = sigm(a0[1]) * hi16(tv.x); o[2] = sigm(a0[2]) * lo16(tv.y); o[3] = sigm(a0[3]) * hi16(tv.y);
;                     o[4] = sigm(a1[0]) * lo16(tv.z); o[5] = sigm(a1[1]) * hi16(tv.z); o[6] = sigm(a1[2]) * lo16(tv.w); o[7] = sigm(a1[3]) * hi16(tv.w);
;                     if (ACC) { o[0] += lo16(pv.x); o[1] += hi16(pv.x); o[2] += lo16(pv.y); o[3] += hi16(pv.y); o[4] += lo16(pv.z); o[5] += hi16(pv.z); o[6] += lo16(pv.w); o[7] += hi16(pv.w); }
;                     u32x4 w; w.x = cvt_pk_bf16(o[0], o[1]); w.y = cvt_pk_bf16(o[2], o[3]); w.z = cvt_pk_bf16(o[4], o[5]); w.w = cvt_pk_bf16(o[6], o[7]);
;                     *(u32x4*)(M + off) = w; } }
	v_exp_f32_e32 v16, v16
	v_exp_f32_e32 v17, v17
	v_lshlrev_b32_e32 v18, 16, v27
	v_and_b32_e32 v19, 0xffff0000, v27
	v_add_f32_e32 v16, 1.0, v16
	v_add_f32_e32 v17, 1.0, v17
	v_rcp_f32_e32 v16, v16
	v_rcp_f32_e32 v17, v17
	v_pk_mul_f32 v[20:21], v[20:21], v[28:29]
	v_pk_mul_f32 v[26:27], v[16:17], v[18:19]
	v_cvt_pk_bf16_f32 v16, v20, v21
	v_cvt_pk_bf16_f32 v17, v22, v23
	v_cvt_pk_bf16_f32 v18, v24, v25
	v_cvt_pk_bf16_f32 v19, v26, v27
	global_store_dwordx4 v[32:33], v[16:19], off offset:256
	s_nop 1
	v_mov_b32_e32 v16, v169
	v_fmamk_f32 v16, v16, 0x3a800000, v187
	v_cmp_gt_f32_e32 vcc, s67, v16
	v_mul_f32_e32 v17, 0x4b800000, v16
	s_nop 0
	v_cndmask_b32_e32 v16, v16, v17, vcc
	v_rsq_f32_e32 v16, v16
	s_nop 0
	v_mul_f32_e32 v17, 0x45800000, v16
	v_cndmask_b32_e32 v18, v16, v17, vcc
	v_add_co_u32_e32 v24, vcc, s2, v158
	v_pk_mul_f32 v[14:15], v[14:15], v[18:19] op_sel_hi:[1,0]
	s_nop 0
	v_addc_co_u32_e32 v25, vcc, 0, v159, vcc
	s_nop 1
	v_mov_b32_e32 v20, v176
	v_mov_b32_e32 v21, v177
	v_mov_b32_e32 v22, v178
	v_mov_b32_e32 v23, v179
	v_pk_mul_f32 v[8:9], v[8:9], v[18:19] op_sel_hi:[1,0]
	v_mul_f32_e32 v14, 0xbfb8aa3b, v14
	v_mul_f32_e32 v15, 0xbfb8aa3b, v15
	v_exp_f32_e32 v14, v14
	v_exp_f32_e32 v15, v15
	v_mul_f32_e32 v8, 0xbfb8aa3b, v8
	v_mul_f32_e32 v9, 0xbfb8aa3b, v9
	v_exp_f32_e32 v8, v8
	v_exp_f32_e32 v9, v9
	v_add_f32_e32 v14, 1.0, v14
	v_add_f32_e32 v15, 1.0, v15
	v_rcp_f32_e32 v14, v14
	v_rcp_f32_e32 v15, v15
	v_add_f32_e32 v8, 1.0, v8
	v_add_f32_e32 v9, 1.0, v9
	v_rcp_f32_e32 v8, v8
	v_rcp_f32_e32 v9, v9
	v_pk_mul_f32 v[12:13], v[12:13], v[18:19] op_sel_hi:[1,0]
	v_pk_mul_f32 v[10:11], v[10:11], v[18:19] op_sel_hi:[1,0]
	v_mul_f32_e32 v12, 0xbfb8aa3b, v12
	v_mul_f32_e32 v13, 0xbfb8aa3b, v13
	v_exp_f32_e32 v12, v12
	v_exp_f32_e32 v13, v13
	v_lshl_add_u64 v[16:17], v[158:159], 0, s[4:5]
	v_pk_mul_f32 v[6:7], v[6:7], v[18:19] op_sel_hi:[1,0]
	v_add_f32_e32 v12, 1.0, v12
	v_add_f32_e32 v13, 1.0, v13
	v_rcp_f32_e32 v12, v12
	v_rcp_f32_e32 v13, v13
	v_pk_mul_f32 v[0:1], v[0:1], v[18:19] op_sel_hi:[1,0]
	v_mul_f32_e32 v6, 0xbfb8aa3b, v6
	v_mul_f32_e32 v7, 0xbfb8aa3b, v7
	v_exp_f32_e32 v6, v6
	v_exp_f32_e32 v7, v7
	v_mul_f32_e32 v0, 0xbfb8aa3b, v0
	v_mul_f32_e32 v1, 0xbfb8aa3b, v1
	v_exp_f32_e32 v0, v0
	v_exp_f32_e32 v1, v1
	v_add_f32_e32 v6, 1.0, v6
	v_add_f32_e32 v7, 1.0, v7
	v_rcp_f32_e32 v6, v6
	v_rcp_f32_e32 v7, v7
	v_add_f32_e32 v0, 1.0, v0
	v_add_f32_e32 v1, 1.0, v1
	v_rcp_f32_e32 v0, v0
	v_rcp_f32_e32 v1, v1
	v_pk_mul_f32 v[4:5], v[4:5], v[18:19] op_sel_hi:[1,0]
	v_pk_mul_f32 v[2:3], v[2:3], v[18:19] op_sel_hi:[1,0]
	v_mul_f32_e32 v4, 0xbfb8aa3b, v4
	v_mul_f32_e32 v5, 0xbfb8aa3b, v5
	v_exp_f32_e32 v4, v4
	v_exp_f32_e32 v5, v5
	s_and_b64 vcc, exec, s[38:39]
	s_mov_b32 s2, s30
	v_add_f32_e32 v4, 1.0, v4
	v_add_f32_e32 v5, 1.0, v5
	v_rcp_f32_e32 v4, v4
	v_rcp_f32_e32 v5, v5
	s_mov_b64 s[4:5], s[48:49]
	v_lshlrev_b32_e32 v26, 16, v20
	v_and_b32_e32 v27, 0xffff0000, v20
	v_lshlrev_b32_e32 v20, 16, v21
	v_and_b32_e32 v21, 0xffff0000, v21
	v_pk_mul_f32 v[14:15], v[14:15], v[20:21]
	v_lshlrev_b32_e32 v20, 16, v22
	v_and_b32_e32 v21, 0xffff0000, v22
	v_pk_mul_f32 v[20:21], v[8:9], v[20:21]
	v_mul_f32_e32 v8, 0xbfb8aa3b, v10
	v_mul_f32_e32 v9, 0xbfb8aa3b, v11
	v_exp_f32_e32 v8, v8
	v_exp_f32_e32 v9, v9
	v_lshlrev_b32_e32 v10, 16, v23
	v_and_b32_e32 v11, 0xffff0000, v23
	v_add_f32_e32 v8, 1.0, v8
	v_add_f32_e32 v9, 1.0, v9
	v_rcp_f32_e32 v8, v8
	v_rcp_f32_e32 v9, v9
	v_pk_mul_f32 v[12:13], v[12:13], v[26:27]
	v_pk_mul_f32 v[22:23], v[8:9], v[10:11]
	v_cvt_pk_bf16_f32 v8, v12, v13
	v_cvt_pk_bf16_f32 v9, v14, v15
	v_cvt_pk_bf16_f32 v10, v20, v21
	v_cvt_pk_bf16_f32 v11, v22, v23
	global_store_dwordx4 v[24:25], v[8:11], off
	s_nop 1
	v_mov_b32_e32 v8, v252
	v_mov_b32_e32 v9, v253
	v_mov_b32_e32 v10, v254
	v_mov_b32_e32 v11, v255
	v_lshlrev_b32_e32 v12, 16, v8
	v_and_b32_e32 v13, 0xffff0000, v8
	v_lshlrev_b32_e32 v8, 16, v9
	v_and_b32_e32 v9, 0xffff0000, v9
	v_pk_mul_f32 v[6:7], v[6:7], v[8:9]
	v_lshlrev_b32_e32 v8, 16, v10
	v_and_b32_e32 v9, 0xffff0000, v10
	v_pk_mul_f32 v[8:9], v[0:1], v[8:9]
	v_mul_f32_e32 v0, 0xbfb8aa3b, v2
	v_mul_f32_e32 v1, 0xbfb8aa3b, v3
	v_exp_f32_e32 v0, v0
	v_exp_f32_e32 v1, v1
	v_lshlrev_b32_e32 v2, 16, v11
	v_and_b32_e32 v3, 0xffff0000, v11
	v_add_f32_e32 v0, 1.0, v0
	v_add_f32_e32 v1, 1.0, v1
	v_rcp_f32_e32 v0, v0
	v_rcp_f32_e32 v1, v1
	v_pk_mul_f32 v[4:5], v[4:5], v[12:13]
	v_pk_mul_f32 v[10:11], v[0:1], v[2:3]
	v_cvt_pk_bf16_f32 v0, v4, v5
	v_cvt_pk_bf16_f32 v1, v6, v7
	v_cvt_pk_bf16_f32 v2, v8, v9
	v_cvt_pk_bf16_f32 v3, v10, v11
	global_store_dwordx4 v[16:17], v[0:3], off offset:256
	s_cbranch_vccz .LBB0_306
	s_cmpk_gt_u32 s36, 0xff
	s_cbranch_scc1 .LBB0_317
	s_barrier

; #define PG8_STAGE(bufoff, gbase, voff) do { _Pragma("unroll") for (int _i = 0; _i < 2; ++_i) \
;         __builtin_amdgcn_global_load_lds((const unsigned*)((const char*)(gbase) + (voff)[_i]), (PG8_LAS unsigned*)(lds + (bufoff) + ldsw + _i * 8192), 16, 0, 0); } while (0)
; #define PG8_LDA(dst, b, h) do { _Pragma("unroll") for (int m = 0; m < 4; ++m) _Pragma("unroll") for (int k = 0; k < 2; ++k) dst[m][k] = *(const PG8_LAS bf16x8*)(lds + PG8_SA(b, h) + aoff + m * 2048 + k * 1024); } while (0)
; #define PG8_LDB(dst, b, h) do { _Pragma("unroll") for (int n = 0; n < 2; ++n) _Pragma("unroll") for (int k = 0; k < 2; ++k) dst[n][k] = *(const PG8_LAS bf16x8*)(lds + PG8_SB(b, h) + boff + n * 2048 + k * 1024); } while (0)
; #define PG8_MMA(ai, bj, At, Bt) do { __builtin_amdgcn_s_setprio(1); _Pragma("unroll") for (int m = 0; m < 4; ++m) _Pragma("unroll") for (int n = 0; n < 2; ++n) _Pragma("unroll") for (int k = 0; k < 2; ++k) \
;         acc[ai][bj][m][n] = __builtin_amdgcn_mfma_f32_16x16x32_bf16(Bt[n][k], At[m][k], acc[ai][bj][m][n], 0, 0, 0); __builtin_amdgcn_s_setprio(0); } while (0)
; #define PG8_BAR __builtin_amdgcn_s_barrier()
; template <class Epi, class Sched, bool STAMP = false>
; __device__ __forceinline__ void gemm_phase(PG8_LAS unsigned char* lds, const Gemm g, const Sched& S, const Epi& E, unsigned long long* stamps) {
;     ...
;         for (int t = 0; t < nt; t += 2) {
;             const bool last = (t == nt - 2);
;             const char* a1 = cA + (size_t)(t + 1) * kstep;
;             const char* a2 = last ? nA : cA + (size_t)(t + 2) * kstep; const char* b2 = last ? nB : cB + (size_t)(t + 2) * kstep;
;             const char* a3 = a2 + kstep; const char* b3 = b2 + kstep;
;             if (last && has_next) S.a_ready(nxt);
;             PG8_LDB(B0, 0, 0); PG8_SCHED; PG8_LDA(At, 0, 0); PG8_STAGE(PG8_SA(1, 1), a1 + hstep, voffA);
;             PG8_WAIT_L(8); PG8_BAR; PG8_WAIT_L(0); PG8_MMA(0, 0, At, B0); PG8_BAR; PG8_SCHED;
;             PG8_LDB(B1, 0, 1); PG8_STAGE(PG8_SB(0, 0), b2, voffB);
;             PG8_BAR; PG8_WAIT_L(0); PG8_MMA(0, 1, At, B1); PG8_BAR;
;             PG8_LDA(At, 0, 1); PG8_STAGE(PG8_SA(0, 0), a2, voffA);
;             PG8_BAR; PG8_WAIT_L(0); PG8_MMA(1, 0, At, B0); PG8_BAR; PG8_SCHED;
;             PG8_STAGE(PG8_SB(0, 1), b2 + hstep, voffB);
;             PG8_WAIT_V(6); PG8_BAR; PG8_MMA(1, 1, At, B1); PG8_BAR;
.LBB0_333:
	s_add_u32 s14, s36, 0xfffe0080
	s_addc_u32 s15, s37, -1
	s_add_i32 s16, 0, 0x10000
	ds_read_b128 v[162:165], v248
	ds_read_b128 v[166:169], v248 offset:1024
	ds_read_b128 v[170:173], v248 offset:2048
	ds_read_b128 v[174:177], v248 offset:3072
	s_cmp_eq_u32 s97, 4
	s_cselect_b32 s59, s13, s15
	s_cselect_b32 s58, s77, s14
	s_cselect_b32 s57, s5, s96
	s_cselect_b32 s56, s88, s89
	s_add_i32 m0, s3, 0xc000
	ds_read_b128 v[178:181], v160
	ds_read_b128 v[192:195], v160 offset:1024
	ds_read_b128 v[196:199], v160 offset:2048
	ds_read_b128 v[200:203], v160 offset:3072
	ds_read_b128 v[204:207], v160 offset:4096
	ds_read_b128 v[208:211], v160 offset:5120
	ds_read_b128 v[212:215], v160 offset:6144
	global_load_lds_dwordx4 v154, s[36:37]
	s_add_i32 m0, s3, 0xe000
	ds_read_b128 v[216:219], v160 offset:7168
	global_load_lds_dwordx4 v156, s[36:37]
	s_waitcnt lgkmcnt(8)
	s_barrier
	s_waitcnt lgkmcnt(0)
	v_mfma_f32_16x16x32_bf16 v[124:127], v[162:165], v[178:181], v[124:127]
	v_mfma_f32_16x16x32_bf16 v[120:123], v[170:173], v[178:181], v[120:123]
	v_mfma_f32_16x16x32_bf16 v[116:119], v[162:165], v[196:199], v[116:119]
	v_mfma_f32_16x16x32_bf16 v[112:115], v[170:173], v[196:199], v[112:115]
	v_mfma_f32_16x16x32_bf16 v[100:103], v[162:165], v[204:207], v[100:103]
	v_mfma_f32_16x16x32_bf16 v[96:99], v[170:173], v[204:207], v[96:99]
	v_mfma_f32_16x16x32_bf16 v[84:87], v[162:165], v[212:215], v[84:87]
	v_mfma_f32_16x16x32_bf16 v[80:83], v[170:173], v[212:215], v[80:83]
	v_mfma_f32_16x16x32_bf16 v[124:127], v[166:169], v[192:195], v[124:127]
	v_mfma_f32_16x16x32_bf16 v[120:123], v[174:177], v[192:195], v[120:123]
	v_mfma_f32_16x16x32_bf16 v[116:119], v[166:169], v[200:203], v[116:119]
	v_mfma_f32_16x16x32_bf16 v[112:115], v[174:177], v[200:203], v[112:115]
	v_mfma_f32_16x16x32_bf16 v[100:103], v[166:169], v[208:211], v[100:103]
	v_mfma_f32_16x16x32_bf16 v[96:99], v[174:177], v[208:211], v[96:99]
	v_mfma_f32_16x16x32_bf16 v[84:87], v[166:169], v[216:219], v[84:87]
	v_mfma_f32_16x16x32_bf16 v[80:83], v[174:177], v[216:219], v[80:83]
	s_barrier
	s_add_i32 s17, 0, 0x14000
	s_add_i32 s14, s16, s53
	s_mov_b32 m0, s14
	ds_read_b128 v[220:223], v249
	ds_read_b128 v[224:227], v249 offset:1024
	ds_read_b128 v[228:231], v249 offset:2048
	global_load_lds_dwordx4 v128, s[56:57]
	s_add_i32 m0, s14, 0x2000
	ds_read_b128 v[232:235], v249 offset:3072
	global_load_lds_dwordx4 v152, s[56:57]
	s_barrier
	s_waitcnt lgkmcnt(0)
	v_mfma_f32_16x16x32_bf16 v[108:111], v[220:223], v[178:181], v[108:111]
	v_mfma_f32_16x16x32_bf16 v[104:107], v[228:231], v[178:181], v[104:107]
	v_mfma_f32_16x16x32_bf16 v[92:95], v[220:223], v[196:199], v[92:95]
	v_mfma_f32_16x16x32_bf16 v[88:91], v[228:231], v[196:199], v[88:91]
	v_mfma_f32_16x16x32_bf16 v[76:79], v[220:223], v[204:207], v[76:79]
	v_mfma_f32_16x16x32_bf16 v[72:75], v[228:231], v[204:207], v[72:75]
	v_mfma_f32_16x16x32_bf16 v[68:71], v[220:223], v[212:215], v[68:71]
	v_mfma_f32_16x16x32_bf16 v[64:67], v[228:231], v[212:215], v[64:67]
	v_mfma_f32_16x16x32_bf16 v[108:111], v[224:227], v[192:195], v[108:111]
	v_mfma_f32_16x16x32_bf16 v[104:107], v[232:235], v[192:195], v[104:107]
	v_mfma_f32_16x16x32_bf16 v[92:95], v[224:227], v[200:203], v[92:95]
	v_mfma_f32_16x16x32_bf16 v[88:91], v[232:235], v[200:203], v[88:91]
	v_mfma_f32_16x16x32_bf16 v[76:79], v[224:227], v[208:211], v[76:79]
	v_mfma_f32_16x16x32_bf16 v[72:75], v[232:235], v[208:211], v[72:75]
	v_mfma_f32_16x16x32_bf16 v[68:71], v[224:227], v[216:219], v[68:71]
	v_mfma_f32_16x16x32_bf16 v[64:67], v[232:235], v[216:219], v[64:67]
	s_barrier
	s_mov_b32 m0, s3
	ds_read_b128 v[178:181], v160 offset:16384
	ds_read_b128 v[192:195], v160 offset:17408
	ds_read_b128 v[196:199], v160 offset:18432
	ds_read_b128 v[200:203], v160 offset:19456
	ds_read_b128 v[204:207], v160 offset:20480
	ds_read_b128 v[208:211], v160 offset:21504
	ds_read_b128 v[212:215], v160 offset:22528
	global_load_lds_dwordx4 v148, s[58:59]
	s_mov_b32 m0, s60
	ds_read_b128 v[216:219], v160 offset:23552
	global_load_lds_dwordx4 v150, s[58:59]
	s_barrier
	s_waitcnt lgkmcnt(0)
	v_mfma_f32_16x16x32_bf16 v[60:63], v[162:165], v[178:181], v[60:63]
	v_mfma_f32_16x16x32_bf16 v[56:59], v[170:173], v[178:181], v[56:59]
	v_mfma_f32_16x16x32_bf16 v[52:55], v[162:165], v[196:199], v[52:55]
	v_mfma_f32_16x16x32_bf16 v[48:51], v[170:173], v[196:199], v[48:51]
	v_mfma_f32_16x16x32_bf16 v[36:39], v[162:165], v[204:207], v[36:39]
	v_mfma_f32_16x16x32_bf16 v[32:35], v[170:173], v[204:207], v[32:35]
	v_mfma_f32_16x16x32_bf16 v[20:23], v[162:165], v[212:215], v[20:23]
	v_mfma_f32_16x16x32_bf16 v[16:19], v[170:173], v[212:215], v[16:19]
	v_mfma_f32_16x16x32_bf16 v[60:63], v[166:169], v[192:195], v[60:63]
	v_mfma_f32_16x16x32_bf16 v[56:59], v[174:177], v[192:195], v[56:59]
	v_mfma_f32_16x16x32_bf16 v[52:55], v[166:169], v[200:203], v[52:55]
	v_mfma_f32_16x16x32_bf16 v[48:51], v[174:177], v[200:203], v[48:51]
	v_mfma_f32_16x16x32_bf16 v[36:39], v[166:169], v[208:211], v[36:39]
	v_mfma_f32_16x16x32_bf16 v[32:35], v[174:177], v[208:211], v[32:35]
	v_mfma_f32_16x16x32_bf16 v[20:23], v[166:169], v[216:219], v[20:23]
	v_mfma_f32_16x16x32_bf16 v[16:19], v[174:177], v[216:219], v[16:19]
	s_barrier
	s_add_u32 s14, s56, 0x20000
	s_addc_u32 s15, s57, 0
	s_add_i32 s16, s17, s53
	s_mov_b32 m0, s16
	s_nop 0
	global_load_lds_dwordx4 v128, s[14:15]
	s_add_i32 m0, s16, 0x2000
	s_nop 0
	global_load_lds_dwordx4 v152, s[14:15]
	s_add_i32 s97, s97, 2
	s_add_u32 s36, s36, 0x100
	s_addc_u32 s37, s37, 0
	s_add_u32 s89, s89, 0x100
	s_addc_u32 s96, s96, 0
	s_waitcnt vmcnt(6)
	s_barrier
; #define PG8_STAGE(bufoff, gbase, voff) do { _Pragma("unroll") for (int _i = 0; _i < 2; ++_i) \
;         __builtin_amdgcn_global_load_lds((const unsigned*)((const char*)(gbase) + (voff)[_i]), (PG8_LAS unsigned*)(lds + (bufoff) + ldsw + _i * 8192), 16, 0, 0); } while (0)
; #define PG8_LDA(dst, b, h) do { _Pragma("unroll") for (int m = 0; m < 4; ++m) _Pragma("unroll") for (int k = 0; k < 2; ++k) dst[m][k] = *(const PG8_LAS bf16x8*)(lds + PG8_SA(b, h) + aoff + m * 2048 + k * 1024); } while (0)
; #define PG8_LDB(dst, b, h) do { _Pragma("unroll") for (int n = 0; n < 2; ++n) _Pragma("unroll") for (int k = 0; k < 2; ++k) dst[n][k] = *(const PG8_LAS bf16x8*)(lds + PG8_SB(b, h) + boff + n * 2048 + k * 1024); } while (0)
; #define PG8_MMA(ai, bj, At, Bt) do { __builtin_amdgcn_s_setprio(1); _Pragma("unroll") for (int m = 0; m < 4; ++m) _Pragma("unroll") for (int n = 0; n < 2; ++n) _Pragma("unroll") for (int k = 0; k < 2; ++k) \
;         acc[ai][bj][m][n] = __builtin_amdgcn_mfma_f32_16x16x32_bf16(Bt[n][k], At[m][k], acc[ai][bj][m][n], 0, 0, 0); __builtin_amdgcn_s_setprio(0); } while (0)
; #define PG8_WAIT_V(n) asm volatile("s_waitcnt vmcnt(" #n ")" ::: "memory")
; #define PG8_WAIT_L(n) asm volatile("s_waitcnt lgkmcnt(" #n ")" ::: "memory")
; #define PG8_BAR __builtin_amdgcn_s_barrier()
; #define PG8_SCHED __builtin_amdgcn_sched_barrier(0)
; template <class Epi, class Sched, bool STAMP = false>
; __device__ __forceinline__ void gemm_phase(PG8_LAS unsigned char* lds, const Gemm g, const Sched& S, const Epi& E, unsigned long long* stamps) {
;     ...
;             PG8_WAIT_V(6); PG8_BAR; PG8_MMA(1, 1, At, B1); PG8_BAR;
;             PG8_LDB(B0, 1, 0); PG8_SCHED; PG8_LDA(At, 1, 0); PG8_STAGE(PG8_SA(0, 1), a2 + hstep, voffA);
;             PG8_WAIT_L(8); PG8_BAR; PG8_WAIT_L(0); PG8_MMA(0, 0, At, B0); PG8_BAR; PG8_SCHED;
;             PG8_LDB(B1, 1, 1); PG8_STAGE(PG8_SB(1, 0), b3, voffB);
;             PG8_BAR; PG8_WAIT_L(0); PG8_MMA(0, 1, At, B1); PG8_BAR;
;             PG8_LDA(At, 1, 1); PG8_STAGE(PG8_SA(1, 0), a3, voffA);
;             PG8_BAR; PG8_WAIT_L(0); PG8_MMA(1, 0, At, B0); PG8_BAR; PG8_SCHED;
	v_mfma_f32_16x16x32_bf16 v[44:47], v[220:223], v[178:181], v[44:47]
	v_mfma_f32_16x16x32_bf16 v[40:43], v[228:231], v[178:181], v[40:43]
	v_mfma_f32_16x16x32_bf16 v[28:31], v[220:223], v[196:199], v[28:31]
	v_mfma_f32_16x16x32_bf16 v[24:27], v[228:231], v[196:199], v[24:27]
	v_mfma_f32_16x16x32_bf16 v[12:15], v[220:223], v[204:207], v[12:15]
	v_mfma_f32_16x16x32_bf16 v[8:11], v[228:231], v[204:207], v[8:11]
	v_mfma_f32_16x16x32_bf16 v[4:7], v[220:223], v[212:215], v[4:7]
	v_mfma_f32_16x16x32_bf16 v[0:3], v[228:231], v[212:215], v[0:3]
	v_mfma_f32_16x16x32_bf16 v[44:47], v[224:227], v[192:195], v[44:47]
	v_mfma_f32_16x16x32_bf16 v[40:43], v[232:235], v[192:195], v[40:43]
	v_mfma_f32_16x16x32_bf16 v[28:31], v[224:227], v[200:203], v[28:31]
	v_mfma_f32_16x16x32_bf16 v[24:27], v[232:235], v[200:203], v[24:27]
	v_mfma_f32_16x16x32_bf16 v[12:15], v[224:227], v[208:211], v[12:15]
	v_mfma_f32_16x16x32_bf16 v[8:11], v[232:235], v[208:211], v[8:11]
	v_mfma_f32_16x16x32_bf16 v[4:7], v[224:227], v[216:219], v[4:7]
	v_mfma_f32_16x16x32_bf16 v[0:3], v[232:235], v[216:219], v[0:3]
	s_barrier
	s_add_i32 s16, 0, 0x18000
	ds_read_b128 v[162:165], v250
	ds_read_b128 v[166:169], v250 offset:1024
	ds_read_b128 v[170:173], v250 offset:2048
	ds_read_b128 v[174:177], v250 offset:3072
	s_add_u32 s14, s58, 0x20000
	s_addc_u32 s15, s59, 0
	s_mov_b32 m0, s61
	ds_read_b128 v[178:181], v160 offset:32768
	ds_read_b128 v[192:195], v160 offset:33792
	ds_read_b128 v[196:199], v160 offset:34816
	ds_read_b128 v[200:203], v160 offset:35840
	ds_read_b128 v[204:207], v160 offset:36864
	ds_read_b128 v[208:211], v160 offset:37888
	ds_read_b128 v[212:215], v160 offset:38912
	global_load_lds_dwordx4 v148, s[14:15]
	s_mov_b32 m0, s62
	ds_read_b128 v[216:219], v160 offset:39936
	global_load_lds_dwordx4 v150, s[14:15]
	s_waitcnt lgkmcnt(8)
	s_barrier
	s_waitcnt lgkmcnt(0)
	v_mfma_f32_16x16x32_bf16 v[124:127], v[162:165], v[178:181], v[124:127]
	v_mfma_f32_16x16x32_bf16 v[120:123], v[170:173], v[178:181], v[120:123]
	v_mfma_f32_16x16x32_bf16 v[116:119], v[162:165], v[196:199], v[116:119]
	v_mfma_f32_16x16x32_bf16 v[112:115], v[170:173], v[196:199], v[112:115]
	v_mfma_f32_16x16x32_bf16 v[100:103], v[162:165], v[204:207], v[100:103]
	v_mfma_f32_16x16x32_bf16 v[96:99], v[170:173], v[204:207], v[96:99]
	v_mfma_f32_16x16x32_bf16 v[84:87], v[162:165], v[212:215], v[84:87]
	v_mfma_f32_16x16x32_bf16 v[80:83], v[170:173], v[212:215], v[80:83]
	v_mfma_f32_16x16x32_bf16 v[124:127], v[166:169], v[192:195], v[124:127]
	v_mfma_f32_16x16x32_bf16 v[120:123], v[174:177], v[192:195], v[120:123]
	v_mfma_f32_16x16x32_bf16 v[116:119], v[166:169], v[200:203], v[116:119]
	v_mfma_f32_16x16x32_bf16 v[112:115], v[174:177], v[200:203], v[112:115]
	v_mfma_f32_16x16x32_bf16 v[100:103], v[166:169], v[208:211], v[100:103]
	v_mfma_f32_16x16x32_bf16 v[96:99], v[174:177], v[208:211], v[96:99]
	v_mfma_f32_16x16x32_bf16 v[84:87], v[166:169], v[216:219], v[84:87]
	v_mfma_f32_16x16x32_bf16 v[80:83], v[174:177], v[216:219], v[80:83]
	s_barrier
	s_add_i32 s17, 0, 0x1c000
	s_add_i32 s14, s16, s53
	s_mov_b32 m0, s14
	ds_read_b128 v[220:223], v251
	ds_read_b128 v[224:227], v251 offset:1024
	ds_read_b128 v[228:231], v251 offset:2048
	global_load_lds_dwordx4 v244, s[56:57]
	s_add_i32 m0, s14, 0x2000
	ds_read_b128 v[232:235], v251 offset:3072
	global_load_lds_dwordx4 v245, s[56:57]
	s_barrier
	s_waitcnt lgkmcnt(0)
	v_mfma_f32_16x16x32_bf16 v[108:111], v[220:223], v[178:181], v[108:111]
	v_mfma_f32_16x16x32_bf16 v[104:107], v[228:231], v[178:181], v[104:107]
	v_mfma_f32_16x16x32_bf16 v[92:95], v[220:223], v[196:199], v[92:95]
	v_mfma_f32_16x16x32_bf16 v[88:91], v[228:231], v[196:199], v[88:91]
	v_mfma_f32_16x16x32_bf16 v[76:79], v[220:223], v[204:207], v[76:79]
	v_mfma_f32_16x16x32_bf16 v[72:75], v[228:231], v[204:207], v[72:75]
	v_mfma_f32_16x16x32_bf16 v[68:71], v[220:223], v[212:215], v[68:71]
	v_mfma_f32_16x16x32_bf16 v[64:67], v[228:231], v[212:215], v[64:67]
	v_mfma_f32_16x16x32_bf16 v[108:111], v[224:227], v[192:195], v[108:111]
	v_mfma_f32_16x16x32_bf16 v[104:107], v[232:235], v[192:195], v[104:107]
	v_mfma_f32_16x16x32_bf16 v[92:95], v[224:227], v[200:203], v[92:95]
	v_mfma_f32_16x16x32_bf16 v[88:91], v[232:235], v[200:203], v[88:91]
	v_mfma_f32_16x16x32_bf16 v[76:79], v[224:227], v[208:211], v[76:79]
	v_mfma_f32_16x16x32_bf16 v[72:75], v[232:235], v[208:211], v[72:75]
	v_mfma_f32_16x16x32_bf16 v[68:71], v[224:227], v[216:219], v[68:71]
	v_mfma_f32_16x16x32_bf16 v[64:67], v[232:235], v[216:219], v[64:67]
	s_barrier
	s_mov_b32 m0, s63
	ds_read_b128 v[178:181], v160 offset:49152
	ds_read_b128 v[192:195], v160 offset:50176
	ds_read_b128 v[196:199], v160 offset:51200
	ds_read_b128 v[200:203], v160 offset:52224
	ds_read_b128 v[204:207], v160 offset:53248
	ds_read_b128 v[208:211], v160 offset:54272
	ds_read_b128 v[212:215], v160 offset:55296
	global_load_lds_dwordx4 v246, s[58:59]
	s_mov_b32 m0, s64
	ds_read_b128 v[216:219], v160 offset:56320
	global_load_lds_dwordx4 v247, s[58:59]
	s_barrier
	s_waitcnt lgkmcnt(0)
	v_mfma_f32_16x16x32_bf16 v[60:63], v[162:165], v[178:181], v[60:63]
	v_mfma_f32_16x16x32_bf16 v[56:59], v[170:173], v[178:181], v[56:59]
	v_mfma_f32_16x16x32_bf16 v[52:55], v[162:165], v[196:199], v[52:55]
	v_mfma_f32_16x16x32_bf16 v[48:51], v[170:173], v[196:199], v[48:51]
	v_mfma_f32_16x16x32_bf16 v[36:39], v[162:165], v[204:207], v[36:39]
	v_mfma_f32_16x16x32_bf16 v[32:35], v[170:173], v[204:207], v[32:35]
	v_mfma_f32_16x16x32_bf16 v[20:23], v[162:165], v[212:215], v[20:23]
	v_mfma_f32_16x16x32_bf16 v[16:19], v[170:173], v[212:215], v[16:19]
	v_mfma_f32_16x16x32_bf16 v[60:63], v[166:169], v[192:195], v[60:63]
	v_mfma_f32_16x16x32_bf16 v[56:59], v[174:177], v[192:195], v[56:59]
	v_mfma_f32_16x16x32_bf16 v[52:55], v[166:169], v[200:203], v[52:55]
	v_mfma_f32_16x16x32_bf16 v[48:51], v[174:177], v[200:203], v[48:51]
	v_mfma_f32_16x16x32_bf16 v[36:39], v[166:169], v[208:211], v[36:39]
	v_mfma_f32_16x16x32_bf16 v[32:35], v[174:177], v[208:211], v[32:35]
	v_mfma_f32_16x16x32_bf16 v[20:23], v[166:169], v[216:219], v[20:23]
	v_mfma_f32_16x16x32_bf16 v[16:19], v[174:177], v[216:219], v[16:19]
	s_barrier
; __device__ __forceinline__ unsigned cvt_pk_bf16(float lo, float hi) { const f32x2_cv v = {lo, hi}; const bf16x2_cv b = __builtin_convertvector(v, bf16x2_cv); return __builtin_bit_cast(unsigned, b); }
; #define PG8_STAGE(bufoff, gbase, voff) do { _Pragma("unroll") for (int _i = 0; _i < 2; ++_i) \
;         __builtin_amdgcn_global_load_lds((const unsigned*)((const char*)(gbase) + (voff)[_i]), (PG8_LAS unsigned*)(lds + (bufoff) + ldsw + _i * 8192), 16, 0, 0); } while (0)
; #define PG8_WAIT_V(n) asm volatile("s_waitcnt vmcnt(" #n ")" ::: "memory")
; #define PG8_BAR __builtin_amdgcn_s_barrier()
; __device__ __forceinline__ float rstd_of(const float* rowss, int row) { return rsqrtf(rowss[row] * (1.0f / 1024.0f) + 1e-6f); }
; template <class Epi, class Sched, bool STAMP = false>
; __device__ __forceinline__ void gemm_phase(PG8_LAS unsigned char* lds, const Gemm g, const Sched& S, const Epi& E, unsigned long long* stamps) {
;     ...
;             PG8_STAGE(PG8_SB(1, 1), b3 + hstep, voffB);
;             PG8_WAIT_V(6); PG8_BAR; PG8_MMA(1, 1, At, B1); PG8_BAR;
;         }
;         if constexpr (!Epi::AFTER_DRAIN) { E(acc, cur, wr, wc, fr, fq); S.done(cur); }
;         if (!has_next) break;
;     __device__ __forceinline__ void operator()(const f32x4 (&acc)[2][2][4][2], const pg8::Unit& u, int wr, int wc, int fr, int fq) const {
;         const int row0 = u.pm * 256 + wr * 64 + fr, col0 = u.pn * 256 + wc * 32 + 8 * fq;
; #pragma unroll
;         for (int ai = 0; ai < 2; ++ai)
; #pragma unroll
;             for (int m = 0; m < 4; ++m) {
;                 const int row = row0 + ai * 128 + m * 16;
;                 const float s = (MODE == 2) ? 1.0f : rstd_of(rowss, row);
;                 bf16_t* rowp = O + (size_t)row * ldc + col0;
; #pragma unroll
;                 for (int bj = 0; bj < 2; ++bj) {
;                     f32x4 v0 = acc[ai][bj][m][0] * s, v1 = acc[ai][bj][m][1] * s;
;                     if (MODE == 1) {
; #pragma unroll
;                         for (int j = 0; j < 4; ++j) { const float a = fmaxf(v0[j], 0.f), b = fmaxf(v1[j], 0.f); v0[j] = a * a; v1[j] = b * b; } }
;                     u32x4 w; w.x = cvt_pk_bf16(v0[0], v0[1]); w.y = cvt_pk_bf16(v0[2], v0[3]); w.z = cvt_pk_bf16(v1[0], v1[1]); w.w = cvt_pk_bf16(v1[2], v1[3]);
;                     *(u32x4*)(rowp + bj * 128) = w; } }
	s_add_u32 s14, s56, 0x20080
	s_addc_u32 s15, s57, 0
	s_add_i32 s16, s17, s53
	s_mov_b32 m0, s16
	s_nop 0
	global_load_lds_dwordx4 v128, s[14:15]
	s_add_i32 m0, s16, 0x2000
	s_nop 0
	global_load_lds_dwordx4 v152, s[14:15]
	s_waitcnt vmcnt(6)
	s_barrier
	s_cmp_gt_u32 s97, 5
	v_mfma_f32_16x16x32_bf16 v[44:47], v[220:223], v[178:181], v[44:47]
	v_mfma_f32_16x16x32_bf16 v[40:43], v[228:231], v[178:181], v[40:43]
	v_mfma_f32_16x16x32_bf16 v[28:31], v[220:223], v[196:199], v[28:31]
	v_mfma_f32_16x16x32_bf16 v[24:27], v[228:231], v[196:199], v[24:27]
	v_mfma_f32_16x16x32_bf16 v[12:15], v[220:223], v[204:207], v[12:15]
	v_mfma_f32_16x16x32_bf16 v[8:11], v[228:231], v[204:207], v[8:11]
	v_mfma_f32_16x16x32_bf16 v[4:7], v[220:223], v[212:215], v[4:7]
	v_mfma_f32_16x16x32_bf16 v[0:3], v[228:231], v[212:215], v[0:3]
	v_mfma_f32_16x16x32_bf16 v[44:47], v[224:227], v[192:195], v[44:47]
	v_mfma_f32_16x16x32_bf16 v[40:43], v[232:235], v[192:195], v[40:43]
	v_mfma_f32_16x16x32_bf16 v[28:31], v[224:227], v[200:203], v[28:31]
	v_mfma_f32_16x16x32_bf16 v[24:27], v[232:235], v[200:203], v[24:27]
	v_mfma_f32_16x16x32_bf16 v[12:15], v[224:227], v[208:211], v[12:15]
	v_mfma_f32_16x16x32_bf16 v[8:11], v[232:235], v[208:211], v[8:11]
	v_mfma_f32_16x16x32_bf16 v[4:7], v[224:227], v[216:219], v[4:7]
	v_mfma_f32_16x16x32_bf16 v[0:3], v[232:235], v[216:219], v[0:3]
	s_barrier
	s_cbranch_scc0 .LBB0_333
	v_lshl_add_u32 v162, s2, 8, v139
	v_lshl_or_b32 v164, s76, 8, v159
	v_ashrrev_i32_e32 v163, 31, v162
	v_ashrrev_i32_e32 v165, 31, v164
	v_lshlrev_b64 v[166:167], 11, v[162:163]
	v_lshl_add_u64 v[166:167], s[30:31], 0, v[166:167]
	v_lshlrev_b64 v[164:165], 1, v[164:165]
	v_lshl_add_u64 v[166:167], v[166:167], 0, v[164:165]
	s_mov_b32 s2, 0x40000
	s_mov_b64 s[14:15], 0x40000
	v_cvt_pk_bf16_f32 v60, v60, v61
	v_cvt_pk_bf16_f32 v61, v62, v63
	v_cvt_pk_bf16_f32 v62, v56, v57
	v_add_co_u32_e32 v56, vcc, s2, v166
	v_cvt_pk_bf16_f32 v68, v68, v69
	v_cvt_pk_bf16_f32 v69, v70, v71
	v_cvt_pk_bf16_f32 v70, v64, v65
	v_lshl_add_u64 v[64:65], v[166:167], 0, s[14:15]
	v_addc_co_u32_e32 v57, vcc, 0, v167, vcc
	v_cvt_pk_bf16_f32 v44, v44, v45
	v_cvt_pk_bf16_f32 v45, v46, v47
	v_cvt_pk_bf16_f32 v46, v40, v41
	v_cvt_pk_bf16_f32 v47, v42, v43
	s_mov_b32 s2, 0x48000
	v_cvt_pk_bf16_f32 v108, v108, v109
	v_cvt_pk_bf16_f32 v109, v110, v111
	v_cvt_pk_bf16_f32 v110, v104, v105
	v_or_b32_e32 v104, 16, v162
	global_store_dwordx4 v[64:65], v[44:47], off offset:256
	s_mov_b64 s[14:15], 0x48000
	v_ashrrev_i32_e32 v105, 31, v104
	v_add_co_u32_e32 v46, vcc, s2, v166
	v_cvt_pk_bf16_f32 v92, v92, v93
	v_cvt_pk_bf16_f32 v93, v94, v95
	v_cvt_pk_bf16_f32 v94, v88, v89
	v_or_b32_e32 v88, 32, v162
	v_lshl_add_u64 v[44:45], v[166:167], 0, s[14:15]
	v_addc_co_u32_e32 v47, vcc, 0, v167, vcc
	v_cvt_pk_bf16_f32 v28, v28, v29
	v_cvt_pk_bf16_f32 v29, v30, v31
	v_cvt_pk_bf16_f32 v30, v24, v25
	v_cvt_pk_bf16_f32 v31, v26, v27
	s_mov_b32 s2, 0x50000
	v_lshlrev_b64 v[104:105], 11, v[104:105]
	v_ashrrev_i32_e32 v89, 31, v88
	v_cvt_pk_bf16_f32 v76, v76, v77
	v_cvt_pk_bf16_f32 v77, v78, v79
	v_cvt_pk_bf16_f32 v78, v72, v73
	v_or_b32_e32 v72, 48, v162
	global_store_dwordx4 v[44:45], v[28:31], off offset:256
	s_mov_b64 s[14:15], 0x50000
	v_cvt_pk_bf16_f32 v111, v106, v107
	v_add_co_u32_e32 v30, vcc, s2, v166
	v_lshl_add_u64 v[104:105], s[30:31], 0, v[104:105]
	v_lshlrev_b64 v[88:89], 11, v[88:89]
	v_ashrrev_i32_e32 v73, 31, v72
	v_lshl_add_u64 v[28:29], v[166:167], 0, s[14:15]
	v_addc_co_u32_e32 v31, vcc, 0, v167, vcc
	v_cvt_pk_bf16_f32 v12, v12, v13
	v_cvt_pk_bf16_f32 v13, v14, v15
	v_cvt_pk_bf16_f32 v14, v8, v9
	v_cvt_pk_bf16_f32 v15, v10, v11
	s_mov_b32 s2, 0x58000
	global_store_dwordx4 v[166:167], v[108:111], off offset:256
	v_cvt_pk_bf16_f32 v95, v90, v91
	v_lshl_add_u64 v[88:89], s[30:31], 0, v[88:89]
	v_lshl_add_u64 v[108:109], v[104:105], 0, v[164:165]
	v_lshlrev_b64 v[72:73], 11, v[72:73]
	global_store_dwordx4 v[28:29], v[12:15], off offset:256
	global_store_dwordx4 v[108:109], v[92:95], off offset:256
	v_cvt_pk_bf16_f32 v79, v74, v75
	v_add_co_u32_e32 v14, vcc, s2, v166
	v_lshl_add_u64 v[92:93], v[88:89], 0, v[164:165]
	v_lshl_add_u64 v[72:73], s[30:31], 0, v[72:73]
	s_mov_b64 s[14:15], 0x58000
	v_addc_co_u32_e32 v15, vcc, 0, v167, vcc
	v_readlane_b32 s88, v242, 39
	v_cvt_pk_bf16_f32 v124, v124, v125
	v_cvt_pk_bf16_f32 v125, v126, v127
	v_cvt_pk_bf16_f32 v126, v120, v121
	v_cvt_pk_bf16_f32 v127, v122, v123
	v_cvt_pk_bf16_f32 v104, v116, v117
	v_cvt_pk_bf16_f32 v105, v118, v119
	v_cvt_pk_bf16_f32 v106, v112, v113
	v_cvt_pk_bf16_f32 v107, v114, v115
	v_cvt_pk_bf16_f32 v88, v100, v101
	v_cvt_pk_bf16_f32 v89, v102, v103
	v_cvt_pk_bf16_f32 v90, v96, v97
	v_cvt_pk_bf16_f32 v91, v98, v99
	global_store_dwordx4 v[92:93], v[76:79], off offset:256
	v_cvt_pk_bf16_f32 v74, v80, v81
	v_cvt_pk_bf16_f32 v75, v82, v83
	v_lshl_add_u64 v[76:77], v[72:73], 0, v[164:165]
	v_cvt_pk_bf16_f32 v72, v84, v85
	v_cvt_pk_bf16_f32 v73, v86, v87
	v_cvt_pk_bf16_f32 v71, v66, v67
	v_cvt_pk_bf16_f32 v63, v58, v59
	v_cvt_pk_bf16_f32 v40, v52, v53
	v_cvt_pk_bf16_f32 v41, v54, v55
	v_cvt_pk_bf16_f32 v42, v48, v49
	v_cvt_pk_bf16_f32 v43, v50, v51
	v_cvt_pk_bf16_f32 v24, v36, v37
	v_cvt_pk_bf16_f32 v25, v38, v39
	v_cvt_pk_bf16_f32 v26, v32, v33
	v_cvt_pk_bf16_f32 v27, v34, v35
	v_lshl_add_u64 v[12:13], v[166:167], 0, s[14:15]
	v_cvt_pk_bf16_f32 v8, v20, v21
	v_cvt_pk_bf16_f32 v9, v22, v23
	v_cvt_pk_bf16_f32 v10, v16, v17
	v_cvt_pk_bf16_f32 v11, v18, v19
	v_cvt_pk_bf16_f32 v4, v4, v5
	v_cvt_pk_bf16_f32 v5, v6, v7
	v_cvt_pk_bf16_f32 v6, v0, v1
	v_cvt_pk_bf16_f32 v7, v2, v3
	s_and_b64 vcc, exec, s[38:39]
	s_mov_b32 s76, s4
	s_mov_b32 s2, s12
	s_mov_b64 s[56:57], s[26:27]
	s_mov_b64 s[36:37], s[24:25]
	s_movk_i32 s77, 0xa0
	s_movk_i32 s58, 0xff60
	v_readlane_b32 s89, v242, 40
	global_store_dwordx4 v[166:167], v[124:127], off
	global_store_dwordx4 v[108:109], v[104:107], off
	global_store_dwordx4 v[92:93], v[88:91], off
	global_store_dwordx4 v[76:77], v[72:75], off
	global_store_dwordx4 v[76:77], v[68:71], off offset:256
	global_store_dwordx4 v[56:57], v[60:63], off
	global_store_dwordx4 v[46:47], v[40:43], off
	global_store_dwordx4 v[30:31], v[24:27], off
	global_store_dwordx4 v[14:15], v[8:11], off
	global_store_dwordx4 v[12:13], v[4:7], off offset:256
	s_cbranch_vccz .LBB0_326
	s_cmpk_gt_u32 s46, 0xff
	s_cbranch_scc1 .LBB0_337
	s_barrier

; #define PG8_STAGE(bufoff, gbase, voff) do { _Pragma("unroll") for (int _i = 0; _i < 2; ++_i) \
;         __builtin_amdgcn_global_load_lds((const unsigned*)((const char*)(gbase) + (voff)[_i]), (PG8_LAS unsigned*)(lds + (bufoff) + ldsw + _i * 8192), 16, 0, 0); } while (0)
; #define PG8_LDA(dst, b, h) do { _Pragma("unroll") for (int m = 0; m < 4; ++m) _Pragma("unroll") for (int k = 0; k < 2; ++k) dst[m][k] = *(const PG8_LAS bf16x8*)(lds + PG8_SA(b, h) + aoff + m * 2048 + k * 1024); } while (0)
; #define PG8_LDB(dst, b, h) do { _Pragma("unroll") for (int n = 0; n < 2; ++n) _Pragma("unroll") for (int k = 0; k < 2; ++k) dst[n][k] = *(const PG8_LAS bf16x8*)(lds + PG8_SB(b, h) + boff + n * 2048 + k * 1024); } while (0)
; #define PG8_MMA(ai, bj, At, Bt) do { __builtin_amdgcn_s_setprio(1); _Pragma("unroll") for (int m = 0; m < 4; ++m) _Pragma("unroll") for (int n = 0; n < 2; ++n) _Pragma("unroll") for (int k = 0; k < 2; ++k) \
;         acc[ai][bj][m][n] = __builtin_amdgcn_mfma_f32_16x16x32_bf16(Bt[n][k], At[m][k], acc[ai][bj][m][n], 0, 0, 0); __builtin_amdgcn_s_setprio(0); } while (0)
; #define PG8_BAR __builtin_amdgcn_s_barrier()
; template <class Epi, class Sched, bool STAMP = false>
; __device__ __forceinline__ void gemm_phase(PG8_LAS unsigned char* lds, const Gemm g, const Sched& S, const Epi& E, unsigned long long* stamps) {
;     ...
;         for (int t = 0; t < nt; t += 2) {
;             const bool last = (t == nt - 2);
;             const char* a1 = cA + (size_t)(t + 1) * kstep;
;             const char* a2 = last ? nA : cA + (size_t)(t + 2) * kstep; const char* b2 = last ? nB : cB + (size_t)(t + 2) * kstep;
;             const char* a3 = a2 + kstep; const char* b3 = b2 + kstep;
;             if (last && has_next) S.a_ready(nxt);
;             PG8_LDB(B0, 0, 0); PG8_SCHED; PG8_LDA(At, 0, 0); PG8_STAGE(PG8_SA(1, 1), a1 + hstep, voffA);
;             PG8_WAIT_L(8); PG8_BAR; PG8_WAIT_L(0); PG8_MMA(0, 0, At, B0); PG8_BAR; PG8_SCHED;
;             PG8_LDB(B1, 0, 1); PG8_STAGE(PG8_SB(0, 0), b2, voffB);
;             PG8_BAR; PG8_WAIT_L(0); PG8_MMA(0, 1, At, B1); PG8_BAR;
;             PG8_LDA(At, 0, 1); PG8_STAGE(PG8_SA(0, 0), a2, voffA);
;             PG8_BAR; PG8_WAIT_L(0); PG8_MMA(1, 0, At, B0); PG8_BAR; PG8_SCHED;
;             PG8_STAGE(PG8_SB(0, 1), b2 + hstep, voffB);
;             PG8_WAIT_V(6); PG8_BAR; PG8_MMA(1, 1, At, B1); PG8_BAR;
.LBB0_353:
	s_add_u32 s14, s56, 0xfffc0080
	s_addc_u32 s15, s57, -1
	s_add_i32 s16, 0, 0x10000
	ds_read_b128 v[158:161], v248
	ds_read_b128 v[162:165], v248 offset:1024
	ds_read_b128 v[172:175], v248 offset:2048
	ds_read_b128 v[176:179], v248 offset:3072
	s_cmp_eq_u32 vcc_lo, 12
	s_cselect_b32 s61, s13, s15
	s_cselect_b32 s60, s47, s14
	s_cselect_b32 s59, s27, s77
	s_cselect_b32 s58, s53, s76
	s_add_i32 m0, s89, 0xc000
	ds_read_b128 v[180:183], v171
	ds_read_b128 v[192:195], v171 offset:1024
	ds_read_b128 v[196:199], v171 offset:2048
	ds_read_b128 v[200:203], v171 offset:3072
	ds_read_b128 v[204:207], v171 offset:4096
	ds_read_b128 v[208:211], v171 offset:5120
	ds_read_b128 v[212:215], v171 offset:6144
	global_load_lds_dwordx4 v154, s[56:57]
	s_add_i32 m0, s89, 0xe000
	ds_read_b128 v[216:219], v171 offset:7168
	global_load_lds_dwordx4 v156, s[56:57]
	s_waitcnt lgkmcnt(8)
	s_barrier
	s_waitcnt lgkmcnt(0)
	v_mfma_f32_16x16x32_bf16 v[124:127], v[158:161], v[180:183], v[124:127]
	v_mfma_f32_16x16x32_bf16 v[120:123], v[172:175], v[180:183], v[120:123]
	v_mfma_f32_16x16x32_bf16 v[108:111], v[158:161], v[196:199], v[108:111]
	v_mfma_f32_16x16x32_bf16 v[104:107], v[172:175], v[196:199], v[104:107]
	v_mfma_f32_16x16x32_bf16 v[92:95], v[158:161], v[204:207], v[92:95]
	v_mfma_f32_16x16x32_bf16 v[88:91], v[172:175], v[204:207], v[88:91]
	v_mfma_f32_16x16x32_bf16 v[76:79], v[158:161], v[212:215], v[76:79]
	v_mfma_f32_16x16x32_bf16 v[72:75], v[172:175], v[212:215], v[72:75]
	v_mfma_f32_16x16x32_bf16 v[124:127], v[162:165], v[192:195], v[124:127]
	v_mfma_f32_16x16x32_bf16 v[120:123], v[176:179], v[192:195], v[120:123]
	v_mfma_f32_16x16x32_bf16 v[108:111], v[162:165], v[200:203], v[108:111]
	v_mfma_f32_16x16x32_bf16 v[104:107], v[176:179], v[200:203], v[104:107]
	v_mfma_f32_16x16x32_bf16 v[92:95], v[162:165], v[208:211], v[92:95]
	v_mfma_f32_16x16x32_bf16 v[88:91], v[176:179], v[208:211], v[88:91]
	v_mfma_f32_16x16x32_bf16 v[76:79], v[162:165], v[216:219], v[76:79]
	v_mfma_f32_16x16x32_bf16 v[72:75], v[176:179], v[216:219], v[72:75]
	s_barrier
	s_add_i32 s17, 0, 0x14000
	s_add_i32 s14, s16, s88
	s_mov_b32 m0, s14
	ds_read_b128 v[220:223], v249
	ds_read_b128 v[224:227], v249 offset:1024
	ds_read_b128 v[228:231], v249 offset:2048
	global_load_lds_dwordx4 v128, s[58:59]
	s_add_i32 m0, s14, 0x2000
	ds_read_b128 v[232:235], v249 offset:3072
	global_load_lds_dwordx4 v152, s[58:59]
	s_barrier
	s_waitcnt lgkmcnt(0)
	v_mfma_f32_16x16x32_bf16 v[116:119], v[220:223], v[180:183], v[116:119]
	v_mfma_f32_16x16x32_bf16 v[112:115], v[228:231], v[180:183], v[112:115]
	v_mfma_f32_16x16x32_bf16 v[100:103], v[220:223], v[196:199], v[100:103]
	v_mfma_f32_16x16x32_bf16 v[96:99], v[228:231], v[196:199], v[96:99]
	v_mfma_f32_16x16x32_bf16 v[84:87], v[220:223], v[204:207], v[84:87]
	v_mfma_f32_16x16x32_bf16 v[80:83], v[228:231], v[204:207], v[80:83]
	v_mfma_f32_16x16x32_bf16 v[68:71], v[220:223], v[212:215], v[68:71]
	v_mfma_f32_16x16x32_bf16 v[64:67], v[228:231], v[212:215], v[64:67]
	v_mfma_f32_16x16x32_bf16 v[116:119], v[224:227], v[192:195], v[116:119]
	v_mfma_f32_16x16x32_bf16 v[112:115], v[232:235], v[192:195], v[112:115]
	v_mfma_f32_16x16x32_bf16 v[100:103], v[224:227], v[200:203], v[100:103]
	v_mfma_f32_16x16x32_bf16 v[96:99], v[232:235], v[200:203], v[96:99]
	v_mfma_f32_16x16x32_bf16 v[84:87], v[224:227], v[208:211], v[84:87]
	v_mfma_f32_16x16x32_bf16 v[80:83], v[232:235], v[208:211], v[80:83]
	v_mfma_f32_16x16x32_bf16 v[68:71], v[224:227], v[216:219], v[68:71]
	v_mfma_f32_16x16x32_bf16 v[64:67], v[232:235], v[216:219], v[64:67]
	s_barrier
	s_mov_b32 m0, s89
	ds_read_b128 v[180:183], v171 offset:16384
	ds_read_b128 v[192:195], v171 offset:17408
	ds_read_b128 v[196:199], v171 offset:18432
	ds_read_b128 v[200:203], v171 offset:19456
	ds_read_b128 v[204:207], v171 offset:20480
	ds_read_b128 v[208:211], v171 offset:21504
	ds_read_b128 v[212:215], v171 offset:22528
	global_load_lds_dwordx4 v148, s[60:61]
	s_mov_b32 m0, s96
	ds_read_b128 v[216:219], v171 offset:23552
	global_load_lds_dwordx4 v150, s[60:61]
	s_barrier
	s_waitcnt lgkmcnt(0)
	v_mfma_f32_16x16x32_bf16 v[60:63], v[158:161], v[180:183], v[60:63]
	v_mfma_f32_16x16x32_bf16 v[56:59], v[172:175], v[180:183], v[56:59]
	v_mfma_f32_16x16x32_bf16 v[44:47], v[158:161], v[196:199], v[44:47]
	v_mfma_f32_16x16x32_bf16 v[40:43], v[172:175], v[196:199], v[40:43]
	v_mfma_f32_16x16x32_bf16 v[28:31], v[158:161], v[204:207], v[28:31]
	v_mfma_f32_16x16x32_bf16 v[24:27], v[172:175], v[204:207], v[24:27]
	v_mfma_f32_16x16x32_bf16 v[12:15], v[158:161], v[212:215], v[12:15]
	v_mfma_f32_16x16x32_bf16 v[8:11], v[172:175], v[212:215], v[8:11]
	v_mfma_f32_16x16x32_bf16 v[60:63], v[162:165], v[192:195], v[60:63]
	v_mfma_f32_16x16x32_bf16 v[56:59], v[176:179], v[192:195], v[56:59]
	v_mfma_f32_16x16x32_bf16 v[44:47], v[162:165], v[200:203], v[44:47]
	v_mfma_f32_16x16x32_bf16 v[40:43], v[176:179], v[200:203], v[40:43]
	v_mfma_f32_16x16x32_bf16 v[28:31], v[162:165], v[208:211], v[28:31]
	v_mfma_f32_16x16x32_bf16 v[24:27], v[176:179], v[208:211], v[24:27]
	v_mfma_f32_16x16x32_bf16 v[12:15], v[162:165], v[216:219], v[12:15]
	v_mfma_f32_16x16x32_bf16 v[8:11], v[176:179], v[216:219], v[8:11]
	s_barrier
	s_add_u32 s14, s58, 0x40000
	s_addc_u32 s15, s59, 0
	s_add_i32 s16, s17, s88
	s_mov_b32 m0, s16
	s_nop 0
	global_load_lds_dwordx4 v128, s[14:15]
	s_add_i32 m0, s16, 0x2000
	s_nop 0
	global_load_lds_dwordx4 v152, s[14:15]
	s_waitcnt vmcnt(6)
	s_barrier
; #define PG8_STAGE(bufoff, gbase, voff) do { _Pragma("unroll") for (int _i = 0; _i < 2; ++_i) \
;         __builtin_amdgcn_global_load_lds((const unsigned*)((const char*)(gbase) + (voff)[_i]), (PG8_LAS unsigned*)(lds + (bufoff) + ldsw + _i * 8192), 16, 0, 0); } while (0)
; #define PG8_LDA(dst, b, h) do { _Pragma("unroll") for (int m = 0; m < 4; ++m) _Pragma("unroll") for (int k = 0; k < 2; ++k) dst[m][k] = *(const PG8_LAS bf16x8*)(lds + PG8_SA(b, h) + aoff + m * 2048 + k * 1024); } while (0)
; #define PG8_LDB(dst, b, h) do { _Pragma("unroll") for (int n = 0; n < 2; ++n) _Pragma("unroll") for (int k = 0; k < 2; ++k) dst[n][k] = *(const PG8_LAS bf16x8*)(lds + PG8_SB(b, h) + boff + n * 2048 + k * 1024); } while (0)
; #define PG8_MMA(ai, bj, At, Bt) do { __builtin_amdgcn_s_setprio(1); _Pragma("unroll") for (int m = 0; m < 4; ++m) _Pragma("unroll") for (int n = 0; n < 2; ++n) _Pragma("unroll") for (int k = 0; k < 2; ++k) \
;         acc[ai][bj][m][n] = __builtin_amdgcn_mfma_f32_16x16x32_bf16(Bt[n][k], At[m][k], acc[ai][bj][m][n], 0, 0, 0); __builtin_amdgcn_s_setprio(0); } while (0)
; #define PG8_WAIT_V(n) asm volatile("s_waitcnt vmcnt(" #n ")" ::: "memory")
; #define PG8_WAIT_L(n) asm volatile("s_waitcnt lgkmcnt(" #n ")" ::: "memory")
; #define PG8_BAR __builtin_amdgcn_s_barrier()
; #define PG8_SCHED __builtin_amdgcn_sched_barrier(0)
; template <class Epi, class Sched, bool STAMP = false>
; __device__ __forceinline__ void gemm_phase(PG8_LAS unsigned char* lds, const Gemm g, const Sched& S, const Epi& E, unsigned long long* stamps) {
;     ...
;             PG8_WAIT_V(6); PG8_BAR; PG8_MMA(1, 1, At, B1); PG8_BAR;
;             PG8_LDB(B0, 1, 0); PG8_SCHED; PG8_LDA(At, 1, 0); PG8_STAGE(PG8_SA(0, 1), a2 + hstep, voffA);
;             PG8_WAIT_L(8); PG8_BAR; PG8_WAIT_L(0); PG8_MMA(0, 0, At, B0); PG8_BAR; PG8_SCHED;
;             PG8_LDB(B1, 1, 1); PG8_STAGE(PG8_SB(1, 0), b3, voffB);
;             PG8_BAR; PG8_WAIT_L(0); PG8_MMA(0, 1, At, B1); PG8_BAR;
;             PG8_LDA(At, 1, 1); PG8_STAGE(PG8_SA(1, 0), a3, voffA);
;             PG8_BAR; PG8_WAIT_L(0); PG8_MMA(1, 0, At, B0); PG8_BAR; PG8_SCHED;
	v_mfma_f32_16x16x32_bf16 v[52:55], v[220:223], v[180:183], v[52:55]
	v_mfma_f32_16x16x32_bf16 v[48:51], v[228:231], v[180:183], v[48:51]
	v_mfma_f32_16x16x32_bf16 v[36:39], v[220:223], v[196:199], v[36:39]
	v_mfma_f32_16x16x32_bf16 v[32:35], v[228:231], v[196:199], v[32:35]
	v_mfma_f32_16x16x32_bf16 v[20:23], v[220:223], v[204:207], v[20:23]
	v_mfma_f32_16x16x32_bf16 v[16:19], v[228:231], v[204:207], v[16:19]
	v_mfma_f32_16x16x32_bf16 v[4:7], v[220:223], v[212:215], v[4:7]
	v_mfma_f32_16x16x32_bf16 v[0:3], v[228:231], v[212:215], v[0:3]
	v_mfma_f32_16x16x32_bf16 v[52:55], v[224:227], v[192:195], v[52:55]
	v_mfma_f32_16x16x32_bf16 v[48:51], v[232:235], v[192:195], v[48:51]
	v_mfma_f32_16x16x32_bf16 v[36:39], v[224:227], v[200:203], v[36:39]
	v_mfma_f32_16x16x32_bf16 v[32:35], v[232:235], v[200:203], v[32:35]
	v_mfma_f32_16x16x32_bf16 v[20:23], v[224:227], v[208:211], v[20:23]
	v_mfma_f32_16x16x32_bf16 v[16:19], v[232:235], v[208:211], v[16:19]
	v_mfma_f32_16x16x32_bf16 v[4:7], v[224:227], v[216:219], v[4:7]
	v_mfma_f32_16x16x32_bf16 v[0:3], v[232:235], v[216:219], v[0:3]
	s_barrier
	s_add_i32 s16, 0, 0x18000
	ds_read_b128 v[158:161], v250
	ds_read_b128 v[162:165], v250 offset:1024
	ds_read_b128 v[172:175], v250 offset:2048
	ds_read_b128 v[176:179], v250 offset:3072
	s_add_u32 s14, s60, 0x40000
	s_addc_u32 s15, s61, 0
	s_mov_b32 m0, s97
	ds_read_b128 v[180:183], v171 offset:32768
	ds_read_b128 v[192:195], v171 offset:33792
	ds_read_b128 v[196:199], v171 offset:34816
	ds_read_b128 v[200:203], v171 offset:35840
	ds_read_b128 v[204:207], v171 offset:36864
	ds_read_b128 v[208:211], v171 offset:37888
	ds_read_b128 v[212:215], v171 offset:38912
	global_load_lds_dwordx4 v148, s[14:15]
	s_mov_b32 m0, s64
	ds_read_b128 v[216:219], v171 offset:39936
	global_load_lds_dwordx4 v150, s[14:15]
	s_waitcnt lgkmcnt(8)
	s_barrier
	s_waitcnt lgkmcnt(0)
	v_mfma_f32_16x16x32_bf16 v[124:127], v[158:161], v[180:183], v[124:127]
	v_mfma_f32_16x16x32_bf16 v[120:123], v[172:175], v[180:183], v[120:123]
	v_mfma_f32_16x16x32_bf16 v[108:111], v[158:161], v[196:199], v[108:111]
	v_mfma_f32_16x16x32_bf16 v[104:107], v[172:175], v[196:199], v[104:107]
	v_mfma_f32_16x16x32_bf16 v[92:95], v[158:161], v[204:207], v[92:95]
	v_mfma_f32_16x16x32_bf16 v[88:91], v[172:175], v[204:207], v[88:91]
	v_mfma_f32_16x16x32_bf16 v[76:79], v[158:161], v[212:215], v[76:79]
	v_mfma_f32_16x16x32_bf16 v[72:75], v[172:175], v[212:215], v[72:75]
	v_mfma_f32_16x16x32_bf16 v[124:127], v[162:165], v[192:195], v[124:127]
	v_mfma_f32_16x16x32_bf16 v[120:123], v[176:179], v[192:195], v[120:123]
	v_mfma_f32_16x16x32_bf16 v[108:111], v[162:165], v[200:203], v[108:111]
	v_mfma_f32_16x16x32_bf16 v[104:107], v[176:179], v[200:203], v[104:107]
	v_mfma_f32_16x16x32_bf16 v[92:95], v[162:165], v[208:211], v[92:95]
	v_mfma_f32_16x16x32_bf16 v[88:91], v[176:179], v[208:211], v[88:91]
	v_mfma_f32_16x16x32_bf16 v[76:79], v[162:165], v[216:219], v[76:79]
	v_mfma_f32_16x16x32_bf16 v[72:75], v[176:179], v[216:219], v[72:75]
	s_barrier
	s_add_i32 s17, 0, 0x1c000
	s_add_i32 s14, s16, s88
	s_mov_b32 m0, s14
	ds_read_b128 v[220:223], v251
	ds_read_b128 v[224:227], v251 offset:1024
	ds_read_b128 v[228:231], v251 offset:2048
	global_load_lds_dwordx4 v244, s[58:59]
	s_add_i32 m0, s14, 0x2000
	ds_read_b128 v[232:235], v251 offset:3072
	global_load_lds_dwordx4 v245, s[58:59]
	s_barrier
	s_waitcnt lgkmcnt(0)
	v_mfma_f32_16x16x32_bf16 v[116:119], v[220:223], v[180:183], v[116:119]
	v_mfma_f32_16x16x32_bf16 v[112:115], v[228:231], v[180:183], v[112:115]
	v_mfma_f32_16x16x32_bf16 v[100:103], v[220:223], v[196:199], v[100:103]
	v_mfma_f32_16x16x32_bf16 v[96:99], v[228:231], v[196:199], v[96:99]
	v_mfma_f32_16x16x32_bf16 v[84:87], v[220:223], v[204:207], v[84:87]
	v_mfma_f32_16x16x32_bf16 v[80:83], v[228:231], v[204:207], v[80:83]
	v_mfma_f32_16x16x32_bf16 v[68:71], v[220:223], v[212:215], v[68:71]
	v_mfma_f32_16x16x32_bf16 v[64:67], v[228:231], v[212:215], v[64:67]
	v_mfma_f32_16x16x32_bf16 v[116:119], v[224:227], v[192:195], v[116:119]
	v_mfma_f32_16x16x32_bf16 v[112:115], v[232:235], v[192:195], v[112:115]
	v_mfma_f32_16x16x32_bf16 v[100:103], v[224:227], v[200:203], v[100:103]
	v_mfma_f32_16x16x32_bf16 v[96:99], v[232:235], v[200:203], v[96:99]
	v_mfma_f32_16x16x32_bf16 v[84:87], v[224:227], v[208:211], v[84:87]
	v_mfma_f32_16x16x32_bf16 v[80:83], v[232:235], v[208:211], v[80:83]
	v_mfma_f32_16x16x32_bf16 v[68:71], v[224:227], v[216:219], v[68:71]
	v_mfma_f32_16x16x32_bf16 v[64:67], v[232:235], v[216:219], v[64:67]
	s_barrier
	s_mov_b32 m0, s62
	ds_read_b128 v[180:183], v171 offset:49152
	ds_read_b128 v[192:195], v171 offset:50176
	ds_read_b128 v[196:199], v171 offset:51200
	ds_read_b128 v[200:203], v171 offset:52224
	ds_read_b128 v[204:207], v171 offset:53248
	ds_read_b128 v[208:211], v171 offset:54272
	ds_read_b128 v[212:215], v171 offset:55296
	global_load_lds_dwordx4 v246, s[60:61]
	s_mov_b32 m0, s63
	ds_read_b128 v[216:219], v171 offset:56320
	global_load_lds_dwordx4 v247, s[60:61]
	s_barrier
	s_waitcnt lgkmcnt(0)
	v_mfma_f32_16x16x32_bf16 v[60:63], v[158:161], v[180:183], v[60:63]
	v_mfma_f32_16x16x32_bf16 v[56:59], v[172:175], v[180:183], v[56:59]
	v_mfma_f32_16x16x32_bf16 v[44:47], v[158:161], v[196:199], v[44:47]
	v_mfma_f32_16x16x32_bf16 v[40:43], v[172:175], v[196:199], v[40:43]
	v_mfma_f32_16x16x32_bf16 v[28:31], v[158:161], v[204:207], v[28:31]
	v_mfma_f32_16x16x32_bf16 v[24:27], v[172:175], v[204:207], v[24:27]
	v_mfma_f32_16x16x32_bf16 v[12:15], v[158:161], v[212:215], v[12:15]
	v_mfma_f32_16x16x32_bf16 v[8:11], v[172:175], v[212:215], v[8:11]
	v_mfma_f32_16x16x32_bf16 v[60:63], v[162:165], v[192:195], v[60:63]
	v_mfma_f32_16x16x32_bf16 v[56:59], v[176:179], v[192:195], v[56:59]
	v_mfma_f32_16x16x32_bf16 v[44:47], v[162:165], v[200:203], v[44:47]
	v_mfma_f32_16x16x32_bf16 v[40:43], v[176:179], v[200:203], v[40:43]
	v_mfma_f32_16x16x32_bf16 v[28:31], v[162:165], v[208:211], v[28:31]
	v_mfma_f32_16x16x32_bf16 v[24:27], v[176:179], v[208:211], v[24:27]
	v_mfma_f32_16x16x32_bf16 v[12:15], v[162:165], v[216:219], v[12:15]
	v_mfma_f32_16x16x32_bf16 v[8:11], v[176:179], v[216:219], v[8:11]
	s_barrier
; #define PG8_STAGE(bufoff, gbase, voff) do { _Pragma("unroll") for (int _i = 0; _i < 2; ++_i) \
;         __builtin_amdgcn_global_load_lds((const unsigned*)((const char*)(gbase) + (voff)[_i]), (PG8_LAS unsigned*)(lds + (bufoff) + ldsw + _i * 8192), 16, 0, 0); } while (0)
; #define PG8_WAIT_V(n) asm volatile("s_waitcnt vmcnt(" #n ")" ::: "memory")
; #define PG8_BAR __builtin_amdgcn_s_barrier()
; __device__ __forceinline__ float sigm(float x) { return __builtin_amdgcn_rcpf(1.0f + __expf(-x)); }
; __device__ __forceinline__ float lo16(unsigned w) { return __uint_as_float(w << 16); }
; template <class Epi, class Sched, bool STAMP = false>
; __device__ __forceinline__ void gemm_phase(PG8_LAS unsigned char* lds, const Gemm g, const Sched& S, const Epi& E, unsigned long long* stamps) {
;     ...
;             PG8_STAGE(PG8_SB(1, 1), b3 + hstep, voffB);
;             PG8_WAIT_V(6); PG8_BAR; PG8_MMA(1, 1, At, B1); PG8_BAR;
;     __device__ __forceinline__ void operator()(const f32x4 (&acc)[2][2][4][2], const pg8::Unit& u, int wr, int wc, int fr, int fq) const {
;         const int row0 = u.pm * 256 + wr * 64 + fr, col0 = u.pn * 256 + wc * 32 + 8 * fq;
; #pragma unroll
;         for (int ai = 0; ai < 2; ++ai)
; #pragma unroll
;             for (int m = 0; m < 4; ++m) {
;                 const int row = row0 + ai * 128 + m * 16;
;                 const float s = rstd_of(rowss, row);
; #pragma unroll
;                 for (int bj = 0; bj < 2; ++bj) {
;                     const size_t off = (size_t)row * 1024 + col0 + bj * 128;
;                     const u32x4 tv = *(const u32x4*)(Tm + off);
;                     u32x4 pv = (u32x4){0u, 0u, 0u, 0u};
;                     if (ACC) pv = *(const u32x4*)(M + off);
;                     const f32x4 a0 = acc[ai][bj][m][0] * s, a1 = acc[ai][bj][m][1] * s;
;                     float o[8];
;                     o[0] = sigm(a0[0]) * lo16(tv.x); o[1] = sigm(a0[1]) * hi16(tv.x); o[2] = sigm(a0[2]) * lo16(tv.y); o[3] = sigm(a0[3]) * hi16(tv.y);
;                     o[4] = sigm(a1[0]) * lo16(tv.z); o[5] = sigm(a1[1]) * hi16(tv.z); o[6] = sigm(a1[2]) * lo16(tv.w); o[7] = sigm(a1[3]) * hi16(tv.w);
;                     if (ACC) { o[0] += lo16(pv.x); o[1] += hi16(pv.x); o[2] += lo16(pv.y); o[3] += hi16(pv.y); o[4] += lo16(pv.z); o[5] += hi16(pv.z); o[6] += lo16(pv.w); o[7] += hi16(pv.w); }
	s_add_u32 s14, s58, 0x40080
	s_addc_u32 s15, s59, 0
	s_add_i32 s16, s17, s88
	s_mov_b32 m0, s16
	s_nop 0
	global_load_lds_dwordx4 v128, s[14:15]
	s_add_i32 m0, s16, 0x2000
	s_nop 0
	global_load_lds_dwordx4 v152, s[14:15]
	s_waitcnt vmcnt(6)
	s_barrier
	v_mfma_f32_16x16x32_bf16 v[52:55], v[220:223], v[180:183], v[52:55]
	v_mfma_f32_16x16x32_bf16 v[48:51], v[228:231], v[180:183], v[48:51]
	v_mfma_f32_16x16x32_bf16 v[36:39], v[220:223], v[196:199], v[36:39]
	v_mfma_f32_16x16x32_bf16 v[32:35], v[228:231], v[196:199], v[32:35]
	v_mfma_f32_16x16x32_bf16 v[20:23], v[220:223], v[204:207], v[20:23]
	v_mfma_f32_16x16x32_bf16 v[16:19], v[228:231], v[204:207], v[16:19]
	v_mfma_f32_16x16x32_bf16 v[4:7], v[220:223], v[212:215], v[4:7]
	v_mfma_f32_16x16x32_bf16 v[0:3], v[228:231], v[212:215], v[0:3]
	v_mfma_f32_16x16x32_bf16 v[52:55], v[224:227], v[192:195], v[52:55]
	v_mfma_f32_16x16x32_bf16 v[48:51], v[232:235], v[192:195], v[48:51]
	v_mfma_f32_16x16x32_bf16 v[36:39], v[224:227], v[200:203], v[36:39]
	v_mfma_f32_16x16x32_bf16 v[32:35], v[232:235], v[200:203], v[32:35]
	v_mfma_f32_16x16x32_bf16 v[20:23], v[224:227], v[208:211], v[20:23]
	v_mfma_f32_16x16x32_bf16 v[16:19], v[232:235], v[208:211], v[16:19]
	v_mfma_f32_16x16x32_bf16 v[4:7], v[224:227], v[216:219], v[4:7]
	v_mfma_f32_16x16x32_bf16 v[0:3], v[232:235], v[216:219], v[0:3]
	s_add_i32 vcc_lo, vcc_lo, 2
	s_add_u32 s56, s56, 0x100
	s_addc_u32 s57, s57, 0
	s_add_u32 s76, s76, 0x100
	s_addc_u32 s77, s77, 0
	s_cmp_gt_u32 vcc_lo, 13
	s_barrier
	s_cbranch_scc0 .LBB0_353
	v_lshl_add_u32 v164, s2, 8, v139
	v_ashrrev_i32_e32 v165, 31, v164
	v_lshl_add_u64 v[160:161], v[164:165], 2, s[40:41]
	global_load_dword v158, v[160:161], off
	v_lshl_or_b32 v162, s3, 8, v170
	v_ashrrev_i32_e32 v163, 31, v162
	s_mov_b64 s[2:3], 0x40000
	s_mov_b64 s[58:59], s[36:37]
	s_mov_b64 s[56:57], s[4:5]
	s_waitcnt vmcnt(0)
	v_fmamk_f32 v158, v158, 0x3a800000, v187
	v_cmp_gt_f32_e32 vcc, s67, v158
	v_mul_f32_e32 v159, 0x4b800000, v158
	s_nop 0
	v_cndmask_b32_e32 v158, v158, v159, vcc
	v_rsq_f32_e32 v158, v158
	s_nop 0
	v_mul_f32_e32 v159, 0x45800000, v158
	v_cndmask_b32_e32 v166, v158, v159, vcc
	v_lshlrev_b64 v[158:159], 10, v[164:165]
	v_lshl_add_u64 v[158:159], v[158:159], 0, v[162:163]
	v_lshlrev_b64 v[158:159], 1, v[158:159]
	v_lshl_add_u64 v[168:169], s[30:31], 0, v[158:159]
	v_mov_b32_e32 v249, v158
	v_mov_b32_e32 v250, v249
	global_load_dwordx4 v[192:195], v250, s[30:31]
	global_load_dwordx4 v[196:199], v250, s[0:1]
	global_load_dwordx4 v[200:203], v250, s[30:31] offset:256
	global_load_dwordx4 v[204:207], v250, s[0:1] offset:256
	v_add_u32_e32 v250, 0x8000, v249
	global_load_dwordx4 v[208:211], v250, s[30:31]
	global_load_dwordx4 v[212:215], v250, s[0:1]
	global_load_dwordx4 v[216:219], v250, s[30:31] offset:256
	global_load_dwordx4 v[220:223], v250, s[0:1] offset:256
	v_add_u32_e32 v250, 0x10000, v249
	global_load_dwordx4 v[224:227], v250, s[30:31]
	global_load_dwordx4 v[228:231], v250, s[0:1]
	global_load_dwordx4 v[232:235], v250, s[30:31] offset:256
	global_load_dwordx4 v[236:239], v250, s[0:1] offset:256
	global_load_dword v240, v[160:161], off offset:64
	global_load_dword v241, v[160:161], off offset:128
	global_load_dword v244, v[160:161], off offset:192
	global_load_dword v245, v[160:161], off offset:512
	global_load_dword v246, v[160:161], off offset:576
	global_load_dword v247, v[160:161], off offset:640
	global_load_dword v248, v[160:161], off offset:704
	v_lshl_add_u64 v[168:169], s[0:1], 0, v[158:159]
	v_pk_mul_f32 v[126:127], v[126:127], v[166:167] op_sel_hi:[1,0]
	v_pk_mul_f32 v[120:121], v[120:121], v[166:167] op_sel_hi:[1,0]
	v_mul_f32_e32 v126, 0xbfb8aa3b, v126
	v_mul_f32_e32 v127, 0xbfb8aa3b, v127
	v_pk_mul_f32 v[124:125], v[124:125], v[166:167] op_sel_hi:[1,0]
	v_pk_mul_f32 v[122:123], v[122:123], v[166:167] op_sel_hi:[1,0]
	v_exp_f32_e32 v126, v126
	v_exp_f32_e32 v127, v127
	v_mul_f32_e32 v120, 0xbfb8aa3b, v120
	v_mul_f32_e32 v121, 0xbfb8aa3b, v121
	v_mul_f32_e32 v124, 0xbfb8aa3b, v124
	v_mul_f32_e32 v125, 0xbfb8aa3b, v125
	v_exp_f32_e32 v120, v120
	v_exp_f32_e32 v121, v121
	v_mul_f32_e32 v122, 0xbfb8aa3b, v122
	v_mul_f32_e32 v123, 0xbfb8aa3b, v123
	v_exp_f32_e32 v124, v124
	v_exp_f32_e32 v125, v125
	v_exp_f32_e32 v122, v122
	v_exp_f32_e32 v123, v123
	v_add_f32_e32 v126, 1.0, v126
	v_add_f32_e32 v127, 1.0, v127
	v_rcp_f32_e32 v126, v126
	v_rcp_f32_e32 v127, v127
	v_add_f32_e32 v120, 1.0, v120
	v_add_f32_e32 v121, 1.0, v121
	v_add_f32_e32 v124, 1.0, v124
	v_add_f32_e32 v125, 1.0, v125
	v_rcp_f32_e32 v120, v120
	v_rcp_f32_e32 v121, v121
	v_add_f32_e32 v122, 1.0, v122
	v_add_f32_e32 v123, 1.0, v123
	v_rcp_f32_e32 v124, v124
	v_rcp_f32_e32 v125, v125
	v_rcp_f32_e32 v122, v122
	v_rcp_f32_e32 v123, v123
	v_pk_mul_f32 v[116:117], v[116:117], v[166:167] op_sel_hi:[1,0]
	v_pk_mul_f32 v[114:115], v[114:115], v[166:167] op_sel_hi:[1,0]
	s_waitcnt vmcnt(0)
; __device__ __forceinline__ unsigned cvt_pk_bf16(float lo, float hi) { const f32x2_cv v = {lo, hi}; const bf16x2_cv b = __builtin_convertvector(v, bf16x2_cv); return __builtin_bit_cast(unsigned, b); }
; __device__ __forceinline__ float sigm(float x) { return __builtin_amdgcn_rcpf(1.0f + __expf(-x)); }
; __device__ __forceinline__ float lo16(unsigned w) { return __uint_as_float(w << 16); }
; __device__ __forceinline__ float hi16(unsigned w) { return __uint_as_float(w & 0xffff0000u); }
; __device__ __forceinline__ float rstd_of(const float* rowss, int row) { return rsqrtf(rowss[row] * (1.0f / 1024.0f) + 1e-6f); }
;     __device__ __forceinline__ void operator()(const f32x4 (&acc)[2][2][4][2], const pg8::Unit& u, int wr, int wc, int fr, int fq) const {
;     ...
;                 const int row = row0 + ai * 128 + m * 16;
;                 const float s = rstd_of(rowss, row);
; #pragma unroll
;                 for (int bj = 0; bj < 2; ++bj) {
;                     const size_t off = (size_t)row * 1024 + col0 + bj * 128;
;                     const u32x4 tv = *(const u32x4*)(Tm + off);
;                     u32x4 pv = (u32x4){0u, 0u, 0u, 0u};
;                     if (ACC) pv = *(const u32x4*)(M + off);
;                     const f32x4 a0 = acc[ai][bj][m][0] * s, a1 = acc[ai][bj][m][1] * s;
;                     float o[8];
;                     o[0] = sigm(a0[0]) * lo16(tv.x); o[1] = sigm(a0[1]) * hi16(tv.x); o[2] = sigm(a0[2]) * lo16(tv.y); o[3] = sigm(a0[3]) * hi16(tv.y);
;                     o[4] = sigm(a1[0]) * lo16(tv.z); o[5] = sigm(a1[1]) * hi16(tv.z); o[6] = sigm(a1[2]) * lo16(tv.w); o[7] = sigm(a1[3]) * hi16(tv.w);
;                     if (ACC) { o[0] += lo16(pv.x); o[1] += hi16(pv.x); o[2] += lo16(pv.y); o[3] += hi16(pv.y); o[4] += lo16(pv.z); o[5] += hi16(pv.z); o[6] += lo16(pv.w); o[7] += hi16(pv.w); }
;                     u32x4 w; w.x = cvt_pk_bf16(o[0], o[1]); w.y = cvt_pk_bf16(o[2], o[3]); w.z = cvt_pk_bf16(o[4], o[5]); w.w = cvt_pk_bf16(o[6], o[7]);
;                     *(u32x4*)(M + off) = w; } }
	v_mov_b32_e32 v172, v192
	v_mov_b32_e32 v173, v193
	v_mov_b32_e32 v174, v194
	v_mov_b32_e32 v175, v195
	v_mov_b32_e32 v176, v196
	v_mov_b32_e32 v177, v197
	v_mov_b32_e32 v178, v198
	v_mov_b32_e32 v179, v199
	v_lshlrev_b32_e32 v180, 16, v172
	v_and_b32_e32 v181, 0xffff0000, v172
	v_lshlrev_b32_e32 v182, 16, v176
	v_and_b32_e32 v183, 0xffff0000, v176
	v_lshlrev_b32_e32 v172, 16, v173
	v_and_b32_e32 v173, 0xffff0000, v173
	v_lshlrev_b32_e32 v176, 16, v177
	v_and_b32_e32 v177, 0xffff0000, v177
	v_pk_fma_f32 v[126:127], v[126:127], v[172:173], v[176:177]
	v_lshlrev_b32_e32 v172, 16, v174
	v_and_b32_e32 v173, 0xffff0000, v174
	v_lshlrev_b32_e32 v176, 16, v178
	v_and_b32_e32 v177, 0xffff0000, v178
	v_pk_fma_f32 v[172:173], v[120:121], v[172:173], v[176:177]
	v_lshlrev_b32_e32 v120, 16, v175
	v_and_b32_e32 v121, 0xffff0000, v175
	v_lshlrev_b32_e32 v174, 16, v179
	v_and_b32_e32 v175, 0xffff0000, v179
	v_pk_fma_f32 v[124:125], v[124:125], v[180:181], v[182:183]
	v_pk_fma_f32 v[174:175], v[122:123], v[120:121], v[174:175]
	v_cvt_pk_bf16_f32 v120, v124, v125
	v_cvt_pk_bf16_f32 v121, v126, v127
	v_cvt_pk_bf16_f32 v122, v172, v173
	v_cvt_pk_bf16_f32 v123, v174, v175
	v_or_b32_e32 v124, 0x100, v158
	v_mov_b32_e32 v125, v159
	global_store_dwordx4 v[168:169], v[120:123], off
	v_lshl_add_u64 v[168:169], s[0:1], 0, v[124:125]
	v_pk_mul_f32 v[172:173], v[118:119], v[166:167] op_sel_hi:[1,0]
	v_lshl_add_u64 v[120:121], s[30:31], 0, v[124:125]
	s_nop 1
	v_mov_b32_e32 v120, v200
	v_mov_b32_e32 v121, v201
	v_mov_b32_e32 v122, v202
	v_mov_b32_e32 v123, v203
	v_pk_mul_f32 v[118:119], v[112:113], v[166:167] op_sel_hi:[1,0]
	s_nop 1
	v_mov_b32_e32 v124, v204
	v_mov_b32_e32 v125, v205
	v_mov_b32_e32 v126, v206
	v_mov_b32_e32 v127, v207
	v_add_u32_e32 v250, 0x18000, v249
	global_load_dwordx4 v[192:195], v250, s[30:31]
	global_load_dwordx4 v[196:199], v250, s[0:1]
	global_load_dwordx4 v[200:203], v250, s[30:31] offset:256
	global_load_dwordx4 v[204:207], v250, s[0:1] offset:256
	v_mul_f32_e32 v112, 0xbfb8aa3b, v116
	v_mul_f32_e32 v113, 0xbfb8aa3b, v117
	v_mul_f32_e32 v116, 0xbfb8aa3b, v172
	v_mul_f32_e32 v117, 0xbfb8aa3b, v173
	v_exp_f32_e32 v116, v116
	v_exp_f32_e32 v117, v117
	v_mul_f32_e32 v118, 0xbfb8aa3b, v118
	v_mul_f32_e32 v119, 0xbfb8aa3b, v119
	v_exp_f32_e32 v118, v118
	v_exp_f32_e32 v119, v119
	v_mul_f32_e32 v114, 0xbfb8aa3b, v114
	v_mul_f32_e32 v115, 0xbfb8aa3b, v115
	v_exp_f32_e32 v112, v112
	v_exp_f32_e32 v113, v113
	v_exp_f32_e32 v114, v114
	v_exp_f32_e32 v115, v115
	v_add_f32_e32 v116, 1.0, v116
	v_add_f32_e32 v117, 1.0, v117
	v_rcp_f32_e32 v116, v116
	v_rcp_f32_e32 v117, v117
	v_add_f32_e32 v118, 1.0, v118
	v_add_f32_e32 v119, 1.0, v119
	v_add_f32_e32 v112, 1.0, v112
	v_add_f32_e32 v113, 1.0, v113
	v_rcp_f32_e32 v118, v118
	v_rcp_f32_e32 v119, v119
	v_add_f32_e32 v114, 1.0, v114
	v_add_f32_e32 v115, 1.0, v115
	v_rcp_f32_e32 v112, v112
	v_rcp_f32_e32 v113, v113
	v_rcp_f32_e32 v114, v114
	v_rcp_f32_e32 v115, v115
	v_lshlrev_b32_e32 v172, 16, v120
	v_and_b32_e32 v173, 0xffff0000, v120
	v_lshlrev_b32_e32 v174, 16, v124
	v_and_b32_e32 v175, 0xffff0000, v124
	v_lshlrev_b32_e32 v120, 16, v121
	v_and_b32_e32 v121, 0xffff0000, v121
	v_lshlrev_b32_e32 v124, 16, v125
	v_and_b32_e32 v125, 0xffff0000, v125
	v_pk_fma_f32 v[116:117], v[116:117], v[120:121], v[124:125]
	v_lshlrev_b32_e32 v120, 16, v122
	v_and_b32_e32 v121, 0xffff0000, v122
	v_lshlrev_b32_e32 v124, 16, v126
	v_and_b32_e32 v125, 0xffff0000, v126
	v_pk_fma_f32 v[118:119], v[118:119], v[120:121], v[124:125]
	v_lshlrev_b32_e32 v120, 16, v123
	v_and_b32_e32 v121, 0xffff0000, v123
	v_lshlrev_b32_e32 v122, 16, v127
	v_and_b32_e32 v123, 0xffff0000, v127
	v_pk_fma_f32 v[112:113], v[112:113], v[172:173], v[174:175]
	v_pk_fma_f32 v[120:121], v[114:115], v[120:121], v[122:123]
	v_cvt_pk_bf16_f32 v112, v112, v113
	v_cvt_pk_bf16_f32 v113, v116, v117
	v_cvt_pk_bf16_f32 v114, v118, v119
	v_cvt_pk_bf16_f32 v115, v120, v121
	global_store_dwordx4 v[168:169], v[112:115], off
	s_nop 1
	v_mov_b32_e32 v112, v240
	s_nop 0
	v_or_b32_e32 v114, 16, v164
	v_ashrrev_i32_e32 v115, 31, v114
	v_lshlrev_b64 v[114:115], 10, v[114:115]
	v_lshl_add_u64 v[114:115], v[114:115], 0, v[162:163]
	v_lshlrev_b64 v[114:115], 1, v[114:115]
	v_lshl_add_u64 v[116:117], s[30:31], 0, v[114:115]
	v_lshl_add_u64 v[124:125], s[0:1], 0, v[114:115]
	s_nop 1
	v_mov_b32_e32 v116, v208
	v_mov_b32_e32 v117, v209
	v_mov_b32_e32 v118, v210
	v_mov_b32_e32 v119, v211
	v_or_b32_e32 v114, 0x100, v114
	s_nop 1
	v_mov_b32_e32 v120, v212
	v_mov_b32_e32 v121, v213
	v_mov_b32_e32 v122, v214
	v_mov_b32_e32 v123, v215
	v_fmamk_f32 v112, v112, 0x3a800000, v187
	v_cmp_gt_f32_e32 vcc, s67, v112
	v_mul_f32_e32 v113, 0x4b800000, v112
	v_lshlrev_b32_e32 v126, 16, v116
	v_cndmask_b32_e32 v112, v112, v113, vcc
	v_rsq_f32_e32 v112, v112
	v_and_b32_e32 v127, 0xffff0000, v116
	v_lshlrev_b32_e32 v168, 16, v120
	v_and_b32_e32 v169, 0xffff0000, v120
	v_mul_f32_e32 v113, 0x45800000, v112
	v_cndmask_b32_e32 v112, v112, v113, vcc
	v_pk_mul_f32 v[110:111], v[110:111], v[112:113] op_sel_hi:[1,0]
	v_pk_mul_f32 v[104:105], v[104:105], v[112:113] op_sel_hi:[1,0]
	v_mul_f32_e32 v110, 0xbfb8aa3b, v110
	v_mul_f32_e32 v111, 0xbfb8aa3b, v111
	v_pk_mul_f32 v[108:109], v[108:109], v[112:113] op_sel_hi:[1,0]
	v_pk_mul_f32 v[106:107], v[106:107], v[112:113] op_sel_hi:[1,0]
	v_exp_f32_e32 v110, v110
	v_exp_f32_e32 v111, v111
	v_mul_f32_e32 v104, 0xbfb8aa3b, v104
	v_mul_f32_e32 v105, 0xbfb8aa3b, v105
	v_mul_f32_e32 v108, 0xbfb8aa3b, v108
	v_mul_f32_e32 v109, 0xbfb8aa3b, v109
	v_exp_f32_e32 v104, v104
	v_exp_f32_e32 v105, v105
	v_mul_f32_e32 v106, 0xbfb8aa3b, v106
	v_mul_f32_e32 v107, 0xbfb8aa3b, v107
; __device__ __forceinline__ unsigned cvt_pk_bf16(float lo, float hi) { const f32x2_cv v = {lo, hi}; const bf16x2_cv b = __builtin_convertvector(v, bf16x2_cv); return __builtin_bit_cast(unsigned, b); }
; __device__ __forceinline__ float sigm(float x) { return __builtin_amdgcn_rcpf(1.0f + __expf(-x)); }
; __device__ __forceinline__ float lo16(unsigned w) { return __uint_as_float(w << 16); }
; __device__ __forceinline__ float hi16(unsigned w) { return __uint_as_float(w & 0xffff0000u); }
; __device__ __forceinline__ float rstd_of(const float* rowss, int row) { return rsqrtf(rowss[row] * (1.0f / 1024.0f) + 1e-6f); }
;     __device__ __forceinline__ void operator()(const f32x4 (&acc)[2][2][4][2], const pg8::Unit& u, int wr, int wc, int fr, int fq) const {
;     ...
;                 const int row = row0 + ai * 128 + m * 16;
;                 const float s = rstd_of(rowss, row);
; #pragma unroll
;                 for (int bj = 0; bj < 2; ++bj) {
;                     const size_t off = (size_t)row * 1024 + col0 + bj * 128;
;                     const u32x4 tv = *(const u32x4*)(Tm + off);
;                     u32x4 pv = (u32x4){0u, 0u, 0u, 0u};
;                     if (ACC) pv = *(const u32x4*)(M + off);
;                     const f32x4 a0 = acc[ai][bj][m][0] * s, a1 = acc[ai][bj][m][1] * s;
;                     float o[8];
;                     o[0] = sigm(a0[0]) * lo16(tv.x); o[1] = sigm(a0[1]) * hi16(tv.x); o[2] = sigm(a0[2]) * lo16(tv.y); o[3] = sigm(a0[3]) * hi16(tv.y);
;                     o[4] = sigm(a1[0]) * lo16(tv.z); o[5] = sigm(a1[1]) * hi16(tv.z); o[6] = sigm(a1[2]) * lo16(tv.w); o[7] = sigm(a1[3]) * hi16(tv.w);
;                     if (ACC) { o[0] += lo16(pv.x); o[1] += hi16(pv.x); o[2] += lo16(pv.y); o[3] += hi16(pv.y); o[4] += lo16(pv.z); o[5] += hi16(pv.z); o[6] += lo16(pv.w); o[7] += hi16(pv.w); }
;                     u32x4 w; w.x = cvt_pk_bf16(o[0], o[1]); w.y = cvt_pk_bf16(o[2], o[3]); w.z = cvt_pk_bf16(o[4], o[5]); w.w = cvt_pk_bf16(o[6], o[7]);
;                     *(u32x4*)(M + off) = w; } }
	v_exp_f32_e32 v108, v108
	v_exp_f32_e32 v109, v109
	v_exp_f32_e32 v106, v106
	v_exp_f32_e32 v107, v107
	v_add_f32_e32 v110, 1.0, v110
	v_add_f32_e32 v111, 1.0, v111
	v_rcp_f32_e32 v110, v110
	v_rcp_f32_e32 v111, v111
	v_add_f32_e32 v104, 1.0, v104
	v_add_f32_e32 v105, 1.0, v105
	v_add_f32_e32 v108, 1.0, v108
	v_add_f32_e32 v109, 1.0, v109
	v_rcp_f32_e32 v104, v104
	v_rcp_f32_e32 v105, v105
	v_add_f32_e32 v106, 1.0, v106
	v_add_f32_e32 v107, 1.0, v107
	v_rcp_f32_e32 v108, v108
	v_rcp_f32_e32 v109, v109
	v_rcp_f32_e32 v106, v106
	v_rcp_f32_e32 v107, v107
	v_lshlrev_b32_e32 v116, 16, v117
	v_and_b32_e32 v117, 0xffff0000, v117
	v_lshlrev_b32_e32 v120, 16, v121
	v_and_b32_e32 v121, 0xffff0000, v121
	v_pk_fma_f32 v[110:111], v[110:111], v[116:117], v[120:121]
	v_lshlrev_b32_e32 v116, 16, v118
	v_and_b32_e32 v117, 0xffff0000, v118
	v_lshlrev_b32_e32 v120, 16, v122
	v_and_b32_e32 v121, 0xffff0000, v122
	v_pk_fma_f32 v[116:117], v[104:105], v[116:117], v[120:121]
	v_lshlrev_b32_e32 v104, 16, v119
	v_and_b32_e32 v105, 0xffff0000, v119
	v_lshlrev_b32_e32 v118, 16, v123
	v_and_b32_e32 v119, 0xffff0000, v123
	v_pk_fma_f32 v[108:109], v[108:109], v[126:127], v[168:169]
	v_pk_fma_f32 v[118:119], v[106:107], v[104:105], v[118:119]
	v_cvt_pk_bf16_f32 v104, v108, v109
	v_cvt_pk_bf16_f32 v105, v110, v111
	v_cvt_pk_bf16_f32 v106, v116, v117
	v_cvt_pk_bf16_f32 v107, v118, v119
	global_store_dwordx4 v[124:125], v[104:107], off
	v_pk_mul_f32 v[102:103], v[102:103], v[112:113] op_sel_hi:[1,0]
	v_pk_mul_f32 v[96:97], v[96:97], v[112:113] op_sel_hi:[1,0]
	v_lshl_add_u64 v[104:105], s[30:31], 0, v[114:115]
	v_lshl_add_u64 v[114:115], s[0:1], 0, v[114:115]
	s_nop 1
	v_mov_b32_e32 v104, v216
	v_mov_b32_e32 v105, v217
	v_mov_b32_e32 v106, v218
	v_mov_b32_e32 v107, v219
	v_mul_f32_e32 v102, 0xbfb8aa3b, v102
	s_nop 1
	v_mov_b32_e32 v108, v220
	v_mov_b32_e32 v109, v221
	v_mov_b32_e32 v110, v222
	v_mov_b32_e32 v111, v223
	v_add_u32_e32 v250, 0x40000, v249
	global_load_dwordx4 v[208:211], v250, s[30:31]
	global_load_dwordx4 v[212:215], v250, s[0:1]
	global_load_dwordx4 v[216:219], v250, s[30:31] offset:256
	global_load_dwordx4 v[220:223], v250, s[0:1] offset:256
	v_mul_f32_e32 v103, 0xbfb8aa3b, v103
	v_pk_mul_f32 v[100:101], v[100:101], v[112:113] op_sel_hi:[1,0]
	v_pk_mul_f32 v[98:99], v[98:99], v[112:113] op_sel_hi:[1,0]
	v_exp_f32_e32 v102, v102
	v_exp_f32_e32 v103, v103
	v_mul_f32_e32 v96, 0xbfb8aa3b, v96
	v_mul_f32_e32 v97, 0xbfb8aa3b, v97
	v_mul_f32_e32 v100, 0xbfb8aa3b, v100
	v_mul_f32_e32 v101, 0xbfb8aa3b, v101
	v_exp_f32_e32 v96, v96
	v_exp_f32_e32 v97, v97
	v_mul_f32_e32 v98, 0xbfb8aa3b, v98
	v_mul_f32_e32 v99, 0xbfb8aa3b, v99
	v_exp_f32_e32 v100, v100
	v_exp_f32_e32 v101, v101
	v_exp_f32_e32 v98, v98
	v_exp_f32_e32 v99, v99
	v_add_f32_e32 v102, 1.0, v102
	v_add_f32_e32 v103, 1.0, v103
	v_rcp_f32_e32 v102, v102
	v_rcp_f32_e32 v103, v103
	v_add_f32_e32 v96, 1.0, v96
	v_add_f32_e32 v97, 1.0, v97
	v_add_f32_e32 v100, 1.0, v100
	v_add_f32_e32 v101, 1.0, v101
	v_rcp_f32_e32 v96, v96
	v_rcp_f32_e32 v97, v97
	v_add_f32_e32 v98, 1.0, v98
	v_add_f32_e32 v99, 1.0, v99
	v_rcp_f32_e32 v100, v100
	v_rcp_f32_e32 v101, v101
	v_rcp_f32_e32 v98, v98
	v_rcp_f32_e32 v99, v99
	v_lshlrev_b32_e32 v112, 16, v104
	v_and_b32_e32 v113, 0xffff0000, v104
	v_lshlrev_b32_e32 v116, 16, v108
	v_and_b32_e32 v117, 0xffff0000, v108
	v_lshlrev_b32_e32 v104, 16, v105
	v_and_b32_e32 v105, 0xffff0000, v105
	v_lshlrev_b32_e32 v108, 16, v109
	v_and_b32_e32 v109, 0xffff0000, v109
	v_pk_fma_f32 v[102:103], v[102:103], v[104:105], v[108:109]
	v_lshlrev_b32_e32 v104, 16, v106
	v_and_b32_e32 v105, 0xffff0000, v106
	v_lshlrev_b32_e32 v108, 16, v110
	v_and_b32_e32 v109, 0xffff0000, v110
	v_pk_fma_f32 v[104:105], v[96:97], v[104:105], v[108:109]
	v_lshlrev_b32_e32 v96, 16, v107
	v_and_b32_e32 v97, 0xffff0000, v107
	v_lshlrev_b32_e32 v106, 16, v111
	v_and_b32_e32 v107, 0xffff0000, v111
	v_pk_fma_f32 v[100:101], v[100:101], v[112:113], v[116:117]
	v_pk_fma_f32 v[106:107], v[98:99], v[96:97], v[106:107]
	v_cvt_pk_bf16_f32 v96, v100, v101
	v_cvt_pk_bf16_f32 v97, v102, v103
	v_cvt_pk_bf16_f32 v98, v104, v105
	v_cvt_pk_bf16_f32 v99, v106, v107
	global_store_dwordx4 v[114:115], v[96:99], off
	s_nop 1
	v_mov_b32_e32 v96, v241
	s_nop 0
	v_or_b32_e32 v98, 32, v164
	v_ashrrev_i32_e32 v99, 31, v98
	v_lshlrev_b64 v[98:99], 10, v[98:99]
	v_lshl_add_u64 v[98:99], v[98:99], 0, v[162:163]
	v_lshlrev_b64 v[98:99], 1, v[98:99]
	v_lshl_add_u64 v[100:101], s[30:31], 0, v[98:99]
	v_lshl_add_u64 v[108:109], s[0:1], 0, v[98:99]
	s_nop 1
	v_mov_b32_e32 v100, v224
	v_mov_b32_e32 v101, v225
	v_mov_b32_e32 v102, v226
	v_mov_b32_e32 v103, v227
	v_or_b32_e32 v98, 0x100, v98
	s_nop 1
	v_mov_b32_e32 v104, v228
	v_mov_b32_e32 v105, v229
	v_mov_b32_e32 v106, v230
	v_mov_b32_e32 v107, v231
	v_fmamk_f32 v96, v96, 0x3a800000, v187
	v_cmp_gt_f32_e32 vcc, s67, v96
	v_mul_f32_e32 v97, 0x4b800000, v96
	v_lshlrev_b32_e32 v110, 16, v100
	v_cndmask_b32_e32 v96, v96, v97, vcc
	v_rsq_f32_e32 v96, v96
	v_and_b32_e32 v111, 0xffff0000, v100
	v_lshlrev_b32_e32 v112, 16, v104
	v_and_b32_e32 v113, 0xffff0000, v104
	v_mul_f32_e32 v97, 0x45800000, v96
	v_cndmask_b32_e32 v96, v96, v97, vcc
	v_pk_mul_f32 v[94:95], v[94:95], v[96:97] op_sel_hi:[1,0]
	v_pk_mul_f32 v[88:89], v[88:89], v[96:97] op_sel_hi:[1,0]
	v_mul_f32_e32 v94, 0xbfb8aa3b, v94
	v_mul_f32_e32 v95, 0xbfb8aa3b, v95
	v_pk_mul_f32 v[92:93], v[92:93], v[96:97] op_sel_hi:[1,0]
	v_pk_mul_f32 v[90:91], v[90:91], v[96:97] op_sel_hi:[1,0]
	v_exp_f32_e32 v94, v94
	v_exp_f32_e32 v95, v95
	v_mul_f32_e32 v88, 0xbfb8aa3b, v88
	v_mul_f32_e32 v89, 0xbfb8aa3b, v89
	v_mul_f32_e32 v92, 0xbfb8aa3b, v92
; __device__ __forceinline__ unsigned cvt_pk_bf16(float lo, float hi) { const f32x2_cv v = {lo, hi}; const bf16x2_cv b = __builtin_convertvector(v, bf16x2_cv); return __builtin_bit_cast(unsigned, b); }
; __device__ __forceinline__ float sigm(float x) { return __builtin_amdgcn_rcpf(1.0f + __expf(-x)); }
; __device__ __forceinline__ float lo16(unsigned w) { return __uint_as_float(w << 16); }
; __device__ __forceinline__ float hi16(unsigned w) { return __uint_as_float(w & 0xffff0000u); }
; __device__ __forceinline__ float rstd_of(const float* rowss, int row) { return rsqrtf(rowss[row] * (1.0f / 1024.0f) + 1e-6f); }
;     __device__ __forceinline__ void operator()(const f32x4 (&acc)[2][2][4][2], const pg8::Unit& u, int wr, int wc, int fr, int fq) const {
;     ...
;                 const int row = row0 + ai * 128 + m * 16;
;                 const float s = rstd_of(rowss, row);
; #pragma unroll
;                 for (int bj = 0; bj < 2; ++bj) {
;                     const size_t off = (size_t)row * 1024 + col0 + bj * 128;
;                     const u32x4 tv = *(const u32x4*)(Tm + off);
;                     u32x4 pv = (u32x4){0u, 0u, 0u, 0u};
;                     if (ACC) pv = *(const u32x4*)(M + off);
;                     const f32x4 a0 = acc[ai][bj][m][0] * s, a1 = acc[ai][bj][m][1] * s;
;                     float o[8];
;                     o[0] = sigm(a0[0]) * lo16(tv.x); o[1] = sigm(a0[1]) * hi16(tv.x); o[2] = sigm(a0[2]) * lo16(tv.y); o[3] = sigm(a0[3]) * hi16(tv.y);
;                     o[4] = sigm(a1[0]) * lo16(tv.z); o[5] = sigm(a1[1]) * hi16(tv.z); o[6] = sigm(a1[2]) * lo16(tv.w); o[7] = sigm(a1[3]) * hi16(tv.w);
;                     if (ACC) { o[0] += lo16(pv.x); o[1] += hi16(pv.x); o[2] += lo16(pv.y); o[3] += hi16(pv.y); o[4] += lo16(pv.z); o[5] += hi16(pv.z); o[6] += lo16(pv.w); o[7] += hi16(pv.w); }
;                     u32x4 w; w.x = cvt_pk_bf16(o[0], o[1]); w.y = cvt_pk_bf16(o[2], o[3]); w.z = cvt_pk_bf16(o[4], o[5]); w.w = cvt_pk_bf16(o[6], o[7]);
;                     *(u32x4*)(M + off) = w; } }
	v_mul_f32_e32 v93, 0xbfb8aa3b, v93
	v_exp_f32_e32 v88, v88
	v_exp_f32_e32 v89, v89
	v_mul_f32_e32 v90, 0xbfb8aa3b, v90
	v_mul_f32_e32 v91, 0xbfb8aa3b, v91
	v_exp_f32_e32 v92, v92
	v_exp_f32_e32 v93, v93
	v_exp_f32_e32 v90, v90
	v_exp_f32_e32 v91, v91
	v_add_f32_e32 v94, 1.0, v94
	v_add_f32_e32 v95, 1.0, v95
	v_rcp_f32_e32 v94, v94
	v_rcp_f32_e32 v95, v95
	v_add_f32_e32 v88, 1.0, v88
	v_add_f32_e32 v89, 1.0, v89
	v_add_f32_e32 v92, 1.0, v92
	v_add_f32_e32 v93, 1.0, v93
	v_rcp_f32_e32 v88, v88
	v_rcp_f32_e32 v89, v89
	v_add_f32_e32 v90, 1.0, v90
	v_add_f32_e32 v91, 1.0, v91
	v_rcp_f32_e32 v92, v92
	v_rcp_f32_e32 v93, v93
	v_rcp_f32_e32 v90, v90
	v_rcp_f32_e32 v91, v91
	v_lshlrev_b32_e32 v100, 16, v101
	v_and_b32_e32 v101, 0xffff0000, v101
	v_lshlrev_b32_e32 v104, 16, v105
	v_and_b32_e32 v105, 0xffff0000, v105
	v_pk_fma_f32 v[94:95], v[94:95], v[100:101], v[104:105]
	v_lshlrev_b32_e32 v100, 16, v102
	v_and_b32_e32 v101, 0xffff0000, v102
	v_lshlrev_b32_e32 v104, 16, v106
	v_and_b32_e32 v105, 0xffff0000, v106
	v_pk_fma_f32 v[100:101], v[88:89], v[100:101], v[104:105]
	v_lshlrev_b32_e32 v88, 16, v103
	v_and_b32_e32 v89, 0xffff0000, v103
	v_lshlrev_b32_e32 v102, 16, v107
	v_and_b32_e32 v103, 0xffff0000, v107
	v_pk_fma_f32 v[92:93], v[92:93], v[110:111], v[112:113]
	v_pk_fma_f32 v[102:103], v[90:91], v[88:89], v[102:103]
	v_cvt_pk_bf16_f32 v88, v92, v93
	v_cvt_pk_bf16_f32 v89, v94, v95
	v_cvt_pk_bf16_f32 v90, v100, v101
	v_cvt_pk_bf16_f32 v91, v102, v103
	global_store_dwordx4 v[108:109], v[88:91], off
	v_pk_mul_f32 v[86:87], v[86:87], v[96:97] op_sel_hi:[1,0]
	v_pk_mul_f32 v[80:81], v[80:81], v[96:97] op_sel_hi:[1,0]
	v_lshl_add_u64 v[88:89], s[30:31], 0, v[98:99]
	v_lshl_add_u64 v[98:99], s[0:1], 0, v[98:99]
	s_nop 1
	v_mov_b32_e32 v92, v232
	v_mov_b32_e32 v93, v233
	v_mov_b32_e32 v94, v234
	v_mov_b32_e32 v95, v235
	v_mul_f32_e32 v86, 0xbfb8aa3b, v86
	s_nop 1
	v_mov_b32_e32 v88, v236
	v_mov_b32_e32 v89, v237
	v_mov_b32_e32 v90, v238
	v_mov_b32_e32 v91, v239
	v_add_u32_e32 v250, 0x48000, v249
	global_load_dwordx4 v[224:227], v250, s[30:31]
	global_load_dwordx4 v[228:231], v250, s[0:1]
	global_load_dwordx4 v[232:235], v250, s[30:31] offset:256
	global_load_dwordx4 v[236:239], v250, s[0:1] offset:256
	v_mul_f32_e32 v87, 0xbfb8aa3b, v87
	v_pk_mul_f32 v[84:85], v[84:85], v[96:97] op_sel_hi:[1,0]
	v_pk_mul_f32 v[82:83], v[82:83], v[96:97] op_sel_hi:[1,0]
	v_exp_f32_e32 v86, v86
	v_exp_f32_e32 v87, v87
	v_mul_f32_e32 v80, 0xbfb8aa3b, v80
	v_mul_f32_e32 v81, 0xbfb8aa3b, v81
	v_mul_f32_e32 v84, 0xbfb8aa3b, v84
	v_mul_f32_e32 v85, 0xbfb8aa3b, v85
	v_exp_f32_e32 v80, v80
	v_exp_f32_e32 v81, v81
	v_mul_f32_e32 v82, 0xbfb8aa3b, v82
	v_mul_f32_e32 v83, 0xbfb8aa3b, v83
	v_exp_f32_e32 v84, v84
	v_exp_f32_e32 v85, v85
	v_exp_f32_e32 v82, v82
	v_exp_f32_e32 v83, v83
	v_add_f32_e32 v86, 1.0, v86
	v_add_f32_e32 v87, 1.0, v87
	v_rcp_f32_e32 v86, v86
	v_rcp_f32_e32 v87, v87
	v_add_f32_e32 v80, 1.0, v80
	v_add_f32_e32 v81, 1.0, v81
	v_add_f32_e32 v84, 1.0, v84
	v_add_f32_e32 v85, 1.0, v85
	v_rcp_f32_e32 v80, v80
	v_rcp_f32_e32 v81, v81
	v_add_f32_e32 v82, 1.0, v82
	v_add_f32_e32 v83, 1.0, v83
	v_rcp_f32_e32 v84, v84
	v_rcp_f32_e32 v85, v85
	v_rcp_f32_e32 v82, v82
	v_rcp_f32_e32 v83, v83
	v_lshlrev_b32_e32 v96, 16, v92
	v_and_b32_e32 v97, 0xffff0000, v92
	v_lshlrev_b32_e32 v100, 16, v88
	v_and_b32_e32 v101, 0xffff0000, v88
	v_lshlrev_b32_e32 v92, 16, v93
	v_and_b32_e32 v93, 0xffff0000, v93
	v_lshlrev_b32_e32 v88, 16, v89
	v_and_b32_e32 v89, 0xffff0000, v89
	v_pk_fma_f32 v[86:87], v[86:87], v[92:93], v[88:89]
	v_lshlrev_b32_e32 v88, 16, v94
	v_and_b32_e32 v89, 0xffff0000, v94
	v_lshlrev_b32_e32 v92, 16, v90
	v_and_b32_e32 v93, 0xffff0000, v90
	v_pk_fma_f32 v[88:89], v[80:81], v[88:89], v[92:93]
	v_lshlrev_b32_e32 v80, 16, v95
	v_and_b32_e32 v81, 0xffff0000, v95
	v_lshlrev_b32_e32 v90, 16, v91
	v_and_b32_e32 v91, 0xffff0000, v91
	v_pk_fma_f32 v[84:85], v[84:85], v[96:97], v[100:101]
	v_pk_fma_f32 v[90:91], v[82:83], v[80:81], v[90:91]
	v_cvt_pk_bf16_f32 v80, v84, v85
	v_cvt_pk_bf16_f32 v81, v86, v87
	v_cvt_pk_bf16_f32 v82, v88, v89
	v_cvt_pk_bf16_f32 v83, v90, v91
	global_store_dwordx4 v[98:99], v[80:83], off
	s_nop 1
	v_mov_b32_e32 v80, v244
	s_nop 0
	v_or_b32_e32 v82, 48, v164
	v_ashrrev_i32_e32 v83, 31, v82
	v_lshlrev_b64 v[82:83], 10, v[82:83]
	v_lshl_add_u64 v[82:83], v[82:83], 0, v[162:163]
	v_lshlrev_b64 v[82:83], 1, v[82:83]
	v_lshl_add_u64 v[84:85], s[30:31], 0, v[82:83]
	v_lshl_add_u64 v[92:93], s[0:1], 0, v[82:83]
	s_waitcnt vmcnt(13)
; __device__ __forceinline__ unsigned cvt_pk_bf16(float lo, float hi) { const f32x2_cv v = {lo, hi}; const bf16x2_cv b = __builtin_convertvector(v, bf16x2_cv); return __builtin_bit_cast(unsigned, b); }
; __device__ __forceinline__ float sigm(float x) { return __builtin_amdgcn_rcpf(1.0f + __expf(-x)); }
; __device__ __forceinline__ float lo16(unsigned w) { return __uint_as_float(w << 16); }
; __device__ __forceinline__ float hi16(unsigned w) { return __uint_as_float(w & 0xffff0000u); }
; __device__ __forceinline__ float rstd_of(const float* rowss, int row) { return rsqrtf(rowss[row] * (1.0f / 1024.0f) + 1e-6f); }
;     __device__ __forceinline__ void operator()(const f32x4 (&acc)[2][2][4][2], const pg8::Unit& u, int wr, int wc, int fr, int fq) const {
;     ...
;                 const int row = row0 + ai * 128 + m * 16;
;                 const float s = rstd_of(rowss, row);
; #pragma unroll
;                 for (int bj = 0; bj < 2; ++bj) {
;                     const size_t off = (size_t)row * 1024 + col0 + bj * 128;
;                     const u32x4 tv = *(const u32x4*)(Tm + off);
;                     u32x4 pv = (u32x4){0u, 0u, 0u, 0u};
;                     if (ACC) pv = *(const u32x4*)(M + off);
;                     const f32x4 a0 = acc[ai][bj][m][0] * s, a1 = acc[ai][bj][m][1] * s;
;                     float o[8];
;                     o[0] = sigm(a0[0]) * lo16(tv.x); o[1] = sigm(a0[1]) * hi16(tv.x); o[2] = sigm(a0[2]) * lo16(tv.y); o[3] = sigm(a0[3]) * hi16(tv.y);
;                     o[4] = sigm(a1[0]) * lo16(tv.z); o[5] = sigm(a1[1]) * hi16(tv.z); o[6] = sigm(a1[2]) * lo16(tv.w); o[7] = sigm(a1[3]) * hi16(tv.w);
;                     if (ACC) { o[0] += lo16(pv.x); o[1] += hi16(pv.x); o[2] += lo16(pv.y); o[3] += hi16(pv.y); o[4] += lo16(pv.z); o[5] += hi16(pv.z); o[6] += lo16(pv.w); o[7] += hi16(pv.w); }
;                     u32x4 w; w.x = cvt_pk_bf16(o[0], o[1]); w.y = cvt_pk_bf16(o[2], o[3]); w.z = cvt_pk_bf16(o[4], o[5]); w.w = cvt_pk_bf16(o[6], o[7]);
;                     *(u32x4*)(M + off) = w; } }
	s_nop 1
	v_mov_b32_e32 v84, v192
	v_mov_b32_e32 v85, v193
	v_mov_b32_e32 v86, v194
	v_mov_b32_e32 v87, v195
	v_or_b32_e32 v82, 0x100, v82
	s_nop 1
	v_mov_b32_e32 v88, v196
	v_mov_b32_e32 v89, v197
	v_mov_b32_e32 v90, v198
	v_mov_b32_e32 v91, v199
	v_fmamk_f32 v80, v80, 0x3a800000, v187
	v_cmp_gt_f32_e32 vcc, s67, v80
	v_mul_f32_e32 v81, 0x4b800000, v80
	v_lshlrev_b32_e32 v94, 16, v84
	v_cndmask_b32_e32 v80, v80, v81, vcc
	v_rsq_f32_e32 v80, v80
	v_and_b32_e32 v95, 0xffff0000, v84
	v_lshlrev_b32_e32 v96, 16, v88
	v_and_b32_e32 v97, 0xffff0000, v88
	v_mul_f32_e32 v81, 0x45800000, v80
	v_cndmask_b32_e32 v80, v80, v81, vcc
	v_pk_mul_f32 v[78:79], v[78:79], v[80:81] op_sel_hi:[1,0]
	v_pk_mul_f32 v[72:73], v[72:73], v[80:81] op_sel_hi:[1,0]
	v_mul_f32_e32 v78, 0xbfb8aa3b, v78
	v_mul_f32_e32 v79, 0xbfb8aa3b, v79
	v_pk_mul_f32 v[76:77], v[76:77], v[80:81] op_sel_hi:[1,0]
	v_pk_mul_f32 v[74:75], v[74:75], v[80:81] op_sel_hi:[1,0]
	v_exp_f32_e32 v78, v78
	v_exp_f32_e32 v79, v79
	v_mul_f32_e32 v72, 0xbfb8aa3b, v72
	v_mul_f32_e32 v73, 0xbfb8aa3b, v73
	v_mul_f32_e32 v76, 0xbfb8aa3b, v76
	v_mul_f32_e32 v77, 0xbfb8aa3b, v77
	v_exp_f32_e32 v72, v72
	v_exp_f32_e32 v73, v73
	v_mul_f32_e32 v74, 0xbfb8aa3b, v74
	v_mul_f32_e32 v75, 0xbfb8aa3b, v75
	v_exp_f32_e32 v76, v76
	v_exp_f32_e32 v77, v77
	v_exp_f32_e32 v74, v74
	v_exp_f32_e32 v75, v75
	v_add_f32_e32 v78, 1.0, v78
	v_add_f32_e32 v79, 1.0, v79
	v_rcp_f32_e32 v78, v78
	v_rcp_f32_e32 v79, v79
	v_add_f32_e32 v72, 1.0, v72
	v_add_f32_e32 v73, 1.0, v73
	v_add_f32_e32 v76, 1.0, v76
	v_add_f32_e32 v77, 1.0, v77
	v_rcp_f32_e32 v72, v72
	v_rcp_f32_e32 v73, v73
	v_add_f32_e32 v74, 1.0, v74
	v_add_f32_e32 v75, 1.0, v75
	v_rcp_f32_e32 v76, v76
	v_rcp_f32_e32 v77, v77
	v_rcp_f32_e32 v74, v74
	v_rcp_f32_e32 v75, v75
	v_lshlrev_b32_e32 v84, 16, v85
	v_and_b32_e32 v85, 0xffff0000, v85
	v_lshlrev_b32_e32 v88, 16, v89
	v_and_b32_e32 v89, 0xffff0000, v89
	v_pk_fma_f32 v[78:79], v[78:79], v[84:85], v[88:89]
	v_lshlrev_b32_e32 v84, 16, v86
	v_and_b32_e32 v85, 0xffff0000, v86
	v_lshlrev_b32_e32 v88, 16, v90
	v_and_b32_e32 v89, 0xffff0000, v90
	v_pk_fma_f32 v[84:85], v[72:73], v[84:85], v[88:89]
	v_lshlrev_b32_e32 v72, 16, v87
	v_and_b32_e32 v73, 0xffff0000, v87
	v_lshlrev_b32_e32 v86, 16, v91
	v_and_b32_e32 v87, 0xffff0000, v91
	v_pk_fma_f32 v[76:77], v[76:77], v[94:95], v[96:97]
	v_pk_fma_f32 v[86:87], v[74:75], v[72:73], v[86:87]
	v_cvt_pk_bf16_f32 v72, v76, v77
	v_cvt_pk_bf16_f32 v73, v78, v79
	v_cvt_pk_bf16_f32 v74, v84, v85
	v_cvt_pk_bf16_f32 v75, v86, v87
	global_store_dwordx4 v[92:93], v[72:75], off
	v_pk_mul_f32 v[70:71], v[70:71], v[80:81] op_sel_hi:[1,0]
	v_pk_mul_f32 v[64:65], v[64:65], v[80:81] op_sel_hi:[1,0]
	v_lshl_add_u64 v[72:73], s[30:31], 0, v[82:83]
	v_lshl_add_u64 v[82:83], s[0:1], 0, v[82:83]
	s_nop 1
	v_mov_b32_e32 v76, v200
	v_mov_b32_e32 v77, v201
	v_mov_b32_e32 v78, v202
	v_mov_b32_e32 v79, v203
	v_mul_f32_e32 v70, 0xbfb8aa3b, v70
	s_nop 1
	v_mov_b32_e32 v72, v204
	v_mov_b32_e32 v73, v205
	v_mov_b32_e32 v74, v206
	v_mov_b32_e32 v75, v207
	v_add_u32_e32 v250, 0x50000, v249
	global_load_dwordx4 v[192:195], v250, s[30:31]
	global_load_dwordx4 v[196:199], v250, s[0:1]
	global_load_dwordx4 v[200:203], v250, s[30:31] offset:256
	global_load_dwordx4 v[204:207], v250, s[0:1] offset:256
	v_mul_f32_e32 v71, 0xbfb8aa3b, v71
	v_pk_mul_f32 v[68:69], v[68:69], v[80:81] op_sel_hi:[1,0]
	v_pk_mul_f32 v[66:67], v[66:67], v[80:81] op_sel_hi:[1,0]
	v_exp_f32_e32 v70, v70
	v_exp_f32_e32 v71, v71
	v_mul_f32_e32 v64, 0xbfb8aa3b, v64
	v_mul_f32_e32 v65, 0xbfb8aa3b, v65
	v_mul_f32_e32 v68, 0xbfb8aa3b, v68
	v_mul_f32_e32 v69, 0xbfb8aa3b, v69
	v_exp_f32_e32 v64, v64
	v_exp_f32_e32 v65, v65
	v_mul_f32_e32 v66, 0xbfb8aa3b, v66
	v_mul_f32_e32 v67, 0xbfb8aa3b, v67
	v_exp_f32_e32 v68, v68
	v_exp_f32_e32 v69, v69
	v_exp_f32_e32 v66, v66
	v_exp_f32_e32 v67, v67
	v_add_f32_e32 v70, 1.0, v70
	v_add_f32_e32 v71, 1.0, v71
	v_rcp_f32_e32 v70, v70
	v_rcp_f32_e32 v71, v71
	v_add_f32_e32 v64, 1.0, v64
	v_add_f32_e32 v65, 1.0, v65
	v_add_f32_e32 v68, 1.0, v68
	v_add_f32_e32 v69, 1.0, v69
	v_rcp_f32_e32 v64, v64
	v_rcp_f32_e32 v65, v65
	v_add_f32_e32 v66, 1.0, v66
	v_add_f32_e32 v67, 1.0, v67
	v_rcp_f32_e32 v68, v68
	v_rcp_f32_e32 v69, v69
	v_rcp_f32_e32 v66, v66
	v_rcp_f32_e32 v67, v67
	v_lshlrev_b32_e32 v80, 16, v76
	v_and_b32_e32 v81, 0xffff0000, v76
	v_lshlrev_b32_e32 v84, 16, v72
	v_and_b32_e32 v85, 0xffff0000, v72
	v_lshlrev_b32_e32 v76, 16, v77
	v_and_b32_e32 v77, 0xffff0000, v77
	v_lshlrev_b32_e32 v72, 16, v73
	v_and_b32_e32 v73, 0xffff0000, v73
	v_pk_fma_f32 v[70:71], v[70:71], v[76:77], v[72:73]
	v_lshlrev_b32_e32 v72, 16, v78
	v_and_b32_e32 v73, 0xffff0000, v78
	v_lshlrev_b32_e32 v76, 16, v74
	v_and_b32_e32 v77, 0xffff0000, v74
	v_pk_fma_f32 v[72:73], v[64:65], v[72:73], v[76:77]
	v_lshlrev_b32_e32 v64, 16, v79
	v_and_b32_e32 v65, 0xffff0000, v79
	v_lshlrev_b32_e32 v74, 16, v75
	v_and_b32_e32 v75, 0xffff0000, v75
	v_pk_fma_f32 v[68:69], v[68:69], v[80:81], v[84:85]
	v_pk_fma_f32 v[74:75], v[66:67], v[64:65], v[74:75]
	v_cvt_pk_bf16_f32 v64, v68, v69
	v_cvt_pk_bf16_f32 v65, v70, v71
	v_cvt_pk_bf16_f32 v66, v72, v73
	v_cvt_pk_bf16_f32 v67, v74, v75
	global_store_dwordx4 v[82:83], v[64:67], off
	s_nop 1
	v_mov_b32_e32 v64, v245
	v_lshl_add_u64 v[70:71], v[158:159], 0, s[2:3]
	v_lshl_add_u64 v[66:67], s[30:31], 0, v[70:71]
	v_lshl_add_u64 v[74:75], s[0:1], 0, v[70:71]
	s_waitcnt vmcnt(13)
; __device__ __forceinline__ unsigned cvt_pk_bf16(float lo, float hi) { const f32x2_cv v = {lo, hi}; const bf16x2_cv b = __builtin_convertvector(v, bf16x2_cv); return __builtin_bit_cast(unsigned, b); }
; __device__ __forceinline__ float sigm(float x) { return __builtin_amdgcn_rcpf(1.0f + __expf(-x)); }
; __device__ __forceinline__ float lo16(unsigned w) { return __uint_as_float(w << 16); }
; __device__ __forceinline__ float hi16(unsigned w) { return __uint_as_float(w & 0xffff0000u); }
; __device__ __forceinline__ float rstd_of(const float* rowss, int row) { return rsqrtf(rowss[row] * (1.0f / 1024.0f) + 1e-6f); }
;     __device__ __forceinline__ void operator()(const f32x4 (&acc)[2][2][4][2], const pg8::Unit& u, int wr, int wc, int fr, int fq) const {
;     ...
;                 const int row = row0 + ai * 128 + m * 16;
;                 const float s = rstd_of(rowss, row);
; #pragma unroll
;                 for (int bj = 0; bj < 2; ++bj) {
;                     const size_t off = (size_t)row * 1024 + col0 + bj * 128;
;                     const u32x4 tv = *(const u32x4*)(Tm + off);
;                     u32x4 pv = (u32x4){0u, 0u, 0u, 0u};
;                     if (ACC) pv = *(const u32x4*)(M + off);
;                     const f32x4 a0 = acc[ai][bj][m][0] * s, a1 = acc[ai][bj][m][1] * s;
;                     float o[8];
;                     o[0] = sigm(a0[0]) * lo16(tv.x); o[1] = sigm(a0[1]) * hi16(tv.x); o[2] = sigm(a0[2]) * lo16(tv.y); o[3] = sigm(a0[3]) * hi16(tv.y);
;                     o[4] = sigm(a1[0]) * lo16(tv.z); o[5] = sigm(a1[1]) * hi16(tv.z); o[6] = sigm(a1[2]) * lo16(tv.w); o[7] = sigm(a1[3]) * hi16(tv.w);
;                     if (ACC) { o[0] += lo16(pv.x); o[1] += hi16(pv.x); o[2] += lo16(pv.y); o[3] += hi16(pv.y); o[4] += lo16(pv.z); o[5] += hi16(pv.z); o[6] += lo16(pv.w); o[7] += hi16(pv.w); }
;                     u32x4 w; w.x = cvt_pk_bf16(o[0], o[1]); w.y = cvt_pk_bf16(o[2], o[3]); w.z = cvt_pk_bf16(o[4], o[5]); w.w = cvt_pk_bf16(o[6], o[7]);
;                     *(u32x4*)(M + off) = w; } }
	s_nop 1
	v_mov_b32_e32 v66, v208
	v_mov_b32_e32 v67, v209
	v_mov_b32_e32 v68, v210
	v_mov_b32_e32 v69, v211
	s_mov_b64 s[2:3], 0x40100
	s_nop 1
	v_mov_b32_e32 v70, v212
	v_mov_b32_e32 v71, v213
	v_mov_b32_e32 v72, v214
	v_mov_b32_e32 v73, v215
	v_fmamk_f32 v64, v64, 0x3a800000, v187
	v_cmp_gt_f32_e32 vcc, s67, v64
	v_mul_f32_e32 v65, 0x4b800000, v64
	v_lshlrev_b32_e32 v76, 16, v66
	v_cndmask_b32_e32 v64, v64, v65, vcc
	v_rsq_f32_e32 v64, v64
	v_and_b32_e32 v77, 0xffff0000, v66
	v_lshlrev_b32_e32 v78, 16, v70
	v_and_b32_e32 v79, 0xffff0000, v70
	v_mul_f32_e32 v65, 0x45800000, v64
	v_cndmask_b32_e32 v64, v64, v65, vcc
	v_pk_mul_f32 v[62:63], v[62:63], v[64:65] op_sel_hi:[1,0]
	v_pk_mul_f32 v[56:57], v[56:57], v[64:65] op_sel_hi:[1,0]
	v_mul_f32_e32 v62, 0xbfb8aa3b, v62
	v_mul_f32_e32 v63, 0xbfb8aa3b, v63
	v_pk_mul_f32 v[60:61], v[60:61], v[64:65] op_sel_hi:[1,0]
	v_pk_mul_f32 v[58:59], v[58:59], v[64:65] op_sel_hi:[1,0]
	v_exp_f32_e32 v62, v62
	v_exp_f32_e32 v63, v63
	v_mul_f32_e32 v56, 0xbfb8aa3b, v56
	v_mul_f32_e32 v57, 0xbfb8aa3b, v57
	v_mul_f32_e32 v60, 0xbfb8aa3b, v60
	v_mul_f32_e32 v61, 0xbfb8aa3b, v61
	v_exp_f32_e32 v56, v56
	v_exp_f32_e32 v57, v57
	v_mul_f32_e32 v58, 0xbfb8aa3b, v58
	v_mul_f32_e32 v59, 0xbfb8aa3b, v59
	v_exp_f32_e32 v60, v60
	v_exp_f32_e32 v61, v61
	v_exp_f32_e32 v58, v58
	v_exp_f32_e32 v59, v59
	v_add_f32_e32 v62, 1.0, v62
	v_add_f32_e32 v63, 1.0, v63
	v_rcp_f32_e32 v62, v62
	v_rcp_f32_e32 v63, v63
	v_add_f32_e32 v56, 1.0, v56
	v_add_f32_e32 v57, 1.0, v57
	v_add_f32_e32 v60, 1.0, v60
	v_add_f32_e32 v61, 1.0, v61
	v_rcp_f32_e32 v56, v56
	v_rcp_f32_e32 v57, v57
	v_add_f32_e32 v58, 1.0, v58
	v_add_f32_e32 v59, 1.0, v59
	v_rcp_f32_e32 v60, v60
	v_rcp_f32_e32 v61, v61
	v_rcp_f32_e32 v58, v58
	v_rcp_f32_e32 v59, v59
	v_lshlrev_b32_e32 v66, 16, v67
	v_and_b32_e32 v67, 0xffff0000, v67
	v_lshlrev_b32_e32 v70, 16, v71
	v_and_b32_e32 v71, 0xffff0000, v71
	v_pk_fma_f32 v[62:63], v[62:63], v[66:67], v[70:71]
	v_lshlrev_b32_e32 v66, 16, v68
	v_and_b32_e32 v67, 0xffff0000, v68
	v_lshlrev_b32_e32 v70, 16, v72
	v_and_b32_e32 v71, 0xffff0000, v72
	v_pk_fma_f32 v[66:67], v[56:57], v[66:67], v[70:71]
	v_lshlrev_b32_e32 v56, 16, v69
	v_and_b32_e32 v57, 0xffff0000, v69
	v_lshlrev_b32_e32 v68, 16, v73
	v_and_b32_e32 v69, 0xffff0000, v73
	v_pk_fma_f32 v[60:61], v[60:61], v[76:77], v[78:79]
	v_pk_fma_f32 v[68:69], v[58:59], v[56:57], v[68:69]
	v_cvt_pk_bf16_f32 v56, v60, v61
	v_cvt_pk_bf16_f32 v57, v62, v63
	v_cvt_pk_bf16_f32 v58, v66, v67
	v_cvt_pk_bf16_f32 v59, v68, v69
	global_store_dwordx4 v[74:75], v[56:59], off
	v_pk_mul_f32 v[54:55], v[54:55], v[64:65] op_sel_hi:[1,0]
	v_pk_mul_f32 v[48:49], v[48:49], v[64:65] op_sel_hi:[1,0]
	v_lshl_add_u64 v[56:57], v[158:159], 0, s[2:3]
	v_lshl_add_u64 v[58:59], s[30:31], 0, v[56:57]
	v_lshl_add_u64 v[66:67], s[0:1], 0, v[56:57]
	s_nop 1
	v_mov_b32_e32 v60, v216
	v_mov_b32_e32 v61, v217
	v_mov_b32_e32 v62, v218
	v_mov_b32_e32 v63, v219
	v_mul_f32_e32 v54, 0xbfb8aa3b, v54
	s_nop 1
	v_mov_b32_e32 v56, v220
	v_mov_b32_e32 v57, v221
	v_mov_b32_e32 v58, v222
	v_mov_b32_e32 v59, v223
	v_add_u32_e32 v250, 0x58000, v249
	global_load_dwordx4 v[208:211], v250, s[30:31]
	global_load_dwordx4 v[212:215], v250, s[0:1]
	global_load_dwordx4 v[216:219], v250, s[30:31] offset:256
	global_load_dwordx4 v[220:223], v250, s[0:1] offset:256
	v_mul_f32_e32 v55, 0xbfb8aa3b, v55
	v_pk_mul_f32 v[52:53], v[52:53], v[64:65] op_sel_hi:[1,0]
	v_pk_mul_f32 v[50:51], v[50:51], v[64:65] op_sel_hi:[1,0]
	v_exp_f32_e32 v54, v54
	v_exp_f32_e32 v55, v55
	v_mul_f32_e32 v48, 0xbfb8aa3b, v48
	v_mul_f32_e32 v49, 0xbfb8aa3b, v49
	v_mul_f32_e32 v52, 0xbfb8aa3b, v52
	v_mul_f32_e32 v53, 0xbfb8aa3b, v53
	v_exp_f32_e32 v48, v48
	v_exp_f32_e32 v49, v49
	v_mul_f32_e32 v50, 0xbfb8aa3b, v50
	v_mul_f32_e32 v51, 0xbfb8aa3b, v51
	v_exp_f32_e32 v52, v52
	v_exp_f32_e32 v53, v53
	v_exp_f32_e32 v50, v50
	v_exp_f32_e32 v51, v51
	v_add_f32_e32 v54, 1.0, v54
	v_add_f32_e32 v55, 1.0, v55
	v_rcp_f32_e32 v54, v54
	v_rcp_f32_e32 v55, v55
	v_add_f32_e32 v48, 1.0, v48
	v_add_f32_e32 v49, 1.0, v49
	v_add_f32_e32 v52, 1.0, v52
	v_add_f32_e32 v53, 1.0, v53
	v_rcp_f32_e32 v48, v48
	v_rcp_f32_e32 v49, v49
	v_add_f32_e32 v50, 1.0, v50
	v_add_f32_e32 v51, 1.0, v51
	v_rcp_f32_e32 v52, v52
	v_rcp_f32_e32 v53, v53
	v_rcp_f32_e32 v50, v50
	v_rcp_f32_e32 v51, v51
	s_mov_b64 s[2:3], 0x48000
	v_lshlrev_b32_e32 v64, 16, v60
	v_and_b32_e32 v65, 0xffff0000, v60
	v_lshlrev_b32_e32 v68, 16, v56
	v_and_b32_e32 v69, 0xffff0000, v56
	v_lshlrev_b32_e32 v60, 16, v61
	v_and_b32_e32 v61, 0xffff0000, v61
	v_lshlrev_b32_e32 v56, 16, v57
	v_and_b32_e32 v57, 0xffff0000, v57
	v_pk_fma_f32 v[54:55], v[54:55], v[60:61], v[56:57]
	v_lshlrev_b32_e32 v56, 16, v62
	v_and_b32_e32 v57, 0xffff0000, v62
	v_lshlrev_b32_e32 v60, 16, v58
	v_and_b32_e32 v61, 0xffff0000, v58
	v_pk_fma_f32 v[56:57], v[48:49], v[56:57], v[60:61]
	v_lshlrev_b32_e32 v48, 16, v63
	v_and_b32_e32 v49, 0xffff0000, v63
	v_lshlrev_b32_e32 v58, 16, v59
	v_and_b32_e32 v59, 0xffff0000, v59
	v_pk_fma_f32 v[52:53], v[52:53], v[64:65], v[68:69]
	v_pk_fma_f32 v[58:59], v[50:51], v[48:49], v[58:59]
	v_cvt_pk_bf16_f32 v48, v52, v53
	v_cvt_pk_bf16_f32 v49, v54, v55
	v_cvt_pk_bf16_f32 v50, v56, v57
	v_cvt_pk_bf16_f32 v51, v58, v59
	global_store_dwordx4 v[66:67], v[48:51], off
	s_nop 1
	v_mov_b32_e32 v48, v246
	v_lshl_add_u64 v[54:55], v[158:159], 0, s[2:3]
	v_lshl_add_u64 v[50:51], s[30:31], 0, v[54:55]
	v_lshl_add_u64 v[58:59], s[0:1], 0, v[54:55]
	s_waitcnt vmcnt(13)
; __device__ __forceinline__ unsigned cvt_pk_bf16(float lo, float hi) { const f32x2_cv v = {lo, hi}; const bf16x2_cv b = __builtin_convertvector(v, bf16x2_cv); return __builtin_bit_cast(unsigned, b); }
; __device__ __forceinline__ float sigm(float x) { return __builtin_amdgcn_rcpf(1.0f + __expf(-x)); }
; __device__ __forceinline__ float lo16(unsigned w) { return __uint_as_float(w << 16); }
; __device__ __forceinline__ float hi16(unsigned w) { return __uint_as_float(w & 0xffff0000u); }
; __device__ __forceinline__ float rstd_of(const float* rowss, int row) { return rsqrtf(rowss[row] * (1.0f / 1024.0f) + 1e-6f); }
;     __device__ __forceinline__ void operator()(const f32x4 (&acc)[2][2][4][2], const pg8::Unit& u, int wr, int wc, int fr, int fq) const {
;     ...
;                 const int row = row0 + ai * 128 + m * 16;
;                 const float s = rstd_of(rowss, row);
; #pragma unroll
;                 for (int bj = 0; bj < 2; ++bj) {
;                     const size_t off = (size_t)row * 1024 + col0 + bj * 128;
;                     const u32x4 tv = *(const u32x4*)(Tm + off);
;                     u32x4 pv = (u32x4){0u, 0u, 0u, 0u};
;                     if (ACC) pv = *(const u32x4*)(M + off);
;                     const f32x4 a0 = acc[ai][bj][m][0] * s, a1 = acc[ai][bj][m][1] * s;
;                     float o[8];
;                     o[0] = sigm(a0[0]) * lo16(tv.x); o[1] = sigm(a0[1]) * hi16(tv.x); o[2] = sigm(a0[2]) * lo16(tv.y); o[3] = sigm(a0[3]) * hi16(tv.y);
;                     o[4] = sigm(a1[0]) * lo16(tv.z); o[5] = sigm(a1[1]) * hi16(tv.z); o[6] = sigm(a1[2]) * lo16(tv.w); o[7] = sigm(a1[3]) * hi16(tv.w);
;                     if (ACC) { o[0] += lo16(pv.x); o[1] += hi16(pv.x); o[2] += lo16(pv.y); o[3] += hi16(pv.y); o[4] += lo16(pv.z); o[5] += hi16(pv.z); o[6] += lo16(pv.w); o[7] += hi16(pv.w); }
;                     u32x4 w; w.x = cvt_pk_bf16(o[0], o[1]); w.y = cvt_pk_bf16(o[2], o[3]); w.z = cvt_pk_bf16(o[4], o[5]); w.w = cvt_pk_bf16(o[6], o[7]);
;                     *(u32x4*)(M + off) = w; } }
	s_nop 1
	v_mov_b32_e32 v50, v224
	v_mov_b32_e32 v51, v225
	v_mov_b32_e32 v52, v226
	v_mov_b32_e32 v53, v227
	s_mov_b64 s[2:3], 0x48100
	s_nop 1
	v_mov_b32_e32 v54, v228
	v_mov_b32_e32 v55, v229
	v_mov_b32_e32 v56, v230
	v_mov_b32_e32 v57, v231
	v_fmamk_f32 v48, v48, 0x3a800000, v187
	v_cmp_gt_f32_e32 vcc, s67, v48
	v_mul_f32_e32 v49, 0x4b800000, v48
	v_lshlrev_b32_e32 v60, 16, v50
	v_cndmask_b32_e32 v48, v48, v49, vcc
	v_rsq_f32_e32 v48, v48
	v_and_b32_e32 v61, 0xffff0000, v50
	v_lshlrev_b32_e32 v62, 16, v54
	v_and_b32_e32 v63, 0xffff0000, v54
	v_mul_f32_e32 v49, 0x45800000, v48
	v_cndmask_b32_e32 v48, v48, v49, vcc
	v_pk_mul_f32 v[46:47], v[46:47], v[48:49] op_sel_hi:[1,0]
	v_pk_mul_f32 v[40:41], v[40:41], v[48:49] op_sel_hi:[1,0]
	v_mul_f32_e32 v46, 0xbfb8aa3b, v46
	v_mul_f32_e32 v47, 0xbfb8aa3b, v47
	v_pk_mul_f32 v[44:45], v[44:45], v[48:49] op_sel_hi:[1,0]
	v_pk_mul_f32 v[42:43], v[42:43], v[48:49] op_sel_hi:[1,0]
	v_exp_f32_e32 v46, v46
	v_exp_f32_e32 v47, v47
	v_mul_f32_e32 v40, 0xbfb8aa3b, v40
	v_mul_f32_e32 v41, 0xbfb8aa3b, v41
	v_mul_f32_e32 v44, 0xbfb8aa3b, v44
	v_mul_f32_e32 v45, 0xbfb8aa3b, v45
	v_exp_f32_e32 v40, v40
	v_exp_f32_e32 v41, v41
	v_mul_f32_e32 v42, 0xbfb8aa3b, v42
	v_mul_f32_e32 v43, 0xbfb8aa3b, v43
	v_exp_f32_e32 v44, v44
	v_exp_f32_e32 v45, v45
	v_exp_f32_e32 v42, v42
	v_exp_f32_e32 v43, v43
	v_add_f32_e32 v46, 1.0, v46
	v_add_f32_e32 v47, 1.0, v47
	v_rcp_f32_e32 v46, v46
	v_rcp_f32_e32 v47, v47
	v_add_f32_e32 v40, 1.0, v40
	v_add_f32_e32 v41, 1.0, v41
	v_add_f32_e32 v44, 1.0, v44
	v_add_f32_e32 v45, 1.0, v45
	v_rcp_f32_e32 v40, v40
	v_rcp_f32_e32 v41, v41
	v_add_f32_e32 v42, 1.0, v42
	v_add_f32_e32 v43, 1.0, v43
	v_rcp_f32_e32 v44, v44
	v_rcp_f32_e32 v45, v45
	v_rcp_f32_e32 v42, v42
	v_rcp_f32_e32 v43, v43
	v_lshlrev_b32_e32 v50, 16, v51
	v_and_b32_e32 v51, 0xffff0000, v51
	v_lshlrev_b32_e32 v54, 16, v55
	v_and_b32_e32 v55, 0xffff0000, v55
	v_pk_fma_f32 v[46:47], v[46:47], v[50:51], v[54:55]
	v_lshlrev_b32_e32 v50, 16, v52
	v_and_b32_e32 v51, 0xffff0000, v52
	v_lshlrev_b32_e32 v54, 16, v56
	v_and_b32_e32 v55, 0xffff0000, v56
	v_pk_fma_f32 v[50:51], v[40:41], v[50:51], v[54:55]
	v_lshlrev_b32_e32 v40, 16, v53
	v_and_b32_e32 v41, 0xffff0000, v53
	v_lshlrev_b32_e32 v52, 16, v57
	v_and_b32_e32 v53, 0xffff0000, v57
	v_pk_fma_f32 v[44:45], v[44:45], v[60:61], v[62:63]
	v_pk_fma_f32 v[52:53], v[42:43], v[40:41], v[52:53]
	v_cvt_pk_bf16_f32 v40, v44, v45
	v_cvt_pk_bf16_f32 v41, v46, v47
	v_cvt_pk_bf16_f32 v42, v50, v51
	v_cvt_pk_bf16_f32 v43, v52, v53
	global_store_dwordx4 v[58:59], v[40:43], off
	v_pk_mul_f32 v[38:39], v[38:39], v[48:49] op_sel_hi:[1,0]
	v_pk_mul_f32 v[32:33], v[32:33], v[48:49] op_sel_hi:[1,0]
	v_lshl_add_u64 v[40:41], v[158:159], 0, s[2:3]
	v_lshl_add_u64 v[42:43], s[30:31], 0, v[40:41]
	v_lshl_add_u64 v[50:51], s[0:1], 0, v[40:41]
	s_nop 1
	v_mov_b32_e32 v44, v232
	v_mov_b32_e32 v45, v233
	v_mov_b32_e32 v46, v234
	v_mov_b32_e32 v47, v235
	v_mul_f32_e32 v38, 0xbfb8aa3b, v38
	s_nop 1
	v_mov_b32_e32 v40, v236
	v_mov_b32_e32 v41, v237
	v_mov_b32_e32 v42, v238
	v_mov_b32_e32 v43, v239
	v_mul_f32_e32 v39, 0xbfb8aa3b, v39
	v_pk_mul_f32 v[36:37], v[36:37], v[48:49] op_sel_hi:[1,0]
	v_pk_mul_f32 v[34:35], v[34:35], v[48:49] op_sel_hi:[1,0]
	v_exp_f32_e32 v38, v38
	v_exp_f32_e32 v39, v39
	v_mul_f32_e32 v32, 0xbfb8aa3b, v32
	v_mul_f32_e32 v33, 0xbfb8aa3b, v33
	v_mul_f32_e32 v36, 0xbfb8aa3b, v36
	v_mul_f32_e32 v37, 0xbfb8aa3b, v37
	v_exp_f32_e32 v32, v32
	v_exp_f32_e32 v33, v33
	v_mul_f32_e32 v34, 0xbfb8aa3b, v34
	v_mul_f32_e32 v35, 0xbfb8aa3b, v35
	v_exp_f32_e32 v36, v36
	v_exp_f32_e32 v37, v37
	v_exp_f32_e32 v34, v34
	v_exp_f32_e32 v35, v35
	v_add_f32_e32 v38, 1.0, v38
	v_add_f32_e32 v39, 1.0, v39
	v_rcp_f32_e32 v38, v38
	v_rcp_f32_e32 v39, v39
	v_add_f32_e32 v32, 1.0, v32
	v_add_f32_e32 v33, 1.0, v33
	v_add_f32_e32 v36, 1.0, v36
	v_add_f32_e32 v37, 1.0, v37
	v_rcp_f32_e32 v32, v32
	v_rcp_f32_e32 v33, v33
	v_add_f32_e32 v34, 1.0, v34
	v_add_f32_e32 v35, 1.0, v35
	v_rcp_f32_e32 v36, v36
	v_rcp_f32_e32 v37, v37
	v_rcp_f32_e32 v34, v34
	v_rcp_f32_e32 v35, v35
	s_mov_b64 s[2:3], 0x50000
	v_lshlrev_b32_e32 v48, 16, v44
	v_and_b32_e32 v49, 0xffff0000, v44
	v_lshlrev_b32_e32 v52, 16, v40
	v_and_b32_e32 v53, 0xffff0000, v40
	v_lshlrev_b32_e32 v44, 16, v45
	v_and_b32_e32 v45, 0xffff0000, v45
	v_lshlrev_b32_e32 v40, 16, v41
	v_and_b32_e32 v41, 0xffff0000, v41
	v_pk_fma_f32 v[38:39], v[38:39], v[44:45], v[40:41]
	v_lshlrev_b32_e32 v40, 16, v46
	v_and_b32_e32 v41, 0xffff0000, v46
	v_lshlrev_b32_e32 v44, 16, v42
	v_and_b32_e32 v45, 0xffff0000, v42
	v_pk_fma_f32 v[40:41], v[32:33], v[40:41], v[44:45]
	v_lshlrev_b32_e32 v32, 16, v47
	v_and_b32_e32 v33, 0xffff0000, v47
	v_lshlrev_b32_e32 v42, 16, v43
	v_and_b32_e32 v43, 0xffff0000, v43
	v_pk_fma_f32 v[36:37], v[36:37], v[48:49], v[52:53]
	v_pk_fma_f32 v[42:43], v[34:35], v[32:33], v[42:43]
	v_cvt_pk_bf16_f32 v32, v36, v37
	v_cvt_pk_bf16_f32 v33, v38, v39
	v_cvt_pk_bf16_f32 v34, v40, v41
	v_cvt_pk_bf16_f32 v35, v42, v43
	global_store_dwordx4 v[50:51], v[32:35], off
	s_nop 1
	v_mov_b32_e32 v32, v247
	v_lshl_add_u64 v[38:39], v[158:159], 0, s[2:3]
	v_lshl_add_u64 v[34:35], s[30:31], 0, v[38:39]
	v_lshl_add_u64 v[42:43], s[0:1], 0, v[38:39]
	s_waitcnt vmcnt(9)
; __device__ __forceinline__ unsigned cvt_pk_bf16(float lo, float hi) { const f32x2_cv v = {lo, hi}; const bf16x2_cv b = __builtin_convertvector(v, bf16x2_cv); return __builtin_bit_cast(unsigned, b); }
; __device__ __forceinline__ float sigm(float x) { return __builtin_amdgcn_rcpf(1.0f + __expf(-x)); }
; __device__ __forceinline__ float lo16(unsigned w) { return __uint_as_float(w << 16); }
; __device__ __forceinline__ float hi16(unsigned w) { return __uint_as_float(w & 0xffff0000u); }
; __device__ __forceinline__ float rstd_of(const float* rowss, int row) { return rsqrtf(rowss[row] * (1.0f / 1024.0f) + 1e-6f); }
;     __device__ __forceinline__ void operator()(const f32x4 (&acc)[2][2][4][2], const pg8::Unit& u, int wr, int wc, int fr, int fq) const {
;     ...
;                 const int row = row0 + ai * 128 + m * 16;
;                 const float s = rstd_of(rowss, row);
; #pragma unroll
;                 for (int bj = 0; bj < 2; ++bj) {
;                     const size_t off = (size_t)row * 1024 + col0 + bj * 128;
;                     const u32x4 tv = *(const u32x4*)(Tm + off);
;                     u32x4 pv = (u32x4){0u, 0u, 0u, 0u};
;                     if (ACC) pv = *(const u32x4*)(M + off);
;                     const f32x4 a0 = acc[ai][bj][m][0] * s, a1 = acc[ai][bj][m][1] * s;
;                     float o[8];
;                     o[0] = sigm(a0[0]) * lo16(tv.x); o[1] = sigm(a0[1]) * hi16(tv.x); o[2] = sigm(a0[2]) * lo16(tv.y); o[3] = sigm(a0[3]) * hi16(tv.y);
;                     o[4] = sigm(a1[0]) * lo16(tv.z); o[5] = sigm(a1[1]) * hi16(tv.z); o[6] = sigm(a1[2]) * lo16(tv.w); o[7] = sigm(a1[3]) * hi16(tv.w);
;                     if (ACC) { o[0] += lo16(pv.x); o[1] += hi16(pv.x); o[2] += lo16(pv.y); o[3] += hi16(pv.y); o[4] += lo16(pv.z); o[5] += hi16(pv.z); o[6] += lo16(pv.w); o[7] += hi16(pv.w); }
;                     u32x4 w; w.x = cvt_pk_bf16(o[0], o[1]); w.y = cvt_pk_bf16(o[2], o[3]); w.z = cvt_pk_bf16(o[4], o[5]); w.w = cvt_pk_bf16(o[6], o[7]);
;                     *(u32x4*)(M + off) = w; } }
	s_nop 1
	v_mov_b32_e32 v34, v192
	v_mov_b32_e32 v35, v193
	v_mov_b32_e32 v36, v194
	v_mov_b32_e32 v37, v195
	s_mov_b64 s[2:3], 0x50100
	s_nop 1
	v_mov_b32_e32 v38, v196
	v_mov_b32_e32 v39, v197
	v_mov_b32_e32 v40, v198
	v_mov_b32_e32 v41, v199
	v_fmamk_f32 v32, v32, 0x3a800000, v187
	v_cmp_gt_f32_e32 vcc, s67, v32
	v_mul_f32_e32 v33, 0x4b800000, v32
	v_lshlrev_b32_e32 v44, 16, v34
	v_cndmask_b32_e32 v32, v32, v33, vcc
	v_rsq_f32_e32 v32, v32
	v_and_b32_e32 v45, 0xffff0000, v34
	v_lshlrev_b32_e32 v46, 16, v38
	v_and_b32_e32 v47, 0xffff0000, v38
	v_mul_f32_e32 v33, 0x45800000, v32
	v_cndmask_b32_e32 v32, v32, v33, vcc
	v_pk_mul_f32 v[30:31], v[30:31], v[32:33] op_sel_hi:[1,0]
	v_pk_mul_f32 v[24:25], v[24:25], v[32:33] op_sel_hi:[1,0]
	v_mul_f32_e32 v30, 0xbfb8aa3b, v30
	v_mul_f32_e32 v31, 0xbfb8aa3b, v31
	v_pk_mul_f32 v[28:29], v[28:29], v[32:33] op_sel_hi:[1,0]
	v_pk_mul_f32 v[26:27], v[26:27], v[32:33] op_sel_hi:[1,0]
	v_exp_f32_e32 v30, v30
	v_exp_f32_e32 v31, v31
	v_mul_f32_e32 v24, 0xbfb8aa3b, v24
	v_mul_f32_e32 v25, 0xbfb8aa3b, v25
	v_mul_f32_e32 v28, 0xbfb8aa3b, v28
	v_mul_f32_e32 v29, 0xbfb8aa3b, v29
	v_exp_f32_e32 v24, v24
	v_exp_f32_e32 v25, v25
	v_mul_f32_e32 v26, 0xbfb8aa3b, v26
	v_mul_f32_e32 v27, 0xbfb8aa3b, v27
	v_exp_f32_e32 v28, v28
	v_exp_f32_e32 v29, v29
	v_exp_f32_e32 v26, v26
	v_exp_f32_e32 v27, v27
	v_add_f32_e32 v30, 1.0, v30
	v_add_f32_e32 v31, 1.0, v31
	v_rcp_f32_e32 v30, v30
	v_rcp_f32_e32 v31, v31
	v_add_f32_e32 v24, 1.0, v24
	v_add_f32_e32 v25, 1.0, v25
	v_add_f32_e32 v28, 1.0, v28
	v_add_f32_e32 v29, 1.0, v29
	v_rcp_f32_e32 v24, v24
	v_rcp_f32_e32 v25, v25
	v_add_f32_e32 v26, 1.0, v26
	v_add_f32_e32 v27, 1.0, v27
	v_rcp_f32_e32 v28, v28
	v_rcp_f32_e32 v29, v29
	v_rcp_f32_e32 v26, v26
	v_rcp_f32_e32 v27, v27
	v_lshlrev_b32_e32 v34, 16, v35
	v_and_b32_e32 v35, 0xffff0000, v35
	v_lshlrev_b32_e32 v38, 16, v39
	v_and_b32_e32 v39, 0xffff0000, v39
	v_pk_fma_f32 v[30:31], v[30:31], v[34:35], v[38:39]
	v_lshlrev_b32_e32 v34, 16, v36
	v_and_b32_e32 v35, 0xffff0000, v36
	v_lshlrev_b32_e32 v38, 16, v40
	v_and_b32_e32 v39, 0xffff0000, v40
	v_pk_fma_f32 v[34:35], v[24:25], v[34:35], v[38:39]
	v_lshlrev_b32_e32 v24, 16, v37
	v_and_b32_e32 v25, 0xffff0000, v37
	v_lshlrev_b32_e32 v36, 16, v41
	v_and_b32_e32 v37, 0xffff0000, v41
	v_pk_fma_f32 v[28:29], v[28:29], v[44:45], v[46:47]
	v_pk_fma_f32 v[36:37], v[26:27], v[24:25], v[36:37]
	v_cvt_pk_bf16_f32 v24, v28, v29
	v_cvt_pk_bf16_f32 v25, v30, v31
	v_cvt_pk_bf16_f32 v26, v34, v35
	v_cvt_pk_bf16_f32 v27, v36, v37
	global_store_dwordx4 v[42:43], v[24:27], off
	v_pk_mul_f32 v[22:23], v[22:23], v[32:33] op_sel_hi:[1,0]
	v_pk_mul_f32 v[16:17], v[16:17], v[32:33] op_sel_hi:[1,0]
	v_lshl_add_u64 v[24:25], v[158:159], 0, s[2:3]
	v_lshl_add_u64 v[26:27], s[30:31], 0, v[24:25]
	v_lshl_add_u64 v[34:35], s[0:1], 0, v[24:25]
	s_nop 1
	v_mov_b32_e32 v28, v200
	v_mov_b32_e32 v29, v201
	v_mov_b32_e32 v30, v202
	v_mov_b32_e32 v31, v203
	v_mul_f32_e32 v22, 0xbfb8aa3b, v22
	s_nop 1
	v_mov_b32_e32 v24, v204
	v_mov_b32_e32 v25, v205
	v_mov_b32_e32 v26, v206
	v_mov_b32_e32 v27, v207
	v_mul_f32_e32 v23, 0xbfb8aa3b, v23
	v_pk_mul_f32 v[20:21], v[20:21], v[32:33] op_sel_hi:[1,0]
	v_pk_mul_f32 v[18:19], v[18:19], v[32:33] op_sel_hi:[1,0]
	v_exp_f32_e32 v22, v22
	v_exp_f32_e32 v23, v23
	v_mul_f32_e32 v16, 0xbfb8aa3b, v16
	v_mul_f32_e32 v17, 0xbfb8aa3b, v17
	v_mul_f32_e32 v20, 0xbfb8aa3b, v20
	v_mul_f32_e32 v21, 0xbfb8aa3b, v21
	v_exp_f32_e32 v16, v16
	v_exp_f32_e32 v17, v17
	v_mul_f32_e32 v18, 0xbfb8aa3b, v18
	v_mul_f32_e32 v19, 0xbfb8aa3b, v19
	v_exp_f32_e32 v20, v20
	v_exp_f32_e32 v21, v21
	v_exp_f32_e32 v18, v18
	v_exp_f32_e32 v19, v19
	v_add_f32_e32 v22, 1.0, v22
	v_add_f32_e32 v23, 1.0, v23
	v_rcp_f32_e32 v22, v22
	v_rcp_f32_e32 v23, v23
	v_add_f32_e32 v16, 1.0, v16
	v_add_f32_e32 v17, 1.0, v17
	v_add_f32_e32 v20, 1.0, v20
	v_add_f32_e32 v21, 1.0, v21
	v_rcp_f32_e32 v16, v16
	v_rcp_f32_e32 v17, v17
	v_add_f32_e32 v18, 1.0, v18
	v_add_f32_e32 v19, 1.0, v19
	v_rcp_f32_e32 v20, v20
	v_rcp_f32_e32 v21, v21
	v_rcp_f32_e32 v18, v18
	v_rcp_f32_e32 v19, v19
	s_mov_b64 s[2:3], 0x58000
	v_lshlrev_b32_e32 v32, 16, v28
	v_and_b32_e32 v33, 0xffff0000, v28
	v_lshlrev_b32_e32 v36, 16, v24
	v_and_b32_e32 v37, 0xffff0000, v24
	v_lshlrev_b32_e32 v28, 16, v29
	v_and_b32_e32 v29, 0xffff0000, v29
	v_lshlrev_b32_e32 v24, 16, v25
	v_and_b32_e32 v25, 0xffff0000, v25
	v_pk_fma_f32 v[22:23], v[22:23], v[28:29], v[24:25]
	v_lshlrev_b32_e32 v24, 16, v30
	v_and_b32_e32 v25, 0xffff0000, v30
	v_lshlrev_b32_e32 v28, 16, v26
	v_and_b32_e32 v29, 0xffff0000, v26
	v_pk_fma_f32 v[24:25], v[16:17], v[24:25], v[28:29]
	v_lshlrev_b32_e32 v16, 16, v31
	v_and_b32_e32 v17, 0xffff0000, v31
	v_lshlrev_b32_e32 v26, 16, v27
	v_and_b32_e32 v27, 0xffff0000, v27
	v_pk_fma_f32 v[20:21], v[20:21], v[32:33], v[36:37]
	v_pk_fma_f32 v[26:27], v[18:19], v[16:17], v[26:27]
	v_cvt_pk_bf16_f32 v16, v20, v21
	v_cvt_pk_bf16_f32 v17, v22, v23
	v_cvt_pk_bf16_f32 v18, v24, v25
	v_cvt_pk_bf16_f32 v19, v26, v27
	global_store_dwordx4 v[34:35], v[16:19], off
	s_nop 1
	v_mov_b32_e32 v16, v248
	v_lshl_add_u64 v[22:23], v[158:159], 0, s[2:3]
	v_lshl_add_u64 v[18:19], s[30:31], 0, v[22:23]
	v_lshl_add_u64 v[26:27], s[0:1], 0, v[22:23]
	s_waitcnt vmcnt(5)
; __device__ __forceinline__ unsigned cvt_pk_bf16(float lo, float hi) { const f32x2_cv v = {lo, hi}; const bf16x2_cv b = __builtin_convertvector(v, bf16x2_cv); return __builtin_bit_cast(unsigned, b); }
; #define PG8_WAIT_V(n) asm volatile("s_waitcnt vmcnt(" #n ")" ::: "memory")
; #define PG8_BAR __builtin_amdgcn_s_barrier()
; template <class Epi, class Sched, bool STAMP = false>
; __device__ __forceinline__ void gemm_phase(PG8_LAS unsigned char* lds, const Gemm g, const Sched& S, const Epi& E, unsigned long long* stamps) {
;     ...
;         if (!has_next) break;
; #pragma unroll
;         for (int a = 0; a < 2; ++a)
; #pragma unroll
;             for (int b = 0; b < 2; ++b)
; #pragma unroll
;                 for (int m = 0; m < 4; ++m)
; #pragma unroll
;                     for (int n = 0; n < 2; ++n) acc[a][b][m][n] = (f32x4){0.f, 0.f, 0.f, 0.f};
;         cur = nxt; cA = nA; cB = nB; ++ui;
;     }
;     PG8_WAIT_V(0);
;     if (wr == 0) PG8_BAR;
;     __device__ __forceinline__ void operator()(const f32x4 (&acc)[2][2][4][2], const pg8::Unit& u, int wr, int wc, int fr, int fq) const {
;     ...
;                 const int row = row0 + ai * 128 + m * 16;
;                 const float s = rstd_of(rowss, row);
; #pragma unroll
;                 for (int bj = 0; bj < 2; ++bj) {
;                     const size_t off = (size_t)row * 1024 + col0 + bj * 128;
;                     const u32x4 tv = *(const u32x4*)(Tm + off);
;                     u32x4 pv = (u32x4){0u, 0u, 0u, 0u};
;                     if (ACC) pv = *(const u32x4*)(M + off);
;                     const f32x4 a0 = acc[ai][bj][m][0] * s, a1 = acc[ai][bj][m][1] * s;
;                     float o[8];
;                     o[0] = sigm(a0[0]) * lo16(tv.x); o[1] = sigm(a0[1]) * hi16(tv.x); o[2] = sigm(a0[2]) * lo16(tv.y); o[3] = sigm(a0[3]) * hi16(tv.y);
;                     o[4] = sigm(a1[0]) * lo16(tv.z); o[5] = sigm(a1[1]) * hi16(tv.z); o[6] = sigm(a1[2]) * lo16(tv.w); o[7] = sigm(a1[3]) * hi16(tv.w);
;                     if (ACC) { o[0] += lo16(pv.x); o[1] += hi16(pv.x); o[2] += lo16(pv.y); o[3] += hi16(pv.y); o[4] += lo16(pv.z); o[5] += hi16(pv.z); o[6] += lo16(pv.w); o[7] += hi16(pv.w); }
;                     u32x4 w; w.x = cvt_pk_bf16(o[0], o[1]); w.y = cvt_pk_bf16(o[2], o[3]); w.z = cvt_pk_bf16(o[4], o[5]); w.w = cvt_pk_bf16(o[6], o[7]);
;                     *(u32x4*)(M + off) = w; } }
	s_nop 1
	v_mov_b32_e32 v18, v208
	v_mov_b32_e32 v19, v209
	v_mov_b32_e32 v20, v210
	v_mov_b32_e32 v21, v211
	s_mov_b64 s[2:3], 0x58100
	s_nop 1
	v_mov_b32_e32 v22, v212
	v_mov_b32_e32 v23, v213
	v_mov_b32_e32 v24, v214
	v_mov_b32_e32 v25, v215
	v_fmamk_f32 v16, v16, 0x3a800000, v187
	v_cmp_gt_f32_e32 vcc, s67, v16
	v_mul_f32_e32 v17, 0x4b800000, v16
	v_lshlrev_b32_e32 v28, 16, v18
	v_cndmask_b32_e32 v16, v16, v17, vcc
	v_rsq_f32_e32 v16, v16
	v_and_b32_e32 v29, 0xffff0000, v18
	v_lshlrev_b32_e32 v30, 16, v22
	v_and_b32_e32 v31, 0xffff0000, v22
	v_mul_f32_e32 v17, 0x45800000, v16
	v_cndmask_b32_e32 v16, v16, v17, vcc
	v_pk_mul_f32 v[14:15], v[14:15], v[16:17] op_sel_hi:[1,0]
	v_pk_mul_f32 v[8:9], v[8:9], v[16:17] op_sel_hi:[1,0]
	v_mul_f32_e32 v14, 0xbfb8aa3b, v14
	v_mul_f32_e32 v15, 0xbfb8aa3b, v15
	v_pk_mul_f32 v[12:13], v[12:13], v[16:17] op_sel_hi:[1,0]
	v_pk_mul_f32 v[10:11], v[10:11], v[16:17] op_sel_hi:[1,0]
	v_exp_f32_e32 v14, v14
	v_exp_f32_e32 v15, v15
	v_mul_f32_e32 v8, 0xbfb8aa3b, v8
	v_mul_f32_e32 v9, 0xbfb8aa3b, v9
	v_mul_f32_e32 v12, 0xbfb8aa3b, v12
	v_mul_f32_e32 v13, 0xbfb8aa3b, v13
	v_exp_f32_e32 v8, v8
	v_exp_f32_e32 v9, v9
	v_mul_f32_e32 v10, 0xbfb8aa3b, v10
	v_mul_f32_e32 v11, 0xbfb8aa3b, v11
	v_exp_f32_e32 v12, v12
	v_exp_f32_e32 v13, v13
	v_exp_f32_e32 v10, v10
	v_exp_f32_e32 v11, v11
	v_add_f32_e32 v14, 1.0, v14
	v_add_f32_e32 v15, 1.0, v15
	v_rcp_f32_e32 v14, v14
	v_rcp_f32_e32 v15, v15
	v_add_f32_e32 v8, 1.0, v8
	v_add_f32_e32 v9, 1.0, v9
	v_add_f32_e32 v12, 1.0, v12
	v_add_f32_e32 v13, 1.0, v13
	v_rcp_f32_e32 v8, v8
	v_rcp_f32_e32 v9, v9
	v_add_f32_e32 v10, 1.0, v10
	v_add_f32_e32 v11, 1.0, v11
	v_rcp_f32_e32 v12, v12
	v_rcp_f32_e32 v13, v13
	v_rcp_f32_e32 v10, v10
	v_rcp_f32_e32 v11, v11
	v_lshlrev_b32_e32 v18, 16, v19
	v_and_b32_e32 v19, 0xffff0000, v19
	v_lshlrev_b32_e32 v22, 16, v23
	v_and_b32_e32 v23, 0xffff0000, v23
	v_pk_fma_f32 v[14:15], v[14:15], v[18:19], v[22:23]
	v_lshlrev_b32_e32 v18, 16, v20
	v_and_b32_e32 v19, 0xffff0000, v20
	v_lshlrev_b32_e32 v22, 16, v24
	v_and_b32_e32 v23, 0xffff0000, v24
	v_pk_fma_f32 v[18:19], v[8:9], v[18:19], v[22:23]
	v_lshlrev_b32_e32 v8, 16, v21
	v_and_b32_e32 v9, 0xffff0000, v21
	v_lshlrev_b32_e32 v20, 16, v25
	v_and_b32_e32 v21, 0xffff0000, v25
	v_pk_fma_f32 v[12:13], v[12:13], v[28:29], v[30:31]
	v_pk_fma_f32 v[20:21], v[10:11], v[8:9], v[20:21]
	v_cvt_pk_bf16_f32 v8, v12, v13
	v_cvt_pk_bf16_f32 v9, v14, v15
	v_cvt_pk_bf16_f32 v10, v18, v19
	v_cvt_pk_bf16_f32 v11, v20, v21
	global_store_dwordx4 v[26:27], v[8:11], off
	v_pk_mul_f32 v[6:7], v[6:7], v[16:17] op_sel_hi:[1,0]
	v_pk_mul_f32 v[0:1], v[0:1], v[16:17] op_sel_hi:[1,0]
	v_lshl_add_u64 v[8:9], v[158:159], 0, s[2:3]
	v_lshl_add_u64 v[10:11], s[30:31], 0, v[8:9]
	v_lshl_add_u64 v[18:19], s[0:1], 0, v[8:9]
	s_nop 1
	v_mov_b32_e32 v12, v216
	v_mov_b32_e32 v13, v217
	v_mov_b32_e32 v14, v218
	v_mov_b32_e32 v15, v219
	v_mul_f32_e32 v6, 0xbfb8aa3b, v6
	s_nop 1
	v_mov_b32_e32 v8, v220
	v_mov_b32_e32 v9, v221
	v_mov_b32_e32 v10, v222
	v_mov_b32_e32 v11, v223
	v_mul_f32_e32 v7, 0xbfb8aa3b, v7
	v_pk_mul_f32 v[4:5], v[4:5], v[16:17] op_sel_hi:[1,0]
	v_pk_mul_f32 v[2:3], v[2:3], v[16:17] op_sel_hi:[1,0]
	v_exp_f32_e32 v6, v6
	v_exp_f32_e32 v7, v7
	v_mul_f32_e32 v0, 0xbfb8aa3b, v0
	v_mul_f32_e32 v1, 0xbfb8aa3b, v1
	v_mul_f32_e32 v4, 0xbfb8aa3b, v4
	v_mul_f32_e32 v5, 0xbfb8aa3b, v5
	v_exp_f32_e32 v0, v0
	v_exp_f32_e32 v1, v1
	v_mul_f32_e32 v2, 0xbfb8aa3b, v2
	v_mul_f32_e32 v3, 0xbfb8aa3b, v3
	v_exp_f32_e32 v4, v4
	v_exp_f32_e32 v5, v5
	v_exp_f32_e32 v2, v2
	v_exp_f32_e32 v3, v3
	v_add_f32_e32 v6, 1.0, v6
	v_add_f32_e32 v7, 1.0, v7
	v_rcp_f32_e32 v6, v6
	v_rcp_f32_e32 v7, v7
	v_add_f32_e32 v0, 1.0, v0
	v_add_f32_e32 v1, 1.0, v1
	v_add_f32_e32 v4, 1.0, v4
	v_add_f32_e32 v5, 1.0, v5
	v_rcp_f32_e32 v0, v0
	v_rcp_f32_e32 v1, v1
	v_add_f32_e32 v2, 1.0, v2
	v_add_f32_e32 v3, 1.0, v3
	v_rcp_f32_e32 v4, v4
	v_rcp_f32_e32 v5, v5
	v_rcp_f32_e32 v2, v2
	v_rcp_f32_e32 v3, v3
	s_and_b64 vcc, exec, s[38:39]
	s_mov_b32 s3, s26
	s_mov_b32 s2, s12
	v_lshlrev_b32_e32 v16, 16, v12
	v_and_b32_e32 v17, 0xffff0000, v12
	v_lshlrev_b32_e32 v20, 16, v8
	v_and_b32_e32 v21, 0xffff0000, v8
	v_lshlrev_b32_e32 v12, 16, v13
	v_and_b32_e32 v13, 0xffff0000, v13
	v_lshlrev_b32_e32 v8, 16, v9
	v_and_b32_e32 v9, 0xffff0000, v9
	v_pk_fma_f32 v[6:7], v[6:7], v[12:13], v[8:9]
	v_lshlrev_b32_e32 v8, 16, v14
	v_and_b32_e32 v9, 0xffff0000, v14
	v_lshlrev_b32_e32 v12, 16, v10
	v_and_b32_e32 v13, 0xffff0000, v10
	v_pk_fma_f32 v[8:9], v[0:1], v[8:9], v[12:13]
	v_lshlrev_b32_e32 v0, 16, v15
	v_and_b32_e32 v1, 0xffff0000, v15
	v_lshlrev_b32_e32 v10, 16, v11
	v_and_b32_e32 v11, 0xffff0000, v11
	v_pk_fma_f32 v[4:5], v[4:5], v[16:17], v[20:21]
	v_pk_fma_f32 v[10:11], v[2:3], v[0:1], v[10:11]
	v_cvt_pk_bf16_f32 v0, v4, v5
	v_cvt_pk_bf16_f32 v1, v6, v7
	v_cvt_pk_bf16_f32 v2, v8, v9
	v_cvt_pk_bf16_f32 v3, v10, v11
	global_store_dwordx4 v[18:19], v[0:3], off
	s_cbranch_vccz .LBB0_346
	s_cmpk_gt_u32 s70, 0xff
	s_cbranch_scc1 .LBB0_357
	s_barrier

; #define PG8_STAGE(bufoff, gbase, voff) do { _Pragma("unroll") for (int _i = 0; _i < 2; ++_i) \
;         __builtin_amdgcn_global_load_lds((const unsigned*)((const char*)(gbase) + (voff)[_i]), (PG8_LAS unsigned*)(lds + (bufoff) + ldsw + _i * 8192), 16, 0, 0); } while (0)
; #define PG8_LDA(dst, b, h) do { _Pragma("unroll") for (int m = 0; m < 4; ++m) _Pragma("unroll") for (int k = 0; k < 2; ++k) dst[m][k] = *(const PG8_LAS bf16x8*)(lds + PG8_SA(b, h) + aoff + m * 2048 + k * 1024); } while (0)
; #define PG8_LDB(dst, b, h) do { _Pragma("unroll") for (int n = 0; n < 2; ++n) _Pragma("unroll") for (int k = 0; k < 2; ++k) dst[n][k] = *(const PG8_LAS bf16x8*)(lds + PG8_SB(b, h) + boff + n * 2048 + k * 1024); } while (0)
; #define PG8_MMA(ai, bj, At, Bt) do { __builtin_amdgcn_s_setprio(1); _Pragma("unroll") for (int m = 0; m < 4; ++m) _Pragma("unroll") for (int n = 0; n < 2; ++n) _Pragma("unroll") for (int k = 0; k < 2; ++k) \
;         acc[ai][bj][m][n] = __builtin_amdgcn_mfma_f32_16x16x32_bf16(Bt[n][k], At[m][k], acc[ai][bj][m][n], 0, 0, 0); __builtin_amdgcn_s_setprio(0); } while (0)
; #define PG8_WAIT_V(n) asm volatile("s_waitcnt vmcnt(" #n ")" ::: "memory")
; template <class Epi, class Sched, bool STAMP = false>
; __device__ __forceinline__ void gemm_phase(PG8_LAS unsigned char* lds, const Gemm g, const Sched& S, const Epi& E, unsigned long long* stamps) {
;     ...
;             const bool last = (t == nt - 2);
;             const char* a1 = cA + (size_t)(t + 1) * kstep;
;             const char* a2 = last ? nA : cA + (size_t)(t + 2) * kstep; const char* b2 = last ? nB : cB + (size_t)(t + 2) * kstep;
;             const char* a3 = a2 + kstep; const char* b3 = b2 + kstep;
;             if (last && has_next) S.a_ready(nxt);
;             PG8_LDB(B0, 0, 0); PG8_SCHED; PG8_LDA(At, 0, 0); PG8_STAGE(PG8_SA(1, 1), a1 + hstep, voffA);
;             PG8_WAIT_L(8); PG8_BAR; PG8_WAIT_L(0); PG8_MMA(0, 0, At, B0); PG8_BAR; PG8_SCHED;
;             PG8_LDB(B1, 0, 1); PG8_STAGE(PG8_SB(0, 0), b2, voffB);
;             PG8_BAR; PG8_WAIT_L(0); PG8_MMA(0, 1, At, B1); PG8_BAR;
;             PG8_LDA(At, 0, 1); PG8_STAGE(PG8_SA(0, 0), a2, voffA);
;             PG8_BAR; PG8_WAIT_L(0); PG8_MMA(1, 0, At, B0); PG8_BAR; PG8_SCHED;
;             PG8_STAGE(PG8_SB(0, 1), b2 + hstep, voffB);
;             PG8_WAIT_V(6); PG8_BAR; PG8_MMA(1, 1, At, B1); PG8_BAR;
.LBB0_495:
	s_add_u32 s14, s24, 0xfffc0080
	s_addc_u32 s15, s25, -1
	s_add_i32 s16, 0, 0x10000
	ds_read_b128 v[158:161], v248
	ds_read_b128 v[162:165], v248 offset:1024
	ds_read_b128 v[170:173], v248 offset:2048
	ds_read_b128 v[174:177], v248 offset:3072
	s_cmp_eq_u32 s61, 12
	s_cselect_b32 s31, s7, s15
	s_cselect_b32 s30, s57, s14
	s_cselect_b32 s27, s5, s60
	s_cselect_b32 s26, s58, s59
	s_add_i32 m0, s23, 0xc000
	ds_read_b128 v[178:181], v168
	ds_read_b128 v[192:195], v168 offset:1024
	ds_read_b128 v[196:199], v168 offset:2048
	ds_read_b128 v[200:203], v168 offset:3072
	ds_read_b128 v[204:207], v168 offset:4096
	ds_read_b128 v[208:211], v168 offset:5120
	ds_read_b128 v[212:215], v168 offset:6144
	global_load_lds_dwordx4 v154, s[24:25]
	s_add_i32 m0, s23, 0xe000
	ds_read_b128 v[216:219], v168 offset:7168
	global_load_lds_dwordx4 v156, s[24:25]
	s_waitcnt lgkmcnt(8)
	s_barrier
	s_waitcnt lgkmcnt(0)
	v_mfma_f32_16x16x32_bf16 v[124:127], v[158:161], v[178:181], v[124:127]
	v_mfma_f32_16x16x32_bf16 v[120:123], v[170:173], v[178:181], v[120:123]
	v_mfma_f32_16x16x32_bf16 v[108:111], v[158:161], v[196:199], v[108:111]
	v_mfma_f32_16x16x32_bf16 v[104:107], v[170:173], v[196:199], v[104:107]
	v_mfma_f32_16x16x32_bf16 v[92:95], v[158:161], v[204:207], v[92:95]
	v_mfma_f32_16x16x32_bf16 v[88:91], v[170:173], v[204:207], v[88:91]
	v_mfma_f32_16x16x32_bf16 v[76:79], v[158:161], v[212:215], v[76:79]
	v_mfma_f32_16x16x32_bf16 v[72:75], v[170:173], v[212:215], v[72:75]
	v_mfma_f32_16x16x32_bf16 v[124:127], v[162:165], v[192:195], v[124:127]
	v_mfma_f32_16x16x32_bf16 v[120:123], v[174:177], v[192:195], v[120:123]
	v_mfma_f32_16x16x32_bf16 v[108:111], v[162:165], v[200:203], v[108:111]
	v_mfma_f32_16x16x32_bf16 v[104:107], v[174:177], v[200:203], v[104:107]
	v_mfma_f32_16x16x32_bf16 v[92:95], v[162:165], v[208:211], v[92:95]
	v_mfma_f32_16x16x32_bf16 v[88:91], v[174:177], v[208:211], v[88:91]
	v_mfma_f32_16x16x32_bf16 v[76:79], v[162:165], v[216:219], v[76:79]
	v_mfma_f32_16x16x32_bf16 v[72:75], v[174:177], v[216:219], v[72:75]
	s_barrier
	s_add_i32 s17, 0, 0x14000
	s_add_i32 s14, s16, s43
	s_mov_b32 m0, s14
	ds_read_b128 v[220:223], v249
	ds_read_b128 v[224:227], v249 offset:1024
	ds_read_b128 v[228:231], v249 offset:2048
	global_load_lds_dwordx4 v128, s[26:27]
	s_add_i32 m0, s14, 0x2000
	ds_read_b128 v[232:235], v249 offset:3072
	global_load_lds_dwordx4 v148, s[26:27]
	s_barrier
	s_waitcnt lgkmcnt(0)
	v_mfma_f32_16x16x32_bf16 v[116:119], v[220:223], v[178:181], v[116:119]
	v_mfma_f32_16x16x32_bf16 v[112:115], v[228:231], v[178:181], v[112:115]
	v_mfma_f32_16x16x32_bf16 v[100:103], v[220:223], v[196:199], v[100:103]
	v_mfma_f32_16x16x32_bf16 v[96:99], v[228:231], v[196:199], v[96:99]
	v_mfma_f32_16x16x32_bf16 v[84:87], v[220:223], v[204:207], v[84:87]
	v_mfma_f32_16x16x32_bf16 v[80:83], v[228:231], v[204:207], v[80:83]
	v_mfma_f32_16x16x32_bf16 v[68:71], v[220:223], v[212:215], v[68:71]
	v_mfma_f32_16x16x32_bf16 v[64:67], v[228:231], v[212:215], v[64:67]
	v_mfma_f32_16x16x32_bf16 v[116:119], v[224:227], v[192:195], v[116:119]
	v_mfma_f32_16x16x32_bf16 v[112:115], v[232:235], v[192:195], v[112:115]
	v_mfma_f32_16x16x32_bf16 v[100:103], v[224:227], v[200:203], v[100:103]
	v_mfma_f32_16x16x32_bf16 v[96:99], v[232:235], v[200:203], v[96:99]
	v_mfma_f32_16x16x32_bf16 v[84:87], v[224:227], v[208:211], v[84:87]
	v_mfma_f32_16x16x32_bf16 v[80:83], v[232:235], v[208:211], v[80:83]
	v_mfma_f32_16x16x32_bf16 v[68:71], v[224:227], v[216:219], v[68:71]
	v_mfma_f32_16x16x32_bf16 v[64:67], v[232:235], v[216:219], v[64:67]
	s_barrier
	s_mov_b32 m0, s23
	ds_read_b128 v[178:181], v168 offset:16384
	ds_read_b128 v[192:195], v168 offset:17408
	ds_read_b128 v[196:199], v168 offset:18432
	ds_read_b128 v[200:203], v168 offset:19456
	ds_read_b128 v[204:207], v168 offset:20480
	ds_read_b128 v[208:211], v168 offset:21504
	ds_read_b128 v[212:215], v168 offset:22528
	global_load_lds_dwordx4 v152, s[30:31]
	s_mov_b32 m0, s45
	ds_read_b128 v[216:219], v168 offset:23552
	global_load_lds_dwordx4 v150, s[30:31]
	s_barrier
	s_waitcnt lgkmcnt(0)
	v_mfma_f32_16x16x32_bf16 v[60:63], v[158:161], v[178:181], v[60:63]
	v_mfma_f32_16x16x32_bf16 v[56:59], v[170:173], v[178:181], v[56:59]
	v_mfma_f32_16x16x32_bf16 v[44:47], v[158:161], v[196:199], v[44:47]
	v_mfma_f32_16x16x32_bf16 v[40:43], v[170:173], v[196:199], v[40:43]
	v_mfma_f32_16x16x32_bf16 v[28:31], v[158:161], v[204:207], v[28:31]
	v_mfma_f32_16x16x32_bf16 v[24:27], v[170:173], v[204:207], v[24:27]
	v_mfma_f32_16x16x32_bf16 v[12:15], v[158:161], v[212:215], v[12:15]
	v_mfma_f32_16x16x32_bf16 v[8:11], v[170:173], v[212:215], v[8:11]
	v_mfma_f32_16x16x32_bf16 v[60:63], v[162:165], v[192:195], v[60:63]
	v_mfma_f32_16x16x32_bf16 v[56:59], v[174:177], v[192:195], v[56:59]
	v_mfma_f32_16x16x32_bf16 v[44:47], v[162:165], v[200:203], v[44:47]
	v_mfma_f32_16x16x32_bf16 v[40:43], v[174:177], v[200:203], v[40:43]
	v_mfma_f32_16x16x32_bf16 v[28:31], v[162:165], v[208:211], v[28:31]
	v_mfma_f32_16x16x32_bf16 v[24:27], v[174:177], v[208:211], v[24:27]
	v_mfma_f32_16x16x32_bf16 v[12:15], v[162:165], v[216:219], v[12:15]
	v_mfma_f32_16x16x32_bf16 v[8:11], v[174:177], v[216:219], v[8:11]
	s_barrier
	s_add_u32 s14, s26, 0x40000
	s_addc_u32 s15, s27, 0
	s_add_i32 s16, s17, s43
	s_mov_b32 m0, s16
	s_nop 0
	global_load_lds_dwordx4 v128, s[14:15]
	s_add_i32 m0, s16, 0x2000
	s_nop 0
	global_load_lds_dwordx4 v148, s[14:15]
	s_add_i32 s61, s61, 2
	s_add_u32 s24, s24, 0x100
	s_addc_u32 s25, s25, 0
	s_add_u32 s59, s59, 0x100
	s_addc_u32 s60, s60, 0
	s_waitcnt vmcnt(6)
	s_barrier
; #define PG8_STAGE(bufoff, gbase, voff) do { _Pragma("unroll") for (int _i = 0; _i < 2; ++_i) \
;         __builtin_amdgcn_global_load_lds((const unsigned*)((const char*)(gbase) + (voff)[_i]), (PG8_LAS unsigned*)(lds + (bufoff) + ldsw + _i * 8192), 16, 0, 0); } while (0)
; #define PG8_LDA(dst, b, h) do { _Pragma("unroll") for (int m = 0; m < 4; ++m) _Pragma("unroll") for (int k = 0; k < 2; ++k) dst[m][k] = *(const PG8_LAS bf16x8*)(lds + PG8_SA(b, h) + aoff + m * 2048 + k * 1024); } while (0)
; #define PG8_LDB(dst, b, h) do { _Pragma("unroll") for (int n = 0; n < 2; ++n) _Pragma("unroll") for (int k = 0; k < 2; ++k) dst[n][k] = *(const PG8_LAS bf16x8*)(lds + PG8_SB(b, h) + boff + n * 2048 + k * 1024); } while (0)
; #define PG8_MMA(ai, bj, At, Bt) do { __builtin_amdgcn_s_setprio(1); _Pragma("unroll") for (int m = 0; m < 4; ++m) _Pragma("unroll") for (int n = 0; n < 2; ++n) _Pragma("unroll") for (int k = 0; k < 2; ++k) \
;         acc[ai][bj][m][n] = __builtin_amdgcn_mfma_f32_16x16x32_bf16(Bt[n][k], At[m][k], acc[ai][bj][m][n], 0, 0, 0); __builtin_amdgcn_s_setprio(0); } while (0)
; #define PG8_WAIT_V(n) asm volatile("s_waitcnt vmcnt(" #n ")" ::: "memory")
; #define PG8_WAIT_L(n) asm volatile("s_waitcnt lgkmcnt(" #n ")" ::: "memory")
; #define PG8_BAR __builtin_amdgcn_s_barrier()
; #define PG8_SCHED __builtin_amdgcn_sched_barrier(0)
; template <class Epi, class Sched, bool STAMP = false>
; __device__ __forceinline__ void gemm_phase(PG8_LAS unsigned char* lds, const Gemm g, const Sched& S, const Epi& E, unsigned long long* stamps) {
;     ...
;             PG8_WAIT_V(6); PG8_BAR; PG8_MMA(1, 1, At, B1); PG8_BAR;
;             PG8_LDB(B0, 1, 0); PG8_SCHED; PG8_LDA(At, 1, 0); PG8_STAGE(PG8_SA(0, 1), a2 + hstep, voffA);
;             PG8_WAIT_L(8); PG8_BAR; PG8_WAIT_L(0); PG8_MMA(0, 0, At, B0); PG8_BAR; PG8_SCHED;
;             PG8_LDB(B1, 1, 1); PG8_STAGE(PG8_SB(1, 0), b3, voffB);
;             PG8_BAR; PG8_WAIT_L(0); PG8_MMA(0, 1, At, B1); PG8_BAR;
;             PG8_LDA(At, 1, 1); PG8_STAGE(PG8_SA(1, 0), a3, voffA);
;             PG8_BAR; PG8_WAIT_L(0); PG8_MMA(1, 0, At, B0); PG8_BAR; PG8_SCHED;
	v_mfma_f32_16x16x32_bf16 v[52:55], v[220:223], v[178:181], v[52:55]
	v_mfma_f32_16x16x32_bf16 v[48:51], v[228:231], v[178:181], v[48:51]
	v_mfma_f32_16x16x32_bf16 v[36:39], v[220:223], v[196:199], v[36:39]
	v_mfma_f32_16x16x32_bf16 v[32:35], v[228:231], v[196:199], v[32:35]
	v_mfma_f32_16x16x32_bf16 v[20:23], v[220:223], v[204:207], v[20:23]
	v_mfma_f32_16x16x32_bf16 v[16:19], v[228:231], v[204:207], v[16:19]
	v_mfma_f32_16x16x32_bf16 v[4:7], v[220:223], v[212:215], v[4:7]
	v_mfma_f32_16x16x32_bf16 v[0:3], v[228:231], v[212:215], v[0:3]
	v_mfma_f32_16x16x32_bf16 v[52:55], v[224:227], v[192:195], v[52:55]
	v_mfma_f32_16x16x32_bf16 v[48:51], v[232:235], v[192:195], v[48:51]
	v_mfma_f32_16x16x32_bf16 v[36:39], v[224:227], v[200:203], v[36:39]
	v_mfma_f32_16x16x32_bf16 v[32:35], v[232:235], v[200:203], v[32:35]
	v_mfma_f32_16x16x32_bf16 v[20:23], v[224:227], v[208:211], v[20:23]
	v_mfma_f32_16x16x32_bf16 v[16:19], v[232:235], v[208:211], v[16:19]
	v_mfma_f32_16x16x32_bf16 v[4:7], v[224:227], v[216:219], v[4:7]
	v_mfma_f32_16x16x32_bf16 v[0:3], v[232:235], v[216:219], v[0:3]
	s_barrier
	s_add_i32 s16, 0, 0x18000
	ds_read_b128 v[158:161], v250
	ds_read_b128 v[162:165], v250 offset:1024
	ds_read_b128 v[170:173], v250 offset:2048
	ds_read_b128 v[174:177], v250 offset:3072
	s_add_u32 s14, s30, 0x40000
	s_addc_u32 s15, s31, 0
	s_mov_b32 m0, s46
	ds_read_b128 v[178:181], v168 offset:32768
	ds_read_b128 v[192:195], v168 offset:33792
	ds_read_b128 v[196:199], v168 offset:34816
	ds_read_b128 v[200:203], v168 offset:35840
	ds_read_b128 v[204:207], v168 offset:36864
	ds_read_b128 v[208:211], v168 offset:37888
	ds_read_b128 v[212:215], v168 offset:38912
	global_load_lds_dwordx4 v152, s[14:15]
	s_mov_b32 m0, s47
	ds_read_b128 v[216:219], v168 offset:39936
	global_load_lds_dwordx4 v150, s[14:15]
	s_waitcnt lgkmcnt(8)
	s_barrier
	s_waitcnt lgkmcnt(0)
	v_mfma_f32_16x16x32_bf16 v[124:127], v[158:161], v[178:181], v[124:127]
	v_mfma_f32_16x16x32_bf16 v[120:123], v[170:173], v[178:181], v[120:123]
	v_mfma_f32_16x16x32_bf16 v[108:111], v[158:161], v[196:199], v[108:111]
	v_mfma_f32_16x16x32_bf16 v[104:107], v[170:173], v[196:199], v[104:107]
	v_mfma_f32_16x16x32_bf16 v[92:95], v[158:161], v[204:207], v[92:95]
	v_mfma_f32_16x16x32_bf16 v[88:91], v[170:173], v[204:207], v[88:91]
	v_mfma_f32_16x16x32_bf16 v[76:79], v[158:161], v[212:215], v[76:79]
	v_mfma_f32_16x16x32_bf16 v[72:75], v[170:173], v[212:215], v[72:75]
	v_mfma_f32_16x16x32_bf16 v[124:127], v[162:165], v[192:195], v[124:127]
	v_mfma_f32_16x16x32_bf16 v[120:123], v[174:177], v[192:195], v[120:123]
	v_mfma_f32_16x16x32_bf16 v[108:111], v[162:165], v[200:203], v[108:111]
	v_mfma_f32_16x16x32_bf16 v[104:107], v[174:177], v[200:203], v[104:107]
	v_mfma_f32_16x16x32_bf16 v[92:95], v[162:165], v[208:211], v[92:95]
	v_mfma_f32_16x16x32_bf16 v[88:91], v[174:177], v[208:211], v[88:91]
	v_mfma_f32_16x16x32_bf16 v[76:79], v[162:165], v[216:219], v[76:79]
	v_mfma_f32_16x16x32_bf16 v[72:75], v[174:177], v[216:219], v[72:75]
	s_barrier
	s_add_i32 s17, 0, 0x1c000
	s_add_i32 s14, s16, s43
	s_mov_b32 m0, s14
	ds_read_b128 v[220:223], v251
	ds_read_b128 v[224:227], v251 offset:1024
	ds_read_b128 v[228:231], v251 offset:2048
	global_load_lds_dwordx4 v244, s[26:27]
	s_add_i32 m0, s14, 0x2000
	ds_read_b128 v[232:235], v251 offset:3072
	global_load_lds_dwordx4 v245, s[26:27]
	s_barrier
	s_waitcnt lgkmcnt(0)
	v_mfma_f32_16x16x32_bf16 v[116:119], v[220:223], v[178:181], v[116:119]
	v_mfma_f32_16x16x32_bf16 v[112:115], v[228:231], v[178:181], v[112:115]
	v_mfma_f32_16x16x32_bf16 v[100:103], v[220:223], v[196:199], v[100:103]
	v_mfma_f32_16x16x32_bf16 v[96:99], v[228:231], v[196:199], v[96:99]
	v_mfma_f32_16x16x32_bf16 v[84:87], v[220:223], v[204:207], v[84:87]
	v_mfma_f32_16x16x32_bf16 v[80:83], v[228:231], v[204:207], v[80:83]
	v_mfma_f32_16x16x32_bf16 v[68:71], v[220:223], v[212:215], v[68:71]
	v_mfma_f32_16x16x32_bf16 v[64:67], v[228:231], v[212:215], v[64:67]
	v_mfma_f32_16x16x32_bf16 v[116:119], v[224:227], v[192:195], v[116:119]
	v_mfma_f32_16x16x32_bf16 v[112:115], v[232:235], v[192:195], v[112:115]
	v_mfma_f32_16x16x32_bf16 v[100:103], v[224:227], v[200:203], v[100:103]
	v_mfma_f32_16x16x32_bf16 v[96:99], v[232:235], v[200:203], v[96:99]
	v_mfma_f32_16x16x32_bf16 v[84:87], v[224:227], v[208:211], v[84:87]
	v_mfma_f32_16x16x32_bf16 v[80:83], v[232:235], v[208:211], v[80:83]
	v_mfma_f32_16x16x32_bf16 v[68:71], v[224:227], v[216:219], v[68:71]
	v_mfma_f32_16x16x32_bf16 v[64:67], v[232:235], v[216:219], v[64:67]
	s_barrier
	s_mov_b32 m0, s49
	ds_read_b128 v[178:181], v168 offset:49152
	ds_read_b128 v[192:195], v168 offset:50176
	ds_read_b128 v[196:199], v168 offset:51200
	ds_read_b128 v[200:203], v168 offset:52224
	ds_read_b128 v[204:207], v168 offset:53248
	ds_read_b128 v[208:211], v168 offset:54272
	ds_read_b128 v[212:215], v168 offset:55296
	global_load_lds_dwordx4 v246, s[30:31]
	s_mov_b32 m0, s53
	ds_read_b128 v[216:219], v168 offset:56320
	global_load_lds_dwordx4 v247, s[30:31]
	s_barrier
	s_waitcnt lgkmcnt(0)
	v_mfma_f32_16x16x32_bf16 v[60:63], v[158:161], v[178:181], v[60:63]
	v_mfma_f32_16x16x32_bf16 v[56:59], v[170:173], v[178:181], v[56:59]
	v_mfma_f32_16x16x32_bf16 v[44:47], v[158:161], v[196:199], v[44:47]
	v_mfma_f32_16x16x32_bf16 v[40:43], v[170:173], v[196:199], v[40:43]
	v_mfma_f32_16x16x32_bf16 v[28:31], v[158:161], v[204:207], v[28:31]
	v_mfma_f32_16x16x32_bf16 v[24:27], v[170:173], v[204:207], v[24:27]
	v_mfma_f32_16x16x32_bf16 v[12:15], v[158:161], v[212:215], v[12:15]
	v_mfma_f32_16x16x32_bf16 v[8:11], v[170:173], v[212:215], v[8:11]
	v_mfma_f32_16x16x32_bf16 v[60:63], v[162:165], v[192:195], v[60:63]
	v_mfma_f32_16x16x32_bf16 v[56:59], v[174:177], v[192:195], v[56:59]
	v_mfma_f32_16x16x32_bf16 v[44:47], v[162:165], v[200:203], v[44:47]
	v_mfma_f32_16x16x32_bf16 v[40:43], v[174:177], v[200:203], v[40:43]
	v_mfma_f32_16x16x32_bf16 v[28:31], v[162:165], v[208:211], v[28:31]
	v_mfma_f32_16x16x32_bf16 v[24:27], v[174:177], v[208:211], v[24:27]
	v_mfma_f32_16x16x32_bf16 v[12:15], v[162:165], v[216:219], v[12:15]
	v_mfma_f32_16x16x32_bf16 v[8:11], v[174:177], v[216:219], v[8:11]
	s_barrier
; __device__ __forceinline__ unsigned cvt_pk_bf16(float lo, float hi) { const f32x2_cv v = {lo, hi}; const bf16x2_cv b = __builtin_convertvector(v, bf16x2_cv); return __builtin_bit_cast(unsigned, b); }
; #define PG8_STAGE(bufoff, gbase, voff) do { _Pragma("unroll") for (int _i = 0; _i < 2; ++_i) \
;         __builtin_amdgcn_global_load_lds((const unsigned*)((const char*)(gbase) + (voff)[_i]), (PG8_LAS unsigned*)(lds + (bufoff) + ldsw + _i * 8192), 16, 0, 0); } while (0)
; #define PG8_MMA(ai, bj, At, Bt) do { __builtin_amdgcn_s_setprio(1); _Pragma("unroll") for (int m = 0; m < 4; ++m) _Pragma("unroll") for (int n = 0; n < 2; ++n) _Pragma("unroll") for (int k = 0; k < 2; ++k) \
;         acc[ai][bj][m][n] = __builtin_amdgcn_mfma_f32_16x16x32_bf16(Bt[n][k], At[m][k], acc[ai][bj][m][n], 0, 0, 0); __builtin_amdgcn_s_setprio(0); } while (0)
; #define PG8_WAIT_V(n) asm volatile("s_waitcnt vmcnt(" #n ")" ::: "memory")
; template <class Epi, class Sched, bool STAMP = false>
; __device__ __forceinline__ void gemm_phase(PG8_LAS unsigned char* lds, const Gemm g, const Sched& S, const Epi& E, unsigned long long* stamps) {
;     ...
;             PG8_STAGE(PG8_SB(1, 1), b3 + hstep, voffB);
;             PG8_WAIT_V(6); PG8_BAR; PG8_MMA(1, 1, At, B1); PG8_BAR;
;     __device__ __forceinline__ void operator()(const f32x4 (&acc)[2][2][4][2], const pg8::Unit& u, int wr, int wc, int fr, int fq) const {
;         const int row0 = u.pm * 256 + wr * 64 + fr, col0 = u.pn * 256 + wc * 32 + 8 * fq;
; #pragma unroll
;         for (int ai = 0; ai < 2; ++ai)
; #pragma unroll
;             for (int m = 0; m < 4; ++m) {
;                 const int row = row0 + ai * 128 + m * 16;
;                 const float s = (MODE == 2) ? 1.0f : rstd_of(rowss, row);
;                 bf16_t* rowp = O + (size_t)row * ldc + col0;
; #pragma unroll
;                 for (int bj = 0; bj < 2; ++bj) {
;                     f32x4 v0 = acc[ai][bj][m][0] * s, v1 = acc[ai][bj][m][1] * s;
;                     if (MODE == 1) {
; #pragma unroll
;                         for (int j = 0; j < 4; ++j) { const float a = fmaxf(v0[j], 0.f), b = fmaxf(v1[j], 0.f); v0[j] = a * a; v1[j] = b * b; } }
;                     u32x4 w; w.x = cvt_pk_bf16(v0[0], v0[1]); w.y = cvt_pk_bf16(v0[2], v0[3]); w.z = cvt_pk_bf16(v1[0], v1[1]); w.w = cvt_pk_bf16(v1[2], v1[3]);
;                     *(u32x4*)(rowp + bj * 128) = w; } }
	s_add_u32 s14, s26, 0x40080
	s_addc_u32 s15, s27, 0
	s_add_i32 s16, s17, s43
	s_mov_b32 m0, s16
	s_nop 0
	global_load_lds_dwordx4 v128, s[14:15]
	s_add_i32 m0, s16, 0x2000
	s_nop 0
	global_load_lds_dwordx4 v148, s[14:15]
	s_waitcnt vmcnt(6)
	s_barrier
	s_cmp_gt_u32 s61, 13
	v_mfma_f32_16x16x32_bf16 v[52:55], v[220:223], v[178:181], v[52:55]
	v_mfma_f32_16x16x32_bf16 v[48:51], v[228:231], v[178:181], v[48:51]
	v_mfma_f32_16x16x32_bf16 v[36:39], v[220:223], v[196:199], v[36:39]
	v_mfma_f32_16x16x32_bf16 v[32:35], v[228:231], v[196:199], v[32:35]
	v_mfma_f32_16x16x32_bf16 v[20:23], v[220:223], v[204:207], v[20:23]
	v_mfma_f32_16x16x32_bf16 v[16:19], v[228:231], v[204:207], v[16:19]
	v_mfma_f32_16x16x32_bf16 v[4:7], v[220:223], v[212:215], v[4:7]
	v_mfma_f32_16x16x32_bf16 v[0:3], v[228:231], v[212:215], v[0:3]
	v_mfma_f32_16x16x32_bf16 v[52:55], v[224:227], v[192:195], v[52:55]
	v_mfma_f32_16x16x32_bf16 v[48:51], v[232:235], v[192:195], v[48:51]
	v_mfma_f32_16x16x32_bf16 v[36:39], v[224:227], v[200:203], v[36:39]
	v_mfma_f32_16x16x32_bf16 v[32:35], v[232:235], v[200:203], v[32:35]
	v_mfma_f32_16x16x32_bf16 v[20:23], v[224:227], v[208:211], v[20:23]
	v_mfma_f32_16x16x32_bf16 v[16:19], v[232:235], v[208:211], v[16:19]
	v_mfma_f32_16x16x32_bf16 v[4:7], v[224:227], v[216:219], v[4:7]
	v_mfma_f32_16x16x32_bf16 v[0:3], v[232:235], v[216:219], v[0:3]
	s_barrier
	s_cbranch_scc0 .LBB0_495
	v_lshl_add_u32 v162, s22, 8, v139
	v_ashrrev_i32_e32 v163, 31, v162
	v_lshl_add_u64 v[158:159], v[162:163], 2, s[0:1]
	global_load_dword v164, v[158:159], off
	global_load_dword v193, v[158:159], off offset:64
	global_load_dword v194, v[158:159], off offset:128
	global_load_dword v195, v[158:159], off offset:192
	global_load_dword v196, v[158:159], off offset:512
	global_load_dword v197, v[158:159], off offset:576
	global_load_dword v198, v[158:159], off offset:640
	global_load_dword v199, v[158:159], off offset:704
	v_lshl_or_b32 v160, s56, 8, v167
	v_ashrrev_i32_e32 v161, 31, v160
	s_mov_b32 s5, 0x80000
	s_mov_b64 s[14:15], 0x80000
	s_mov_b32 s56, s4
	s_mov_b32 s22, s6
	s_mov_b64 s[26:27], s[20:21]
	s_mov_b64 s[24:25], s[12:13]
	s_waitcnt vmcnt(0)
	v_fmamk_f32 v164, v164, 0x3a800000, v187
	v_cmp_gt_f32_e32 vcc, s67, v164
	v_mul_f32_e32 v165, 0x4b800000, v164
	s_nop 0
	v_cndmask_b32_e32 v164, v164, v165, vcc
	v_rsq_f32_e32 v164, v164
	s_nop 0
	v_mul_f32_e32 v165, 0x45800000, v164
	v_cndmask_b32_e32 v170, v164, v165, vcc
	v_lshlrev_b64 v[164:165], 12, v[162:163]
	v_lshl_add_u64 v[172:173], s[2:3], 0, v[164:165]
	v_lshlrev_b64 v[164:165], 1, v[160:161]
	v_lshl_add_u64 v[160:161], v[172:173], 0, v[164:165]
	v_pk_mul_f32 v[126:127], v[126:127], v[170:171] op_sel_hi:[1,0]
	v_pk_mul_f32 v[124:125], v[124:125], v[170:171] op_sel_hi:[1,0]
	v_pk_mul_f32 v[172:173], v[122:123], v[170:171] op_sel_hi:[1,0]
	v_pk_mul_f32 v[122:123], v[120:121], v[170:171] op_sel_hi:[1,0]
	v_cvt_pk_bf16_f32 v120, v124, v125
	v_cvt_pk_bf16_f32 v121, v126, v127
	v_cvt_pk_bf16_f32 v122, v122, v123
	v_cvt_pk_bf16_f32 v123, v172, v173
	global_store_dwordx4 v[160:161], v[120:123], off
	v_pk_mul_f32 v[118:119], v[118:119], v[170:171] op_sel_hi:[1,0]
	v_pk_mul_f32 v[116:117], v[116:117], v[170:171] op_sel_hi:[1,0]
	v_pk_mul_f32 v[120:121], v[114:115], v[170:171] op_sel_hi:[1,0]
	v_pk_mul_f32 v[114:115], v[112:113], v[170:171] op_sel_hi:[1,0]
	v_cvt_pk_bf16_f32 v112, v116, v117
	v_cvt_pk_bf16_f32 v113, v118, v119
	v_cvt_pk_bf16_f32 v114, v114, v115
	v_cvt_pk_bf16_f32 v115, v120, v121
	global_store_dwordx4 v[160:161], v[112:115], off offset:256
	s_nop 1
	v_mov_b32_e32 v114, v193
	s_nop 0
	v_or_b32_e32 v112, 16, v162
	v_ashrrev_i32_e32 v113, 31, v112
	v_lshlrev_b64 v[112:113], 12, v[112:113]
	v_lshl_add_u64 v[112:113], s[2:3], 0, v[112:113]
	v_lshl_add_u64 v[112:113], v[112:113], 0, v[164:165]
	v_fmamk_f32 v114, v114, 0x3a800000, v187
	v_cmp_gt_f32_e32 vcc, s67, v114
	v_mul_f32_e32 v115, 0x4b800000, v114
	s_nop 0
	v_cndmask_b32_e32 v114, v114, v115, vcc
	v_rsq_f32_e32 v114, v114
	s_nop 0
	v_mul_f32_e32 v115, 0x45800000, v114
	v_cndmask_b32_e32 v114, v114, v115, vcc
	v_pk_mul_f32 v[110:111], v[110:111], v[114:115] op_sel_hi:[1,0]
	v_pk_mul_f32 v[108:109], v[108:109], v[114:115] op_sel_hi:[1,0]
	v_pk_mul_f32 v[116:117], v[106:107], v[114:115] op_sel_hi:[1,0]
	v_pk_mul_f32 v[106:107], v[104:105], v[114:115] op_sel_hi:[1,0]
	v_cvt_pk_bf16_f32 v104, v108, v109
	v_cvt_pk_bf16_f32 v105, v110, v111
	v_cvt_pk_bf16_f32 v106, v106, v107
	v_cvt_pk_bf16_f32 v107, v116, v117
	global_store_dwordx4 v[112:113], v[104:107], off
	v_pk_mul_f32 v[102:103], v[102:103], v[114:115] op_sel_hi:[1,0]
	v_pk_mul_f32 v[100:101], v[100:101], v[114:115] op_sel_hi:[1,0]
	v_pk_mul_f32 v[104:105], v[98:99], v[114:115] op_sel_hi:[1,0]
	v_pk_mul_f32 v[98:99], v[96:97], v[114:115] op_sel_hi:[1,0]
	v_cvt_pk_bf16_f32 v96, v100, v101
	v_cvt_pk_bf16_f32 v97, v102, v103
	v_cvt_pk_bf16_f32 v98, v98, v99
	v_cvt_pk_bf16_f32 v99, v104, v105
	global_store_dwordx4 v[112:113], v[96:99], off offset:256
	s_nop 1
	v_mov_b32_e32 v98, v194
	s_nop 0
	v_or_b32_e32 v96, 32, v162
	v_ashrrev_i32_e32 v97, 31, v96
	v_lshlrev_b64 v[96:97], 12, v[96:97]
	v_lshl_add_u64 v[96:97], s[2:3], 0, v[96:97]
	v_lshl_add_u64 v[96:97], v[96:97], 0, v[164:165]
	v_fmamk_f32 v98, v98, 0x3a800000, v187
	v_cmp_gt_f32_e32 vcc, s67, v98
	v_mul_f32_e32 v99, 0x4b800000, v98
	s_nop 0
	v_cndmask_b32_e32 v98, v98, v99, vcc
	v_rsq_f32_e32 v98, v98
	s_nop 0
	v_mul_f32_e32 v99, 0x45800000, v98
	v_cndmask_b32_e32 v98, v98, v99, vcc
	v_pk_mul_f32 v[94:95], v[94:95], v[98:99] op_sel_hi:[1,0]
	v_pk_mul_f32 v[92:93], v[92:93], v[98:99] op_sel_hi:[1,0]
	v_pk_mul_f32 v[100:101], v[90:91], v[98:99] op_sel_hi:[1,0]
; __device__ __forceinline__ unsigned cvt_pk_bf16(float lo, float hi) { const f32x2_cv v = {lo, hi}; const bf16x2_cv b = __builtin_convertvector(v, bf16x2_cv); return __builtin_bit_cast(unsigned, b); }
; __device__ __forceinline__ float rstd_of(const float* rowss, int row) { return rsqrtf(rowss[row] * (1.0f / 1024.0f) + 1e-6f); }
;     __device__ __forceinline__ void operator()(const f32x4 (&acc)[2][2][4][2], const pg8::Unit& u, int wr, int wc, int fr, int fq) const {
;     ...
;             for (int m = 0; m < 4; ++m) {
;                 const int row = row0 + ai * 128 + m * 16;
;                 const float s = (MODE == 2) ? 1.0f : rstd_of(rowss, row);
;                 bf16_t* rowp = O + (size_t)row * ldc + col0;
; #pragma unroll
;                 for (int bj = 0; bj < 2; ++bj) {
;                     f32x4 v0 = acc[ai][bj][m][0] * s, v1 = acc[ai][bj][m][1] * s;
;                     if (MODE == 1) {
; #pragma unroll
;                         for (int j = 0; j < 4; ++j) { const float a = fmaxf(v0[j], 0.f), b = fmaxf(v1[j], 0.f); v0[j] = a * a; v1[j] = b * b; } }
;                     u32x4 w; w.x = cvt_pk_bf16(v0[0], v0[1]); w.y = cvt_pk_bf16(v0[2], v0[3]); w.z = cvt_pk_bf16(v1[0], v1[1]); w.w = cvt_pk_bf16(v1[2], v1[3]);
;                     *(u32x4*)(rowp + bj * 128) = w; } }
	v_pk_mul_f32 v[90:91], v[88:89], v[98:99] op_sel_hi:[1,0]
	v_cvt_pk_bf16_f32 v88, v92, v93
	v_cvt_pk_bf16_f32 v89, v94, v95
	v_cvt_pk_bf16_f32 v90, v90, v91
	v_cvt_pk_bf16_f32 v91, v100, v101
	global_store_dwordx4 v[96:97], v[88:91], off
	v_pk_mul_f32 v[86:87], v[86:87], v[98:99] op_sel_hi:[1,0]
	v_pk_mul_f32 v[84:85], v[84:85], v[98:99] op_sel_hi:[1,0]
	v_pk_mul_f32 v[88:89], v[82:83], v[98:99] op_sel_hi:[1,0]
	v_pk_mul_f32 v[82:83], v[80:81], v[98:99] op_sel_hi:[1,0]
	v_cvt_pk_bf16_f32 v80, v84, v85
	v_cvt_pk_bf16_f32 v81, v86, v87
	v_cvt_pk_bf16_f32 v82, v82, v83
	v_cvt_pk_bf16_f32 v83, v88, v89
	global_store_dwordx4 v[96:97], v[80:83], off offset:256
	s_nop 1
	v_mov_b32_e32 v82, v195
	s_nop 0
	v_or_b32_e32 v80, 48, v162
	v_ashrrev_i32_e32 v81, 31, v80
	v_lshlrev_b64 v[80:81], 12, v[80:81]
	v_lshl_add_u64 v[80:81], s[2:3], 0, v[80:81]
	v_lshl_add_u64 v[80:81], v[80:81], 0, v[164:165]
	v_fmamk_f32 v82, v82, 0x3a800000, v187
	v_cmp_gt_f32_e32 vcc, s67, v82
	v_mul_f32_e32 v83, 0x4b800000, v82
	s_nop 0
	v_cndmask_b32_e32 v82, v82, v83, vcc
	v_rsq_f32_e32 v82, v82
	s_nop 0
	v_mul_f32_e32 v83, 0x45800000, v82
	v_cndmask_b32_e32 v82, v82, v83, vcc
	v_pk_mul_f32 v[78:79], v[78:79], v[82:83] op_sel_hi:[1,0]
	v_pk_mul_f32 v[76:77], v[76:77], v[82:83] op_sel_hi:[1,0]
	v_pk_mul_f32 v[84:85], v[74:75], v[82:83] op_sel_hi:[1,0]
	v_pk_mul_f32 v[74:75], v[72:73], v[82:83] op_sel_hi:[1,0]
	v_cvt_pk_bf16_f32 v72, v76, v77
	v_cvt_pk_bf16_f32 v73, v78, v79
	v_cvt_pk_bf16_f32 v74, v74, v75
	v_cvt_pk_bf16_f32 v75, v84, v85
	global_store_dwordx4 v[80:81], v[72:75], off
	v_pk_mul_f32 v[70:71], v[70:71], v[82:83] op_sel_hi:[1,0]
	v_pk_mul_f32 v[68:69], v[68:69], v[82:83] op_sel_hi:[1,0]
	v_pk_mul_f32 v[72:73], v[66:67], v[82:83] op_sel_hi:[1,0]
	v_pk_mul_f32 v[66:67], v[64:65], v[82:83] op_sel_hi:[1,0]
	v_cvt_pk_bf16_f32 v64, v68, v69
	v_cvt_pk_bf16_f32 v65, v70, v71
	v_cvt_pk_bf16_f32 v66, v66, v67
	v_cvt_pk_bf16_f32 v67, v72, v73
	global_store_dwordx4 v[80:81], v[64:67], off offset:256
	s_nop 1
	v_mov_b32_e32 v64, v196
	s_nop 0
	v_lshl_add_u64 v[66:67], v[160:161], 0, s[14:15]
	s_mov_b64 s[14:15], 0x90000
	v_fmamk_f32 v64, v64, 0x3a800000, v187
	v_cmp_gt_f32_e32 vcc, s67, v64
	v_mul_f32_e32 v65, 0x4b800000, v64
	s_nop 0
	v_cndmask_b32_e32 v64, v64, v65, vcc
	v_rsq_f32_e32 v64, v64
	s_nop 0
	v_mul_f32_e32 v65, 0x45800000, v64
	v_cndmask_b32_e32 v64, v64, v65, vcc
	v_pk_mul_f32 v[60:61], v[60:61], v[64:65] op_sel_hi:[1,0]
	v_pk_mul_f32 v[62:63], v[62:63], v[64:65] op_sel_hi:[1,0]
	v_pk_mul_f32 v[68:69], v[58:59], v[64:65] op_sel_hi:[1,0]
	v_pk_mul_f32 v[58:59], v[56:57], v[64:65] op_sel_hi:[1,0]
	v_cvt_pk_bf16_f32 v56, v60, v61
	v_add_co_u32_e32 v60, vcc, s5, v160
	v_cvt_pk_bf16_f32 v57, v62, v63
	v_cvt_pk_bf16_f32 v58, v58, v59
	v_cvt_pk_bf16_f32 v59, v68, v69
	v_addc_co_u32_e32 v61, vcc, 0, v161, vcc
	global_store_dwordx4 v[60:61], v[56:59], off
	v_pk_mul_f32 v[54:55], v[54:55], v[64:65] op_sel_hi:[1,0]
	v_pk_mul_f32 v[52:53], v[52:53], v[64:65] op_sel_hi:[1,0]
	v_pk_mul_f32 v[56:57], v[50:51], v[64:65] op_sel_hi:[1,0]
	v_pk_mul_f32 v[50:51], v[48:49], v[64:65] op_sel_hi:[1,0]
	v_cvt_pk_bf16_f32 v48, v52, v53
	v_cvt_pk_bf16_f32 v49, v54, v55
	v_cvt_pk_bf16_f32 v50, v50, v51
	v_cvt_pk_bf16_f32 v51, v56, v57
	global_store_dwordx4 v[66:67], v[48:51], off offset:256
	s_nop 1
	v_mov_b32_e32 v48, v197
	s_mov_b32 s5, 0x90000
	v_lshl_add_u64 v[50:51], v[160:161], 0, s[14:15]
	s_mov_b64 s[14:15], 0xa0000
	v_fmamk_f32 v48, v48, 0x3a800000, v187
	v_cmp_gt_f32_e32 vcc, s67, v48
	v_mul_f32_e32 v49, 0x4b800000, v48
	s_nop 0
	v_cndmask_b32_e32 v48, v48, v49, vcc
	v_rsq_f32_e32 v48, v48
	s_nop 0
	v_mul_f32_e32 v49, 0x45800000, v48
; __device__ __forceinline__ unsigned cvt_pk_bf16(float lo, float hi) { const f32x2_cv v = {lo, hi}; const bf16x2_cv b = __builtin_convertvector(v, bf16x2_cv); return __builtin_bit_cast(unsigned, b); }
; #define PG8_WAIT_V(n) asm volatile("s_waitcnt vmcnt(" #n ")" ::: "memory")
; #define PG8_BAR __builtin_amdgcn_s_barrier()
; __device__ __forceinline__ float rstd_of(const float* rowss, int row) { return rsqrtf(rowss[row] * (1.0f / 1024.0f) + 1e-6f); }
; template <class Epi, class Sched, bool STAMP = false>
; __device__ __forceinline__ void gemm_phase(PG8_LAS unsigned char* lds, const Gemm g, const Sched& S, const Epi& E, unsigned long long* stamps) {
;     ...
;         if (!has_next) break;
; #pragma unroll
;         for (int a = 0; a < 2; ++a)
; #pragma unroll
;             for (int b = 0; b < 2; ++b)
; #pragma unroll
;                 for (int m = 0; m < 4; ++m)
; #pragma unroll
;                     for (int n = 0; n < 2; ++n) acc[a][b][m][n] = (f32x4){0.f, 0.f, 0.f, 0.f};
;         cur = nxt; cA = nA; cB = nB; ++ui;
;     }
;     PG8_WAIT_V(0);
;     if (wr == 0) PG8_BAR;
;     __device__ __forceinline__ void operator()(const f32x4 (&acc)[2][2][4][2], const pg8::Unit& u, int wr, int wc, int fr, int fq) const {
;     ...
;             for (int m = 0; m < 4; ++m) {
;                 const int row = row0 + ai * 128 + m * 16;
;                 const float s = (MODE == 2) ? 1.0f : rstd_of(rowss, row);
;                 bf16_t* rowp = O + (size_t)row * ldc + col0;
; #pragma unroll
;                 for (int bj = 0; bj < 2; ++bj) {
;                     f32x4 v0 = acc[ai][bj][m][0] * s, v1 = acc[ai][bj][m][1] * s;
;                     if (MODE == 1) {
; #pragma unroll
;                         for (int j = 0; j < 4; ++j) { const float a = fmaxf(v0[j], 0.f), b = fmaxf(v1[j], 0.f); v0[j] = a * a; v1[j] = b * b; } }
;                     u32x4 w; w.x = cvt_pk_bf16(v0[0], v0[1]); w.y = cvt_pk_bf16(v0[2], v0[3]); w.z = cvt_pk_bf16(v1[0], v1[1]); w.w = cvt_pk_bf16(v1[2], v1[3]);
;                     *(u32x4*)(rowp + bj * 128) = w; } }
	v_cndmask_b32_e32 v48, v48, v49, vcc
	v_pk_mul_f32 v[44:45], v[44:45], v[48:49] op_sel_hi:[1,0]
	v_pk_mul_f32 v[46:47], v[46:47], v[48:49] op_sel_hi:[1,0]
	v_pk_mul_f32 v[52:53], v[42:43], v[48:49] op_sel_hi:[1,0]
	v_pk_mul_f32 v[42:43], v[40:41], v[48:49] op_sel_hi:[1,0]
	v_cvt_pk_bf16_f32 v40, v44, v45
	v_add_co_u32_e32 v44, vcc, s5, v160
	v_cvt_pk_bf16_f32 v41, v46, v47
	v_cvt_pk_bf16_f32 v42, v42, v43
	v_cvt_pk_bf16_f32 v43, v52, v53
	v_addc_co_u32_e32 v45, vcc, 0, v161, vcc
	global_store_dwordx4 v[44:45], v[40:43], off
	v_pk_mul_f32 v[38:39], v[38:39], v[48:49] op_sel_hi:[1,0]
	v_pk_mul_f32 v[36:37], v[36:37], v[48:49] op_sel_hi:[1,0]
	v_pk_mul_f32 v[40:41], v[34:35], v[48:49] op_sel_hi:[1,0]
	v_pk_mul_f32 v[34:35], v[32:33], v[48:49] op_sel_hi:[1,0]
	v_cvt_pk_bf16_f32 v32, v36, v37
	v_cvt_pk_bf16_f32 v33, v38, v39
	v_cvt_pk_bf16_f32 v34, v34, v35
	v_cvt_pk_bf16_f32 v35, v40, v41
	global_store_dwordx4 v[50:51], v[32:35], off offset:256
	s_nop 1
	v_mov_b32_e32 v32, v198
	s_mov_b32 s5, 0xa0000
	v_lshl_add_u64 v[34:35], v[160:161], 0, s[14:15]
	s_mov_b64 s[14:15], 0xb0000
	v_fmamk_f32 v32, v32, 0x3a800000, v187
	v_cmp_gt_f32_e32 vcc, s67, v32
	v_mul_f32_e32 v33, 0x4b800000, v32
	s_nop 0
	v_cndmask_b32_e32 v32, v32, v33, vcc
	v_rsq_f32_e32 v32, v32
	s_nop 0
	v_mul_f32_e32 v33, 0x45800000, v32
	v_cndmask_b32_e32 v32, v32, v33, vcc
	v_pk_mul_f32 v[28:29], v[28:29], v[32:33] op_sel_hi:[1,0]
	v_pk_mul_f32 v[30:31], v[30:31], v[32:33] op_sel_hi:[1,0]
	v_pk_mul_f32 v[36:37], v[26:27], v[32:33] op_sel_hi:[1,0]
	v_pk_mul_f32 v[26:27], v[24:25], v[32:33] op_sel_hi:[1,0]
	v_cvt_pk_bf16_f32 v24, v28, v29
	v_add_co_u32_e32 v28, vcc, s5, v160
	v_cvt_pk_bf16_f32 v25, v30, v31
	v_cvt_pk_bf16_f32 v26, v26, v27
	v_cvt_pk_bf16_f32 v27, v36, v37
	v_addc_co_u32_e32 v29, vcc, 0, v161, vcc
	global_store_dwordx4 v[28:29], v[24:27], off
	v_pk_mul_f32 v[22:23], v[22:23], v[32:33] op_sel_hi:[1,0]
	v_pk_mul_f32 v[20:21], v[20:21], v[32:33] op_sel_hi:[1,0]
	v_pk_mul_f32 v[24:25], v[18:19], v[32:33] op_sel_hi:[1,0]
	v_pk_mul_f32 v[18:19], v[16:17], v[32:33] op_sel_hi:[1,0]
	v_cvt_pk_bf16_f32 v16, v20, v21
	v_cvt_pk_bf16_f32 v17, v22, v23
	v_cvt_pk_bf16_f32 v18, v18, v19
	v_cvt_pk_bf16_f32 v19, v24, v25
	global_store_dwordx4 v[34:35], v[16:19], off offset:256
	s_nop 1
	v_mov_b32_e32 v16, v199
	s_mov_b32 s5, 0xb0000
	v_lshl_add_u64 v[18:19], v[160:161], 0, s[14:15]
	v_fmamk_f32 v16, v16, 0x3a800000, v187
	v_cmp_gt_f32_e32 vcc, s67, v16
	v_mul_f32_e32 v17, 0x4b800000, v16
	s_nop 0
	v_cndmask_b32_e32 v16, v16, v17, vcc
	v_rsq_f32_e32 v16, v16
	s_nop 0
	v_mul_f32_e32 v17, 0x45800000, v16
	v_cndmask_b32_e32 v16, v16, v17, vcc
	v_pk_mul_f32 v[12:13], v[12:13], v[16:17] op_sel_hi:[1,0]
	v_pk_mul_f32 v[14:15], v[14:15], v[16:17] op_sel_hi:[1,0]
	v_pk_mul_f32 v[20:21], v[10:11], v[16:17] op_sel_hi:[1,0]
	v_pk_mul_f32 v[10:11], v[8:9], v[16:17] op_sel_hi:[1,0]
	v_cvt_pk_bf16_f32 v8, v12, v13
	v_add_co_u32_e32 v12, vcc, s5, v160
	v_cvt_pk_bf16_f32 v9, v14, v15
	v_cvt_pk_bf16_f32 v10, v10, v11
	v_cvt_pk_bf16_f32 v11, v20, v21
	v_addc_co_u32_e32 v13, vcc, 0, v161, vcc
	global_store_dwordx4 v[12:13], v[8:11], off
	v_pk_mul_f32 v[6:7], v[6:7], v[16:17] op_sel_hi:[1,0]
	v_pk_mul_f32 v[4:5], v[4:5], v[16:17] op_sel_hi:[1,0]
	v_pk_mul_f32 v[8:9], v[2:3], v[16:17] op_sel_hi:[1,0]
	v_pk_mul_f32 v[2:3], v[0:1], v[16:17] op_sel_hi:[1,0]
	v_cvt_pk_bf16_f32 v0, v4, v5
	v_cvt_pk_bf16_f32 v1, v6, v7
	v_cvt_pk_bf16_f32 v2, v2, v3
	v_cvt_pk_bf16_f32 v3, v8, v9
	s_and_b64 vcc, exec, s[38:39]
	global_store_dwordx4 v[18:19], v[0:3], off offset:256
	s_cbranch_vccz .LBB0_492
	s_waitcnt vmcnt(0)
	s_cmpk_gt_u32 s36, 0xff
	s_cbranch_scc1 .LBB0_499
	s_barrier

; #define PG8_STAGE(bufoff, gbase, voff) do { _Pragma("unroll") for (int _i = 0; _i < 2; ++_i) \
;         __builtin_amdgcn_global_load_lds((const unsigned*)((const char*)(gbase) + (voff)[_i]), (PG8_LAS unsigned*)(lds + (bufoff) + ldsw + _i * 8192), 16, 0, 0); } while (0)
; #define PG8_LDA(dst, b, h) do { _Pragma("unroll") for (int m = 0; m < 4; ++m) _Pragma("unroll") for (int k = 0; k < 2; ++k) dst[m][k] = *(const PG8_LAS bf16x8*)(lds + PG8_SA(b, h) + aoff + m * 2048 + k * 1024); } while (0)
; #define PG8_LDB(dst, b, h) do { _Pragma("unroll") for (int n = 0; n < 2; ++n) _Pragma("unroll") for (int k = 0; k < 2; ++k) dst[n][k] = *(const PG8_LAS bf16x8*)(lds + PG8_SB(b, h) + boff + n * 2048 + k * 1024); } while (0)
; #define PG8_MMA(ai, bj, At, Bt) do { __builtin_amdgcn_s_setprio(1); _Pragma("unroll") for (int m = 0; m < 4; ++m) _Pragma("unroll") for (int n = 0; n < 2; ++n) _Pragma("unroll") for (int k = 0; k < 2; ++k) \
;         acc[ai][bj][m][n] = __builtin_amdgcn_mfma_f32_16x16x32_bf16(Bt[n][k], At[m][k], acc[ai][bj][m][n], 0, 0, 0); __builtin_amdgcn_s_setprio(0); } while (0)
; #define PG8_WAIT_V(n) asm volatile("s_waitcnt vmcnt(" #n ")" ::: "memory")
; template <class Epi, class Sched, bool STAMP = false>
; __device__ __forceinline__ void gemm_phase(PG8_LAS unsigned char* lds, const Gemm g, const Sched& S, const Epi& E, unsigned long long* stamps) {
;     ...
;             const bool last = (t == nt - 2);
;             const char* a1 = cA + (size_t)(t + 1) * kstep;
;             const char* a2 = last ? nA : cA + (size_t)(t + 2) * kstep; const char* b2 = last ? nB : cB + (size_t)(t + 2) * kstep;
;             const char* a3 = a2 + kstep; const char* b3 = b2 + kstep;
;             if (last && has_next) S.a_ready(nxt);
;             PG8_LDB(B0, 0, 0); PG8_SCHED; PG8_LDA(At, 0, 0); PG8_STAGE(PG8_SA(1, 1), a1 + hstep, voffA);
;             PG8_WAIT_L(8); PG8_BAR; PG8_WAIT_L(0); PG8_MMA(0, 0, At, B0); PG8_BAR; PG8_SCHED;
;             PG8_LDB(B1, 0, 1); PG8_STAGE(PG8_SB(0, 0), b2, voffB);
;             PG8_BAR; PG8_WAIT_L(0); PG8_MMA(0, 1, At, B1); PG8_BAR;
;             PG8_LDA(At, 0, 1); PG8_STAGE(PG8_SA(0, 0), a2, voffA);
;             PG8_BAR; PG8_WAIT_L(0); PG8_MMA(1, 0, At, B0); PG8_BAR; PG8_SCHED;
;             PG8_STAGE(PG8_SB(0, 1), b2 + hstep, voffB);
;             PG8_WAIT_V(6); PG8_BAR; PG8_MMA(1, 1, At, B1); PG8_BAR;
.LBB0_1183:
	s_add_u32 s30, s26, 0x100
	s_addc_u32 s31, s27, 0
	s_add_i32 s14, 0, 0x10000
	ds_read_b128 v[154:157], v248
	ds_read_b128 v[162:165], v248 offset:1024
	ds_read_b128 v[166:169], v248 offset:2048
	ds_read_b128 v[170:173], v248 offset:3072
	s_cmp_eq_u32 s65, 60
	s_cselect_b32 s37, s7, s31
	s_cselect_b32 s36, s23, s30
	s_cselect_b32 s35, s5, s64
	s_cselect_b32 s34, s62, s63
	s_add_i32 m0, s25, 0xc000
	ds_read_b128 v[174:177], v160
	ds_read_b128 v[178:181], v160 offset:1024
	ds_read_b128 v[192:195], v160 offset:2048
	ds_read_b128 v[196:199], v160 offset:3072
	ds_read_b128 v[200:203], v160 offset:4096
	ds_read_b128 v[204:207], v160 offset:5120
	ds_read_b128 v[208:211], v160 offset:6144
	global_load_lds_dwordx4 v150, s[26:27]
	s_add_i32 m0, s25, 0xe000
	ds_read_b128 v[212:215], v160 offset:7168
	global_load_lds_dwordx4 v152, s[26:27]
	s_waitcnt lgkmcnt(8)
	s_barrier
	s_waitcnt lgkmcnt(0)
	v_mfma_f32_16x16x32_bf16 v[124:127], v[154:157], v[174:177], v[124:127]
	v_mfma_f32_16x16x32_bf16 v[120:123], v[166:169], v[174:177], v[120:123]
	v_mfma_f32_16x16x32_bf16 v[108:111], v[154:157], v[192:195], v[108:111]
	v_mfma_f32_16x16x32_bf16 v[104:107], v[166:169], v[192:195], v[104:107]
	v_mfma_f32_16x16x32_bf16 v[92:95], v[154:157], v[200:203], v[92:95]
	v_mfma_f32_16x16x32_bf16 v[88:91], v[166:169], v[200:203], v[88:91]
	v_mfma_f32_16x16x32_bf16 v[76:79], v[154:157], v[208:211], v[76:79]
	v_mfma_f32_16x16x32_bf16 v[72:75], v[166:169], v[208:211], v[72:75]
	v_mfma_f32_16x16x32_bf16 v[124:127], v[162:165], v[178:181], v[124:127]
	v_mfma_f32_16x16x32_bf16 v[120:123], v[170:173], v[178:181], v[120:123]
	v_mfma_f32_16x16x32_bf16 v[108:111], v[162:165], v[196:199], v[108:111]
	v_mfma_f32_16x16x32_bf16 v[104:107], v[170:173], v[196:199], v[104:107]
	v_mfma_f32_16x16x32_bf16 v[92:95], v[162:165], v[204:207], v[92:95]
	v_mfma_f32_16x16x32_bf16 v[88:91], v[170:173], v[204:207], v[88:91]
	v_mfma_f32_16x16x32_bf16 v[76:79], v[162:165], v[212:215], v[76:79]
	v_mfma_f32_16x16x32_bf16 v[72:75], v[170:173], v[212:215], v[72:75]
	s_barrier
	s_add_i32 s16, 0, 0x14000
	s_add_i32 s14, s14, s49
	s_mov_b32 m0, s14
	ds_read_b128 v[216:219], v249
	ds_read_b128 v[220:223], v249 offset:1024
	ds_read_b128 v[224:227], v249 offset:2048
	global_load_lds_dwordx4 v128, s[34:35]
	s_add_i32 m0, s14, 0x2000
	ds_read_b128 v[228:231], v249 offset:3072
	global_load_lds_dwordx4 v148, s[34:35]
	s_barrier
	s_waitcnt lgkmcnt(0)
	v_mfma_f32_16x16x32_bf16 v[116:119], v[216:219], v[174:177], v[116:119]
	v_mfma_f32_16x16x32_bf16 v[112:115], v[224:227], v[174:177], v[112:115]
	v_mfma_f32_16x16x32_bf16 v[100:103], v[216:219], v[192:195], v[100:103]
	v_mfma_f32_16x16x32_bf16 v[96:99], v[224:227], v[192:195], v[96:99]
	v_mfma_f32_16x16x32_bf16 v[84:87], v[216:219], v[200:203], v[84:87]
	v_mfma_f32_16x16x32_bf16 v[80:83], v[224:227], v[200:203], v[80:83]
	v_mfma_f32_16x16x32_bf16 v[68:71], v[216:219], v[208:211], v[68:71]
	v_mfma_f32_16x16x32_bf16 v[64:67], v[224:227], v[208:211], v[64:67]
	v_mfma_f32_16x16x32_bf16 v[116:119], v[220:223], v[178:181], v[116:119]
	v_mfma_f32_16x16x32_bf16 v[112:115], v[228:231], v[178:181], v[112:115]
	v_mfma_f32_16x16x32_bf16 v[100:103], v[220:223], v[196:199], v[100:103]
	v_mfma_f32_16x16x32_bf16 v[96:99], v[228:231], v[196:199], v[96:99]
	v_mfma_f32_16x16x32_bf16 v[84:87], v[220:223], v[204:207], v[84:87]
	v_mfma_f32_16x16x32_bf16 v[80:83], v[228:231], v[204:207], v[80:83]
	v_mfma_f32_16x16x32_bf16 v[68:71], v[220:223], v[212:215], v[68:71]
	v_mfma_f32_16x16x32_bf16 v[64:67], v[228:231], v[212:215], v[64:67]
	s_barrier
	s_mov_b32 m0, s25
	ds_read_b128 v[174:177], v160 offset:16384
	ds_read_b128 v[178:181], v160 offset:17408
	ds_read_b128 v[192:195], v160 offset:18432
	ds_read_b128 v[196:199], v160 offset:19456
	ds_read_b128 v[200:203], v160 offset:20480
	ds_read_b128 v[204:207], v160 offset:21504
	ds_read_b128 v[208:211], v160 offset:22528
	global_load_lds_dwordx4 v128, s[36:37]
	s_mov_b32 m0, s53
	ds_read_b128 v[212:215], v160 offset:23552
	global_load_lds_dwordx4 v148, s[36:37]
	s_barrier
	s_waitcnt lgkmcnt(0)
	v_mfma_f32_16x16x32_bf16 v[60:63], v[154:157], v[174:177], v[60:63]
	v_mfma_f32_16x16x32_bf16 v[56:59], v[166:169], v[174:177], v[56:59]
	v_mfma_f32_16x16x32_bf16 v[44:47], v[154:157], v[192:195], v[44:47]
	v_mfma_f32_16x16x32_bf16 v[40:43], v[166:169], v[192:195], v[40:43]
	v_mfma_f32_16x16x32_bf16 v[28:31], v[154:157], v[200:203], v[28:31]
	v_mfma_f32_16x16x32_bf16 v[24:27], v[166:169], v[200:203], v[24:27]
	v_mfma_f32_16x16x32_bf16 v[12:15], v[154:157], v[208:211], v[12:15]
	v_mfma_f32_16x16x32_bf16 v[8:11], v[166:169], v[208:211], v[8:11]
	v_mfma_f32_16x16x32_bf16 v[60:63], v[162:165], v[178:181], v[60:63]
	v_mfma_f32_16x16x32_bf16 v[56:59], v[170:173], v[178:181], v[56:59]
	v_mfma_f32_16x16x32_bf16 v[44:47], v[162:165], v[196:199], v[44:47]
	v_mfma_f32_16x16x32_bf16 v[40:43], v[170:173], v[196:199], v[40:43]
	v_mfma_f32_16x16x32_bf16 v[28:31], v[162:165], v[204:207], v[28:31]
	v_mfma_f32_16x16x32_bf16 v[24:27], v[170:173], v[204:207], v[24:27]
	v_mfma_f32_16x16x32_bf16 v[12:15], v[162:165], v[212:215], v[12:15]
	v_mfma_f32_16x16x32_bf16 v[8:11], v[170:173], v[212:215], v[8:11]
	s_barrier
	s_add_u32 s14, s34, 0x100000
	s_addc_u32 s15, s35, 0
	s_add_i32 s16, s16, s49
	s_mov_b32 m0, s16
	s_nop 0
	global_load_lds_dwordx4 v128, s[14:15]
	s_add_i32 m0, s16, 0x2000
	s_nop 0
	global_load_lds_dwordx4 v148, s[14:15]
	s_add_i32 s65, s65, 2
	s_add_u32 s63, s63, 0x100
	s_addc_u32 s64, s64, 0
	s_waitcnt vmcnt(6)
	s_barrier
; #define PG8_STAGE(bufoff, gbase, voff) do { _Pragma("unroll") for (int _i = 0; _i < 2; ++_i) \
;         __builtin_amdgcn_global_load_lds((const unsigned*)((const char*)(gbase) + (voff)[_i]), (PG8_LAS unsigned*)(lds + (bufoff) + ldsw + _i * 8192), 16, 0, 0); } while (0)
; #define PG8_LDA(dst, b, h) do { _Pragma("unroll") for (int m = 0; m < 4; ++m) _Pragma("unroll") for (int k = 0; k < 2; ++k) dst[m][k] = *(const PG8_LAS bf16x8*)(lds + PG8_SA(b, h) + aoff + m * 2048 + k * 1024); } while (0)
; #define PG8_LDB(dst, b, h) do { _Pragma("unroll") for (int n = 0; n < 2; ++n) _Pragma("unroll") for (int k = 0; k < 2; ++k) dst[n][k] = *(const PG8_LAS bf16x8*)(lds + PG8_SB(b, h) + boff + n * 2048 + k * 1024); } while (0)
; #define PG8_MMA(ai, bj, At, Bt) do { __builtin_amdgcn_s_setprio(1); _Pragma("unroll") for (int m = 0; m < 4; ++m) _Pragma("unroll") for (int n = 0; n < 2; ++n) _Pragma("unroll") for (int k = 0; k < 2; ++k) \
;         acc[ai][bj][m][n] = __builtin_amdgcn_mfma_f32_16x16x32_bf16(Bt[n][k], At[m][k], acc[ai][bj][m][n], 0, 0, 0); __builtin_amdgcn_s_setprio(0); } while (0)
; #define PG8_WAIT_V(n) asm volatile("s_waitcnt vmcnt(" #n ")" ::: "memory")
; #define PG8_WAIT_L(n) asm volatile("s_waitcnt lgkmcnt(" #n ")" ::: "memory")
; #define PG8_BAR __builtin_amdgcn_s_barrier()
; #define PG8_SCHED __builtin_amdgcn_sched_barrier(0)
; template <class Epi, class Sched, bool STAMP = false>
; __device__ __forceinline__ void gemm_phase(PG8_LAS unsigned char* lds, const Gemm g, const Sched& S, const Epi& E, unsigned long long* stamps) {
;     ...
;             PG8_WAIT_V(6); PG8_BAR; PG8_MMA(1, 1, At, B1); PG8_BAR;
;             PG8_LDB(B0, 1, 0); PG8_SCHED; PG8_LDA(At, 1, 0); PG8_STAGE(PG8_SA(0, 1), a2 + hstep, voffA);
;             PG8_WAIT_L(8); PG8_BAR; PG8_WAIT_L(0); PG8_MMA(0, 0, At, B0); PG8_BAR; PG8_SCHED;
;             PG8_LDB(B1, 1, 1); PG8_STAGE(PG8_SB(1, 0), b3, voffB);
;             PG8_BAR; PG8_WAIT_L(0); PG8_MMA(0, 1, At, B1); PG8_BAR;
;             PG8_LDA(At, 1, 1); PG8_STAGE(PG8_SA(1, 0), a3, voffA);
;             PG8_BAR; PG8_WAIT_L(0); PG8_MMA(1, 0, At, B0); PG8_BAR; PG8_SCHED;
	v_mfma_f32_16x16x32_bf16 v[52:55], v[216:219], v[174:177], v[52:55]
	v_mfma_f32_16x16x32_bf16 v[48:51], v[224:227], v[174:177], v[48:51]
	v_mfma_f32_16x16x32_bf16 v[36:39], v[216:219], v[192:195], v[36:39]
	v_mfma_f32_16x16x32_bf16 v[32:35], v[224:227], v[192:195], v[32:35]
	v_mfma_f32_16x16x32_bf16 v[20:23], v[216:219], v[200:203], v[20:23]
	v_mfma_f32_16x16x32_bf16 v[16:19], v[224:227], v[200:203], v[16:19]
	v_mfma_f32_16x16x32_bf16 v[4:7], v[216:219], v[208:211], v[4:7]
	v_mfma_f32_16x16x32_bf16 v[0:3], v[224:227], v[208:211], v[0:3]
	v_mfma_f32_16x16x32_bf16 v[52:55], v[220:223], v[178:181], v[52:55]
	v_mfma_f32_16x16x32_bf16 v[48:51], v[228:231], v[178:181], v[48:51]
	v_mfma_f32_16x16x32_bf16 v[36:39], v[220:223], v[196:199], v[36:39]
	v_mfma_f32_16x16x32_bf16 v[32:35], v[228:231], v[196:199], v[32:35]
	v_mfma_f32_16x16x32_bf16 v[20:23], v[220:223], v[204:207], v[20:23]
	v_mfma_f32_16x16x32_bf16 v[16:19], v[228:231], v[204:207], v[16:19]
	v_mfma_f32_16x16x32_bf16 v[4:7], v[220:223], v[212:215], v[4:7]
	v_mfma_f32_16x16x32_bf16 v[0:3], v[228:231], v[212:215], v[0:3]
	s_barrier
	s_add_i32 s16, 0, 0x18000
	ds_read_b128 v[154:157], v250
	ds_read_b128 v[162:165], v250 offset:1024
	ds_read_b128 v[166:169], v250 offset:2048
	ds_read_b128 v[170:173], v250 offset:3072
	s_add_u32 s14, s36, 0x100000
	s_addc_u32 s15, s37, 0
	s_mov_b32 m0, s56
	ds_read_b128 v[174:177], v160 offset:32768
	ds_read_b128 v[178:181], v160 offset:33792
	ds_read_b128 v[192:195], v160 offset:34816
	ds_read_b128 v[196:199], v160 offset:35840
	ds_read_b128 v[200:203], v160 offset:36864
	ds_read_b128 v[204:207], v160 offset:37888
	ds_read_b128 v[208:211], v160 offset:38912
	global_load_lds_dwordx4 v128, s[14:15]
	s_mov_b32 m0, s57
	ds_read_b128 v[212:215], v160 offset:39936
	global_load_lds_dwordx4 v148, s[14:15]
	s_waitcnt lgkmcnt(8)
	s_barrier
	s_waitcnt lgkmcnt(0)
	v_mfma_f32_16x16x32_bf16 v[124:127], v[154:157], v[174:177], v[124:127]
	v_mfma_f32_16x16x32_bf16 v[120:123], v[166:169], v[174:177], v[120:123]
	v_mfma_f32_16x16x32_bf16 v[108:111], v[154:157], v[192:195], v[108:111]
	v_mfma_f32_16x16x32_bf16 v[104:107], v[166:169], v[192:195], v[104:107]
	v_mfma_f32_16x16x32_bf16 v[92:95], v[154:157], v[200:203], v[92:95]
	v_mfma_f32_16x16x32_bf16 v[88:91], v[166:169], v[200:203], v[88:91]
	v_mfma_f32_16x16x32_bf16 v[76:79], v[154:157], v[208:211], v[76:79]
	v_mfma_f32_16x16x32_bf16 v[72:75], v[166:169], v[208:211], v[72:75]
	v_mfma_f32_16x16x32_bf16 v[124:127], v[162:165], v[178:181], v[124:127]
	v_mfma_f32_16x16x32_bf16 v[120:123], v[170:173], v[178:181], v[120:123]
	v_mfma_f32_16x16x32_bf16 v[108:111], v[162:165], v[196:199], v[108:111]
	v_mfma_f32_16x16x32_bf16 v[104:107], v[170:173], v[196:199], v[104:107]
	v_mfma_f32_16x16x32_bf16 v[92:95], v[162:165], v[204:207], v[92:95]
	v_mfma_f32_16x16x32_bf16 v[88:91], v[170:173], v[204:207], v[88:91]
	v_mfma_f32_16x16x32_bf16 v[76:79], v[162:165], v[212:215], v[76:79]
	v_mfma_f32_16x16x32_bf16 v[72:75], v[170:173], v[212:215], v[72:75]
	s_barrier
	s_add_i32 s17, 0, 0x1c000
	s_add_i32 s14, s16, s49
	s_mov_b32 m0, s14
	ds_read_b128 v[216:219], v251
	ds_read_b128 v[220:223], v251 offset:1024
	ds_read_b128 v[224:227], v251 offset:2048
	global_load_lds_dwordx4 v244, s[34:35]
	s_add_i32 m0, s14, 0x2000
	ds_read_b128 v[228:231], v251 offset:3072
	global_load_lds_dwordx4 v245, s[34:35]
	s_barrier
	s_waitcnt lgkmcnt(0)
	v_mfma_f32_16x16x32_bf16 v[116:119], v[216:219], v[174:177], v[116:119]
	v_mfma_f32_16x16x32_bf16 v[112:115], v[224:227], v[174:177], v[112:115]
	v_mfma_f32_16x16x32_bf16 v[100:103], v[216:219], v[192:195], v[100:103]
	v_mfma_f32_16x16x32_bf16 v[96:99], v[224:227], v[192:195], v[96:99]
	v_mfma_f32_16x16x32_bf16 v[84:87], v[216:219], v[200:203], v[84:87]
	v_mfma_f32_16x16x32_bf16 v[80:83], v[224:227], v[200:203], v[80:83]
	v_mfma_f32_16x16x32_bf16 v[68:71], v[216:219], v[208:211], v[68:71]
	v_mfma_f32_16x16x32_bf16 v[64:67], v[224:227], v[208:211], v[64:67]
	v_mfma_f32_16x16x32_bf16 v[116:119], v[220:223], v[178:181], v[116:119]
	v_mfma_f32_16x16x32_bf16 v[112:115], v[228:231], v[178:181], v[112:115]
	v_mfma_f32_16x16x32_bf16 v[100:103], v[220:223], v[196:199], v[100:103]
	v_mfma_f32_16x16x32_bf16 v[96:99], v[228:231], v[196:199], v[96:99]
	v_mfma_f32_16x16x32_bf16 v[84:87], v[220:223], v[204:207], v[84:87]
	v_mfma_f32_16x16x32_bf16 v[80:83], v[228:231], v[204:207], v[80:83]
	v_mfma_f32_16x16x32_bf16 v[68:71], v[220:223], v[212:215], v[68:71]
	v_mfma_f32_16x16x32_bf16 v[64:67], v[228:231], v[212:215], v[64:67]
	s_barrier
	s_mov_b32 m0, s59
	ds_read_b128 v[174:177], v160 offset:49152
	ds_read_b128 v[178:181], v160 offset:50176
	ds_read_b128 v[192:195], v160 offset:51200
	ds_read_b128 v[196:199], v160 offset:52224
	ds_read_b128 v[200:203], v160 offset:53248
	ds_read_b128 v[204:207], v160 offset:54272
	ds_read_b128 v[208:211], v160 offset:55296
	global_load_lds_dwordx4 v244, s[36:37]
	s_mov_b32 m0, s60
	ds_read_b128 v[212:215], v160 offset:56320
	global_load_lds_dwordx4 v245, s[36:37]
	s_barrier
	s_waitcnt lgkmcnt(0)
	v_mfma_f32_16x16x32_bf16 v[60:63], v[154:157], v[174:177], v[60:63]
	v_mfma_f32_16x16x32_bf16 v[56:59], v[166:169], v[174:177], v[56:59]
	v_mfma_f32_16x16x32_bf16 v[44:47], v[154:157], v[192:195], v[44:47]
	v_mfma_f32_16x16x32_bf16 v[40:43], v[166:169], v[192:195], v[40:43]
	v_mfma_f32_16x16x32_bf16 v[28:31], v[154:157], v[200:203], v[28:31]
	v_mfma_f32_16x16x32_bf16 v[24:27], v[166:169], v[200:203], v[24:27]
	v_mfma_f32_16x16x32_bf16 v[12:15], v[154:157], v[208:211], v[12:15]
	v_mfma_f32_16x16x32_bf16 v[8:11], v[166:169], v[208:211], v[8:11]
	v_mfma_f32_16x16x32_bf16 v[60:63], v[162:165], v[178:181], v[60:63]
	v_mfma_f32_16x16x32_bf16 v[56:59], v[170:173], v[178:181], v[56:59]
	v_mfma_f32_16x16x32_bf16 v[44:47], v[162:165], v[196:199], v[44:47]
	v_mfma_f32_16x16x32_bf16 v[40:43], v[170:173], v[196:199], v[40:43]
	v_mfma_f32_16x16x32_bf16 v[28:31], v[162:165], v[204:207], v[28:31]
	v_mfma_f32_16x16x32_bf16 v[24:27], v[170:173], v[204:207], v[24:27]
	v_mfma_f32_16x16x32_bf16 v[12:15], v[162:165], v[212:215], v[12:15]
	v_mfma_f32_16x16x32_bf16 v[8:11], v[170:173], v[212:215], v[8:11]
	s_barrier
; __device__ __forceinline__ unsigned cvt_pk_bf16(float lo, float hi) { const f32x2_cv v = {lo, hi}; const bf16x2_cv b = __builtin_convertvector(v, bf16x2_cv); return __builtin_bit_cast(unsigned, b); }
; #define PG8_STAGE(bufoff, gbase, voff) do { _Pragma("unroll") for (int _i = 0; _i < 2; ++_i) \
;         __builtin_amdgcn_global_load_lds((const unsigned*)((const char*)(gbase) + (voff)[_i]), (PG8_LAS unsigned*)(lds + (bufoff) + ldsw + _i * 8192), 16, 0, 0); } while (0)
; #define PG8_WAIT_V(n) asm volatile("s_waitcnt vmcnt(" #n ")" ::: "memory")
; #define PG8_BAR __builtin_amdgcn_s_barrier()
; template <class Epi, class Sched, bool STAMP = false>
; __device__ __forceinline__ void gemm_phase(PG8_LAS unsigned char* lds, const Gemm g, const Sched& S, const Epi& E, unsigned long long* stamps) {
;     ...
;             PG8_STAGE(PG8_SB(1, 1), b3 + hstep, voffB);
;             PG8_WAIT_V(6); PG8_BAR; PG8_MMA(1, 1, At, B1); PG8_BAR;
;     __device__ __forceinline__ void operator()(const f32x4 (&acc)[2][2][4][2], const pg8::Unit& u, int wr, int wc, int fr, int fq) const {
;         const int row0 = u.pm * 256 + wr * 64 + fr, col0 = u.pn * 256 + wc * 32 + 4 * fq;
; #pragma unroll
;         for (int ai = 0; ai < 2; ++ai)
; #pragma unroll
;             for (int m = 0; m < 4; ++m) {
;                 const int row = row0 + ai * 128 + m * 16;
;                 float* xp = X + (size_t)row * 1024 + col0; bf16_t* bp = XB + (size_t)row * 1024 + col0;
;                 const float* xi = Xp0 ? (row < T_P ? Xp0 + (size_t)row * 1024 + col0 : Xs0 + (size_t)(row - T_P) * 1024 + col0) : xp;
;                 float ss = 0.f;
; #pragma unroll
;                 for (int bj = 0; bj < 2; ++bj)
; #pragma unroll
;                     for (int n = 0; n < 2; ++n) {
;                         f32x4 xv = *(const f32x4*)(xi + bj * 128 + n * 16) + acc[ai][bj][m][n];
;                         *(f32x4*)(xp + bj * 128 + n * 16) = xv;
;                         ss += (xv[0] * xv[0] + xv[1] * xv[1]) + (xv[2] * xv[2] + xv[3] * xv[3]);
;                         u32x2 w; w.x = cvt_pk_bf16(xv[0], xv[1]); w.y = cvt_pk_bf16(xv[2], xv[3]);
;                         *(u32x2*)(bp + bj * 128 + n * 16) = w; }
;                 ss += __shfl_xor(ss, 16); ss += __shfl_xor(ss, 32);
;                 if (fq == 0) atomicAdd(rowss_out + row, ss); }
	s_add_u32 s14, s34, 0x100080
	s_addc_u32 s15, s35, 0
	s_add_i32 s16, s17, s49
	s_mov_b32 m0, s16
	s_nop 0
	global_load_lds_dwordx4 v128, s[14:15]
	s_add_i32 m0, s16, 0x2000
	s_nop 0
	global_load_lds_dwordx4 v148, s[14:15]
	s_waitcnt vmcnt(6)
	s_barrier
	v_mfma_f32_16x16x32_bf16 v[52:55], v[216:219], v[174:177], v[52:55]
	v_mfma_f32_16x16x32_bf16 v[48:51], v[224:227], v[174:177], v[48:51]
	v_mfma_f32_16x16x32_bf16 v[36:39], v[216:219], v[192:195], v[36:39]
	v_mfma_f32_16x16x32_bf16 v[32:35], v[224:227], v[192:195], v[32:35]
	v_mfma_f32_16x16x32_bf16 v[20:23], v[216:219], v[200:203], v[20:23]
	v_mfma_f32_16x16x32_bf16 v[16:19], v[224:227], v[200:203], v[16:19]
	v_mfma_f32_16x16x32_bf16 v[4:7], v[216:219], v[208:211], v[4:7]
	v_mfma_f32_16x16x32_bf16 v[0:3], v[224:227], v[208:211], v[0:3]
	v_mfma_f32_16x16x32_bf16 v[52:55], v[220:223], v[178:181], v[52:55]
	v_mfma_f32_16x16x32_bf16 v[48:51], v[228:231], v[178:181], v[48:51]
	v_mfma_f32_16x16x32_bf16 v[36:39], v[220:223], v[196:199], v[36:39]
	v_mfma_f32_16x16x32_bf16 v[32:35], v[228:231], v[196:199], v[32:35]
	v_mfma_f32_16x16x32_bf16 v[20:23], v[220:223], v[204:207], v[20:23]
	v_mfma_f32_16x16x32_bf16 v[16:19], v[228:231], v[204:207], v[16:19]
	v_mfma_f32_16x16x32_bf16 v[4:7], v[220:223], v[212:215], v[4:7]
	v_mfma_f32_16x16x32_bf16 v[0:3], v[228:231], v[212:215], v[0:3]
	s_cmp_gt_u32 s65, 61
	s_mov_b64 s[26:27], s[30:31]
	s_barrier
	s_cbranch_scc0 .LBB0_1183
	v_lshl_add_u32 v156, s22, 8, v139
	v_ashrrev_i32_e32 v157, 31, v156
	v_lshl_or_b32 v154, s24, 8, v159
	v_lshlrev_b64 v[162:163], 12, v[156:157]
	v_ashrrev_i32_e32 v155, 31, v154
	v_lshl_add_u64 v[162:163], s[84:85], 0, v[162:163]
	v_lshl_add_u64 v[170:171], v[154:155], 2, v[162:163]
	global_load_dwordx4 v[192:195], v[170:171], off
	global_load_dwordx4 v[196:199], v[170:171], off offset:64
	global_load_dwordx4 v[200:203], v[170:171], off offset:512
	global_load_dwordx4 v[204:207], v[170:171], off offset:576
	v_add_co_u32_e32 v224, vcc, 0x10000, v170
	s_nop 1
	v_addc_co_u32_e32 v225, vcc, 0, v171, vcc
	global_load_dwordx4 v[208:211], v[224:225], off
	global_load_dwordx4 v[212:215], v[224:225], off offset:64
	global_load_dwordx4 v[216:219], v[224:225], off offset:512
	global_load_dwordx4 v[220:223], v[224:225], off offset:576
	v_lshlrev_b64 v[166:167], 11, v[156:157]
	v_lshl_add_u64 v[166:167], s[0:1], 0, v[166:167]
	v_lshl_add_u64 v[172:173], v[154:155], 1, v[166:167]
	v_xor_b32_e32 v161, 32, v189
	s_waitcnt vmcnt(4)
	v_mov_b32_e32 v162, v192
	v_mov_b32_e32 v163, v193
	v_mov_b32_e32 v164, v194
	v_mov_b32_e32 v165, v195
	v_pk_add_f32 v[126:127], v[126:127], v[164:165]
	v_pk_add_f32 v[124:125], v[124:125], v[162:163]
	v_cvt_pk_bf16_f32 v163, v126, v127
	v_cvt_pk_bf16_f32 v162, v124, v125
	global_store_dwordx4 v[170:171], v[124:127], off
	global_store_dwordx2 v[172:173], v[162:163], off
	s_nop 1
	v_mov_b32_e32 v162, v196
	v_mov_b32_e32 v163, v197
	v_mov_b32_e32 v164, v198
	v_mov_b32_e32 v165, v199
	v_pk_add_f32 v[122:123], v[122:123], v[164:165]
	v_pk_add_f32 v[120:121], v[120:121], v[162:163]
	v_cvt_pk_bf16_f32 v163, v122, v123
	v_cvt_pk_bf16_f32 v162, v120, v121
	global_store_dwordx4 v[170:171], v[120:123], off offset:64
	global_store_dwordx2 v[172:173], v[162:163], off offset:32
	s_nop 1
	v_mov_b32_e32 v162, v200
	v_mov_b32_e32 v163, v201
	v_mov_b32_e32 v164, v202
	v_mov_b32_e32 v165, v203
	v_pk_add_f32 v[164:165], v[118:119], v[164:165]
	v_pk_add_f32 v[162:163], v[116:117], v[162:163]
	v_cvt_pk_bf16_f32 v117, v164, v165
	v_cvt_pk_bf16_f32 v116, v162, v163
	global_store_dwordx4 v[170:171], v[162:165], off offset:512
	global_store_dwordx2 v[172:173], v[116:117], off offset:256
	s_nop 1
	v_mov_b32_e32 v166, v204
	v_mov_b32_e32 v167, v205
	v_mov_b32_e32 v168, v206
	v_mov_b32_e32 v169, v207
	v_mul_f32_e32 v118, v125, v125
	v_mul_f32_e32 v119, v127, v127
	v_fmac_f32_e32 v118, v124, v124
	v_fmac_f32_e32 v119, v126, v126
	v_add_f32_e32 v118, v118, v119
	v_mul_f32_e32 v119, v121, v121
	v_mul_f32_e32 v121, v123, v123
	v_fmac_f32_e32 v119, v120, v120
	v_fmac_f32_e32 v121, v122, v122
	v_add_f32_e32 v119, v119, v121
	v_add_f32_e32 v118, v118, v119
	v_mul_f32_e32 v119, v163, v163
	v_mul_f32_e32 v120, v165, v165
	v_fmac_f32_e32 v119, v162, v162
	v_fmac_f32_e32 v120, v164, v164
	v_add_f32_e32 v119, v119, v120
	v_and_b32_e32 v117, 64, v189
	v_add_f32_e32 v122, v118, v119
	v_xor_b32_e32 v116, 16, v189
	v_add_u32_e32 v117, 64, v117
	v_cmp_lt_i32_e32 vcc, v116, v117
	v_pk_add_f32 v[120:121], v[114:115], v[168:169]
	v_pk_add_f32 v[118:119], v[112:113], v[166:167]
	v_mul_f32_e32 v113, v121, v121
	v_mul_f32_e32 v112, v119, v119
	v_fmac_f32_e32 v112, v118, v118
	v_fmac_f32_e32 v113, v120, v120
	v_cndmask_b32_e32 v116, v189, v116, vcc
	v_add_f32_e32 v112, v112, v113
	v_lshlrev_b32_e32 v116, 2, v116
	v_add_f32_e32 v112, v122, v112
	ds_bpermute_b32 v113, v116, v112
	v_cmp_lt_i32_e32 vcc, v161, v117
	global_store_dwordx4 v[170:171], v[118:121], off offset:576
	s_waitcnt lgkmcnt(0)
	v_add_f32_e32 v115, v112, v113
	v_cndmask_b32_e32 v114, v189, v161, vcc
	v_lshlrev_b32_e32 v114, 2, v114
	ds_bpermute_b32 v117, v114, v115
	v_cvt_pk_bf16_f32 v112, v118, v119
	v_cvt_pk_bf16_f32 v113, v120, v121
	global_store_dwordx2 v[172:173], v[112:113], off offset:288
	v_lshl_add_u64 v[112:113], v[156:157], 2, s[2:3]
	s_and_saveexec_b64 s[22:23], s[38:39]
	s_cbranch_execz .LBB0_1186
	s_waitcnt lgkmcnt(0)
	v_add_f32_e32 v115, v115, v117
	global_atomic_add_f32 v[112:113], v115, off

; #define PG8_STAGE(bufoff, gbase, voff) do { _Pragma("unroll") for (int _i = 0; _i < 2; ++_i) \
;         __builtin_amdgcn_global_load_lds((const unsigned*)((const char*)(gbase) + (voff)[_i]), (PG8_LAS unsigned*)(lds + (bufoff) + ldsw + _i * 8192), 16, 0, 0); } while (0)
; #define PG8_LDA(dst, b, h) do { _Pragma("unroll") for (int m = 0; m < 4; ++m) _Pragma("unroll") for (int k = 0; k < 2; ++k) dst[m][k] = *(const PG8_LAS bf16x8*)(lds + PG8_SA(b, h) + aoff + m * 2048 + k * 1024); } while (0)
; #define PG8_LDB(dst, b, h) do { _Pragma("unroll") for (int n = 0; n < 2; ++n) _Pragma("unroll") for (int k = 0; k < 2; ++k) dst[n][k] = *(const PG8_LAS bf16x8*)(lds + PG8_SB(b, h) + boff + n * 2048 + k * 1024); } while (0)
; #define PG8_MMA(ai, bj, At, Bt) do { __builtin_amdgcn_s_setprio(1); _Pragma("unroll") for (int m = 0; m < 4; ++m) _Pragma("unroll") for (int n = 0; n < 2; ++n) _Pragma("unroll") for (int k = 0; k < 2; ++k) \
;         acc[ai][bj][m][n] = __builtin_amdgcn_mfma_f32_16x16x32_bf16(Bt[n][k], At[m][k], acc[ai][bj][m][n], 0, 0, 0); __builtin_amdgcn_s_setprio(0); } while (0)
; #define PG8_WAIT_L(n) asm volatile("s_waitcnt lgkmcnt(" #n ")" ::: "memory")
; #define PG8_BAR __builtin_amdgcn_s_barrier()
; #define PG8_SCHED __builtin_amdgcn_sched_barrier(0)
; template <class Epi, class Sched, bool STAMP = false>
; __device__ __forceinline__ void gemm_phase(PG8_LAS unsigned char* lds, const Gemm g, const Sched& S, const Epi& E, unsigned long long* stamps) {
;     ...
;             const bool last = (t == nt - 2);
;             const char* a1 = cA + (size_t)(t + 1) * kstep;
;             const char* a2 = last ? nA : cA + (size_t)(t + 2) * kstep; const char* b2 = last ? nB : cB + (size_t)(t + 2) * kstep;
;             const char* a3 = a2 + kstep; const char* b3 = b2 + kstep;
;             if (last && has_next) S.a_ready(nxt);
;             PG8_LDB(B0, 0, 0); PG8_SCHED; PG8_LDA(At, 0, 0); PG8_STAGE(PG8_SA(1, 1), a1 + hstep, voffA);
;             PG8_WAIT_L(8); PG8_BAR; PG8_WAIT_L(0); PG8_MMA(0, 0, At, B0); PG8_BAR; PG8_SCHED;
;             PG8_LDB(B1, 0, 1); PG8_STAGE(PG8_SB(0, 0), b2, voffB);
;             PG8_BAR; PG8_WAIT_L(0); PG8_MMA(0, 1, At, B1); PG8_BAR;
;             PG8_LDA(At, 0, 1); PG8_STAGE(PG8_SA(0, 0), a2, voffA);
;             PG8_BAR; PG8_WAIT_L(0); PG8_MMA(1, 0, At, B0); PG8_BAR; PG8_SCHED;
.LBB0_1207:
	s_add_u32 s6, s4, 0x100
	s_addc_u32 s7, s5, 0
	s_cmp_lg_u32 s39, 4
	s_cselect_b32 s12, s6, 0
	s_cselect_b32 s13, s7, 0
	s_add_u32 s20, s2, s12
	s_addc_u32 s21, s3, s13
	s_add_i32 s14, 0, 0x10000
	ds_read_b128 v[158:161], v248
	ds_read_b128 v[162:165], v248 offset:1024
	ds_read_b128 v[166:169], v248 offset:2048
	ds_read_b128 v[170:173], v248 offset:3072
	s_add_u32 s12, s0, s12
	s_addc_u32 s13, s1, s13
	v_lshl_add_u64 v[182:183], v[150:151], 0, s[4:5]
	s_add_i32 m0, s27, 0xc000
	ds_read_b128 v[174:177], v156
	ds_read_b128 v[178:181], v156 offset:1024
	ds_read_b128 v[192:195], v156 offset:2048
	ds_read_b128 v[196:199], v156 offset:3072
	ds_read_b128 v[200:203], v156 offset:4096
	ds_read_b128 v[204:207], v156 offset:5120
	ds_read_b128 v[208:211], v156 offset:6144
	ds_read_b128 v[212:215], v156 offset:7168
	global_load_lds_dwordx4 v[182:183], off
	v_lshl_add_u64 v[182:183], v[152:153], 0, s[4:5]
	s_add_i32 m0, s27, 0xe000
	s_nop 0
	global_load_lds_dwordx4 v[182:183], off
	s_waitcnt lgkmcnt(8)
	s_barrier
	s_waitcnt lgkmcnt(0)
	v_mfma_f32_16x16x32_bf16 v[124:127], v[158:161], v[174:177], v[124:127]
	v_mfma_f32_16x16x32_bf16 v[120:123], v[166:169], v[174:177], v[120:123]
	v_mfma_f32_16x16x32_bf16 v[116:119], v[158:161], v[192:195], v[116:119]
	v_mfma_f32_16x16x32_bf16 v[112:115], v[166:169], v[192:195], v[112:115]
	v_mfma_f32_16x16x32_bf16 v[104:107], v[158:161], v[200:203], v[104:107]
	v_mfma_f32_16x16x32_bf16 v[96:99], v[166:169], v[200:203], v[96:99]
	v_mfma_f32_16x16x32_bf16 v[88:91], v[158:161], v[208:211], v[88:91]
	v_mfma_f32_16x16x32_bf16 v[80:83], v[166:169], v[208:211], v[80:83]
	v_mfma_f32_16x16x32_bf16 v[124:127], v[162:165], v[178:181], v[124:127]
	v_mfma_f32_16x16x32_bf16 v[120:123], v[170:173], v[178:181], v[120:123]
	v_mfma_f32_16x16x32_bf16 v[116:119], v[162:165], v[196:199], v[116:119]
	v_mfma_f32_16x16x32_bf16 v[112:115], v[170:173], v[196:199], v[112:115]
	v_mfma_f32_16x16x32_bf16 v[104:107], v[162:165], v[204:207], v[104:107]
	v_mfma_f32_16x16x32_bf16 v[96:99], v[170:173], v[204:207], v[96:99]
	v_mfma_f32_16x16x32_bf16 v[88:91], v[162:165], v[212:215], v[88:91]
	v_mfma_f32_16x16x32_bf16 v[80:83], v[170:173], v[212:215], v[80:83]
	s_barrier
	s_add_i32 s15, 0, 0x14000
	s_add_i32 s4, s14, s26
	v_lshl_add_u64 v[182:183], s[12:13], 0, v[128:129]
	s_mov_b32 m0, s4
	ds_read_b128 v[216:219], v249
	ds_read_b128 v[220:223], v249 offset:1024
	ds_read_b128 v[224:227], v249 offset:2048
	ds_read_b128 v[228:231], v249 offset:3072
	global_load_lds_dwordx4 v128, s[12:13]
	v_lshl_add_u64 v[232:233], s[12:13], 0, v[148:149]
	s_add_i32 m0, s4, 0x2000
	s_nop 0
	global_load_lds_dwordx4 v148, s[12:13]
	s_barrier
	s_waitcnt lgkmcnt(0)
	v_mfma_f32_16x16x32_bf16 v[108:111], v[216:219], v[174:177], v[108:111]
	v_mfma_f32_16x16x32_bf16 v[100:103], v[224:227], v[174:177], v[100:103]
	v_mfma_f32_16x16x32_bf16 v[92:95], v[216:219], v[192:195], v[92:95]
	v_mfma_f32_16x16x32_bf16 v[84:87], v[224:227], v[192:195], v[84:87]
	v_mfma_f32_16x16x32_bf16 v[76:79], v[216:219], v[200:203], v[76:79]
	v_mfma_f32_16x16x32_bf16 v[72:75], v[224:227], v[200:203], v[72:75]
	v_mfma_f32_16x16x32_bf16 v[68:71], v[216:219], v[208:211], v[68:71]
	v_mfma_f32_16x16x32_bf16 v[64:67], v[224:227], v[208:211], v[64:67]
	v_mfma_f32_16x16x32_bf16 v[108:111], v[220:223], v[178:181], v[108:111]
	v_mfma_f32_16x16x32_bf16 v[100:103], v[228:231], v[178:181], v[100:103]
	v_mfma_f32_16x16x32_bf16 v[92:95], v[220:223], v[196:199], v[92:95]
	v_mfma_f32_16x16x32_bf16 v[84:87], v[228:231], v[196:199], v[84:87]
	v_mfma_f32_16x16x32_bf16 v[76:79], v[220:223], v[204:207], v[76:79]
	v_mfma_f32_16x16x32_bf16 v[72:75], v[228:231], v[204:207], v[72:75]
	v_mfma_f32_16x16x32_bf16 v[68:71], v[220:223], v[212:215], v[68:71]
	v_mfma_f32_16x16x32_bf16 v[64:67], v[228:231], v[212:215], v[64:67]
	s_mov_b32 m0, s27
	v_lshl_add_u64 v[234:235], s[20:21], 0, v[128:129]
	s_barrier
	ds_read_b128 v[174:177], v156 offset:16384
	ds_read_b128 v[178:181], v156 offset:17408
	ds_read_b128 v[192:195], v156 offset:18432
	ds_read_b128 v[196:199], v156 offset:19456
	ds_read_b128 v[200:203], v156 offset:20480
	ds_read_b128 v[204:207], v156 offset:21504
	ds_read_b128 v[208:211], v156 offset:22528
	ds_read_b128 v[212:215], v156 offset:23552
	global_load_lds_dwordx4 v128, s[20:21]
	v_lshl_add_u64 v[236:237], s[20:21], 0, v[148:149]
	s_mov_b32 m0, s30
	s_nop 0
	global_load_lds_dwordx4 v148, s[20:21]
	s_barrier
	s_waitcnt lgkmcnt(0)
	v_mfma_f32_16x16x32_bf16 v[60:63], v[158:161], v[174:177], v[60:63]
	v_mfma_f32_16x16x32_bf16 v[56:59], v[166:169], v[174:177], v[56:59]
	v_mfma_f32_16x16x32_bf16 v[52:55], v[158:161], v[192:195], v[52:55]
	v_mfma_f32_16x16x32_bf16 v[48:51], v[166:169], v[192:195], v[48:51]
	v_mfma_f32_16x16x32_bf16 v[36:39], v[158:161], v[200:203], v[36:39]
	v_mfma_f32_16x16x32_bf16 v[32:35], v[166:169], v[200:203], v[32:35]
	v_mfma_f32_16x16x32_bf16 v[20:23], v[158:161], v[208:211], v[20:23]
	v_mfma_f32_16x16x32_bf16 v[16:19], v[166:169], v[208:211], v[16:19]
	v_mfma_f32_16x16x32_bf16 v[60:63], v[162:165], v[178:181], v[60:63]
	v_mfma_f32_16x16x32_bf16 v[56:59], v[170:173], v[178:181], v[56:59]
	v_mfma_f32_16x16x32_bf16 v[52:55], v[162:165], v[196:199], v[52:55]
	v_mfma_f32_16x16x32_bf16 v[48:51], v[170:173], v[196:199], v[48:51]
	v_mfma_f32_16x16x32_bf16 v[36:39], v[162:165], v[204:207], v[36:39]
	v_mfma_f32_16x16x32_bf16 v[32:35], v[170:173], v[204:207], v[32:35]
	v_mfma_f32_16x16x32_bf16 v[20:23], v[162:165], v[212:215], v[20:23]
	v_mfma_f32_16x16x32_bf16 v[16:19], v[170:173], v[212:215], v[16:19]
	s_barrier
; #define PG8_STAGE(bufoff, gbase, voff) do { _Pragma("unroll") for (int _i = 0; _i < 2; ++_i) \
;         __builtin_amdgcn_global_load_lds((const unsigned*)((const char*)(gbase) + (voff)[_i]), (PG8_LAS unsigned*)(lds + (bufoff) + ldsw + _i * 8192), 16, 0, 0); } while (0)
; #define PG8_LDA(dst, b, h) do { _Pragma("unroll") for (int m = 0; m < 4; ++m) _Pragma("unroll") for (int k = 0; k < 2; ++k) dst[m][k] = *(const PG8_LAS bf16x8*)(lds + PG8_SA(b, h) + aoff + m * 2048 + k * 1024); } while (0)
; #define PG8_LDB(dst, b, h) do { _Pragma("unroll") for (int n = 0; n < 2; ++n) _Pragma("unroll") for (int k = 0; k < 2; ++k) dst[n][k] = *(const PG8_LAS bf16x8*)(lds + PG8_SB(b, h) + boff + n * 2048 + k * 1024); } while (0)
; #define PG8_MMA(ai, bj, At, Bt) do { __builtin_amdgcn_s_setprio(1); _Pragma("unroll") for (int m = 0; m < 4; ++m) _Pragma("unroll") for (int n = 0; n < 2; ++n) _Pragma("unroll") for (int k = 0; k < 2; ++k) \
;         acc[ai][bj][m][n] = __builtin_amdgcn_mfma_f32_16x16x32_bf16(Bt[n][k], At[m][k], acc[ai][bj][m][n], 0, 0, 0); __builtin_amdgcn_s_setprio(0); } while (0)
; #define PG8_WAIT_V(n) asm volatile("s_waitcnt vmcnt(" #n ")" ::: "memory")
; #define PG8_WAIT_L(n) asm volatile("s_waitcnt lgkmcnt(" #n ")" ::: "memory")
; #define PG8_BAR __builtin_amdgcn_s_barrier()
; #define PG8_SCHED __builtin_amdgcn_sched_barrier(0)
; template <class Epi, class Sched, bool STAMP = false>
; __device__ __forceinline__ void gemm_phase(PG8_LAS unsigned char* lds, const Gemm g, const Sched& S, const Epi& E, unsigned long long* stamps) {
;     ...
;             PG8_STAGE(PG8_SB(0, 1), b2 + hstep, voffB);
;             PG8_WAIT_V(6); PG8_BAR; PG8_MMA(1, 1, At, B1); PG8_BAR;
;             PG8_LDB(B0, 1, 0); PG8_SCHED; PG8_LDA(At, 1, 0); PG8_STAGE(PG8_SA(0, 1), a2 + hstep, voffA);
;             PG8_WAIT_L(8); PG8_BAR; PG8_WAIT_L(0); PG8_MMA(0, 0, At, B0); PG8_BAR; PG8_SCHED;
;             PG8_LDB(B1, 1, 1); PG8_STAGE(PG8_SB(1, 0), b3, voffB);
;             PG8_BAR; PG8_WAIT_L(0); PG8_MMA(0, 1, At, B1); PG8_BAR;
;             PG8_LDA(At, 1, 1); PG8_STAGE(PG8_SA(1, 0), a3, voffA);
;             PG8_BAR; PG8_WAIT_L(0); PG8_MMA(1, 0, At, B0); PG8_BAR; PG8_SCHED;
	s_add_u32 s4, s12, 0x100000
	s_addc_u32 s5, s13, 0
	s_add_i32 s14, s15, s26
	s_mov_b32 m0, s14
	s_nop 0
	global_load_lds_dwordx4 v128, s[4:5]
	s_add_i32 m0, s14, 0x2000
	s_nop 0
	global_load_lds_dwordx4 v148, s[4:5]
	s_add_i32 s39, s39, 2
	s_waitcnt vmcnt(6)
	s_barrier
	v_mfma_f32_16x16x32_bf16 v[44:47], v[216:219], v[174:177], v[44:47]
	v_mfma_f32_16x16x32_bf16 v[40:43], v[224:227], v[174:177], v[40:43]
	v_mfma_f32_16x16x32_bf16 v[28:31], v[216:219], v[192:195], v[28:31]
	v_mfma_f32_16x16x32_bf16 v[24:27], v[224:227], v[192:195], v[24:27]
	v_mfma_f32_16x16x32_bf16 v[12:15], v[216:219], v[200:203], v[12:15]
	v_mfma_f32_16x16x32_bf16 v[8:11], v[224:227], v[200:203], v[8:11]
	v_mfma_f32_16x16x32_bf16 v[4:7], v[216:219], v[208:211], v[4:7]
	v_mfma_f32_16x16x32_bf16 v[0:3], v[224:227], v[208:211], v[0:3]
	v_mfma_f32_16x16x32_bf16 v[44:47], v[220:223], v[178:181], v[44:47]
	v_mfma_f32_16x16x32_bf16 v[40:43], v[228:231], v[178:181], v[40:43]
	v_mfma_f32_16x16x32_bf16 v[28:31], v[220:223], v[196:199], v[28:31]
	v_mfma_f32_16x16x32_bf16 v[24:27], v[228:231], v[196:199], v[24:27]
	v_mfma_f32_16x16x32_bf16 v[12:15], v[220:223], v[204:207], v[12:15]
	v_mfma_f32_16x16x32_bf16 v[8:11], v[228:231], v[204:207], v[8:11]
	v_mfma_f32_16x16x32_bf16 v[4:7], v[220:223], v[212:215], v[4:7]
	v_mfma_f32_16x16x32_bf16 v[0:3], v[228:231], v[212:215], v[0:3]
	s_barrier
	s_add_i32 s14, 0, 0x18000
	ds_read_b128 v[158:161], v250
	ds_read_b128 v[162:165], v250 offset:1024
	ds_read_b128 v[166:169], v250 offset:2048
	ds_read_b128 v[170:173], v250 offset:3072
	s_add_u32 s4, s20, 0x100000
	s_addc_u32 s5, s21, 0
	s_mov_b32 m0, s31
	ds_read_b128 v[174:177], v156 offset:32768
	ds_read_b128 v[178:181], v156 offset:33792
	ds_read_b128 v[192:195], v156 offset:34816
	ds_read_b128 v[196:199], v156 offset:35840
	ds_read_b128 v[200:203], v156 offset:36864
	ds_read_b128 v[204:207], v156 offset:37888
	ds_read_b128 v[208:211], v156 offset:38912
	global_load_lds_dwordx4 v128, s[4:5]
	s_mov_b32 m0, s34
	ds_read_b128 v[212:215], v156 offset:39936
	global_load_lds_dwordx4 v148, s[4:5]
	s_waitcnt lgkmcnt(8)
	s_barrier
	s_waitcnt lgkmcnt(0)
	v_mfma_f32_16x16x32_bf16 v[124:127], v[158:161], v[174:177], v[124:127]
	v_mfma_f32_16x16x32_bf16 v[120:123], v[166:169], v[174:177], v[120:123]
	v_mfma_f32_16x16x32_bf16 v[116:119], v[158:161], v[192:195], v[116:119]
	v_mfma_f32_16x16x32_bf16 v[112:115], v[166:169], v[192:195], v[112:115]
	v_mfma_f32_16x16x32_bf16 v[104:107], v[158:161], v[200:203], v[104:107]
	v_mfma_f32_16x16x32_bf16 v[96:99], v[166:169], v[200:203], v[96:99]
	v_mfma_f32_16x16x32_bf16 v[88:91], v[158:161], v[208:211], v[88:91]
	v_mfma_f32_16x16x32_bf16 v[80:83], v[166:169], v[208:211], v[80:83]
	v_mfma_f32_16x16x32_bf16 v[124:127], v[162:165], v[178:181], v[124:127]
	v_mfma_f32_16x16x32_bf16 v[120:123], v[170:173], v[178:181], v[120:123]
	v_mfma_f32_16x16x32_bf16 v[116:119], v[162:165], v[196:199], v[116:119]
	v_mfma_f32_16x16x32_bf16 v[112:115], v[170:173], v[196:199], v[112:115]
	v_mfma_f32_16x16x32_bf16 v[104:107], v[162:165], v[204:207], v[104:107]
	v_mfma_f32_16x16x32_bf16 v[96:99], v[170:173], v[204:207], v[96:99]
	v_mfma_f32_16x16x32_bf16 v[88:91], v[162:165], v[212:215], v[88:91]
	v_mfma_f32_16x16x32_bf16 v[80:83], v[170:173], v[212:215], v[80:83]
	s_barrier
	s_add_i32 s15, 0, 0x1c000
	s_add_i32 s4, s14, s26
	v_lshl_add_u64 v[182:183], v[182:183], 0, s[18:19]
	s_mov_b32 m0, s4
	ds_read_b128 v[216:219], v251
	ds_read_b128 v[220:223], v251 offset:1024
	ds_read_b128 v[224:227], v251 offset:2048
	ds_read_b128 v[228:231], v251 offset:3072
	global_load_lds_dwordx4 v244, s[12:13]
	v_lshl_add_u64 v[182:183], v[232:233], 0, s[18:19]
	s_add_i32 m0, s4, 0x2000
	s_nop 0
	global_load_lds_dwordx4 v245, s[12:13]
	s_barrier
	s_waitcnt lgkmcnt(0)
	v_mfma_f32_16x16x32_bf16 v[108:111], v[216:219], v[174:177], v[108:111]
	v_mfma_f32_16x16x32_bf16 v[100:103], v[224:227], v[174:177], v[100:103]
	v_mfma_f32_16x16x32_bf16 v[92:95], v[216:219], v[192:195], v[92:95]
	v_mfma_f32_16x16x32_bf16 v[84:87], v[224:227], v[192:195], v[84:87]
	v_mfma_f32_16x16x32_bf16 v[76:79], v[216:219], v[200:203], v[76:79]
	v_mfma_f32_16x16x32_bf16 v[72:75], v[224:227], v[200:203], v[72:75]
	v_mfma_f32_16x16x32_bf16 v[68:71], v[216:219], v[208:211], v[68:71]
	v_mfma_f32_16x16x32_bf16 v[64:67], v[224:227], v[208:211], v[64:67]
	v_mfma_f32_16x16x32_bf16 v[108:111], v[220:223], v[178:181], v[108:111]
	v_mfma_f32_16x16x32_bf16 v[100:103], v[228:231], v[178:181], v[100:103]
	v_mfma_f32_16x16x32_bf16 v[92:95], v[220:223], v[196:199], v[92:95]
	v_mfma_f32_16x16x32_bf16 v[84:87], v[228:231], v[196:199], v[84:87]
	v_mfma_f32_16x16x32_bf16 v[76:79], v[220:223], v[204:207], v[76:79]
	v_mfma_f32_16x16x32_bf16 v[72:75], v[228:231], v[204:207], v[72:75]
	v_mfma_f32_16x16x32_bf16 v[68:71], v[220:223], v[212:215], v[68:71]
	v_mfma_f32_16x16x32_bf16 v[64:67], v[228:231], v[212:215], v[64:67]
	s_mov_b32 m0, s37
	v_lshl_add_u64 v[182:183], v[234:235], 0, s[18:19]
	s_barrier
	ds_read_b128 v[174:177], v156 offset:49152
	ds_read_b128 v[178:181], v156 offset:50176
	ds_read_b128 v[192:195], v156 offset:51200
	ds_read_b128 v[196:199], v156 offset:52224
	ds_read_b128 v[200:203], v156 offset:53248
	ds_read_b128 v[204:207], v156 offset:54272
	ds_read_b128 v[208:211], v156 offset:55296
	ds_read_b128 v[212:215], v156 offset:56320
	global_load_lds_dwordx4 v244, s[20:21]
	v_lshl_add_u64 v[182:183], v[236:237], 0, s[18:19]
	s_mov_b32 m0, s38
	s_nop 0
	global_load_lds_dwordx4 v245, s[20:21]
	s_barrier
; #define PG8_STAGE(bufoff, gbase, voff) do { _Pragma("unroll") for (int _i = 0; _i < 2; ++_i) \
;         __builtin_amdgcn_global_load_lds((const unsigned*)((const char*)(gbase) + (voff)[_i]), (PG8_LAS unsigned*)(lds + (bufoff) + ldsw + _i * 8192), 16, 0, 0); } while (0)
; #define PG8_MMA(ai, bj, At, Bt) do { __builtin_amdgcn_s_setprio(1); _Pragma("unroll") for (int m = 0; m < 4; ++m) _Pragma("unroll") for (int n = 0; n < 2; ++n) _Pragma("unroll") for (int k = 0; k < 2; ++k) \
;         acc[ai][bj][m][n] = __builtin_amdgcn_mfma_f32_16x16x32_bf16(Bt[n][k], At[m][k], acc[ai][bj][m][n], 0, 0, 0); __builtin_amdgcn_s_setprio(0); } while (0)
; #define PG8_WAIT_V(n) asm volatile("s_waitcnt vmcnt(" #n ")" ::: "memory")
; #define PG8_WAIT_L(n) asm volatile("s_waitcnt lgkmcnt(" #n ")" ::: "memory")
; #define PG8_BAR __builtin_amdgcn_s_barrier()
; #define PG8_SCHED __builtin_amdgcn_sched_barrier(0)
; template <class Epi, class Sched, bool STAMP = false>
; __device__ __forceinline__ void gemm_phase(PG8_LAS unsigned char* lds, const Gemm g, const Sched& S, const Epi& E, unsigned long long* stamps) {
;     ...
;             PG8_BAR; PG8_WAIT_L(0); PG8_MMA(1, 0, At, B0); PG8_BAR; PG8_SCHED;
;             PG8_STAGE(PG8_SB(1, 1), b3 + hstep, voffB);
;             PG8_WAIT_V(6); PG8_BAR; PG8_MMA(1, 1, At, B1); PG8_BAR;
;     __device__ __forceinline__ void operator()(const f32x4 (&acc)[2][2][4][2], const pg8::Unit& u, int wr, int wc, int fr, int fq) const {
;         const int row0 = (u.pm - 64) * 256 + wr * 64 + fr, col0 = u.pn * 256 + wc * 32 + 4 * fq;
; #pragma unroll
;         for (int ai = 0; ai < 2; ++ai)
; #pragma unroll
;             for (int m = 0; m < 4; ++m) { float* xp = PART + (size_t)(row0 + ai * 128 + m * 16) * ldp + col0;
; #pragma unroll
;                 for (int bj = 0; bj < 2; ++bj)
; #pragma unroll
;                     for (int n = 0; n < 2; ++n) *(f32x4*)(xp + bj * 128 + n * 16) = acc[ai][bj][m][n]; }
;     }
	s_waitcnt lgkmcnt(0)
	v_mfma_f32_16x16x32_bf16 v[60:63], v[158:161], v[174:177], v[60:63]
	v_mfma_f32_16x16x32_bf16 v[56:59], v[166:169], v[174:177], v[56:59]
	v_mfma_f32_16x16x32_bf16 v[52:55], v[158:161], v[192:195], v[52:55]
	v_mfma_f32_16x16x32_bf16 v[48:51], v[166:169], v[192:195], v[48:51]
	v_mfma_f32_16x16x32_bf16 v[36:39], v[158:161], v[200:203], v[36:39]
	v_mfma_f32_16x16x32_bf16 v[32:35], v[166:169], v[200:203], v[32:35]
	v_mfma_f32_16x16x32_bf16 v[20:23], v[158:161], v[208:211], v[20:23]
	v_mfma_f32_16x16x32_bf16 v[16:19], v[166:169], v[208:211], v[16:19]
	v_mfma_f32_16x16x32_bf16 v[60:63], v[162:165], v[178:181], v[60:63]
	v_mfma_f32_16x16x32_bf16 v[56:59], v[170:173], v[178:181], v[56:59]
	v_mfma_f32_16x16x32_bf16 v[52:55], v[162:165], v[196:199], v[52:55]
	v_mfma_f32_16x16x32_bf16 v[48:51], v[170:173], v[196:199], v[48:51]
	v_mfma_f32_16x16x32_bf16 v[36:39], v[162:165], v[204:207], v[36:39]
	v_mfma_f32_16x16x32_bf16 v[32:35], v[170:173], v[204:207], v[32:35]
	v_mfma_f32_16x16x32_bf16 v[20:23], v[162:165], v[212:215], v[20:23]
	v_mfma_f32_16x16x32_bf16 v[16:19], v[170:173], v[212:215], v[16:19]
	s_barrier
	s_add_u32 s4, s12, 0x100080
	s_addc_u32 s5, s13, 0
	s_add_i32 s12, s15, s26
	s_mov_b32 m0, s12
	s_nop 0
	global_load_lds_dwordx4 v128, s[4:5]
	s_add_i32 m0, s12, 0x2000
	s_nop 0
	global_load_lds_dwordx4 v148, s[4:5]
	s_waitcnt vmcnt(6)
	s_barrier
	v_mfma_f32_16x16x32_bf16 v[44:47], v[216:219], v[174:177], v[44:47]
	v_mfma_f32_16x16x32_bf16 v[40:43], v[224:227], v[174:177], v[40:43]
	v_mfma_f32_16x16x32_bf16 v[28:31], v[216:219], v[192:195], v[28:31]
	v_mfma_f32_16x16x32_bf16 v[24:27], v[224:227], v[192:195], v[24:27]
	v_mfma_f32_16x16x32_bf16 v[12:15], v[216:219], v[200:203], v[12:15]
	v_mfma_f32_16x16x32_bf16 v[8:11], v[224:227], v[200:203], v[8:11]
	v_mfma_f32_16x16x32_bf16 v[4:7], v[216:219], v[208:211], v[4:7]
	v_mfma_f32_16x16x32_bf16 v[0:3], v[224:227], v[208:211], v[0:3]
	v_mfma_f32_16x16x32_bf16 v[44:47], v[220:223], v[178:181], v[44:47]
	v_mfma_f32_16x16x32_bf16 v[40:43], v[228:231], v[178:181], v[40:43]
	v_mfma_f32_16x16x32_bf16 v[28:31], v[220:223], v[196:199], v[28:31]
	v_mfma_f32_16x16x32_bf16 v[24:27], v[228:231], v[196:199], v[24:27]
	v_mfma_f32_16x16x32_bf16 v[12:15], v[220:223], v[204:207], v[12:15]
	v_mfma_f32_16x16x32_bf16 v[8:11], v[228:231], v[204:207], v[8:11]
	v_mfma_f32_16x16x32_bf16 v[4:7], v[220:223], v[212:215], v[4:7]
	v_mfma_f32_16x16x32_bf16 v[0:3], v[228:231], v[212:215], v[0:3]
	s_cmp_gt_u32 s39, 5
	s_mov_b64 s[4:5], s[6:7]
	s_barrier
	s_cbranch_scc0 .LBB0_1207
	s_lshl_b32 s0, s25, 22
	s_add_u32 s0, s10, s0
	s_addc_u32 s1, s42, 0
	s_add_u32 s0, s0, 0xdd00000
	s_addc_u32 s1, s1, 0
	s_lshl_b32 s2, s24, 8
	s_add_i32 s2, s2, s35
	v_add_u32_e32 v150, s2, v154
	v_add_u32_e32 v148, 0xffffc000, v150
	s_lshl_b32 s2, s23, 8
	v_lshl_or_b32 v128, v139, 2, s2
	v_ashrrev_i32_e32 v149, 31, v148
	v_or_b32_e32 v128, s36, v128
	v_lshlrev_b64 v[148:149], 12, v[148:149]
	v_lshl_add_u64 v[148:149], s[0:1], 0, v[148:149]
	v_lshlrev_b32_e32 v128, 2, v128
	v_lshl_add_u64 v[148:149], v[148:149], 0, v[128:129]
	global_store_dwordx4 v[148:149], v[124:127], off
	global_store_dwordx4 v[148:149], v[120:123], off offset:64
	global_store_dwordx4 v[148:149], v[108:111], off offset:512
	global_store_dwordx4 v[148:149], v[100:103], off offset:576
	s_cmpk_lt_u32 s22, 0x100
	v_readlane_b32 s39, v242, 28
	v_add_u32_e32 v100, 0xffffc010, v150
	v_ashrrev_i32_e32 v101, 31, v100
	v_lshlrev_b64 v[100:101], 12, v[100:101]
	v_lshl_add_u64 v[100:101], s[0:1], 0, v[100:101]
	v_lshl_add_u64 v[100:101], v[100:101], 0, v[128:129]
	global_store_dwordx4 v[100:101], v[116:119], off
	global_store_dwordx4 v[100:101], v[112:115], off offset:64
	global_store_dwordx4 v[100:101], v[92:95], off offset:512
	global_store_dwordx4 v[100:101], v[84:87], off offset:576
	s_mov_b32 s38, 0x1ffff
	s_nop 0
	v_add_u32_e32 v84, 0xffffc020, v150
	v_ashrrev_i32_e32 v85, 31, v84
	v_lshlrev_b64 v[84:85], 12, v[84:85]
	v_lshl_add_u64 v[84:85], s[0:1], 0, v[84:85]
	v_lshl_add_u64 v[84:85], v[84:85], 0, v[128:129]
	global_store_dwordx4 v[84:85], v[104:107], off
	global_store_dwordx4 v[84:85], v[96:99], off offset:64
	global_store_dwordx4 v[84:85], v[76:79], off offset:512
	global_store_dwordx4 v[84:85], v[72:75], off offset:576
	s_nop 1
	v_add_u32_e32 v72, 0xffffc030, v150
	v_ashrrev_i32_e32 v73, 31, v72
	v_lshlrev_b64 v[72:73], 12, v[72:73]
	v_lshl_add_u64 v[72:73], s[0:1], 0, v[72:73]
	v_lshl_add_u64 v[72:73], v[72:73], 0, v[128:129]
	s_mov_b64 s[0:1], 0x80000
	global_store_dwordx4 v[72:73], v[88:91], off
	global_store_dwordx4 v[72:73], v[80:83], off offset:64
	global_store_dwordx4 v[72:73], v[68:71], off offset:512
	global_store_dwordx4 v[72:73], v[64:67], off offset:576
	s_nop 1
	v_lshl_add_u64 v[64:65], v[148:149], 0, s[0:1]
	s_mov_b32 s0, 0x80000
	v_add_co_u32_e32 v66, vcc, s0, v148
	s_mov_b64 s[0:1], 0x90000
	s_nop 0
	v_addc_co_u32_e32 v67, vcc, 0, v149, vcc
	global_store_dwordx4 v[66:67], v[60:63], off
	global_store_dwordx4 v[64:65], v[56:59], off offset:64
	global_store_dwordx4 v[64:65], v[44:47], off offset:512
	global_store_dwordx4 v[64:65], v[40:43], off offset:576
	s_nop 1
	v_lshl_add_u64 v[40:41], v[148:149], 0, s[0:1]
	s_mov_b32 s0, 0x90000
	v_add_co_u32_e32 v42, vcc, s0, v148
	s_mov_b64 s[0:1], 0xa0000
	s_nop 0
	v_addc_co_u32_e32 v43, vcc, 0, v149, vcc
	global_store_dwordx4 v[42:43], v[52:55], off
	global_store_dwordx4 v[40:41], v[48:51], off offset:64
	global_store_dwordx4 v[40:41], v[28:31], off offset:512
	global_store_dwordx4 v[40:41], v[24:27], off offset:576
	s_nop 1
	v_lshl_add_u64 v[24:25], v[148:149], 0, s[0:1]
	s_mov_b32 s0, 0xa0000
	v_add_co_u32_e32 v26, vcc, s0, v148
	s_mov_b64 s[0:1], 0xb0000
	s_nop 0
	v_addc_co_u32_e32 v27, vcc, 0, v149, vcc
	global_store_dwordx4 v[26:27], v[36:39], off
	global_store_dwordx4 v[24:25], v[32:35], off offset:64
	global_store_dwordx4 v[24:25], v[12:15], off offset:512
	global_store_dwordx4 v[24:25], v[8:11], off offset:576
	s_nop 1
	v_add_co_u32_e32 v10, vcc, 0xb0000, v148
	v_lshl_add_u64 v[8:9], v[148:149], 0, s[0:1]
	s_nop 0
	v_addc_co_u32_e32 v11, vcc, 0, v149, vcc
	global_store_dwordx4 v[10:11], v[20:23], off
	global_store_dwordx4 v[8:9], v[16:19], off offset:64
	global_store_dwordx4 v[8:9], v[4:7], off offset:512
	global_store_dwordx4 v[8:9], v[0:3], off offset:576
	s_waitcnt vmcnt(0)
	s_cbranch_scc0 .LBB0_1210
	s_barrier

; #define PG8_STAGE(bufoff, gbase, voff) do { _Pragma("unroll") for (int _i = 0; _i < 2; ++_i) \
;         __builtin_amdgcn_global_load_lds((const unsigned*)((const char*)(gbase) + (voff)[_i]), (PG8_LAS unsigned*)(lds + (bufoff) + ldsw + _i * 8192), 16, 0, 0); } while (0)
; #define PG8_LDA(dst, b, h) do { _Pragma("unroll") for (int m = 0; m < 4; ++m) _Pragma("unroll") for (int k = 0; k < 2; ++k) dst[m][k] = *(const PG8_LAS bf16x8*)(lds + PG8_SA(b, h) + aoff + m * 2048 + k * 1024); } while (0)
; #define PG8_LDB(dst, b, h) do { _Pragma("unroll") for (int n = 0; n < 2; ++n) _Pragma("unroll") for (int k = 0; k < 2; ++k) dst[n][k] = *(const PG8_LAS bf16x8*)(lds + PG8_SB(b, h) + boff + n * 2048 + k * 1024); } while (0)
; #define PG8_MMA(ai, bj, At, Bt) do { __builtin_amdgcn_s_setprio(1); _Pragma("unroll") for (int m = 0; m < 4; ++m) _Pragma("unroll") for (int n = 0; n < 2; ++n) _Pragma("unroll") for (int k = 0; k < 2; ++k) \
;         acc[ai][bj][m][n] = __builtin_amdgcn_mfma_f32_16x16x32_bf16(Bt[n][k], At[m][k], acc[ai][bj][m][n], 0, 0, 0); __builtin_amdgcn_s_setprio(0); } while (0)
; #define PG8_WAIT_V(n) asm volatile("s_waitcnt vmcnt(" #n ")" ::: "memory")
; template <class Epi, class Sched, bool STAMP = false>
; __device__ __forceinline__ void gemm_phase(PG8_LAS unsigned char* lds, const Gemm g, const Sched& S, const Epi& E, unsigned long long* stamps) {
;     ...
;             const bool last = (t == nt - 2);
;             const char* a1 = cA + (size_t)(t + 1) * kstep;
;             const char* a2 = last ? nA : cA + (size_t)(t + 2) * kstep; const char* b2 = last ? nB : cB + (size_t)(t + 2) * kstep;
;             const char* a3 = a2 + kstep; const char* b3 = b2 + kstep;
;             if (last && has_next) S.a_ready(nxt);
;             PG8_LDB(B0, 0, 0); PG8_SCHED; PG8_LDA(At, 0, 0); PG8_STAGE(PG8_SA(1, 1), a1 + hstep, voffA);
;             PG8_WAIT_L(8); PG8_BAR; PG8_WAIT_L(0); PG8_MMA(0, 0, At, B0); PG8_BAR; PG8_SCHED;
;             PG8_LDB(B1, 0, 1); PG8_STAGE(PG8_SB(0, 0), b2, voffB);
;             PG8_BAR; PG8_WAIT_L(0); PG8_MMA(0, 1, At, B1); PG8_BAR;
;             PG8_LDA(At, 0, 1); PG8_STAGE(PG8_SA(0, 0), a2, voffA);
;             PG8_BAR; PG8_WAIT_L(0); PG8_MMA(1, 0, At, B0); PG8_BAR; PG8_SCHED;
;             PG8_STAGE(PG8_SB(0, 1), b2 + hstep, voffB);
;             PG8_WAIT_V(6); PG8_BAR; PG8_MMA(1, 1, At, B1); PG8_BAR;
.LBB0_1340:
	s_add_u32 s14, s24, 0xfffc0080
	s_addc_u32 s15, s25, -1
	s_add_i32 s16, 0, 0x10000
	ds_read_b128 v[158:161], v248
	ds_read_b128 v[162:165], v248 offset:1024
	ds_read_b128 v[170:173], v248 offset:2048
	ds_read_b128 v[174:177], v248 offset:3072
	s_cmp_eq_u32 s61, 12
	s_cselect_b32 s31, s7, s15
	s_cselect_b32 s30, s57, s14
	s_cselect_b32 s27, s5, s60
	s_cselect_b32 s26, s58, s59
	s_add_i32 m0, s23, 0xc000
	ds_read_b128 v[178:181], v168
	ds_read_b128 v[192:195], v168 offset:1024
	ds_read_b128 v[196:199], v168 offset:2048
	ds_read_b128 v[200:203], v168 offset:3072
	ds_read_b128 v[204:207], v168 offset:4096
	ds_read_b128 v[208:211], v168 offset:5120
	ds_read_b128 v[212:215], v168 offset:6144
	global_load_lds_dwordx4 v154, s[24:25]
	s_add_i32 m0, s23, 0xe000
	ds_read_b128 v[216:219], v168 offset:7168
	global_load_lds_dwordx4 v156, s[24:25]
	s_waitcnt lgkmcnt(8)
	s_barrier
	s_waitcnt lgkmcnt(0)
	v_mfma_f32_16x16x32_bf16 v[124:127], v[158:161], v[178:181], v[124:127]
	v_mfma_f32_16x16x32_bf16 v[120:123], v[170:173], v[178:181], v[120:123]
	v_mfma_f32_16x16x32_bf16 v[108:111], v[158:161], v[196:199], v[108:111]
	v_mfma_f32_16x16x32_bf16 v[104:107], v[170:173], v[196:199], v[104:107]
	v_mfma_f32_16x16x32_bf16 v[92:95], v[158:161], v[204:207], v[92:95]
	v_mfma_f32_16x16x32_bf16 v[88:91], v[170:173], v[204:207], v[88:91]
	v_mfma_f32_16x16x32_bf16 v[76:79], v[158:161], v[212:215], v[76:79]
	v_mfma_f32_16x16x32_bf16 v[72:75], v[170:173], v[212:215], v[72:75]
	v_mfma_f32_16x16x32_bf16 v[124:127], v[162:165], v[192:195], v[124:127]
	v_mfma_f32_16x16x32_bf16 v[120:123], v[174:177], v[192:195], v[120:123]
	v_mfma_f32_16x16x32_bf16 v[108:111], v[162:165], v[200:203], v[108:111]
	v_mfma_f32_16x16x32_bf16 v[104:107], v[174:177], v[200:203], v[104:107]
	v_mfma_f32_16x16x32_bf16 v[92:95], v[162:165], v[208:211], v[92:95]
	v_mfma_f32_16x16x32_bf16 v[88:91], v[174:177], v[208:211], v[88:91]
	v_mfma_f32_16x16x32_bf16 v[76:79], v[162:165], v[216:219], v[76:79]
	v_mfma_f32_16x16x32_bf16 v[72:75], v[174:177], v[216:219], v[72:75]
	s_barrier
	s_add_i32 s17, 0, 0x14000
	s_add_i32 s14, s16, s43
	s_mov_b32 m0, s14
	ds_read_b128 v[220:223], v249
	ds_read_b128 v[224:227], v249 offset:1024
	ds_read_b128 v[228:231], v249 offset:2048
	global_load_lds_dwordx4 v128, s[26:27]
	s_add_i32 m0, s14, 0x2000
	ds_read_b128 v[232:235], v249 offset:3072
	global_load_lds_dwordx4 v148, s[26:27]
	s_barrier
	s_waitcnt lgkmcnt(0)
	v_mfma_f32_16x16x32_bf16 v[116:119], v[220:223], v[178:181], v[116:119]
	v_mfma_f32_16x16x32_bf16 v[112:115], v[228:231], v[178:181], v[112:115]
	v_mfma_f32_16x16x32_bf16 v[100:103], v[220:223], v[196:199], v[100:103]
	v_mfma_f32_16x16x32_bf16 v[96:99], v[228:231], v[196:199], v[96:99]
	v_mfma_f32_16x16x32_bf16 v[84:87], v[220:223], v[204:207], v[84:87]
	v_mfma_f32_16x16x32_bf16 v[80:83], v[228:231], v[204:207], v[80:83]
	v_mfma_f32_16x16x32_bf16 v[68:71], v[220:223], v[212:215], v[68:71]
	v_mfma_f32_16x16x32_bf16 v[64:67], v[228:231], v[212:215], v[64:67]
	v_mfma_f32_16x16x32_bf16 v[116:119], v[224:227], v[192:195], v[116:119]
	v_mfma_f32_16x16x32_bf16 v[112:115], v[232:235], v[192:195], v[112:115]
	v_mfma_f32_16x16x32_bf16 v[100:103], v[224:227], v[200:203], v[100:103]
	v_mfma_f32_16x16x32_bf16 v[96:99], v[232:235], v[200:203], v[96:99]
	v_mfma_f32_16x16x32_bf16 v[84:87], v[224:227], v[208:211], v[84:87]
	v_mfma_f32_16x16x32_bf16 v[80:83], v[232:235], v[208:211], v[80:83]
	v_mfma_f32_16x16x32_bf16 v[68:71], v[224:227], v[216:219], v[68:71]
	v_mfma_f32_16x16x32_bf16 v[64:67], v[232:235], v[216:219], v[64:67]
	s_barrier
	s_mov_b32 m0, s23
	ds_read_b128 v[178:181], v168 offset:16384
	ds_read_b128 v[192:195], v168 offset:17408
	ds_read_b128 v[196:199], v168 offset:18432
	ds_read_b128 v[200:203], v168 offset:19456
	ds_read_b128 v[204:207], v168 offset:20480
	ds_read_b128 v[208:211], v168 offset:21504
	ds_read_b128 v[212:215], v168 offset:22528
	global_load_lds_dwordx4 v152, s[30:31]
	s_mov_b32 m0, s45
	ds_read_b128 v[216:219], v168 offset:23552
	global_load_lds_dwordx4 v150, s[30:31]
	s_barrier
	s_waitcnt lgkmcnt(0)
	v_mfma_f32_16x16x32_bf16 v[60:63], v[158:161], v[178:181], v[60:63]
	v_mfma_f32_16x16x32_bf16 v[56:59], v[170:173], v[178:181], v[56:59]
	v_mfma_f32_16x16x32_bf16 v[44:47], v[158:161], v[196:199], v[44:47]
	v_mfma_f32_16x16x32_bf16 v[40:43], v[170:173], v[196:199], v[40:43]
	v_mfma_f32_16x16x32_bf16 v[28:31], v[158:161], v[204:207], v[28:31]
	v_mfma_f32_16x16x32_bf16 v[24:27], v[170:173], v[204:207], v[24:27]
	v_mfma_f32_16x16x32_bf16 v[12:15], v[158:161], v[212:215], v[12:15]
	v_mfma_f32_16x16x32_bf16 v[8:11], v[170:173], v[212:215], v[8:11]
	v_mfma_f32_16x16x32_bf16 v[60:63], v[162:165], v[192:195], v[60:63]
	v_mfma_f32_16x16x32_bf16 v[56:59], v[174:177], v[192:195], v[56:59]
	v_mfma_f32_16x16x32_bf16 v[44:47], v[162:165], v[200:203], v[44:47]
	v_mfma_f32_16x16x32_bf16 v[40:43], v[174:177], v[200:203], v[40:43]
	v_mfma_f32_16x16x32_bf16 v[28:31], v[162:165], v[208:211], v[28:31]
	v_mfma_f32_16x16x32_bf16 v[24:27], v[174:177], v[208:211], v[24:27]
	v_mfma_f32_16x16x32_bf16 v[12:15], v[162:165], v[216:219], v[12:15]
	v_mfma_f32_16x16x32_bf16 v[8:11], v[174:177], v[216:219], v[8:11]
	s_barrier
	s_add_u32 s14, s26, 0x40000
	s_addc_u32 s15, s27, 0
	s_add_i32 s16, s17, s43
	s_mov_b32 m0, s16
	s_nop 0
	global_load_lds_dwordx4 v128, s[14:15]
	s_add_i32 m0, s16, 0x2000
	s_nop 0
	global_load_lds_dwordx4 v148, s[14:15]
	s_add_i32 s61, s61, 2
	s_add_u32 s24, s24, 0x100
	s_addc_u32 s25, s25, 0
	s_add_u32 s59, s59, 0x100
	s_addc_u32 s60, s60, 0
	s_waitcnt vmcnt(6)
	s_barrier
; #define PG8_STAGE(bufoff, gbase, voff) do { _Pragma("unroll") for (int _i = 0; _i < 2; ++_i) \
;         __builtin_amdgcn_global_load_lds((const unsigned*)((const char*)(gbase) + (voff)[_i]), (PG8_LAS unsigned*)(lds + (bufoff) + ldsw + _i * 8192), 16, 0, 0); } while (0)
; #define PG8_LDA(dst, b, h) do { _Pragma("unroll") for (int m = 0; m < 4; ++m) _Pragma("unroll") for (int k = 0; k < 2; ++k) dst[m][k] = *(const PG8_LAS bf16x8*)(lds + PG8_SA(b, h) + aoff + m * 2048 + k * 1024); } while (0)
; #define PG8_LDB(dst, b, h) do { _Pragma("unroll") for (int n = 0; n < 2; ++n) _Pragma("unroll") for (int k = 0; k < 2; ++k) dst[n][k] = *(const PG8_LAS bf16x8*)(lds + PG8_SB(b, h) + boff + n * 2048 + k * 1024); } while (0)
; #define PG8_MMA(ai, bj, At, Bt) do { __builtin_amdgcn_s_setprio(1); _Pragma("unroll") for (int m = 0; m < 4; ++m) _Pragma("unroll") for (int n = 0; n < 2; ++n) _Pragma("unroll") for (int k = 0; k < 2; ++k) \
;         acc[ai][bj][m][n] = __builtin_amdgcn_mfma_f32_16x16x32_bf16(Bt[n][k], At[m][k], acc[ai][bj][m][n], 0, 0, 0); __builtin_amdgcn_s_setprio(0); } while (0)
; #define PG8_WAIT_V(n) asm volatile("s_waitcnt vmcnt(" #n ")" ::: "memory")
; #define PG8_WAIT_L(n) asm volatile("s_waitcnt lgkmcnt(" #n ")" ::: "memory")
; #define PG8_BAR __builtin_amdgcn_s_barrier()
; #define PG8_SCHED __builtin_amdgcn_sched_barrier(0)
; template <class Epi, class Sched, bool STAMP = false>
; __device__ __forceinline__ void gemm_phase(PG8_LAS unsigned char* lds, const Gemm g, const Sched& S, const Epi& E, unsigned long long* stamps) {
;     ...
;             PG8_WAIT_V(6); PG8_BAR; PG8_MMA(1, 1, At, B1); PG8_BAR;
;             PG8_LDB(B0, 1, 0); PG8_SCHED; PG8_LDA(At, 1, 0); PG8_STAGE(PG8_SA(0, 1), a2 + hstep, voffA);
;             PG8_WAIT_L(8); PG8_BAR; PG8_WAIT_L(0); PG8_MMA(0, 0, At, B0); PG8_BAR; PG8_SCHED;
;             PG8_LDB(B1, 1, 1); PG8_STAGE(PG8_SB(1, 0), b3, voffB);
;             PG8_BAR; PG8_WAIT_L(0); PG8_MMA(0, 1, At, B1); PG8_BAR;
;             PG8_LDA(At, 1, 1); PG8_STAGE(PG8_SA(1, 0), a3, voffA);
;             PG8_BAR; PG8_WAIT_L(0); PG8_MMA(1, 0, At, B0); PG8_BAR; PG8_SCHED;
	v_mfma_f32_16x16x32_bf16 v[52:55], v[220:223], v[178:181], v[52:55]
	v_mfma_f32_16x16x32_bf16 v[48:51], v[228:231], v[178:181], v[48:51]
	v_mfma_f32_16x16x32_bf16 v[36:39], v[220:223], v[196:199], v[36:39]
	v_mfma_f32_16x16x32_bf16 v[32:35], v[228:231], v[196:199], v[32:35]
	v_mfma_f32_16x16x32_bf16 v[20:23], v[220:223], v[204:207], v[20:23]
	v_mfma_f32_16x16x32_bf16 v[16:19], v[228:231], v[204:207], v[16:19]
	v_mfma_f32_16x16x32_bf16 v[4:7], v[220:223], v[212:215], v[4:7]
	v_mfma_f32_16x16x32_bf16 v[0:3], v[228:231], v[212:215], v[0:3]
	v_mfma_f32_16x16x32_bf16 v[52:55], v[224:227], v[192:195], v[52:55]
	v_mfma_f32_16x16x32_bf16 v[48:51], v[232:235], v[192:195], v[48:51]
	v_mfma_f32_16x16x32_bf16 v[36:39], v[224:227], v[200:203], v[36:39]
	v_mfma_f32_16x16x32_bf16 v[32:35], v[232:235], v[200:203], v[32:35]
	v_mfma_f32_16x16x32_bf16 v[20:23], v[224:227], v[208:211], v[20:23]
	v_mfma_f32_16x16x32_bf16 v[16:19], v[232:235], v[208:211], v[16:19]
	v_mfma_f32_16x16x32_bf16 v[4:7], v[224:227], v[216:219], v[4:7]
	v_mfma_f32_16x16x32_bf16 v[0:3], v[232:235], v[216:219], v[0:3]
	s_barrier
	s_add_i32 s16, 0, 0x18000
	ds_read_b128 v[158:161], v250
	ds_read_b128 v[162:165], v250 offset:1024
	ds_read_b128 v[170:173], v250 offset:2048
	ds_read_b128 v[174:177], v250 offset:3072
	s_add_u32 s14, s30, 0x40000
	s_addc_u32 s15, s31, 0
	s_mov_b32 m0, s46
	ds_read_b128 v[178:181], v168 offset:32768
	ds_read_b128 v[192:195], v168 offset:33792
	ds_read_b128 v[196:199], v168 offset:34816
	ds_read_b128 v[200:203], v168 offset:35840
	ds_read_b128 v[204:207], v168 offset:36864
	ds_read_b128 v[208:211], v168 offset:37888
	ds_read_b128 v[212:215], v168 offset:38912
	global_load_lds_dwordx4 v152, s[14:15]
	s_mov_b32 m0, s47
	ds_read_b128 v[216:219], v168 offset:39936
	global_load_lds_dwordx4 v150, s[14:15]
	s_waitcnt lgkmcnt(8)
	s_barrier
	s_waitcnt lgkmcnt(0)
	v_mfma_f32_16x16x32_bf16 v[124:127], v[158:161], v[178:181], v[124:127]
	v_mfma_f32_16x16x32_bf16 v[120:123], v[170:173], v[178:181], v[120:123]
	v_mfma_f32_16x16x32_bf16 v[108:111], v[158:161], v[196:199], v[108:111]
	v_mfma_f32_16x16x32_bf16 v[104:107], v[170:173], v[196:199], v[104:107]
	v_mfma_f32_16x16x32_bf16 v[92:95], v[158:161], v[204:207], v[92:95]
	v_mfma_f32_16x16x32_bf16 v[88:91], v[170:173], v[204:207], v[88:91]
	v_mfma_f32_16x16x32_bf16 v[76:79], v[158:161], v[212:215], v[76:79]
	v_mfma_f32_16x16x32_bf16 v[72:75], v[170:173], v[212:215], v[72:75]
	v_mfma_f32_16x16x32_bf16 v[124:127], v[162:165], v[192:195], v[124:127]
	v_mfma_f32_16x16x32_bf16 v[120:123], v[174:177], v[192:195], v[120:123]
	v_mfma_f32_16x16x32_bf16 v[108:111], v[162:165], v[200:203], v[108:111]
	v_mfma_f32_16x16x32_bf16 v[104:107], v[174:177], v[200:203], v[104:107]
	v_mfma_f32_16x16x32_bf16 v[92:95], v[162:165], v[208:211], v[92:95]
	v_mfma_f32_16x16x32_bf16 v[88:91], v[174:177], v[208:211], v[88:91]
	v_mfma_f32_16x16x32_bf16 v[76:79], v[162:165], v[216:219], v[76:79]
	v_mfma_f32_16x16x32_bf16 v[72:75], v[174:177], v[216:219], v[72:75]
	s_barrier
	s_add_i32 s17, 0, 0x1c000
	s_add_i32 s14, s16, s43
	s_mov_b32 m0, s14
	ds_read_b128 v[220:223], v251
	ds_read_b128 v[224:227], v251 offset:1024
	ds_read_b128 v[228:231], v251 offset:2048
	global_load_lds_dwordx4 v244, s[26:27]
	s_add_i32 m0, s14, 0x2000
	ds_read_b128 v[232:235], v251 offset:3072
	global_load_lds_dwordx4 v245, s[26:27]
	s_barrier
	s_waitcnt lgkmcnt(0)
	v_mfma_f32_16x16x32_bf16 v[116:119], v[220:223], v[178:181], v[116:119]
	v_mfma_f32_16x16x32_bf16 v[112:115], v[228:231], v[178:181], v[112:115]
	v_mfma_f32_16x16x32_bf16 v[100:103], v[220:223], v[196:199], v[100:103]
	v_mfma_f32_16x16x32_bf16 v[96:99], v[228:231], v[196:199], v[96:99]
	v_mfma_f32_16x16x32_bf16 v[84:87], v[220:223], v[204:207], v[84:87]
	v_mfma_f32_16x16x32_bf16 v[80:83], v[228:231], v[204:207], v[80:83]
	v_mfma_f32_16x16x32_bf16 v[68:71], v[220:223], v[212:215], v[68:71]
	v_mfma_f32_16x16x32_bf16 v[64:67], v[228:231], v[212:215], v[64:67]
	v_mfma_f32_16x16x32_bf16 v[116:119], v[224:227], v[192:195], v[116:119]
	v_mfma_f32_16x16x32_bf16 v[112:115], v[232:235], v[192:195], v[112:115]
	v_mfma_f32_16x16x32_bf16 v[100:103], v[224:227], v[200:203], v[100:103]
	v_mfma_f32_16x16x32_bf16 v[96:99], v[232:235], v[200:203], v[96:99]
	v_mfma_f32_16x16x32_bf16 v[84:87], v[224:227], v[208:211], v[84:87]
	v_mfma_f32_16x16x32_bf16 v[80:83], v[232:235], v[208:211], v[80:83]
	v_mfma_f32_16x16x32_bf16 v[68:71], v[224:227], v[216:219], v[68:71]
	v_mfma_f32_16x16x32_bf16 v[64:67], v[232:235], v[216:219], v[64:67]
	s_barrier
	s_mov_b32 m0, s48
	ds_read_b128 v[178:181], v168 offset:49152
	ds_read_b128 v[192:195], v168 offset:50176
	ds_read_b128 v[196:199], v168 offset:51200
	ds_read_b128 v[200:203], v168 offset:52224
	ds_read_b128 v[204:207], v168 offset:53248
	ds_read_b128 v[208:211], v168 offset:54272
	ds_read_b128 v[212:215], v168 offset:55296
	global_load_lds_dwordx4 v246, s[30:31]
	s_mov_b32 m0, s49
	ds_read_b128 v[216:219], v168 offset:56320
	global_load_lds_dwordx4 v247, s[30:31]
	s_barrier
	s_waitcnt lgkmcnt(0)
	v_mfma_f32_16x16x32_bf16 v[60:63], v[158:161], v[178:181], v[60:63]
	v_mfma_f32_16x16x32_bf16 v[56:59], v[170:173], v[178:181], v[56:59]
	v_mfma_f32_16x16x32_bf16 v[44:47], v[158:161], v[196:199], v[44:47]
	v_mfma_f32_16x16x32_bf16 v[40:43], v[170:173], v[196:199], v[40:43]
	v_mfma_f32_16x16x32_bf16 v[28:31], v[158:161], v[204:207], v[28:31]
	v_mfma_f32_16x16x32_bf16 v[24:27], v[170:173], v[204:207], v[24:27]
	v_mfma_f32_16x16x32_bf16 v[12:15], v[158:161], v[212:215], v[12:15]
	v_mfma_f32_16x16x32_bf16 v[8:11], v[170:173], v[212:215], v[8:11]
	v_mfma_f32_16x16x32_bf16 v[60:63], v[162:165], v[192:195], v[60:63]
	v_mfma_f32_16x16x32_bf16 v[56:59], v[174:177], v[192:195], v[56:59]
	v_mfma_f32_16x16x32_bf16 v[44:47], v[162:165], v[200:203], v[44:47]
	v_mfma_f32_16x16x32_bf16 v[40:43], v[174:177], v[200:203], v[40:43]
	v_mfma_f32_16x16x32_bf16 v[28:31], v[162:165], v[208:211], v[28:31]
	v_mfma_f32_16x16x32_bf16 v[24:27], v[174:177], v[208:211], v[24:27]
	v_mfma_f32_16x16x32_bf16 v[12:15], v[162:165], v[216:219], v[12:15]
	v_mfma_f32_16x16x32_bf16 v[8:11], v[174:177], v[216:219], v[8:11]
	s_barrier
; __device__ __forceinline__ unsigned cvt_pk_bf16(float lo, float hi) { const f32x2_cv v = {lo, hi}; const bf16x2_cv b = __builtin_convertvector(v, bf16x2_cv); return __builtin_bit_cast(unsigned, b); }
; #define PG8_STAGE(bufoff, gbase, voff) do { _Pragma("unroll") for (int _i = 0; _i < 2; ++_i) \
;         __builtin_amdgcn_global_load_lds((const unsigned*)((const char*)(gbase) + (voff)[_i]), (PG8_LAS unsigned*)(lds + (bufoff) + ldsw + _i * 8192), 16, 0, 0); } while (0)
; #define PG8_MMA(ai, bj, At, Bt) do { __builtin_amdgcn_s_setprio(1); _Pragma("unroll") for (int m = 0; m < 4; ++m) _Pragma("unroll") for (int n = 0; n < 2; ++n) _Pragma("unroll") for (int k = 0; k < 2; ++k) \
;         acc[ai][bj][m][n] = __builtin_amdgcn_mfma_f32_16x16x32_bf16(Bt[n][k], At[m][k], acc[ai][bj][m][n], 0, 0, 0); __builtin_amdgcn_s_setprio(0); } while (0)
; #define PG8_WAIT_V(n) asm volatile("s_waitcnt vmcnt(" #n ")" ::: "memory")
; template <class Epi, class Sched, bool STAMP = false>
; __device__ __forceinline__ void gemm_phase(PG8_LAS unsigned char* lds, const Gemm g, const Sched& S, const Epi& E, unsigned long long* stamps) {
;     ...
;             PG8_STAGE(PG8_SB(1, 1), b3 + hstep, voffB);
;             PG8_WAIT_V(6); PG8_BAR; PG8_MMA(1, 1, At, B1); PG8_BAR;
;     __device__ __forceinline__ void operator()(const f32x4 (&acc)[2][2][4][2], const pg8::Unit& u, int wr, int wc, int fr, int fq) const {
;         const int row0 = u.pm * 256 + wr * 64 + fr, col0 = u.pn * 256 + wc * 32 + 8 * fq;
; #pragma unroll
;         for (int ai = 0; ai < 2; ++ai)
; #pragma unroll
;             for (int m = 0; m < 4; ++m) {
;                 const int row = row0 + ai * 128 + m * 16;
;                 const float s = (MODE == 2) ? 1.0f : rstd_of(rowss, row);
;                 bf16_t* rowp = O + (size_t)row * ldc + col0;
; #pragma unroll
;                 for (int bj = 0; bj < 2; ++bj) {
;                     f32x4 v0 = acc[ai][bj][m][0] * s, v1 = acc[ai][bj][m][1] * s;
;                     if (MODE == 1) {
; #pragma unroll
;                         for (int j = 0; j < 4; ++j) { const float a = fmaxf(v0[j], 0.f), b = fmaxf(v1[j], 0.f); v0[j] = a * a; v1[j] = b * b; } }
;                     u32x4 w; w.x = cvt_pk_bf16(v0[0], v0[1]); w.y = cvt_pk_bf16(v0[2], v0[3]); w.z = cvt_pk_bf16(v1[0], v1[1]); w.w = cvt_pk_bf16(v1[2], v1[3]);
;                     *(u32x4*)(rowp + bj * 128) = w; } }
	s_add_u32 s14, s26, 0x40080
	s_addc_u32 s15, s27, 0
	s_add_i32 s16, s17, s43
	s_mov_b32 m0, s16
	s_nop 0
	global_load_lds_dwordx4 v128, s[14:15]
	s_add_i32 m0, s16, 0x2000
	s_nop 0
	global_load_lds_dwordx4 v148, s[14:15]
	s_waitcnt vmcnt(6)
	s_barrier
	s_cmp_gt_u32 s61, 13
	v_mfma_f32_16x16x32_bf16 v[52:55], v[220:223], v[178:181], v[52:55]
	v_mfma_f32_16x16x32_bf16 v[48:51], v[228:231], v[178:181], v[48:51]
	v_mfma_f32_16x16x32_bf16 v[36:39], v[220:223], v[196:199], v[36:39]
	v_mfma_f32_16x16x32_bf16 v[32:35], v[228:231], v[196:199], v[32:35]
	v_mfma_f32_16x16x32_bf16 v[20:23], v[220:223], v[204:207], v[20:23]
	v_mfma_f32_16x16x32_bf16 v[16:19], v[228:231], v[204:207], v[16:19]
	v_mfma_f32_16x16x32_bf16 v[4:7], v[220:223], v[212:215], v[4:7]
	v_mfma_f32_16x16x32_bf16 v[0:3], v[228:231], v[212:215], v[0:3]
	v_mfma_f32_16x16x32_bf16 v[52:55], v[224:227], v[192:195], v[52:55]
	v_mfma_f32_16x16x32_bf16 v[48:51], v[232:235], v[192:195], v[48:51]
	v_mfma_f32_16x16x32_bf16 v[36:39], v[224:227], v[200:203], v[36:39]
	v_mfma_f32_16x16x32_bf16 v[32:35], v[232:235], v[200:203], v[32:35]
	v_mfma_f32_16x16x32_bf16 v[20:23], v[224:227], v[208:211], v[20:23]
	v_mfma_f32_16x16x32_bf16 v[16:19], v[232:235], v[208:211], v[16:19]
	v_mfma_f32_16x16x32_bf16 v[4:7], v[224:227], v[216:219], v[4:7]
	v_mfma_f32_16x16x32_bf16 v[0:3], v[232:235], v[216:219], v[0:3]
	s_barrier
	s_cbranch_scc0 .LBB0_1340
	v_lshl_add_u32 v162, s22, 8, v139
	v_ashrrev_i32_e32 v163, 31, v162
	v_lshl_add_u64 v[158:159], v[162:163], 2, s[0:1]
	global_load_dword v164, v[158:159], off
	global_load_dword v231, v[158:159], off offset:64
	global_load_dword v232, v[158:159], off offset:128
	global_load_dword v233, v[158:159], off offset:192
	global_load_dword v234, v[158:159], off offset:512
	global_load_dword v235, v[158:159], off offset:576
	global_load_dword v236, v[158:159], off offset:640
	global_load_dword v237, v[158:159], off offset:704
	v_lshl_or_b32 v160, s56, 8, v167
	v_ashrrev_i32_e32 v161, 31, v160
	s_mov_b32 s5, 0x80000
	s_mov_b64 s[14:15], 0x80000
	s_mov_b32 s56, s4
	s_mov_b32 s22, s6
	s_mov_b64 s[26:27], s[20:21]
	s_mov_b64 s[24:25], s[12:13]
	s_waitcnt vmcnt(0)
	v_fmamk_f32 v164, v164, 0x3a800000, v187
	v_cmp_gt_f32_e32 vcc, s67, v164
	v_mul_f32_e32 v165, 0x4b800000, v164
	s_nop 0
	v_cndmask_b32_e32 v164, v164, v165, vcc
	v_rsq_f32_e32 v164, v164
	s_nop 0
	v_mul_f32_e32 v165, 0x45800000, v164
	v_cndmask_b32_e32 v170, v164, v165, vcc
	v_lshlrev_b64 v[164:165], 12, v[162:163]
	v_lshl_add_u64 v[172:173], s[2:3], 0, v[164:165]
	v_lshlrev_b64 v[164:165], 1, v[160:161]
	v_lshl_add_u64 v[160:161], v[172:173], 0, v[164:165]
	v_pk_mul_f32 v[126:127], v[126:127], v[170:171] op_sel_hi:[1,0]
	v_pk_mul_f32 v[124:125], v[124:125], v[170:171] op_sel_hi:[1,0]
	v_pk_mul_f32 v[172:173], v[122:123], v[170:171] op_sel_hi:[1,0]
	v_pk_mul_f32 v[122:123], v[120:121], v[170:171] op_sel_hi:[1,0]
	v_cvt_pk_bf16_f32 v120, v124, v125
	v_cvt_pk_bf16_f32 v121, v126, v127
	v_cvt_pk_bf16_f32 v122, v122, v123
	v_cvt_pk_bf16_f32 v123, v172, v173
	global_store_dwordx4 v[160:161], v[120:123], off
	v_pk_mul_f32 v[118:119], v[118:119], v[170:171] op_sel_hi:[1,0]
	v_pk_mul_f32 v[116:117], v[116:117], v[170:171] op_sel_hi:[1,0]
	v_pk_mul_f32 v[120:121], v[114:115], v[170:171] op_sel_hi:[1,0]
	v_pk_mul_f32 v[114:115], v[112:113], v[170:171] op_sel_hi:[1,0]
	v_cvt_pk_bf16_f32 v112, v116, v117
	v_cvt_pk_bf16_f32 v113, v118, v119
	v_cvt_pk_bf16_f32 v114, v114, v115
	v_cvt_pk_bf16_f32 v115, v120, v121
	global_store_dwordx4 v[160:161], v[112:115], off offset:256
	s_nop 1
	v_mov_b32_e32 v114, v231
	s_nop 0
	v_or_b32_e32 v112, 16, v162
	v_ashrrev_i32_e32 v113, 31, v112
	v_lshlrev_b64 v[112:113], 12, v[112:113]
	v_lshl_add_u64 v[112:113], s[2:3], 0, v[112:113]
	v_lshl_add_u64 v[112:113], v[112:113], 0, v[164:165]
	v_fmamk_f32 v114, v114, 0x3a800000, v187
	v_cmp_gt_f32_e32 vcc, s67, v114
	v_mul_f32_e32 v115, 0x4b800000, v114
	s_nop 0
	v_cndmask_b32_e32 v114, v114, v115, vcc
	v_rsq_f32_e32 v114, v114
	s_nop 0
	v_mul_f32_e32 v115, 0x45800000, v114
	v_cndmask_b32_e32 v114, v114, v115, vcc
	v_pk_mul_f32 v[110:111], v[110:111], v[114:115] op_sel_hi:[1,0]
	v_pk_mul_f32 v[108:109], v[108:109], v[114:115] op_sel_hi:[1,0]
	v_pk_mul_f32 v[116:117], v[106:107], v[114:115] op_sel_hi:[1,0]
	v_pk_mul_f32 v[106:107], v[104:105], v[114:115] op_sel_hi:[1,0]
	v_cvt_pk_bf16_f32 v104, v108, v109
	v_cvt_pk_bf16_f32 v105, v110, v111
	v_cvt_pk_bf16_f32 v106, v106, v107
	v_cvt_pk_bf16_f32 v107, v116, v117
	global_store_dwordx4 v[112:113], v[104:107], off
	v_pk_mul_f32 v[102:103], v[102:103], v[114:115] op_sel_hi:[1,0]
	v_pk_mul_f32 v[100:101], v[100:101], v[114:115] op_sel_hi:[1,0]
	v_pk_mul_f32 v[104:105], v[98:99], v[114:115] op_sel_hi:[1,0]
	v_pk_mul_f32 v[98:99], v[96:97], v[114:115] op_sel_hi:[1,0]
	v_cvt_pk_bf16_f32 v96, v100, v101
	v_cvt_pk_bf16_f32 v97, v102, v103
	v_cvt_pk_bf16_f32 v98, v98, v99
	v_cvt_pk_bf16_f32 v99, v104, v105
	global_store_dwordx4 v[112:113], v[96:99], off offset:256
	s_nop 1
	v_mov_b32_e32 v98, v232
	s_nop 0
	v_or_b32_e32 v96, 32, v162
	v_ashrrev_i32_e32 v97, 31, v96
	v_lshlrev_b64 v[96:97], 12, v[96:97]
	v_lshl_add_u64 v[96:97], s[2:3], 0, v[96:97]
	v_lshl_add_u64 v[96:97], v[96:97], 0, v[164:165]
	v_fmamk_f32 v98, v98, 0x3a800000, v187
	v_cmp_gt_f32_e32 vcc, s67, v98
	v_mul_f32_e32 v99, 0x4b800000, v98
	s_nop 0
	v_cndmask_b32_e32 v98, v98, v99, vcc
	v_rsq_f32_e32 v98, v98
	s_nop 0
	v_mul_f32_e32 v99, 0x45800000, v98
	v_cndmask_b32_e32 v98, v98, v99, vcc
	v_pk_mul_f32 v[94:95], v[94:95], v[98:99] op_sel_hi:[1,0]
	v_pk_mul_f32 v[92:93], v[92:93], v[98:99] op_sel_hi:[1,0]
	v_pk_mul_f32 v[100:101], v[90:91], v[98:99] op_sel_hi:[1,0]
; __device__ __forceinline__ unsigned cvt_pk_bf16(float lo, float hi) { const f32x2_cv v = {lo, hi}; const bf16x2_cv b = __builtin_convertvector(v, bf16x2_cv); return __builtin_bit_cast(unsigned, b); }
; __device__ __forceinline__ float rstd_of(const float* rowss, int row) { return rsqrtf(rowss[row] * (1.0f / 1024.0f) + 1e-6f); }
;     __device__ __forceinline__ void operator()(const f32x4 (&acc)[2][2][4][2], const pg8::Unit& u, int wr, int wc, int fr, int fq) const {
;     ...
;             for (int m = 0; m < 4; ++m) {
;                 const int row = row0 + ai * 128 + m * 16;
;                 const float s = (MODE == 2) ? 1.0f : rstd_of(rowss, row);
;                 bf16_t* rowp = O + (size_t)row * ldc + col0;
; #pragma unroll
;                 for (int bj = 0; bj < 2; ++bj) {
;                     f32x4 v0 = acc[ai][bj][m][0] * s, v1 = acc[ai][bj][m][1] * s;
;                     if (MODE == 1) {
; #pragma unroll
;                         for (int j = 0; j < 4; ++j) { const float a = fmaxf(v0[j], 0.f), b = fmaxf(v1[j], 0.f); v0[j] = a * a; v1[j] = b * b; } }
;                     u32x4 w; w.x = cvt_pk_bf16(v0[0], v0[1]); w.y = cvt_pk_bf16(v0[2], v0[3]); w.z = cvt_pk_bf16(v1[0], v1[1]); w.w = cvt_pk_bf16(v1[2], v1[3]);
;                     *(u32x4*)(rowp + bj * 128) = w; } }
	v_pk_mul_f32 v[90:91], v[88:89], v[98:99] op_sel_hi:[1,0]
	v_cvt_pk_bf16_f32 v88, v92, v93
	v_cvt_pk_bf16_f32 v89, v94, v95
	v_cvt_pk_bf16_f32 v90, v90, v91
	v_cvt_pk_bf16_f32 v91, v100, v101
	global_store_dwordx4 v[96:97], v[88:91], off
	v_pk_mul_f32 v[86:87], v[86:87], v[98:99] op_sel_hi:[1,0]
	v_pk_mul_f32 v[84:85], v[84:85], v[98:99] op_sel_hi:[1,0]
	v_pk_mul_f32 v[88:89], v[82:83], v[98:99] op_sel_hi:[1,0]
	v_pk_mul_f32 v[82:83], v[80:81], v[98:99] op_sel_hi:[1,0]
	v_cvt_pk_bf16_f32 v80, v84, v85
	v_cvt_pk_bf16_f32 v81, v86, v87
	v_cvt_pk_bf16_f32 v82, v82, v83
	v_cvt_pk_bf16_f32 v83, v88, v89
	global_store_dwordx4 v[96:97], v[80:83], off offset:256
	s_nop 1
	v_mov_b32_e32 v82, v233
	s_nop 0
	v_or_b32_e32 v80, 48, v162
	v_ashrrev_i32_e32 v81, 31, v80
	v_lshlrev_b64 v[80:81], 12, v[80:81]
	v_lshl_add_u64 v[80:81], s[2:3], 0, v[80:81]
	v_lshl_add_u64 v[80:81], v[80:81], 0, v[164:165]
	v_fmamk_f32 v82, v82, 0x3a800000, v187
	v_cmp_gt_f32_e32 vcc, s67, v82
	v_mul_f32_e32 v83, 0x4b800000, v82
	s_nop 0
	v_cndmask_b32_e32 v82, v82, v83, vcc
	v_rsq_f32_e32 v82, v82
	s_nop 0
	v_mul_f32_e32 v83, 0x45800000, v82
	v_cndmask_b32_e32 v82, v82, v83, vcc
	v_pk_mul_f32 v[78:79], v[78:79], v[82:83] op_sel_hi:[1,0]
	v_pk_mul_f32 v[76:77], v[76:77], v[82:83] op_sel_hi:[1,0]
	v_pk_mul_f32 v[84:85], v[74:75], v[82:83] op_sel_hi:[1,0]
	v_pk_mul_f32 v[74:75], v[72:73], v[82:83] op_sel_hi:[1,0]
	v_cvt_pk_bf16_f32 v72, v76, v77
	v_cvt_pk_bf16_f32 v73, v78, v79
	v_cvt_pk_bf16_f32 v74, v74, v75
	v_cvt_pk_bf16_f32 v75, v84, v85
	global_store_dwordx4 v[80:81], v[72:75], off
	v_pk_mul_f32 v[70:71], v[70:71], v[82:83] op_sel_hi:[1,0]
	v_pk_mul_f32 v[68:69], v[68:69], v[82:83] op_sel_hi:[1,0]
	v_pk_mul_f32 v[72:73], v[66:67], v[82:83] op_sel_hi:[1,0]
	v_pk_mul_f32 v[66:67], v[64:65], v[82:83] op_sel_hi:[1,0]
	v_cvt_pk_bf16_f32 v64, v68, v69
	v_cvt_pk_bf16_f32 v65, v70, v71
	v_cvt_pk_bf16_f32 v66, v66, v67
	v_cvt_pk_bf16_f32 v67, v72, v73
	global_store_dwordx4 v[80:81], v[64:67], off offset:256
	s_nop 1
	v_mov_b32_e32 v64, v234
	s_nop 0
	v_lshl_add_u64 v[66:67], v[160:161], 0, s[14:15]
	s_mov_b64 s[14:15], 0x90000
	v_fmamk_f32 v64, v64, 0x3a800000, v187
	v_cmp_gt_f32_e32 vcc, s67, v64
	v_mul_f32_e32 v65, 0x4b800000, v64
	s_nop 0
	v_cndmask_b32_e32 v64, v64, v65, vcc
	v_rsq_f32_e32 v64, v64
	s_nop 0
	v_mul_f32_e32 v65, 0x45800000, v64
	v_cndmask_b32_e32 v64, v64, v65, vcc
	v_pk_mul_f32 v[60:61], v[60:61], v[64:65] op_sel_hi:[1,0]
	v_pk_mul_f32 v[62:63], v[62:63], v[64:65] op_sel_hi:[1,0]
	v_pk_mul_f32 v[68:69], v[58:59], v[64:65] op_sel_hi:[1,0]
	v_pk_mul_f32 v[58:59], v[56:57], v[64:65] op_sel_hi:[1,0]
	v_cvt_pk_bf16_f32 v56, v60, v61
	v_add_co_u32_e32 v60, vcc, s5, v160
	v_cvt_pk_bf16_f32 v57, v62, v63
	v_cvt_pk_bf16_f32 v58, v58, v59
	v_cvt_pk_bf16_f32 v59, v68, v69
	v_addc_co_u32_e32 v61, vcc, 0, v161, vcc
	global_store_dwordx4 v[60:61], v[56:59], off
	v_pk_mul_f32 v[54:55], v[54:55], v[64:65] op_sel_hi:[1,0]
	v_pk_mul_f32 v[52:53], v[52:53], v[64:65] op_sel_hi:[1,0]
	v_pk_mul_f32 v[56:57], v[50:51], v[64:65] op_sel_hi:[1,0]
	v_pk_mul_f32 v[50:51], v[48:49], v[64:65] op_sel_hi:[1,0]
	v_cvt_pk_bf16_f32 v48, v52, v53
	v_cvt_pk_bf16_f32 v49, v54, v55
	v_cvt_pk_bf16_f32 v50, v50, v51
	v_cvt_pk_bf16_f32 v51, v56, v57
	global_store_dwordx4 v[66:67], v[48:51], off offset:256
	s_nop 1
	v_mov_b32_e32 v48, v235
	s_mov_b32 s5, 0x90000
	v_lshl_add_u64 v[50:51], v[160:161], 0, s[14:15]
	s_mov_b64 s[14:15], 0xa0000
	v_fmamk_f32 v48, v48, 0x3a800000, v187
	v_cmp_gt_f32_e32 vcc, s67, v48
	v_mul_f32_e32 v49, 0x4b800000, v48
	s_nop 0
	v_cndmask_b32_e32 v48, v48, v49, vcc
	v_rsq_f32_e32 v48, v48
	s_nop 0
	v_mul_f32_e32 v49, 0x45800000, v48
; __device__ __forceinline__ unsigned cvt_pk_bf16(float lo, float hi) { const f32x2_cv v = {lo, hi}; const bf16x2_cv b = __builtin_convertvector(v, bf16x2_cv); return __builtin_bit_cast(unsigned, b); }
; #define PG8_WAIT_V(n) asm volatile("s_waitcnt vmcnt(" #n ")" ::: "memory")
; #define PG8_BAR __builtin_amdgcn_s_barrier()
; __device__ __forceinline__ float rstd_of(const float* rowss, int row) { return rsqrtf(rowss[row] * (1.0f / 1024.0f) + 1e-6f); }
; template <class Epi, class Sched, bool STAMP = false>
; __device__ __forceinline__ void gemm_phase(PG8_LAS unsigned char* lds, const Gemm g, const Sched& S, const Epi& E, unsigned long long* stamps) {
;     ...
;         if (!has_next) break;
; #pragma unroll
;         for (int a = 0; a < 2; ++a)
; #pragma unroll
;             for (int b = 0; b < 2; ++b)
; #pragma unroll
;                 for (int m = 0; m < 4; ++m)
; #pragma unroll
;                     for (int n = 0; n < 2; ++n) acc[a][b][m][n] = (f32x4){0.f, 0.f, 0.f, 0.f};
;         cur = nxt; cA = nA; cB = nB; ++ui;
;     }
;     PG8_WAIT_V(0);
;     if (wr == 0) PG8_BAR;
;     __device__ __forceinline__ void operator()(const f32x4 (&acc)[2][2][4][2], const pg8::Unit& u, int wr, int wc, int fr, int fq) const {
;     ...
;             for (int m = 0; m < 4; ++m) {
;                 const int row = row0 + ai * 128 + m * 16;
;                 const float s = (MODE == 2) ? 1.0f : rstd_of(rowss, row);
;                 bf16_t* rowp = O + (size_t)row * ldc + col0;
; #pragma unroll
;                 for (int bj = 0; bj < 2; ++bj) {
;                     f32x4 v0 = acc[ai][bj][m][0] * s, v1 = acc[ai][bj][m][1] * s;
;                     if (MODE == 1) {
; #pragma unroll
;                         for (int j = 0; j < 4; ++j) { const float a = fmaxf(v0[j], 0.f), b = fmaxf(v1[j], 0.f); v0[j] = a * a; v1[j] = b * b; } }
;                     u32x4 w; w.x = cvt_pk_bf16(v0[0], v0[1]); w.y = cvt_pk_bf16(v0[2], v0[3]); w.z = cvt_pk_bf16(v1[0], v1[1]); w.w = cvt_pk_bf16(v1[2], v1[3]);
;                     *(u32x4*)(rowp + bj * 128) = w; } }
	v_cndmask_b32_e32 v48, v48, v49, vcc
	v_pk_mul_f32 v[44:45], v[44:45], v[48:49] op_sel_hi:[1,0]
	v_pk_mul_f32 v[46:47], v[46:47], v[48:49] op_sel_hi:[1,0]
	v_pk_mul_f32 v[52:53], v[42:43], v[48:49] op_sel_hi:[1,0]
	v_pk_mul_f32 v[42:43], v[40:41], v[48:49] op_sel_hi:[1,0]
	v_cvt_pk_bf16_f32 v40, v44, v45
	v_add_co_u32_e32 v44, vcc, s5, v160
	v_cvt_pk_bf16_f32 v41, v46, v47
	v_cvt_pk_bf16_f32 v42, v42, v43
	v_cvt_pk_bf16_f32 v43, v52, v53
	v_addc_co_u32_e32 v45, vcc, 0, v161, vcc
	global_store_dwordx4 v[44:45], v[40:43], off
	v_pk_mul_f32 v[38:39], v[38:39], v[48:49] op_sel_hi:[1,0]
	v_pk_mul_f32 v[36:37], v[36:37], v[48:49] op_sel_hi:[1,0]
	v_pk_mul_f32 v[40:41], v[34:35], v[48:49] op_sel_hi:[1,0]
	v_pk_mul_f32 v[34:35], v[32:33], v[48:49] op_sel_hi:[1,0]
	v_cvt_pk_bf16_f32 v32, v36, v37
	v_cvt_pk_bf16_f32 v33, v38, v39
	v_cvt_pk_bf16_f32 v34, v34, v35
	v_cvt_pk_bf16_f32 v35, v40, v41
	global_store_dwordx4 v[50:51], v[32:35], off offset:256
	s_nop 1
	v_mov_b32_e32 v32, v236
	s_mov_b32 s5, 0xa0000
	v_lshl_add_u64 v[34:35], v[160:161], 0, s[14:15]
	s_mov_b64 s[14:15], 0xb0000
	v_fmamk_f32 v32, v32, 0x3a800000, v187
	v_cmp_gt_f32_e32 vcc, s67, v32
	v_mul_f32_e32 v33, 0x4b800000, v32
	s_nop 0
	v_cndmask_b32_e32 v32, v32, v33, vcc
	v_rsq_f32_e32 v32, v32
	s_nop 0
	v_mul_f32_e32 v33, 0x45800000, v32
	v_cndmask_b32_e32 v32, v32, v33, vcc
	v_pk_mul_f32 v[28:29], v[28:29], v[32:33] op_sel_hi:[1,0]
	v_pk_mul_f32 v[30:31], v[30:31], v[32:33] op_sel_hi:[1,0]
	v_pk_mul_f32 v[36:37], v[26:27], v[32:33] op_sel_hi:[1,0]
	v_pk_mul_f32 v[26:27], v[24:25], v[32:33] op_sel_hi:[1,0]
	v_cvt_pk_bf16_f32 v24, v28, v29
	v_add_co_u32_e32 v28, vcc, s5, v160
	v_cvt_pk_bf16_f32 v25, v30, v31
	v_cvt_pk_bf16_f32 v26, v26, v27
	v_cvt_pk_bf16_f32 v27, v36, v37
	v_addc_co_u32_e32 v29, vcc, 0, v161, vcc
	global_store_dwordx4 v[28:29], v[24:27], off
	v_pk_mul_f32 v[22:23], v[22:23], v[32:33] op_sel_hi:[1,0]
	v_pk_mul_f32 v[20:21], v[20:21], v[32:33] op_sel_hi:[1,0]
	v_pk_mul_f32 v[24:25], v[18:19], v[32:33] op_sel_hi:[1,0]
	v_pk_mul_f32 v[18:19], v[16:17], v[32:33] op_sel_hi:[1,0]
	v_cvt_pk_bf16_f32 v16, v20, v21
	v_cvt_pk_bf16_f32 v17, v22, v23
	v_cvt_pk_bf16_f32 v18, v18, v19
	v_cvt_pk_bf16_f32 v19, v24, v25
	global_store_dwordx4 v[34:35], v[16:19], off offset:256
	s_nop 1
	v_mov_b32_e32 v16, v237
	s_mov_b32 s5, 0xb0000
	v_lshl_add_u64 v[18:19], v[160:161], 0, s[14:15]
	v_fmamk_f32 v16, v16, 0x3a800000, v187
	v_cmp_gt_f32_e32 vcc, s67, v16
	v_mul_f32_e32 v17, 0x4b800000, v16
	s_nop 0
	v_cndmask_b32_e32 v16, v16, v17, vcc
	v_rsq_f32_e32 v16, v16
	s_nop 0
	v_mul_f32_e32 v17, 0x45800000, v16
	v_cndmask_b32_e32 v16, v16, v17, vcc
	v_pk_mul_f32 v[12:13], v[12:13], v[16:17] op_sel_hi:[1,0]
	v_pk_mul_f32 v[14:15], v[14:15], v[16:17] op_sel_hi:[1,0]
	v_pk_mul_f32 v[20:21], v[10:11], v[16:17] op_sel_hi:[1,0]
	v_pk_mul_f32 v[10:11], v[8:9], v[16:17] op_sel_hi:[1,0]
	v_cvt_pk_bf16_f32 v8, v12, v13
	v_add_co_u32_e32 v12, vcc, s5, v160
	v_cvt_pk_bf16_f32 v9, v14, v15
	v_cvt_pk_bf16_f32 v10, v10, v11
	v_cvt_pk_bf16_f32 v11, v20, v21
	v_addc_co_u32_e32 v13, vcc, 0, v161, vcc
	global_store_dwordx4 v[12:13], v[8:11], off
	v_pk_mul_f32 v[6:7], v[6:7], v[16:17] op_sel_hi:[1,0]
	v_pk_mul_f32 v[4:5], v[4:5], v[16:17] op_sel_hi:[1,0]
	v_pk_mul_f32 v[8:9], v[2:3], v[16:17] op_sel_hi:[1,0]
	v_pk_mul_f32 v[2:3], v[0:1], v[16:17] op_sel_hi:[1,0]
	v_cvt_pk_bf16_f32 v0, v4, v5
	v_cvt_pk_bf16_f32 v1, v6, v7
	v_cvt_pk_bf16_f32 v2, v2, v3
	v_cvt_pk_bf16_f32 v3, v8, v9
	s_and_b64 vcc, exec, s[38:39]
	global_store_dwordx4 v[18:19], v[0:3], off offset:256
	s_cbranch_vccz .LBB0_1337
	s_waitcnt vmcnt(0)
	s_cmpk_gt_u32 s42, 0xff
	s_cbranch_scc1 .LBB0_1344
	s_barrier
